# speedup vs baseline: 1.0139x; 1.0139x over previous
; #define PG8_STAGE(bufoff, gbase, voff) do { _Pragma("unroll") for (int _i = 0; _i < 2; ++_i) \
;         __builtin_amdgcn_global_load_lds((const unsigned*)((const char*)(gbase) + (voff)[_i]), (LAS unsigned*)(lds + (bufoff) + ldsw + _i * 8192), 16, 0, 0); } while (0)
; #define PG8_LDA(dst, b, h) do { _Pragma("unroll") for (int m = 0; m < 4; ++m) _Pragma("unroll") for (int k = 0; k < 2; ++k) dst[m][k] = *(const LAS bf16x8*)(lds + PG8_SA(b, h) + aoff + m * 2048 + k * 1024); } while (0)
; #define PG8_LDB(dst, b, h) do { _Pragma("unroll") for (int n = 0; n < 2; ++n) _Pragma("unroll") for (int k = 0; k < 2; ++k) dst[n][k] = *(const LAS bf16x8*)(lds + PG8_SB(b, h) + boff + n * 2048 + k * 1024); } while (0)
; #define PG8_MMA(ai, bj, At, Bt) do { __builtin_amdgcn_s_setprio(1); _Pragma("unroll") for (int m = 0; m < 4; ++m) _Pragma("unroll") for (int n = 0; n < 2; ++n) _Pragma("unroll") for (int k = 0; k < 2; ++k) \
;         acc[ai][bj][m][n] = __builtin_amdgcn_mfma_f32_16x16x32_bf16(Bt[n][k], At[m][k], acc[ai][bj][m][n], 0, 0, 0); __builtin_amdgcn_s_setprio(0); } while (0)
; #define PG8_WAIT_L(n) asm volatile("s_waitcnt lgkmcnt(" #n ")" ::: "memory")
; #define PG8_BAR __builtin_amdgcn_s_barrier()
; #define PG8_SCHED __builtin_amdgcn_sched_barrier(0)
; template <class Epi>
; DEV void gemm_phase(LAS unsigned char* lds, const Gemm g, const StaticOrder& S, const Epi& E) {
;     ...
;             PG8_LDB(B0, 0, 0); PG8_SCHED; PG8_LDA(At, 0, 0); PG8_STAGE(PG8_SA(1, 1), a1 + hstep, voffA);
;             PG8_WAIT_L(8); PG8_BAR; PG8_WAIT_L(0); PG8_MMA(0, 0, At, B0); PG8_BAR; PG8_SCHED;
;             PG8_LDB(B1, 0, 1); PG8_STAGE(PG8_SB(0, 0), b2, voffB);
;             PG8_BAR; PG8_WAIT_L(0); PG8_MMA(0, 1, At, B1); PG8_BAR;
;             PG8_LDA(At, 0, 1); PG8_STAGE(PG8_SA(0, 0), a2, voffA);
;             PG8_BAR; PG8_WAIT_L(0); PG8_MMA(1, 0, At, B0); PG8_BAR; PG8_SCHED;
.LBB0_61:
	s_add_u32 s28, s26, 0xfff80080
	s_addc_u32 s29, s27, -1
	s_add_i32 s49, 0, 0x10000
	v_add_u32_e32 v140, s49, v178
	ds_read_b128 v[128:131], v140
	ds_read_b128 v[132:135], v140 offset:1024
	ds_read_b128 v[136:139], v140 offset:2048
	ds_read_b128 v[140:143], v140 offset:3072
	s_cmp_eq_u32 s48, 28
	s_cselect_b32 s31, s15, s29
	s_cselect_b32 s30, s19, s28
	s_cselect_b32 s29, s17, s47
	s_cselect_b32 s28, s25, s46
	v_lshl_add_u64 v[158:159], s[26:27], 0, v[150:151]
	s_add_i32 m0, s37, 0xc000
	ds_read_b128 v[154:157], v181
	ds_read_b128 v[174:177], v181 offset:1024
	ds_read_b128 v[182:185], v181 offset:2048
	ds_read_b128 v[186:189], v181 offset:3072
	ds_read_b128 v[190:193], v181 offset:4096
	ds_read_b128 v[194:197], v181 offset:5120
	ds_read_b128 v[214:217], v181 offset:6144
	ds_read_b128 v[218:221], v181 offset:7168
	global_load_lds_dwordx4 v[158:159], off
	v_lshl_add_u64 v[158:159], s[26:27], 0, v[152:153]
	s_add_i32 m0, s37, 0xe000
	s_nop 0
	global_load_lds_dwordx4 v[158:159], off
	s_waitcnt lgkmcnt(8)
	s_barrier
	s_waitcnt lgkmcnt(0)
	s_setprio 1
	v_mfma_f32_16x16x32_bf16 v[124:127], v[128:131], v[154:157], v[124:127]
	v_mfma_f32_16x16x32_bf16 v[120:123], v[136:139], v[154:157], v[120:123]
	v_mfma_f32_16x16x32_bf16 v[108:111], v[128:131], v[182:185], v[108:111]
	v_mfma_f32_16x16x32_bf16 v[104:107], v[136:139], v[182:185], v[104:107]
	v_mfma_f32_16x16x32_bf16 v[92:95], v[128:131], v[190:193], v[92:95]
	v_mfma_f32_16x16x32_bf16 v[88:91], v[136:139], v[190:193], v[88:91]
	v_mfma_f32_16x16x32_bf16 v[76:79], v[128:131], v[214:217], v[76:79]
	v_mfma_f32_16x16x32_bf16 v[72:75], v[136:139], v[214:217], v[72:75]
	v_mfma_f32_16x16x32_bf16 v[124:127], v[132:135], v[174:177], v[124:127]
	v_mfma_f32_16x16x32_bf16 v[120:123], v[140:143], v[174:177], v[120:123]
	v_mfma_f32_16x16x32_bf16 v[108:111], v[132:135], v[186:189], v[108:111]
	v_mfma_f32_16x16x32_bf16 v[104:107], v[140:143], v[186:189], v[104:107]
	v_mfma_f32_16x16x32_bf16 v[92:95], v[132:135], v[194:197], v[92:95]
	v_mfma_f32_16x16x32_bf16 v[88:91], v[140:143], v[194:197], v[88:91]
	v_mfma_f32_16x16x32_bf16 v[76:79], v[132:135], v[218:221], v[76:79]
	v_mfma_f32_16x16x32_bf16 v[72:75], v[140:143], v[218:221], v[72:75]
	s_setprio 0
	s_barrier
	s_add_i32 s52, 0, 0x14000
	v_add_u32_e32 v158, s52, v178
	s_add_i32 s49, s49, s36
	ds_read_b128 v[222:225], v158
	ds_read_b128 v[226:229], v158 offset:1024
	ds_read_b128 v[230:233], v158 offset:2048
	ds_read_b128 v[234:237], v158 offset:3072
	v_lshl_add_u64 v[158:159], s[28:29], 0, v[160:161]
	s_mov_b32 m0, s49
	v_lshl_add_u64 v[238:239], s[28:29], 0, v[148:149]
	global_load_lds_dwordx4 v[158:159], off
	s_add_i32 m0, s49, 0x2000
	s_nop 0
	global_load_lds_dwordx4 v[238:239], off
	s_barrier
	s_waitcnt lgkmcnt(0)
	s_setprio 1
	v_mfma_f32_16x16x32_bf16 v[116:119], v[222:225], v[154:157], v[116:119]
	v_mfma_f32_16x16x32_bf16 v[112:115], v[230:233], v[154:157], v[112:115]
	v_mfma_f32_16x16x32_bf16 v[100:103], v[222:225], v[182:185], v[100:103]
	v_mfma_f32_16x16x32_bf16 v[96:99], v[230:233], v[182:185], v[96:99]
	v_mfma_f32_16x16x32_bf16 v[84:87], v[222:225], v[190:193], v[84:87]
	v_mfma_f32_16x16x32_bf16 v[80:83], v[230:233], v[190:193], v[80:83]
	v_mfma_f32_16x16x32_bf16 v[68:71], v[222:225], v[214:217], v[68:71]
	v_mfma_f32_16x16x32_bf16 v[64:67], v[230:233], v[214:217], v[64:67]
	v_mfma_f32_16x16x32_bf16 v[116:119], v[226:229], v[174:177], v[116:119]
	v_mfma_f32_16x16x32_bf16 v[112:115], v[234:237], v[174:177], v[112:115]
	v_mfma_f32_16x16x32_bf16 v[100:103], v[226:229], v[186:189], v[100:103]
	v_mfma_f32_16x16x32_bf16 v[96:99], v[234:237], v[186:189], v[96:99]
	v_mfma_f32_16x16x32_bf16 v[84:87], v[226:229], v[194:197], v[84:87]
	v_mfma_f32_16x16x32_bf16 v[80:83], v[234:237], v[194:197], v[80:83]
	v_mfma_f32_16x16x32_bf16 v[68:71], v[226:229], v[218:221], v[68:71]
	v_mfma_f32_16x16x32_bf16 v[64:67], v[234:237], v[218:221], v[64:67]
	s_setprio 0
	s_mov_b32 m0, s37
	v_lshl_add_u64 v[240:241], s[30:31], 0, v[144:145]
	s_barrier
	ds_read_b128 v[154:157], v181 offset:16384
	ds_read_b128 v[174:177], v181 offset:17408
	ds_read_b128 v[182:185], v181 offset:18432
	ds_read_b128 v[186:189], v181 offset:19456
	ds_read_b128 v[190:193], v181 offset:20480
	ds_read_b128 v[194:197], v181 offset:21504
	ds_read_b128 v[214:217], v181 offset:22528
	ds_read_b128 v[218:221], v181 offset:23552
	global_load_lds_dwordx4 v[240:241], off
	v_lshl_add_u64 v[242:243], s[30:31], 0, v[146:147]
	s_mov_b32 m0, s38
	s_nop 0
	global_load_lds_dwordx4 v[242:243], off
	s_barrier
	s_waitcnt lgkmcnt(0)
	s_setprio 1
	v_mfma_f32_16x16x32_bf16 v[60:63], v[128:131], v[154:157], v[60:63]
	v_mfma_f32_16x16x32_bf16 v[56:59], v[136:139], v[154:157], v[56:59]
	v_mfma_f32_16x16x32_bf16 v[44:47], v[128:131], v[182:185], v[44:47]
	v_mfma_f32_16x16x32_bf16 v[40:43], v[136:139], v[182:185], v[40:43]
	v_mfma_f32_16x16x32_bf16 v[28:31], v[128:131], v[190:193], v[28:31]
	v_mfma_f32_16x16x32_bf16 v[24:27], v[136:139], v[190:193], v[24:27]
	v_mfma_f32_16x16x32_bf16 v[12:15], v[128:131], v[214:217], v[12:15]
	v_mfma_f32_16x16x32_bf16 v[8:11], v[136:139], v[214:217], v[8:11]
	v_mfma_f32_16x16x32_bf16 v[60:63], v[132:135], v[174:177], v[60:63]
	v_mfma_f32_16x16x32_bf16 v[56:59], v[140:143], v[174:177], v[56:59]
	v_mfma_f32_16x16x32_bf16 v[44:47], v[132:135], v[186:189], v[44:47]
	v_mfma_f32_16x16x32_bf16 v[40:43], v[140:143], v[186:189], v[40:43]
	v_mfma_f32_16x16x32_bf16 v[28:31], v[132:135], v[194:197], v[28:31]
	v_mfma_f32_16x16x32_bf16 v[24:27], v[140:143], v[194:197], v[24:27]
	v_mfma_f32_16x16x32_bf16 v[12:15], v[132:135], v[218:221], v[12:15]
	v_mfma_f32_16x16x32_bf16 v[8:11], v[140:143], v[218:221], v[8:11]
	s_setprio 0
	s_barrier
; #define PG8_STAGE(bufoff, gbase, voff) do { _Pragma("unroll") for (int _i = 0; _i < 2; ++_i) \
;         __builtin_amdgcn_global_load_lds((const unsigned*)((const char*)(gbase) + (voff)[_i]), (LAS unsigned*)(lds + (bufoff) + ldsw + _i * 8192), 16, 0, 0); } while (0)
; #define PG8_LDA(dst, b, h) do { _Pragma("unroll") for (int m = 0; m < 4; ++m) _Pragma("unroll") for (int k = 0; k < 2; ++k) dst[m][k] = *(const LAS bf16x8*)(lds + PG8_SA(b, h) + aoff + m * 2048 + k * 1024); } while (0)
; #define PG8_LDB(dst, b, h) do { _Pragma("unroll") for (int n = 0; n < 2; ++n) _Pragma("unroll") for (int k = 0; k < 2; ++k) dst[n][k] = *(const LAS bf16x8*)(lds + PG8_SB(b, h) + boff + n * 2048 + k * 1024); } while (0)
; #define PG8_MMA(ai, bj, At, Bt) do { __builtin_amdgcn_s_setprio(1); _Pragma("unroll") for (int m = 0; m < 4; ++m) _Pragma("unroll") for (int n = 0; n < 2; ++n) _Pragma("unroll") for (int k = 0; k < 2; ++k) \
;         acc[ai][bj][m][n] = __builtin_amdgcn_mfma_f32_16x16x32_bf16(Bt[n][k], At[m][k], acc[ai][bj][m][n], 0, 0, 0); __builtin_amdgcn_s_setprio(0); } while (0)
; #define PG8_WAIT_V(n) asm volatile("s_waitcnt vmcnt(" #n ")" ::: "memory")
; #define PG8_WAIT_L(n) asm volatile("s_waitcnt lgkmcnt(" #n ")" ::: "memory")
; #define PG8_BAR __builtin_amdgcn_s_barrier()
; #define PG8_SCHED __builtin_amdgcn_sched_barrier(0)
; template <class Epi>
; DEV void gemm_phase(LAS unsigned char* lds, const Gemm g, const StaticOrder& S, const Epi& E) {
;     ...
;             PG8_STAGE(PG8_SB(0, 1), b2 + hstep, voffB);
;             PG8_WAIT_V(6); PG8_BAR; PG8_MMA(1, 1, At, B1); PG8_BAR;
;             PG8_LDB(B0, 1, 0); PG8_SCHED; PG8_LDA(At, 1, 0); PG8_STAGE(PG8_SA(0, 1), a2 + hstep, voffA);
;             PG8_WAIT_L(8); PG8_BAR; PG8_WAIT_L(0); PG8_MMA(0, 0, At, B0); PG8_BAR; PG8_SCHED;
;             PG8_LDB(B1, 1, 1); PG8_STAGE(PG8_SB(1, 0), b3, voffB);
;             PG8_BAR; PG8_WAIT_L(0); PG8_MMA(0, 1, At, B1); PG8_BAR;
;             PG8_LDA(At, 1, 1); PG8_STAGE(PG8_SA(1, 0), a3, voffA);
	s_add_u32 s50, s28, 0x80000
	s_addc_u32 s51, s29, 0
	s_add_i32 s49, s52, s36
	v_lshl_add_u64 v[128:129], s[50:51], 0, v[160:161]
	s_mov_b32 m0, s49
	s_nop 0
	global_load_lds_dwordx4 v[128:129], off
	v_lshl_add_u64 v[128:129], s[50:51], 0, v[148:149]
	s_add_i32 m0, s49, 0x2000
	s_nop 0
	global_load_lds_dwordx4 v[128:129], off
	s_waitcnt vmcnt(6)
	s_barrier
	s_setprio 1
	v_mfma_f32_16x16x32_bf16 v[52:55], v[222:225], v[154:157], v[52:55]
	v_mfma_f32_16x16x32_bf16 v[48:51], v[230:233], v[154:157], v[48:51]
	v_mfma_f32_16x16x32_bf16 v[36:39], v[222:225], v[182:185], v[36:39]
	v_mfma_f32_16x16x32_bf16 v[32:35], v[230:233], v[182:185], v[32:35]
	v_mfma_f32_16x16x32_bf16 v[20:23], v[222:225], v[190:193], v[20:23]
	v_mfma_f32_16x16x32_bf16 v[16:19], v[230:233], v[190:193], v[16:19]
	v_mfma_f32_16x16x32_bf16 v[4:7], v[222:225], v[214:217], v[4:7]
	v_mfma_f32_16x16x32_bf16 v[0:3], v[230:233], v[214:217], v[0:3]
	v_mfma_f32_16x16x32_bf16 v[52:55], v[226:229], v[174:177], v[52:55]
	v_mfma_f32_16x16x32_bf16 v[48:51], v[234:237], v[174:177], v[48:51]
	v_mfma_f32_16x16x32_bf16 v[36:39], v[226:229], v[186:189], v[36:39]
	v_mfma_f32_16x16x32_bf16 v[32:35], v[234:237], v[186:189], v[32:35]
	v_mfma_f32_16x16x32_bf16 v[20:23], v[226:229], v[194:197], v[20:23]
	v_mfma_f32_16x16x32_bf16 v[16:19], v[234:237], v[194:197], v[16:19]
	v_mfma_f32_16x16x32_bf16 v[4:7], v[226:229], v[218:221], v[4:7]
	v_mfma_f32_16x16x32_bf16 v[0:3], v[234:237], v[218:221], v[0:3]
	s_setprio 0
	s_add_i32 s49, 0, 0x18000
	v_add_u32_e32 v140, s49, v178
	s_barrier
	ds_read_b128 v[128:131], v140
	ds_read_b128 v[132:135], v140 offset:1024
	ds_read_b128 v[136:139], v140 offset:2048
	ds_read_b128 v[140:143], v140 offset:3072
	s_add_u32 s30, s30, 0x80000
	s_addc_u32 s31, s31, 0
	s_mov_b32 m0, s39
	v_lshl_add_u64 v[222:223], s[30:31], 0, v[144:145]
	ds_read_b128 v[154:157], v181 offset:32768
	ds_read_b128 v[174:177], v181 offset:33792
	ds_read_b128 v[182:185], v181 offset:34816
	ds_read_b128 v[186:189], v181 offset:35840
	ds_read_b128 v[190:193], v181 offset:36864
	ds_read_b128 v[194:197], v181 offset:37888
	ds_read_b128 v[214:217], v181 offset:38912
	ds_read_b128 v[218:221], v181 offset:39936
	global_load_lds_dwordx4 v[222:223], off
	v_lshl_add_u64 v[222:223], s[30:31], 0, v[146:147]
	s_mov_b32 m0, s40
	s_nop 0
	global_load_lds_dwordx4 v[222:223], off
	s_waitcnt lgkmcnt(8)
	s_barrier
	s_waitcnt lgkmcnt(0)
	s_setprio 1
	v_mfma_f32_16x16x32_bf16 v[124:127], v[128:131], v[154:157], v[124:127]
	v_mfma_f32_16x16x32_bf16 v[120:123], v[136:139], v[154:157], v[120:123]
	v_mfma_f32_16x16x32_bf16 v[108:111], v[128:131], v[182:185], v[108:111]
	v_mfma_f32_16x16x32_bf16 v[104:107], v[136:139], v[182:185], v[104:107]
	v_mfma_f32_16x16x32_bf16 v[92:95], v[128:131], v[190:193], v[92:95]
	v_mfma_f32_16x16x32_bf16 v[88:91], v[136:139], v[190:193], v[88:91]
	v_mfma_f32_16x16x32_bf16 v[76:79], v[128:131], v[214:217], v[76:79]
	v_mfma_f32_16x16x32_bf16 v[72:75], v[136:139], v[214:217], v[72:75]
	v_mfma_f32_16x16x32_bf16 v[124:127], v[132:135], v[174:177], v[124:127]
	v_mfma_f32_16x16x32_bf16 v[120:123], v[140:143], v[174:177], v[120:123]
	v_mfma_f32_16x16x32_bf16 v[108:111], v[132:135], v[186:189], v[108:111]
	v_mfma_f32_16x16x32_bf16 v[104:107], v[140:143], v[186:189], v[104:107]
	v_mfma_f32_16x16x32_bf16 v[92:95], v[132:135], v[194:197], v[92:95]
	v_mfma_f32_16x16x32_bf16 v[88:91], v[140:143], v[194:197], v[88:91]
	v_mfma_f32_16x16x32_bf16 v[76:79], v[132:135], v[218:221], v[76:79]
	v_mfma_f32_16x16x32_bf16 v[72:75], v[140:143], v[218:221], v[72:75]
	s_setprio 0
	s_barrier
	s_add_i32 s30, 0, 0x1c000
	s_add_i32 s31, s49, s36
	v_add_u32_e32 v234, s30, v178
	v_lshl_add_u64 v[158:159], v[158:159], 0, s[2:3]
	s_mov_b32 m0, s31
	ds_read_b128 v[222:225], v234
	ds_read_b128 v[226:229], v234 offset:1024
	ds_read_b128 v[230:233], v234 offset:2048
	ds_read_b128 v[234:237], v234 offset:3072
	global_load_lds_dwordx4 v[158:159], off
	v_lshl_add_u64 v[158:159], v[238:239], 0, s[2:3]
	s_add_i32 m0, s31, 0x2000
	s_nop 0
	global_load_lds_dwordx4 v[158:159], off
	s_barrier
	s_waitcnt lgkmcnt(0)
	s_setprio 1
	v_mfma_f32_16x16x32_bf16 v[116:119], v[222:225], v[154:157], v[116:119]
	v_mfma_f32_16x16x32_bf16 v[112:115], v[230:233], v[154:157], v[112:115]
	v_mfma_f32_16x16x32_bf16 v[100:103], v[222:225], v[182:185], v[100:103]
	v_mfma_f32_16x16x32_bf16 v[96:99], v[230:233], v[182:185], v[96:99]
	v_mfma_f32_16x16x32_bf16 v[84:87], v[222:225], v[190:193], v[84:87]
	v_mfma_f32_16x16x32_bf16 v[80:83], v[230:233], v[190:193], v[80:83]
	v_mfma_f32_16x16x32_bf16 v[68:71], v[222:225], v[214:217], v[68:71]
	v_mfma_f32_16x16x32_bf16 v[64:67], v[230:233], v[214:217], v[64:67]
	v_mfma_f32_16x16x32_bf16 v[116:119], v[226:229], v[174:177], v[116:119]
	v_mfma_f32_16x16x32_bf16 v[112:115], v[234:237], v[174:177], v[112:115]
	v_mfma_f32_16x16x32_bf16 v[100:103], v[226:229], v[186:189], v[100:103]
	v_mfma_f32_16x16x32_bf16 v[96:99], v[234:237], v[186:189], v[96:99]
	v_mfma_f32_16x16x32_bf16 v[84:87], v[226:229], v[194:197], v[84:87]
	v_mfma_f32_16x16x32_bf16 v[80:83], v[234:237], v[194:197], v[80:83]
	v_mfma_f32_16x16x32_bf16 v[68:71], v[226:229], v[218:221], v[68:71]
	v_mfma_f32_16x16x32_bf16 v[64:67], v[234:237], v[218:221], v[64:67]
	s_setprio 0
	s_mov_b32 m0, s41
	v_lshl_add_u64 v[158:159], v[240:241], 0, s[2:3]
	s_barrier
	ds_read_b128 v[154:157], v181 offset:49152
	ds_read_b128 v[174:177], v181 offset:50176
	ds_read_b128 v[182:185], v181 offset:51200
	ds_read_b128 v[186:189], v181 offset:52224
	ds_read_b128 v[190:193], v181 offset:53248
	ds_read_b128 v[194:197], v181 offset:54272
	ds_read_b128 v[214:217], v181 offset:55296
	ds_read_b128 v[218:221], v181 offset:56320
	global_load_lds_dwordx4 v[158:159], off
	v_lshl_add_u64 v[158:159], v[242:243], 0, s[2:3]
	s_mov_b32 m0, s42
	s_nop 0
	global_load_lds_dwordx4 v[158:159], off
	s_barrier
; DEV bf16x8 pack8(f32x4 a, f32x4 b) { u32x4 w; w.x = cvt_pk_bf16(a[0], a[1]); w.y = cvt_pk_bf16(a[2], a[3]); w.z = cvt_pk_bf16(b[0], b[1]); w.w = cvt_pk_bf16(b[2], b[3]); return __builtin_bit_cast(bf16x8, w); }
; #define PG8_WAIT_V(n) asm volatile("s_waitcnt vmcnt(" #n ")" ::: "memory")
; #define PG8_WAIT_L(n) asm volatile("s_waitcnt lgkmcnt(" #n ")" ::: "memory")
; #define PG8_BAR __builtin_amdgcn_s_barrier()
; template <class Epi>
; DEV void gemm_phase(LAS unsigned char* lds, const Gemm g, const StaticOrder& S, const Epi& E) {
;     ...
;             PG8_BAR; PG8_WAIT_L(0); PG8_MMA(1, 0, At, B0); PG8_BAR; PG8_SCHED;
;             PG8_STAGE(PG8_SB(1, 1), b3 + hstep, voffB);
;             PG8_WAIT_V(6); PG8_BAR; PG8_MMA(1, 1, At, B1); PG8_BAR;
;         }
;     DEV void operator()(AccRef acc, const pg8::Unit& u, int wr, int wc, int fr, int fq) const {
;         const int row0 = u.pm * 256 + wr * 64 + fr, col0 = u.pn * 256 + wc * 32 + 8 * fq;
; #pragma unroll
;         for (int am = 0; am < 4; ++am) { const int ai = am >> 1, m0 = (am & 1) * 2;
;             f32x4 bv[4][2][2];
; #pragma unroll
;             for (int m = m0; m < m0 + 2; ++m)
; #pragma unroll
;                 for (int bj = 0; bj < 2; ++bj)
; #pragma unroll
;                     for (int n = 0; n < 2; ++n) bv[m][bj][n] = *(const f32x4*)(base + (size_t)(row0 + ai * 128 + m * 16) * 2048 + col0 + bj * 128 + n * 4);
; #pragma unroll
;             for (int m = m0; m < m0 + 2; ++m) { const size_t off = (size_t)(row0 + ai * 128 + m * 16) * 2048 + col0; float sq = 0.f;
; #pragma unroll
;                 for (int bj = 0; bj < 2; ++bj) { const f32x4 o0 = bv[m][bj][0] + scale * acc[ai][bj][m][0], o1 = bv[m][bj][1] + scale * acc[ai][bj][m][1];
;                     *(f32x4*)(out + off + bj * 128) = o0; *(f32x4*)(out + off + bj * 128 + 4) = o1;
;                     if (xb) { *(u32x4*)(xb + off + bj * 128) = __builtin_bit_cast(u32x4, pack8(o0, o1));
;                         sq += (o0[0] * o0[0] + o0[1] * o0[1] + o0[2] * o0[2] + o0[3] * o0[3]) + (o1[0] * o1[0] + o1[1] * o1[1] + o1[2] * o1[2] + o1[3] * o1[3]); } }
;                 if (ssout) { sq += __shfl_xor(sq, 16); sq += __shfl_xor(sq, 32);
;                     if (fq == 0) { if (red) red[(ai * 128 + wr * 64 + m * 16 + fr) * 4 + wc] = sq; else atomicAdd(ssout + (size_t)(row0 + ai * 128 + m * 16) * 8 + u.pn, sq); } } }
	s_waitcnt lgkmcnt(0)
	s_setprio 1
	v_mfma_f32_16x16x32_bf16 v[60:63], v[128:131], v[154:157], v[60:63]
	v_mfma_f32_16x16x32_bf16 v[56:59], v[136:139], v[154:157], v[56:59]
	v_mfma_f32_16x16x32_bf16 v[44:47], v[128:131], v[182:185], v[44:47]
	v_mfma_f32_16x16x32_bf16 v[40:43], v[136:139], v[182:185], v[40:43]
	v_mfma_f32_16x16x32_bf16 v[28:31], v[128:131], v[190:193], v[28:31]
	v_mfma_f32_16x16x32_bf16 v[24:27], v[136:139], v[190:193], v[24:27]
	v_mfma_f32_16x16x32_bf16 v[12:15], v[128:131], v[214:217], v[12:15]
	v_mfma_f32_16x16x32_bf16 v[8:11], v[136:139], v[214:217], v[8:11]
	v_mfma_f32_16x16x32_bf16 v[60:63], v[132:135], v[174:177], v[60:63]
	v_mfma_f32_16x16x32_bf16 v[56:59], v[140:143], v[174:177], v[56:59]
	v_mfma_f32_16x16x32_bf16 v[44:47], v[132:135], v[186:189], v[44:47]
	v_mfma_f32_16x16x32_bf16 v[40:43], v[140:143], v[186:189], v[40:43]
	v_mfma_f32_16x16x32_bf16 v[28:31], v[132:135], v[194:197], v[28:31]
	v_mfma_f32_16x16x32_bf16 v[24:27], v[140:143], v[194:197], v[24:27]
	v_mfma_f32_16x16x32_bf16 v[12:15], v[132:135], v[218:221], v[12:15]
	v_mfma_f32_16x16x32_bf16 v[8:11], v[140:143], v[218:221], v[8:11]
	s_setprio 0
	s_barrier
	s_add_u32 s28, s28, 0x80080
	s_addc_u32 s29, s29, 0
	s_add_i32 s30, s30, s36
	v_lshl_add_u64 v[128:129], s[28:29], 0, v[160:161]
	s_mov_b32 m0, s30
	s_nop 0
	global_load_lds_dwordx4 v[128:129], off
	v_lshl_add_u64 v[128:129], s[28:29], 0, v[148:149]
	s_add_i32 m0, s30, 0x2000
	s_nop 0
	global_load_lds_dwordx4 v[128:129], off
	s_waitcnt vmcnt(6)
	s_barrier
	s_setprio 1
	v_mfma_f32_16x16x32_bf16 v[52:55], v[222:225], v[154:157], v[52:55]
	v_mfma_f32_16x16x32_bf16 v[48:51], v[230:233], v[154:157], v[48:51]
	v_mfma_f32_16x16x32_bf16 v[36:39], v[222:225], v[182:185], v[36:39]
	v_mfma_f32_16x16x32_bf16 v[32:35], v[230:233], v[182:185], v[32:35]
	v_mfma_f32_16x16x32_bf16 v[20:23], v[222:225], v[190:193], v[20:23]
	v_mfma_f32_16x16x32_bf16 v[16:19], v[230:233], v[190:193], v[16:19]
	v_mfma_f32_16x16x32_bf16 v[4:7], v[222:225], v[214:217], v[4:7]
	v_mfma_f32_16x16x32_bf16 v[0:3], v[230:233], v[214:217], v[0:3]
	v_mfma_f32_16x16x32_bf16 v[52:55], v[226:229], v[174:177], v[52:55]
	v_mfma_f32_16x16x32_bf16 v[48:51], v[234:237], v[174:177], v[48:51]
	v_mfma_f32_16x16x32_bf16 v[36:39], v[226:229], v[186:189], v[36:39]
	v_mfma_f32_16x16x32_bf16 v[32:35], v[234:237], v[186:189], v[32:35]
	v_mfma_f32_16x16x32_bf16 v[20:23], v[226:229], v[194:197], v[20:23]
	v_mfma_f32_16x16x32_bf16 v[16:19], v[234:237], v[194:197], v[16:19]
	v_mfma_f32_16x16x32_bf16 v[4:7], v[226:229], v[218:221], v[4:7]
	v_mfma_f32_16x16x32_bf16 v[0:3], v[234:237], v[218:221], v[0:3]
	s_setprio 0
	s_add_i32 s48, s48, 2
	s_add_u32 s26, s26, 0x100
	s_addc_u32 s27, s27, 0
	s_add_u32 s46, s46, 0x100
	s_addc_u32 s47, s47, 0
	s_cmp_gt_u32 s48, 29
	s_barrier
	s_cbranch_scc0 .LBB0_61
	v_lshl_add_u32 v156, s24, 8, v167
	v_lshl_or_b32 v154, s14, 8, v179
	v_readlane_b32 s24, v254, 16
	v_ashrrev_i32_e32 v155, 31, v154
	v_readlane_b32 s25, v254, 17
	v_ashrrev_i32_e32 v157, 31, v156
	v_lshlrev_b64 v[128:129], 13, v[156:157]
	v_lshl_add_u64 v[158:159], v[154:155], 2, s[24:25]
	v_lshl_add_u64 v[214:215], v[158:159], 0, v[128:129]
	global_load_dwordx4 v[182:185], v[214:215], off offset:16
	global_load_dwordx4 v[186:189], v[214:215], off
	global_load_dwordx4 v[190:193], v[214:215], off offset:528
	global_load_dwordx4 v[194:197], v[214:215], off offset:512
	v_or_b32_e32 v174, 16, v156
	v_ashrrev_i32_e32 v175, 31, v174
	v_lshlrev_b64 v[128:129], 13, v[174:175]
	v_lshl_add_u64 v[176:177], v[158:159], 0, v[128:129]
	global_load_dwordx4 v[136:139], v[176:177], off offset:16
	global_load_dwordx4 v[140:143], v[176:177], off
	global_load_dwordx4 v[128:131], v[176:177], off offset:528
	global_load_dwordx4 v[132:135], v[176:177], off offset:512
	v_lshlrev_b64 v[216:217], 11, v[156:157]
	v_readlane_b32 s24, v250, 9
	v_lshl_add_u64 v[216:217], v[216:217], 0, v[154:155]
	v_readlane_b32 s25, v250, 10
	v_cmp_lt_i32_e32 vcc, v208, v206
	s_ashr_i32 s15, s14, 31
	s_waitcnt vmcnt(0)
	v_pk_add_f32 v[120:121], v[120:121], v[182:183]
	v_pk_add_f32 v[126:127], v[126:127], v[188:189]
	v_pk_add_f32 v[124:125], v[124:125], v[186:187]
	v_pk_add_f32 v[122:123], v[122:123], v[184:185]
	global_store_dwordx4 v[214:215], v[124:127], off
	global_store_dwordx4 v[214:215], v[120:123], off offset:16
	v_cvt_pk_bf16_f32 v184, v120, v121
	v_cvt_pk_bf16_f32 v182, v124, v125
	v_mul_f32_e32 v121, v121, v121
	v_cvt_pk_bf16_f32 v183, v126, v127
	v_cvt_pk_bf16_f32 v185, v122, v123
	v_lshl_add_u64 v[186:187], v[216:217], 1, s[24:25]
	v_fmac_f32_e32 v121, v120, v120
	v_pk_add_f32 v[118:119], v[118:119], v[196:197]
	v_pk_add_f32 v[116:117], v[116:117], v[194:195]
	v_pk_add_f32 v[112:113], v[112:113], v[190:191]
	global_store_dwordx4 v[186:187], v[182:185], off
	v_mul_f32_e32 v125, v125, v125
	v_fmac_f32_e32 v121, v122, v122
	v_pk_add_f32 v[114:115], v[114:115], v[192:193]
	global_store_dwordx4 v[214:215], v[116:119], off offset:512
	global_store_dwordx4 v[214:215], v[112:115], off offset:528
	v_cvt_pk_bf16_f32 v120, v116, v117
	v_cvt_pk_bf16_f32 v122, v112, v113
	v_mul_f32_e32 v117, v117, v117
	v_mul_f32_e32 v113, v113, v113
	v_fmac_f32_e32 v125, v124, v124
	v_fmac_f32_e32 v117, v116, v116
	v_fmac_f32_e32 v113, v112, v112
	v_fmac_f32_e32 v125, v126, v126
	v_fmac_f32_e32 v117, v118, v118
	v_fmac_f32_e32 v113, v114, v114
	v_fmac_f32_e32 v125, v127, v127
	v_fmac_f32_e32 v121, v123, v123
	v_fmac_f32_e32 v117, v119, v119
	v_fmac_f32_e32 v113, v115, v115
	v_add_f32_e32 v124, v125, v121
	v_add_f32_e32 v112, v117, v113
	v_cndmask_b32_e32 v113, v204, v208, vcc
	v_cvt_pk_bf16_f32 v121, v118, v119
	v_add_f32_e32 v112, v124, v112
	v_lshlrev_b32_e32 v118, 2, v113
	ds_bpermute_b32 v113, v118, v112
	v_cmp_lt_i32_e32 vcc, v207, v206
	v_cvt_pk_bf16_f32 v123, v114, v115
	global_store_dwordx4 v[186:187], v[120:123], off offset:256
	s_waitcnt lgkmcnt(0)
	v_add_f32_e32 v112, v112, v113
	v_cndmask_b32_e32 v113, v204, v207, vcc
	v_lshlrev_b32_e32 v119, 2, v113
	ds_bpermute_b32 v113, v119, v112
	s_and_saveexec_b64 s[24:25], s[6:7]
	s_cbranch_execz .LBB0_67
	s_waitcnt lgkmcnt(0)
	v_add_f32_e32 v112, v112, v113
	s_mov_b64 s[26:27], -1
	s_and_b64 vcc, exec, s[12:13]
	s_cbranch_vccz .LBB0_65
	v_readlane_b32 s26, v250, 37
	v_lshlrev_b64 v[114:115], 5, v[156:157]
	v_readlane_b32 s27, v250, 38
	s_nop 1
	v_lshl_add_u64 v[114:115], s[26:27], 0, v[114:115]
	v_lshl_add_u64 v[114:115], s[14:15], 2, v[114:115]
	global_atomic_add_f32 v[114:115], v112, off
	s_mov_b64 s[26:27], 0

; #define PG8_STAGE(bufoff, gbase, voff) do { _Pragma("unroll") for (int _i = 0; _i < 2; ++_i) \
;         __builtin_amdgcn_global_load_lds((const unsigned*)((const char*)(gbase) + (voff)[_i]), (LAS unsigned*)(lds + (bufoff) + ldsw + _i * 8192), 16, 0, 0); } while (0)
; #define PG8_LDA(dst, b, h) do { _Pragma("unroll") for (int m = 0; m < 4; ++m) _Pragma("unroll") for (int k = 0; k < 2; ++k) dst[m][k] = *(const LAS bf16x8*)(lds + PG8_SA(b, h) + aoff + m * 2048 + k * 1024); } while (0)
; #define PG8_LDB(dst, b, h) do { _Pragma("unroll") for (int n = 0; n < 2; ++n) _Pragma("unroll") for (int k = 0; k < 2; ++k) dst[n][k] = *(const LAS bf16x8*)(lds + PG8_SB(b, h) + boff + n * 2048 + k * 1024); } while (0)
; #define PG8_MMA(ai, bj, At, Bt) do { __builtin_amdgcn_s_setprio(1); _Pragma("unroll") for (int m = 0; m < 4; ++m) _Pragma("unroll") for (int n = 0; n < 2; ++n) _Pragma("unroll") for (int k = 0; k < 2; ++k) \
;         acc[ai][bj][m][n] = __builtin_amdgcn_mfma_f32_16x16x32_bf16(Bt[n][k], At[m][k], acc[ai][bj][m][n], 0, 0, 0); __builtin_amdgcn_s_setprio(0); } while (0)
; #define PG8_WAIT_L(n) asm volatile("s_waitcnt lgkmcnt(" #n ")" ::: "memory")
; #define PG8_BAR __builtin_amdgcn_s_barrier()
; #define PG8_SCHED __builtin_amdgcn_sched_barrier(0)
; template <class Epi>
; DEV void gemm_phase(LAS unsigned char* lds, const Gemm g, const StaticOrder& S, const Epi& E) {
;     ...
;             PG8_LDB(B0, 0, 0); PG8_SCHED; PG8_LDA(At, 0, 0); PG8_STAGE(PG8_SA(1, 1), a1 + hstep, voffA);
;             PG8_WAIT_L(8); PG8_BAR; PG8_WAIT_L(0); PG8_MMA(0, 0, At, B0); PG8_BAR; PG8_SCHED;
;             PG8_LDB(B1, 0, 1); PG8_STAGE(PG8_SB(0, 0), b2, voffB);
;             PG8_BAR; PG8_WAIT_L(0); PG8_MMA(0, 1, At, B1); PG8_BAR;
;             PG8_LDA(At, 0, 1); PG8_STAGE(PG8_SA(0, 0), a2, voffA);
;             PG8_BAR; PG8_WAIT_L(0); PG8_MMA(1, 0, At, B0); PG8_BAR; PG8_SCHED;
.LBB0_152:
	s_add_u32 s20, s18, 0xfff80080
	s_addc_u32 s21, s19, -1
	s_add_i32 s41, 0, 0x10000
	v_add_u32_e32 v140, s41, v176
	ds_read_b128 v[128:131], v140
	ds_read_b128 v[132:135], v140 offset:1024
	ds_read_b128 v[136:139], v140 offset:2048
	ds_read_b128 v[140:143], v140 offset:3072
	s_cmp_eq_u32 s40, 28
	s_cselect_b32 s23, s5, s21
	s_cselect_b32 s22, s11, s20
	s_cselect_b32 s21, s9, s39
	s_cselect_b32 s20, s37, s38
	v_lshl_add_u64 v[158:159], s[18:19], 0, v[154:155]
	s_add_i32 m0, s17, 0xc000
	ds_read_b128 v[180:183], v178
	ds_read_b128 v[184:187], v178 offset:1024
	ds_read_b128 v[188:191], v178 offset:2048
	ds_read_b128 v[192:195], v178 offset:3072
	ds_read_b128 v[214:217], v178 offset:4096
	ds_read_b128 v[218:221], v178 offset:5120
	ds_read_b128 v[222:225], v178 offset:6144
	ds_read_b128 v[226:229], v178 offset:7168
	global_load_lds_dwordx4 v[158:159], off
	v_lshl_add_u64 v[158:159], s[18:19], 0, v[156:157]
	s_add_i32 m0, s17, 0xe000
	s_nop 0
	global_load_lds_dwordx4 v[158:159], off
	s_waitcnt lgkmcnt(8)
	s_barrier
	s_waitcnt lgkmcnt(0)
	s_setprio 1
	v_mfma_f32_16x16x32_bf16 v[124:127], v[128:131], v[180:183], v[124:127]
	v_mfma_f32_16x16x32_bf16 v[120:123], v[136:139], v[180:183], v[120:123]
	v_mfma_f32_16x16x32_bf16 v[108:111], v[128:131], v[188:191], v[108:111]
	v_mfma_f32_16x16x32_bf16 v[104:107], v[136:139], v[188:191], v[104:107]
	v_mfma_f32_16x16x32_bf16 v[92:95], v[128:131], v[214:217], v[92:95]
	v_mfma_f32_16x16x32_bf16 v[88:91], v[136:139], v[214:217], v[88:91]
	v_mfma_f32_16x16x32_bf16 v[76:79], v[128:131], v[222:225], v[76:79]
	v_mfma_f32_16x16x32_bf16 v[72:75], v[136:139], v[222:225], v[72:75]
	v_mfma_f32_16x16x32_bf16 v[124:127], v[132:135], v[184:187], v[124:127]
	v_mfma_f32_16x16x32_bf16 v[120:123], v[140:143], v[184:187], v[120:123]
	v_mfma_f32_16x16x32_bf16 v[108:111], v[132:135], v[192:195], v[108:111]
	v_mfma_f32_16x16x32_bf16 v[104:107], v[140:143], v[192:195], v[104:107]
	v_mfma_f32_16x16x32_bf16 v[92:95], v[132:135], v[218:221], v[92:95]
	v_mfma_f32_16x16x32_bf16 v[88:91], v[140:143], v[218:221], v[88:91]
	v_mfma_f32_16x16x32_bf16 v[76:79], v[132:135], v[226:229], v[76:79]
	v_mfma_f32_16x16x32_bf16 v[72:75], v[140:143], v[226:229], v[72:75]
	s_setprio 0
	s_barrier
	s_add_i32 s44, 0, 0x14000
	v_add_u32_e32 v158, s44, v176
	s_add_i32 s41, s41, s26
	ds_read_b128 v[230:233], v158
	ds_read_b128 v[234:237], v158 offset:1024
	ds_read_b128 v[238:241], v158 offset:2048
	ds_read_b128 v[242:245], v158 offset:3072
	v_lshl_add_u64 v[158:159], s[20:21], 0, v[160:161]
	s_mov_b32 m0, s41
	v_lshl_add_u64 v[174:175], s[20:21], 0, v[144:145]
	global_load_lds_dwordx4 v[158:159], off
	s_add_i32 m0, s41, 0x2000
	s_nop 0
	global_load_lds_dwordx4 v[174:175], off
	s_barrier
	s_waitcnt lgkmcnt(0)
	s_setprio 1
	v_mfma_f32_16x16x32_bf16 v[116:119], v[230:233], v[180:183], v[116:119]
	v_mfma_f32_16x16x32_bf16 v[112:115], v[238:241], v[180:183], v[112:115]
	v_mfma_f32_16x16x32_bf16 v[100:103], v[230:233], v[188:191], v[100:103]
	v_mfma_f32_16x16x32_bf16 v[96:99], v[238:241], v[188:191], v[96:99]
	v_mfma_f32_16x16x32_bf16 v[84:87], v[230:233], v[214:217], v[84:87]
	v_mfma_f32_16x16x32_bf16 v[80:83], v[238:241], v[214:217], v[80:83]
	v_mfma_f32_16x16x32_bf16 v[68:71], v[230:233], v[222:225], v[68:71]
	v_mfma_f32_16x16x32_bf16 v[64:67], v[238:241], v[222:225], v[64:67]
	v_mfma_f32_16x16x32_bf16 v[116:119], v[234:237], v[184:187], v[116:119]
	v_mfma_f32_16x16x32_bf16 v[112:115], v[242:245], v[184:187], v[112:115]
	v_mfma_f32_16x16x32_bf16 v[100:103], v[234:237], v[192:195], v[100:103]
	v_mfma_f32_16x16x32_bf16 v[96:99], v[242:245], v[192:195], v[96:99]
	v_mfma_f32_16x16x32_bf16 v[84:87], v[234:237], v[218:221], v[84:87]
	v_mfma_f32_16x16x32_bf16 v[80:83], v[242:245], v[218:221], v[80:83]
	v_mfma_f32_16x16x32_bf16 v[68:71], v[234:237], v[226:229], v[68:71]
	v_mfma_f32_16x16x32_bf16 v[64:67], v[242:245], v[226:229], v[64:67]
	s_setprio 0
	s_mov_b32 m0, s17
	v_lshl_add_u64 v[196:197], s[22:23], 0, v[160:161]
	s_barrier
	ds_read_b128 v[180:183], v178 offset:16384
	ds_read_b128 v[184:187], v178 offset:17408
	ds_read_b128 v[188:191], v178 offset:18432
	ds_read_b128 v[192:195], v178 offset:19456
	ds_read_b128 v[214:217], v178 offset:20480
	ds_read_b128 v[218:221], v178 offset:21504
	ds_read_b128 v[222:225], v178 offset:22528
	ds_read_b128 v[226:229], v178 offset:23552
	global_load_lds_dwordx4 v[196:197], off
	v_lshl_add_u64 v[246:247], s[22:23], 0, v[144:145]
	s_mov_b32 m0, s27
	s_nop 0
	global_load_lds_dwordx4 v[246:247], off
	s_barrier
	s_waitcnt lgkmcnt(0)
	s_setprio 1
	v_mfma_f32_16x16x32_bf16 v[60:63], v[128:131], v[180:183], v[60:63]
	v_mfma_f32_16x16x32_bf16 v[56:59], v[136:139], v[180:183], v[56:59]
	v_mfma_f32_16x16x32_bf16 v[44:47], v[128:131], v[188:191], v[44:47]
	v_mfma_f32_16x16x32_bf16 v[40:43], v[136:139], v[188:191], v[40:43]
	v_mfma_f32_16x16x32_bf16 v[28:31], v[128:131], v[214:217], v[28:31]
	v_mfma_f32_16x16x32_bf16 v[24:27], v[136:139], v[214:217], v[24:27]
	v_mfma_f32_16x16x32_bf16 v[12:15], v[128:131], v[222:225], v[12:15]
	v_mfma_f32_16x16x32_bf16 v[8:11], v[136:139], v[222:225], v[8:11]
	v_mfma_f32_16x16x32_bf16 v[60:63], v[132:135], v[184:187], v[60:63]
	v_mfma_f32_16x16x32_bf16 v[56:59], v[140:143], v[184:187], v[56:59]
	v_mfma_f32_16x16x32_bf16 v[44:47], v[132:135], v[192:195], v[44:47]
	v_mfma_f32_16x16x32_bf16 v[40:43], v[140:143], v[192:195], v[40:43]
	v_mfma_f32_16x16x32_bf16 v[28:31], v[132:135], v[218:221], v[28:31]
	v_mfma_f32_16x16x32_bf16 v[24:27], v[140:143], v[218:221], v[24:27]
	v_mfma_f32_16x16x32_bf16 v[12:15], v[132:135], v[226:229], v[12:15]
	v_mfma_f32_16x16x32_bf16 v[8:11], v[140:143], v[226:229], v[8:11]
	s_setprio 0
	s_barrier
; #define PG8_STAGE(bufoff, gbase, voff) do { _Pragma("unroll") for (int _i = 0; _i < 2; ++_i) \
;         __builtin_amdgcn_global_load_lds((const unsigned*)((const char*)(gbase) + (voff)[_i]), (LAS unsigned*)(lds + (bufoff) + ldsw + _i * 8192), 16, 0, 0); } while (0)
; #define PG8_LDA(dst, b, h) do { _Pragma("unroll") for (int m = 0; m < 4; ++m) _Pragma("unroll") for (int k = 0; k < 2; ++k) dst[m][k] = *(const LAS bf16x8*)(lds + PG8_SA(b, h) + aoff + m * 2048 + k * 1024); } while (0)
; #define PG8_LDB(dst, b, h) do { _Pragma("unroll") for (int n = 0; n < 2; ++n) _Pragma("unroll") for (int k = 0; k < 2; ++k) dst[n][k] = *(const LAS bf16x8*)(lds + PG8_SB(b, h) + boff + n * 2048 + k * 1024); } while (0)
; #define PG8_MMA(ai, bj, At, Bt) do { __builtin_amdgcn_s_setprio(1); _Pragma("unroll") for (int m = 0; m < 4; ++m) _Pragma("unroll") for (int n = 0; n < 2; ++n) _Pragma("unroll") for (int k = 0; k < 2; ++k) \
;         acc[ai][bj][m][n] = __builtin_amdgcn_mfma_f32_16x16x32_bf16(Bt[n][k], At[m][k], acc[ai][bj][m][n], 0, 0, 0); __builtin_amdgcn_s_setprio(0); } while (0)
; #define PG8_WAIT_V(n) asm volatile("s_waitcnt vmcnt(" #n ")" ::: "memory")
; #define PG8_WAIT_L(n) asm volatile("s_waitcnt lgkmcnt(" #n ")" ::: "memory")
; #define PG8_BAR __builtin_amdgcn_s_barrier()
; #define PG8_SCHED __builtin_amdgcn_sched_barrier(0)
; template <class Epi>
; DEV void gemm_phase(LAS unsigned char* lds, const Gemm g, const StaticOrder& S, const Epi& E) {
;     ...
;             PG8_STAGE(PG8_SB(0, 1), b2 + hstep, voffB);
;             PG8_WAIT_V(6); PG8_BAR; PG8_MMA(1, 1, At, B1); PG8_BAR;
;             PG8_LDB(B0, 1, 0); PG8_SCHED; PG8_LDA(At, 1, 0); PG8_STAGE(PG8_SA(0, 1), a2 + hstep, voffA);
;             PG8_WAIT_L(8); PG8_BAR; PG8_WAIT_L(0); PG8_MMA(0, 0, At, B0); PG8_BAR; PG8_SCHED;
;             PG8_LDB(B1, 1, 1); PG8_STAGE(PG8_SB(1, 0), b3, voffB);
;             PG8_BAR; PG8_WAIT_L(0); PG8_MMA(0, 1, At, B1); PG8_BAR;
;             PG8_LDA(At, 1, 1); PG8_STAGE(PG8_SA(1, 0), a3, voffA);
	s_add_u32 s42, s20, 0x80000
	s_addc_u32 s43, s21, 0
	s_add_i32 s41, s44, s26
	v_lshl_add_u64 v[128:129], s[42:43], 0, v[160:161]
	s_mov_b32 m0, s41
	s_nop 0
	global_load_lds_dwordx4 v[128:129], off
	v_lshl_add_u64 v[128:129], s[42:43], 0, v[144:145]
	s_add_i32 m0, s41, 0x2000
	s_nop 0
	global_load_lds_dwordx4 v[128:129], off
	s_waitcnt vmcnt(6)
	s_barrier
	s_setprio 1
	v_mfma_f32_16x16x32_bf16 v[52:55], v[230:233], v[180:183], v[52:55]
	v_mfma_f32_16x16x32_bf16 v[48:51], v[238:241], v[180:183], v[48:51]
	v_mfma_f32_16x16x32_bf16 v[36:39], v[230:233], v[188:191], v[36:39]
	v_mfma_f32_16x16x32_bf16 v[32:35], v[238:241], v[188:191], v[32:35]
	v_mfma_f32_16x16x32_bf16 v[20:23], v[230:233], v[214:217], v[20:23]
	v_mfma_f32_16x16x32_bf16 v[16:19], v[238:241], v[214:217], v[16:19]
	v_mfma_f32_16x16x32_bf16 v[4:7], v[230:233], v[222:225], v[4:7]
	v_mfma_f32_16x16x32_bf16 v[0:3], v[238:241], v[222:225], v[0:3]
	v_mfma_f32_16x16x32_bf16 v[52:55], v[234:237], v[184:187], v[52:55]
	v_mfma_f32_16x16x32_bf16 v[48:51], v[242:245], v[184:187], v[48:51]
	v_mfma_f32_16x16x32_bf16 v[36:39], v[234:237], v[192:195], v[36:39]
	v_mfma_f32_16x16x32_bf16 v[32:35], v[242:245], v[192:195], v[32:35]
	v_mfma_f32_16x16x32_bf16 v[20:23], v[234:237], v[218:221], v[20:23]
	v_mfma_f32_16x16x32_bf16 v[16:19], v[242:245], v[218:221], v[16:19]
	v_mfma_f32_16x16x32_bf16 v[4:7], v[234:237], v[226:229], v[4:7]
	v_mfma_f32_16x16x32_bf16 v[0:3], v[242:245], v[226:229], v[0:3]
	s_setprio 0
	s_add_i32 s41, 0, 0x18000
	v_add_u32_e32 v140, s41, v176
	s_barrier
	ds_read_b128 v[128:131], v140
	ds_read_b128 v[132:135], v140 offset:1024
	ds_read_b128 v[136:139], v140 offset:2048
	ds_read_b128 v[140:143], v140 offset:3072
	s_add_u32 s22, s22, 0x80000
	s_addc_u32 s23, s23, 0
	s_mov_b32 m0, s28
	v_lshl_add_u64 v[230:231], s[22:23], 0, v[160:161]
	ds_read_b128 v[180:183], v178 offset:32768
	ds_read_b128 v[184:187], v178 offset:33792
	ds_read_b128 v[188:191], v178 offset:34816
	ds_read_b128 v[192:195], v178 offset:35840
	ds_read_b128 v[214:217], v178 offset:36864
	ds_read_b128 v[218:221], v178 offset:37888
	ds_read_b128 v[222:225], v178 offset:38912
	ds_read_b128 v[226:229], v178 offset:39936
	global_load_lds_dwordx4 v[230:231], off
	v_lshl_add_u64 v[230:231], s[22:23], 0, v[144:145]
	s_mov_b32 m0, s29
	s_nop 0
	global_load_lds_dwordx4 v[230:231], off
	s_waitcnt lgkmcnt(8)
	s_barrier
	s_waitcnt lgkmcnt(0)
	s_setprio 1
	v_mfma_f32_16x16x32_bf16 v[124:127], v[128:131], v[180:183], v[124:127]
	v_mfma_f32_16x16x32_bf16 v[120:123], v[136:139], v[180:183], v[120:123]
	v_mfma_f32_16x16x32_bf16 v[108:111], v[128:131], v[188:191], v[108:111]
	v_mfma_f32_16x16x32_bf16 v[104:107], v[136:139], v[188:191], v[104:107]
	v_mfma_f32_16x16x32_bf16 v[92:95], v[128:131], v[214:217], v[92:95]
	v_mfma_f32_16x16x32_bf16 v[88:91], v[136:139], v[214:217], v[88:91]
	v_mfma_f32_16x16x32_bf16 v[76:79], v[128:131], v[222:225], v[76:79]
	v_mfma_f32_16x16x32_bf16 v[72:75], v[136:139], v[222:225], v[72:75]
	v_mfma_f32_16x16x32_bf16 v[124:127], v[132:135], v[184:187], v[124:127]
	v_mfma_f32_16x16x32_bf16 v[120:123], v[140:143], v[184:187], v[120:123]
	v_mfma_f32_16x16x32_bf16 v[108:111], v[132:135], v[192:195], v[108:111]
	v_mfma_f32_16x16x32_bf16 v[104:107], v[140:143], v[192:195], v[104:107]
	v_mfma_f32_16x16x32_bf16 v[92:95], v[132:135], v[218:221], v[92:95]
	v_mfma_f32_16x16x32_bf16 v[88:91], v[140:143], v[218:221], v[88:91]
	v_mfma_f32_16x16x32_bf16 v[76:79], v[132:135], v[226:229], v[76:79]
	v_mfma_f32_16x16x32_bf16 v[72:75], v[140:143], v[226:229], v[72:75]
	s_setprio 0
	s_barrier
	s_add_i32 s22, 0, 0x1c000
	s_add_i32 s23, s41, s26
	v_add_u32_e32 v179, s22, v176
	v_lshl_add_u64 v[158:159], v[158:159], 0, s[2:3]
	s_mov_b32 m0, s23
	ds_read_b128 v[230:233], v179
	ds_read_b128 v[234:237], v179 offset:1024
	ds_read_b128 v[238:241], v179 offset:2048
	ds_read_b128 v[242:245], v179 offset:3072
	global_load_lds_dwordx4 v[158:159], off
	v_lshl_add_u64 v[158:159], v[174:175], 0, s[2:3]
	s_add_i32 m0, s23, 0x2000
	s_nop 0
	global_load_lds_dwordx4 v[158:159], off
	s_barrier
	s_waitcnt lgkmcnt(0)
	s_setprio 1
	v_mfma_f32_16x16x32_bf16 v[116:119], v[230:233], v[180:183], v[116:119]
	v_mfma_f32_16x16x32_bf16 v[112:115], v[238:241], v[180:183], v[112:115]
	v_mfma_f32_16x16x32_bf16 v[100:103], v[230:233], v[188:191], v[100:103]
	v_mfma_f32_16x16x32_bf16 v[96:99], v[238:241], v[188:191], v[96:99]
	v_mfma_f32_16x16x32_bf16 v[84:87], v[230:233], v[214:217], v[84:87]
	v_mfma_f32_16x16x32_bf16 v[80:83], v[238:241], v[214:217], v[80:83]
	v_mfma_f32_16x16x32_bf16 v[68:71], v[230:233], v[222:225], v[68:71]
	v_mfma_f32_16x16x32_bf16 v[64:67], v[238:241], v[222:225], v[64:67]
	v_mfma_f32_16x16x32_bf16 v[116:119], v[234:237], v[184:187], v[116:119]
	v_mfma_f32_16x16x32_bf16 v[112:115], v[242:245], v[184:187], v[112:115]
	v_mfma_f32_16x16x32_bf16 v[100:103], v[234:237], v[192:195], v[100:103]
	v_mfma_f32_16x16x32_bf16 v[96:99], v[242:245], v[192:195], v[96:99]
	v_mfma_f32_16x16x32_bf16 v[84:87], v[234:237], v[218:221], v[84:87]
	v_mfma_f32_16x16x32_bf16 v[80:83], v[242:245], v[218:221], v[80:83]
	v_mfma_f32_16x16x32_bf16 v[68:71], v[234:237], v[226:229], v[68:71]
	v_mfma_f32_16x16x32_bf16 v[64:67], v[242:245], v[226:229], v[64:67]
	s_setprio 0
	s_mov_b32 m0, s30
	v_lshl_add_u64 v[158:159], v[196:197], 0, s[2:3]
	s_barrier
; #define PG8_STAGE(bufoff, gbase, voff) do { _Pragma("unroll") for (int _i = 0; _i < 2; ++_i) \
;         __builtin_amdgcn_global_load_lds((const unsigned*)((const char*)(gbase) + (voff)[_i]), (LAS unsigned*)(lds + (bufoff) + ldsw + _i * 8192), 16, 0, 0); } while (0)
; #define PG8_MMA(ai, bj, At, Bt) do { __builtin_amdgcn_s_setprio(1); _Pragma("unroll") for (int m = 0; m < 4; ++m) _Pragma("unroll") for (int n = 0; n < 2; ++n) _Pragma("unroll") for (int k = 0; k < 2; ++k) \
;         acc[ai][bj][m][n] = __builtin_amdgcn_mfma_f32_16x16x32_bf16(Bt[n][k], At[m][k], acc[ai][bj][m][n], 0, 0, 0); __builtin_amdgcn_s_setprio(0); } while (0)
; #define PG8_WAIT_V(n) asm volatile("s_waitcnt vmcnt(" #n ")" ::: "memory")
; #define PG8_WAIT_L(n) asm volatile("s_waitcnt lgkmcnt(" #n ")" ::: "memory")
; #define PG8_BAR __builtin_amdgcn_s_barrier()
; #define PG8_SCHED __builtin_amdgcn_sched_barrier(0)
;     DEV void operator()(AccRef acc, const pg8::Unit& u, int wr, int wc, int fr, int fq) const { store_bf16_tile<0, false>(acc, O, ld, u.pm * 256 + wr * 64 + fr, u.pn * 256 + wc * 32 + 4 * fq, ss); }
; template <class Epi>
; DEV void gemm_phase(LAS unsigned char* lds, const Gemm g, const StaticOrder& S, const Epi& E) {
;     ...
;             PG8_BAR; PG8_WAIT_L(0); PG8_MMA(1, 0, At, B0); PG8_BAR; PG8_SCHED;
;             PG8_STAGE(PG8_SB(1, 1), b3 + hstep, voffB);
;             PG8_WAIT_V(6); PG8_BAR; PG8_MMA(1, 1, At, B1); PG8_BAR;
;         }
;     DEV void operator()(AccRef acc, const pg8::Unit& u, int wr, int wc, int fr, int fq) const {
;         const int row0 = u.pm * 256 + wr * 64 + fr, col0 = u.pn * 256 + wc * 32 + 4 * fq;
;         const bool rope = (u.pn < 9) && ((wc & 1) == 0);
; #pragma unroll
;         for (int ai = 0; ai < 2; ++ai)
; #pragma unroll
;             for (int m = 0; m < 4; ++m) { const int row = row0 + ai * 128 + m * 16; u16* rowp = O + (size_t)row * 2560 + col0; const float rs = rowscale(ss, row);
;                 f32x4 cs = (f32x4){1.f, 1.f, 1.f, 1.f}, sn = (f32x4){0.f, 0.f, 0.f, 0.f};
;                 if (rope) { cs = *(const f32x4*)(cosT + row * 8 + 4 * (fq & 1)); sn = *(const f32x4*)(sinT + row * 8 + 4 * (fq & 1)); }
	ds_read_b128 v[180:183], v178 offset:49152
	ds_read_b128 v[184:187], v178 offset:50176
	ds_read_b128 v[188:191], v178 offset:51200
	ds_read_b128 v[192:195], v178 offset:52224
	ds_read_b128 v[214:217], v178 offset:53248
	ds_read_b128 v[218:221], v178 offset:54272
	ds_read_b128 v[222:225], v178 offset:55296
	ds_read_b128 v[226:229], v178 offset:56320
	global_load_lds_dwordx4 v[158:159], off
	v_lshl_add_u64 v[158:159], v[246:247], 0, s[2:3]
	s_mov_b32 m0, s31
	s_nop 0
	global_load_lds_dwordx4 v[158:159], off
	s_barrier
	s_waitcnt lgkmcnt(0)
	s_setprio 1
	v_mfma_f32_16x16x32_bf16 v[60:63], v[128:131], v[180:183], v[60:63]
	v_mfma_f32_16x16x32_bf16 v[56:59], v[136:139], v[180:183], v[56:59]
	v_mfma_f32_16x16x32_bf16 v[44:47], v[128:131], v[188:191], v[44:47]
	v_mfma_f32_16x16x32_bf16 v[40:43], v[136:139], v[188:191], v[40:43]
	v_mfma_f32_16x16x32_bf16 v[28:31], v[128:131], v[214:217], v[28:31]
	v_mfma_f32_16x16x32_bf16 v[24:27], v[136:139], v[214:217], v[24:27]
	v_mfma_f32_16x16x32_bf16 v[12:15], v[128:131], v[222:225], v[12:15]
	v_mfma_f32_16x16x32_bf16 v[8:11], v[136:139], v[222:225], v[8:11]
	v_mfma_f32_16x16x32_bf16 v[60:63], v[132:135], v[184:187], v[60:63]
	v_mfma_f32_16x16x32_bf16 v[56:59], v[140:143], v[184:187], v[56:59]
	v_mfma_f32_16x16x32_bf16 v[44:47], v[132:135], v[192:195], v[44:47]
	v_mfma_f32_16x16x32_bf16 v[40:43], v[140:143], v[192:195], v[40:43]
	v_mfma_f32_16x16x32_bf16 v[28:31], v[132:135], v[218:221], v[28:31]
	v_mfma_f32_16x16x32_bf16 v[24:27], v[140:143], v[218:221], v[24:27]
	v_mfma_f32_16x16x32_bf16 v[12:15], v[132:135], v[226:229], v[12:15]
	v_mfma_f32_16x16x32_bf16 v[8:11], v[140:143], v[226:229], v[8:11]
	s_setprio 0
	s_barrier
	s_add_u32 s20, s20, 0x80080
	s_addc_u32 s21, s21, 0
	s_add_i32 s22, s22, s26
	v_lshl_add_u64 v[128:129], s[20:21], 0, v[160:161]
	s_mov_b32 m0, s22
	s_nop 0
	global_load_lds_dwordx4 v[128:129], off
	v_lshl_add_u64 v[128:129], s[20:21], 0, v[144:145]
	s_add_i32 m0, s22, 0x2000
	s_nop 0
	global_load_lds_dwordx4 v[128:129], off
	s_waitcnt vmcnt(6)
	s_barrier
	s_setprio 1
	v_mfma_f32_16x16x32_bf16 v[52:55], v[230:233], v[180:183], v[52:55]
	v_mfma_f32_16x16x32_bf16 v[48:51], v[238:241], v[180:183], v[48:51]
	v_mfma_f32_16x16x32_bf16 v[36:39], v[230:233], v[188:191], v[36:39]
	v_mfma_f32_16x16x32_bf16 v[32:35], v[238:241], v[188:191], v[32:35]
	v_mfma_f32_16x16x32_bf16 v[20:23], v[230:233], v[214:217], v[20:23]
	v_mfma_f32_16x16x32_bf16 v[16:19], v[238:241], v[214:217], v[16:19]
	v_mfma_f32_16x16x32_bf16 v[4:7], v[230:233], v[222:225], v[4:7]
	v_mfma_f32_16x16x32_bf16 v[0:3], v[238:241], v[222:225], v[0:3]
	v_mfma_f32_16x16x32_bf16 v[52:55], v[234:237], v[184:187], v[52:55]
	v_mfma_f32_16x16x32_bf16 v[48:51], v[242:245], v[184:187], v[48:51]
	v_mfma_f32_16x16x32_bf16 v[36:39], v[234:237], v[192:195], v[36:39]
	v_mfma_f32_16x16x32_bf16 v[32:35], v[242:245], v[192:195], v[32:35]
	v_mfma_f32_16x16x32_bf16 v[20:23], v[234:237], v[218:221], v[20:23]
	v_mfma_f32_16x16x32_bf16 v[16:19], v[242:245], v[218:221], v[16:19]
	v_mfma_f32_16x16x32_bf16 v[4:7], v[234:237], v[226:229], v[4:7]
	v_mfma_f32_16x16x32_bf16 v[0:3], v[242:245], v[226:229], v[0:3]
	s_setprio 0
	s_add_i32 s40, s40, 2
	s_add_u32 s18, s18, 0x100
	s_addc_u32 s19, s19, 0
	s_add_u32 s38, s38, 0x100
	s_addc_u32 s39, s39, 0
	s_cmp_gt_u32 s40, 29
	s_barrier
	s_cbranch_scc0 .LBB0_152
	v_lshl_add_u32 v174, s4, 8, v167
	v_ashrrev_i32_e32 v175, 31, v174
	v_readlane_b32 s20, v250, 47
	v_lshlrev_b64 v[128:129], 5, v[174:175]
	v_readlane_b32 s21, v250, 48
	s_cmp_lt_i32 s16, 9
	s_cselect_b64 s[4:5], -1, 0
	v_lshl_add_u64 v[128:129], s[20:21], 0, v[128:129]
	global_load_dwordx4 v[136:139], v[128:129], off offset:16
	global_load_dwordx4 v[140:143], v[128:129], off
	s_and_b64 s[18:19], s[6:7], s[4:5]
	v_cndmask_b32_e64 v128, 0, 1, s[18:19]
	v_cmp_ne_u32_e64 s[4:5], 1, v128
	s_andn2_b64 vcc, exec, s[18:19]
	s_cbranch_vccnz .LBB0_155
	v_lshlrev_b32_e32 v128, 3, v174
	v_ashrrev_i32_e32 v129, 31, v128
	v_lshlrev_b64 v[128:129], 2, v[128:129]
	v_lshl_add_u64 v[130:131], v[152:153], 0, v[128:129]
	v_lshl_add_u64 v[132:133], v[150:151], 0, v[128:129]
	global_load_dwordx4 v[128:131], v[130:131], off
	s_nop 0
	global_load_dwordx4 v[132:135], v[132:133], off
	s_branch .LBB0_156

; #define PG8_STAGE(bufoff, gbase, voff) do { _Pragma("unroll") for (int _i = 0; _i < 2; ++_i) \
;         __builtin_amdgcn_global_load_lds((const unsigned*)((const char*)(gbase) + (voff)[_i]), (LAS unsigned*)(lds + (bufoff) + ldsw + _i * 8192), 16, 0, 0); } while (0)
; #define PG8_LDA(dst, b, h) do { _Pragma("unroll") for (int m = 0; m < 4; ++m) _Pragma("unroll") for (int k = 0; k < 2; ++k) dst[m][k] = *(const LAS bf16x8*)(lds + PG8_SA(b, h) + aoff + m * 2048 + k * 1024); } while (0)
; #define PG8_LDB(dst, b, h) do { _Pragma("unroll") for (int n = 0; n < 2; ++n) _Pragma("unroll") for (int k = 0; k < 2; ++k) dst[n][k] = *(const LAS bf16x8*)(lds + PG8_SB(b, h) + boff + n * 2048 + k * 1024); } while (0)
; #define PG8_MMA(ai, bj, At, Bt) do { __builtin_amdgcn_s_setprio(1); _Pragma("unroll") for (int m = 0; m < 4; ++m) _Pragma("unroll") for (int n = 0; n < 2; ++n) _Pragma("unroll") for (int k = 0; k < 2; ++k) \
;         acc[ai][bj][m][n] = __builtin_amdgcn_mfma_f32_16x16x32_bf16(Bt[n][k], At[m][k], acc[ai][bj][m][n], 0, 0, 0); __builtin_amdgcn_s_setprio(0); } while (0)
; #define PG8_WAIT_L(n) asm volatile("s_waitcnt lgkmcnt(" #n ")" ::: "memory")
; #define PG8_BAR __builtin_amdgcn_s_barrier()
; #define PG8_SCHED __builtin_amdgcn_sched_barrier(0)
; template <class Epi>
; DEV void gemm_phase(LAS unsigned char* lds, const Gemm g, const StaticOrder& S, const Epi& E) {
;     ...
;             PG8_LDB(B0, 0, 0); PG8_SCHED; PG8_LDA(At, 0, 0); PG8_STAGE(PG8_SA(1, 1), a1 + hstep, voffA);
;             PG8_WAIT_L(8); PG8_BAR; PG8_WAIT_L(0); PG8_MMA(0, 0, At, B0); PG8_BAR; PG8_SCHED;
;             PG8_LDB(B1, 0, 1); PG8_STAGE(PG8_SB(0, 0), b2, voffB);
;             PG8_BAR; PG8_WAIT_L(0); PG8_MMA(0, 1, At, B1); PG8_BAR;
;             PG8_LDA(At, 0, 1); PG8_STAGE(PG8_SA(0, 0), a2, voffA);
;             PG8_BAR; PG8_WAIT_L(0); PG8_MMA(1, 0, At, B0); PG8_BAR; PG8_SCHED;
.LBB0_260:
	s_add_u32 s34, s30, 0xfffe0080
	s_addc_u32 s35, s31, -1
	s_add_i32 s55, 0, 0x10000
	v_add_u32_e32 v140, s55, v178
	ds_read_b128 v[128:131], v140
	ds_read_b128 v[132:135], v140 offset:1024
	ds_read_b128 v[136:139], v140 offset:2048
	ds_read_b128 v[140:143], v140 offset:3072
	s_cmp_eq_u32 s54, 4
	s_cselect_b32 s37, s19, s35
	s_cselect_b32 s36, s23, s34
	s_cselect_b32 s35, s21, s53
	s_cselect_b32 s34, s29, s52
	v_lshl_add_u64 v[158:159], s[30:31], 0, v[150:151]
	s_add_i32 m0, s43, 0xc000
	ds_read_b128 v[154:157], v181
	ds_read_b128 v[174:177], v181 offset:1024
	ds_read_b128 v[182:185], v181 offset:2048
	ds_read_b128 v[186:189], v181 offset:3072
	ds_read_b128 v[190:193], v181 offset:4096
	ds_read_b128 v[194:197], v181 offset:5120
	ds_read_b128 v[214:217], v181 offset:6144
	ds_read_b128 v[218:221], v181 offset:7168
	global_load_lds_dwordx4 v[158:159], off
	v_lshl_add_u64 v[158:159], s[30:31], 0, v[152:153]
	s_add_i32 m0, s43, 0xe000
	s_nop 0
	global_load_lds_dwordx4 v[158:159], off
	s_waitcnt lgkmcnt(8)
	s_barrier
	s_waitcnt lgkmcnt(0)
	s_setprio 1
	v_mfma_f32_16x16x32_bf16 v[124:127], v[128:131], v[154:157], v[124:127]
	v_mfma_f32_16x16x32_bf16 v[120:123], v[136:139], v[154:157], v[120:123]
	v_mfma_f32_16x16x32_bf16 v[108:111], v[128:131], v[182:185], v[108:111]
	v_mfma_f32_16x16x32_bf16 v[104:107], v[136:139], v[182:185], v[104:107]
	v_mfma_f32_16x16x32_bf16 v[92:95], v[128:131], v[190:193], v[92:95]
	v_mfma_f32_16x16x32_bf16 v[88:91], v[136:139], v[190:193], v[88:91]
	v_mfma_f32_16x16x32_bf16 v[76:79], v[128:131], v[214:217], v[76:79]
	v_mfma_f32_16x16x32_bf16 v[72:75], v[136:139], v[214:217], v[72:75]
	v_mfma_f32_16x16x32_bf16 v[124:127], v[132:135], v[174:177], v[124:127]
	v_mfma_f32_16x16x32_bf16 v[120:123], v[140:143], v[174:177], v[120:123]
	v_mfma_f32_16x16x32_bf16 v[108:111], v[132:135], v[186:189], v[108:111]
	v_mfma_f32_16x16x32_bf16 v[104:107], v[140:143], v[186:189], v[104:107]
	v_mfma_f32_16x16x32_bf16 v[92:95], v[132:135], v[194:197], v[92:95]
	v_mfma_f32_16x16x32_bf16 v[88:91], v[140:143], v[194:197], v[88:91]
	v_mfma_f32_16x16x32_bf16 v[76:79], v[132:135], v[218:221], v[76:79]
	v_mfma_f32_16x16x32_bf16 v[72:75], v[140:143], v[218:221], v[72:75]
	s_setprio 0
	s_barrier
	s_add_i32 s58, 0, 0x14000
	v_add_u32_e32 v158, s58, v178
	s_add_i32 s55, s55, s42
	ds_read_b128 v[222:225], v158
	ds_read_b128 v[226:229], v158 offset:1024
	ds_read_b128 v[230:233], v158 offset:2048
	ds_read_b128 v[234:237], v158 offset:3072
	v_lshl_add_u64 v[158:159], s[34:35], 0, v[160:161]
	s_mov_b32 m0, s55
	v_lshl_add_u64 v[238:239], s[34:35], 0, v[148:149]
	global_load_lds_dwordx4 v[158:159], off
	s_add_i32 m0, s55, 0x2000
	s_nop 0
	global_load_lds_dwordx4 v[238:239], off
	s_barrier
	s_waitcnt lgkmcnt(0)
	s_setprio 1
	v_mfma_f32_16x16x32_bf16 v[116:119], v[222:225], v[154:157], v[116:119]
	v_mfma_f32_16x16x32_bf16 v[112:115], v[230:233], v[154:157], v[112:115]
	v_mfma_f32_16x16x32_bf16 v[100:103], v[222:225], v[182:185], v[100:103]
	v_mfma_f32_16x16x32_bf16 v[96:99], v[230:233], v[182:185], v[96:99]
	v_mfma_f32_16x16x32_bf16 v[84:87], v[222:225], v[190:193], v[84:87]
	v_mfma_f32_16x16x32_bf16 v[80:83], v[230:233], v[190:193], v[80:83]
	v_mfma_f32_16x16x32_bf16 v[68:71], v[222:225], v[214:217], v[68:71]
	v_mfma_f32_16x16x32_bf16 v[64:67], v[230:233], v[214:217], v[64:67]
	v_mfma_f32_16x16x32_bf16 v[116:119], v[226:229], v[174:177], v[116:119]
	v_mfma_f32_16x16x32_bf16 v[112:115], v[234:237], v[174:177], v[112:115]
	v_mfma_f32_16x16x32_bf16 v[100:103], v[226:229], v[186:189], v[100:103]
	v_mfma_f32_16x16x32_bf16 v[96:99], v[234:237], v[186:189], v[96:99]
	v_mfma_f32_16x16x32_bf16 v[84:87], v[226:229], v[194:197], v[84:87]
	v_mfma_f32_16x16x32_bf16 v[80:83], v[234:237], v[194:197], v[80:83]
	v_mfma_f32_16x16x32_bf16 v[68:71], v[226:229], v[218:221], v[68:71]
	v_mfma_f32_16x16x32_bf16 v[64:67], v[234:237], v[218:221], v[64:67]
	s_setprio 0
	s_mov_b32 m0, s43
	v_lshl_add_u64 v[240:241], s[36:37], 0, v[144:145]
	s_barrier
	ds_read_b128 v[154:157], v181 offset:16384
	ds_read_b128 v[174:177], v181 offset:17408
	ds_read_b128 v[182:185], v181 offset:18432
	ds_read_b128 v[186:189], v181 offset:19456
	ds_read_b128 v[190:193], v181 offset:20480
	ds_read_b128 v[194:197], v181 offset:21504
	ds_read_b128 v[214:217], v181 offset:22528
	ds_read_b128 v[218:221], v181 offset:23552
	global_load_lds_dwordx4 v[240:241], off
	v_lshl_add_u64 v[242:243], s[36:37], 0, v[146:147]
	s_mov_b32 m0, s44
	s_nop 0
	global_load_lds_dwordx4 v[242:243], off
	s_barrier
	s_waitcnt lgkmcnt(0)
	s_setprio 1
	v_mfma_f32_16x16x32_bf16 v[60:63], v[128:131], v[154:157], v[60:63]
	v_mfma_f32_16x16x32_bf16 v[56:59], v[136:139], v[154:157], v[56:59]
	v_mfma_f32_16x16x32_bf16 v[44:47], v[128:131], v[182:185], v[44:47]
	v_mfma_f32_16x16x32_bf16 v[40:43], v[136:139], v[182:185], v[40:43]
	v_mfma_f32_16x16x32_bf16 v[28:31], v[128:131], v[190:193], v[28:31]
	v_mfma_f32_16x16x32_bf16 v[24:27], v[136:139], v[190:193], v[24:27]
	v_mfma_f32_16x16x32_bf16 v[12:15], v[128:131], v[214:217], v[12:15]
	v_mfma_f32_16x16x32_bf16 v[8:11], v[136:139], v[214:217], v[8:11]
	v_mfma_f32_16x16x32_bf16 v[60:63], v[132:135], v[174:177], v[60:63]
	v_mfma_f32_16x16x32_bf16 v[56:59], v[140:143], v[174:177], v[56:59]
	v_mfma_f32_16x16x32_bf16 v[44:47], v[132:135], v[186:189], v[44:47]
	v_mfma_f32_16x16x32_bf16 v[40:43], v[140:143], v[186:189], v[40:43]
	v_mfma_f32_16x16x32_bf16 v[28:31], v[132:135], v[194:197], v[28:31]
	v_mfma_f32_16x16x32_bf16 v[24:27], v[140:143], v[194:197], v[24:27]
	v_mfma_f32_16x16x32_bf16 v[12:15], v[132:135], v[218:221], v[12:15]
	v_mfma_f32_16x16x32_bf16 v[8:11], v[140:143], v[218:221], v[8:11]
	s_setprio 0
	s_barrier
; #define PG8_STAGE(bufoff, gbase, voff) do { _Pragma("unroll") for (int _i = 0; _i < 2; ++_i) \
;         __builtin_amdgcn_global_load_lds((const unsigned*)((const char*)(gbase) + (voff)[_i]), (LAS unsigned*)(lds + (bufoff) + ldsw + _i * 8192), 16, 0, 0); } while (0)
; #define PG8_LDA(dst, b, h) do { _Pragma("unroll") for (int m = 0; m < 4; ++m) _Pragma("unroll") for (int k = 0; k < 2; ++k) dst[m][k] = *(const LAS bf16x8*)(lds + PG8_SA(b, h) + aoff + m * 2048 + k * 1024); } while (0)
; #define PG8_LDB(dst, b, h) do { _Pragma("unroll") for (int n = 0; n < 2; ++n) _Pragma("unroll") for (int k = 0; k < 2; ++k) dst[n][k] = *(const LAS bf16x8*)(lds + PG8_SB(b, h) + boff + n * 2048 + k * 1024); } while (0)
; #define PG8_MMA(ai, bj, At, Bt) do { __builtin_amdgcn_s_setprio(1); _Pragma("unroll") for (int m = 0; m < 4; ++m) _Pragma("unroll") for (int n = 0; n < 2; ++n) _Pragma("unroll") for (int k = 0; k < 2; ++k) \
;         acc[ai][bj][m][n] = __builtin_amdgcn_mfma_f32_16x16x32_bf16(Bt[n][k], At[m][k], acc[ai][bj][m][n], 0, 0, 0); __builtin_amdgcn_s_setprio(0); } while (0)
; #define PG8_WAIT_V(n) asm volatile("s_waitcnt vmcnt(" #n ")" ::: "memory")
; #define PG8_WAIT_L(n) asm volatile("s_waitcnt lgkmcnt(" #n ")" ::: "memory")
; #define PG8_BAR __builtin_amdgcn_s_barrier()
; #define PG8_SCHED __builtin_amdgcn_sched_barrier(0)
; template <class Epi>
; DEV void gemm_phase(LAS unsigned char* lds, const Gemm g, const StaticOrder& S, const Epi& E) {
;     ...
;             PG8_STAGE(PG8_SB(0, 1), b2 + hstep, voffB);
;             PG8_WAIT_V(6); PG8_BAR; PG8_MMA(1, 1, At, B1); PG8_BAR;
;             PG8_LDB(B0, 1, 0); PG8_SCHED; PG8_LDA(At, 1, 0); PG8_STAGE(PG8_SA(0, 1), a2 + hstep, voffA);
;             PG8_WAIT_L(8); PG8_BAR; PG8_WAIT_L(0); PG8_MMA(0, 0, At, B0); PG8_BAR; PG8_SCHED;
;             PG8_LDB(B1, 1, 1); PG8_STAGE(PG8_SB(1, 0), b3, voffB);
;             PG8_BAR; PG8_WAIT_L(0); PG8_MMA(0, 1, At, B1); PG8_BAR;
;             PG8_LDA(At, 1, 1); PG8_STAGE(PG8_SA(1, 0), a3, voffA);
	s_add_u32 s56, s34, 0x20000
	s_addc_u32 s57, s35, 0
	s_add_i32 s55, s58, s42
	v_lshl_add_u64 v[128:129], s[56:57], 0, v[160:161]
	s_mov_b32 m0, s55
	s_nop 0
	global_load_lds_dwordx4 v[128:129], off
	v_lshl_add_u64 v[128:129], s[56:57], 0, v[148:149]
	s_add_i32 m0, s55, 0x2000
	s_nop 0
	global_load_lds_dwordx4 v[128:129], off
	s_waitcnt vmcnt(6)
	s_barrier
	s_setprio 1
	v_mfma_f32_16x16x32_bf16 v[52:55], v[222:225], v[154:157], v[52:55]
	v_mfma_f32_16x16x32_bf16 v[48:51], v[230:233], v[154:157], v[48:51]
	v_mfma_f32_16x16x32_bf16 v[36:39], v[222:225], v[182:185], v[36:39]
	v_mfma_f32_16x16x32_bf16 v[32:35], v[230:233], v[182:185], v[32:35]
	v_mfma_f32_16x16x32_bf16 v[20:23], v[222:225], v[190:193], v[20:23]
	v_mfma_f32_16x16x32_bf16 v[16:19], v[230:233], v[190:193], v[16:19]
	v_mfma_f32_16x16x32_bf16 v[4:7], v[222:225], v[214:217], v[4:7]
	v_mfma_f32_16x16x32_bf16 v[0:3], v[230:233], v[214:217], v[0:3]
	v_mfma_f32_16x16x32_bf16 v[52:55], v[226:229], v[174:177], v[52:55]
	v_mfma_f32_16x16x32_bf16 v[48:51], v[234:237], v[174:177], v[48:51]
	v_mfma_f32_16x16x32_bf16 v[36:39], v[226:229], v[186:189], v[36:39]
	v_mfma_f32_16x16x32_bf16 v[32:35], v[234:237], v[186:189], v[32:35]
	v_mfma_f32_16x16x32_bf16 v[20:23], v[226:229], v[194:197], v[20:23]
	v_mfma_f32_16x16x32_bf16 v[16:19], v[234:237], v[194:197], v[16:19]
	v_mfma_f32_16x16x32_bf16 v[4:7], v[226:229], v[218:221], v[4:7]
	v_mfma_f32_16x16x32_bf16 v[0:3], v[234:237], v[218:221], v[0:3]
	s_setprio 0
	s_add_i32 s55, 0, 0x18000
	v_add_u32_e32 v140, s55, v178
	s_barrier
	ds_read_b128 v[128:131], v140
	ds_read_b128 v[132:135], v140 offset:1024
	ds_read_b128 v[136:139], v140 offset:2048
	ds_read_b128 v[140:143], v140 offset:3072
	s_add_u32 s36, s36, 0x20000
	s_addc_u32 s37, s37, 0
	s_mov_b32 m0, s45
	v_lshl_add_u64 v[222:223], s[36:37], 0, v[144:145]
	ds_read_b128 v[154:157], v181 offset:32768
	ds_read_b128 v[174:177], v181 offset:33792
	ds_read_b128 v[182:185], v181 offset:34816
	ds_read_b128 v[186:189], v181 offset:35840
	ds_read_b128 v[190:193], v181 offset:36864
	ds_read_b128 v[194:197], v181 offset:37888
	ds_read_b128 v[214:217], v181 offset:38912
	ds_read_b128 v[218:221], v181 offset:39936
	global_load_lds_dwordx4 v[222:223], off
	v_lshl_add_u64 v[222:223], s[36:37], 0, v[146:147]
	s_mov_b32 m0, s46
	s_nop 0
	global_load_lds_dwordx4 v[222:223], off
	s_waitcnt lgkmcnt(8)
	s_barrier
	s_waitcnt lgkmcnt(0)
	s_setprio 1
	v_mfma_f32_16x16x32_bf16 v[124:127], v[128:131], v[154:157], v[124:127]
	v_mfma_f32_16x16x32_bf16 v[120:123], v[136:139], v[154:157], v[120:123]
	v_mfma_f32_16x16x32_bf16 v[108:111], v[128:131], v[182:185], v[108:111]
	v_mfma_f32_16x16x32_bf16 v[104:107], v[136:139], v[182:185], v[104:107]
	v_mfma_f32_16x16x32_bf16 v[92:95], v[128:131], v[190:193], v[92:95]
	v_mfma_f32_16x16x32_bf16 v[88:91], v[136:139], v[190:193], v[88:91]
	v_mfma_f32_16x16x32_bf16 v[76:79], v[128:131], v[214:217], v[76:79]
	v_mfma_f32_16x16x32_bf16 v[72:75], v[136:139], v[214:217], v[72:75]
	v_mfma_f32_16x16x32_bf16 v[124:127], v[132:135], v[174:177], v[124:127]
	v_mfma_f32_16x16x32_bf16 v[120:123], v[140:143], v[174:177], v[120:123]
	v_mfma_f32_16x16x32_bf16 v[108:111], v[132:135], v[186:189], v[108:111]
	v_mfma_f32_16x16x32_bf16 v[104:107], v[140:143], v[186:189], v[104:107]
	v_mfma_f32_16x16x32_bf16 v[92:95], v[132:135], v[194:197], v[92:95]
	v_mfma_f32_16x16x32_bf16 v[88:91], v[140:143], v[194:197], v[88:91]
	v_mfma_f32_16x16x32_bf16 v[76:79], v[132:135], v[218:221], v[76:79]
	v_mfma_f32_16x16x32_bf16 v[72:75], v[140:143], v[218:221], v[72:75]
	s_setprio 0
	s_barrier
	s_add_i32 s36, 0, 0x1c000
	s_add_i32 s37, s55, s42
	v_add_u32_e32 v234, s36, v178
	v_lshl_add_u64 v[158:159], v[158:159], 0, s[2:3]
	s_mov_b32 m0, s37
	ds_read_b128 v[222:225], v234
	ds_read_b128 v[226:229], v234 offset:1024
	ds_read_b128 v[230:233], v234 offset:2048
	ds_read_b128 v[234:237], v234 offset:3072
	global_load_lds_dwordx4 v[158:159], off
	v_lshl_add_u64 v[158:159], v[238:239], 0, s[2:3]
	s_add_i32 m0, s37, 0x2000
	s_nop 0
	global_load_lds_dwordx4 v[158:159], off
	s_barrier
	s_waitcnt lgkmcnt(0)
	s_setprio 1
	v_mfma_f32_16x16x32_bf16 v[116:119], v[222:225], v[154:157], v[116:119]
	v_mfma_f32_16x16x32_bf16 v[112:115], v[230:233], v[154:157], v[112:115]
	v_mfma_f32_16x16x32_bf16 v[100:103], v[222:225], v[182:185], v[100:103]
	v_mfma_f32_16x16x32_bf16 v[96:99], v[230:233], v[182:185], v[96:99]
	v_mfma_f32_16x16x32_bf16 v[84:87], v[222:225], v[190:193], v[84:87]
	v_mfma_f32_16x16x32_bf16 v[80:83], v[230:233], v[190:193], v[80:83]
	v_mfma_f32_16x16x32_bf16 v[68:71], v[222:225], v[214:217], v[68:71]
	v_mfma_f32_16x16x32_bf16 v[64:67], v[230:233], v[214:217], v[64:67]
	v_mfma_f32_16x16x32_bf16 v[116:119], v[226:229], v[174:177], v[116:119]
	v_mfma_f32_16x16x32_bf16 v[112:115], v[234:237], v[174:177], v[112:115]
	v_mfma_f32_16x16x32_bf16 v[100:103], v[226:229], v[186:189], v[100:103]
	v_mfma_f32_16x16x32_bf16 v[96:99], v[234:237], v[186:189], v[96:99]
	v_mfma_f32_16x16x32_bf16 v[84:87], v[226:229], v[194:197], v[84:87]
	v_mfma_f32_16x16x32_bf16 v[80:83], v[234:237], v[194:197], v[80:83]
	v_mfma_f32_16x16x32_bf16 v[68:71], v[226:229], v[218:221], v[68:71]
	v_mfma_f32_16x16x32_bf16 v[64:67], v[234:237], v[218:221], v[64:67]
	s_setprio 0
	s_mov_b32 m0, s47
	v_lshl_add_u64 v[158:159], v[240:241], 0, s[2:3]
	s_barrier
	ds_read_b128 v[154:157], v181 offset:49152
	ds_read_b128 v[174:177], v181 offset:50176
	ds_read_b128 v[182:185], v181 offset:51200
	ds_read_b128 v[186:189], v181 offset:52224
	ds_read_b128 v[190:193], v181 offset:53248
	ds_read_b128 v[194:197], v181 offset:54272
	ds_read_b128 v[214:217], v181 offset:55296
	ds_read_b128 v[218:221], v181 offset:56320
	global_load_lds_dwordx4 v[158:159], off
	v_lshl_add_u64 v[158:159], v[242:243], 0, s[2:3]
	s_mov_b32 m0, s48
	s_nop 0
	global_load_lds_dwordx4 v[158:159], off
	s_barrier
; DEV bf16x8 pack8(f32x4 a, f32x4 b) { u32x4 w; w.x = cvt_pk_bf16(a[0], a[1]); w.y = cvt_pk_bf16(a[2], a[3]); w.z = cvt_pk_bf16(b[0], b[1]); w.w = cvt_pk_bf16(b[2], b[3]); return __builtin_bit_cast(bf16x8, w); }
; #define PG8_WAIT_V(n) asm volatile("s_waitcnt vmcnt(" #n ")" ::: "memory")
; #define PG8_WAIT_L(n) asm volatile("s_waitcnt lgkmcnt(" #n ")" ::: "memory")
; #define PG8_BAR __builtin_amdgcn_s_barrier()
; template <class Epi>
; DEV void gemm_phase(LAS unsigned char* lds, const Gemm g, const StaticOrder& S, const Epi& E) {
;     ...
;             PG8_BAR; PG8_WAIT_L(0); PG8_MMA(1, 0, At, B0); PG8_BAR; PG8_SCHED;
;             PG8_STAGE(PG8_SB(1, 1), b3 + hstep, voffB);
;             PG8_WAIT_V(6); PG8_BAR; PG8_MMA(1, 1, At, B1); PG8_BAR;
;         }
;     DEV void operator()(AccRef acc, const pg8::Unit& u, int wr, int wc, int fr, int fq) const {
;         const int row0 = u.pm * 256 + wr * 64 + fr, col0 = u.pn * 256 + wc * 32 + 8 * fq;
; #pragma unroll
;         for (int am = 0; am < 4; ++am) { const int ai = am >> 1, m0 = (am & 1) * 2;
;             f32x4 bv[4][2][2];
; #pragma unroll
;             for (int m = m0; m < m0 + 2; ++m)
; #pragma unroll
;                 for (int bj = 0; bj < 2; ++bj)
; #pragma unroll
;                     for (int n = 0; n < 2; ++n) bv[m][bj][n] = *(const f32x4*)(base + (size_t)(row0 + ai * 128 + m * 16) * 2048 + col0 + bj * 128 + n * 4);
; #pragma unroll
;             for (int m = m0; m < m0 + 2; ++m) { const size_t off = (size_t)(row0 + ai * 128 + m * 16) * 2048 + col0; float sq = 0.f;
; #pragma unroll
;                 for (int bj = 0; bj < 2; ++bj) { const f32x4 o0 = bv[m][bj][0] + scale * acc[ai][bj][m][0], o1 = bv[m][bj][1] + scale * acc[ai][bj][m][1];
;                     *(f32x4*)(out + off + bj * 128) = o0; *(f32x4*)(out + off + bj * 128 + 4) = o1;
;                     if (xb) { *(u32x4*)(xb + off + bj * 128) = __builtin_bit_cast(u32x4, pack8(o0, o1));
;                         sq += (o0[0] * o0[0] + o0[1] * o0[1] + o0[2] * o0[2] + o0[3] * o0[3]) + (o1[0] * o1[0] + o1[1] * o1[1] + o1[2] * o1[2] + o1[3] * o1[3]); } }
;                 if (ssout) { sq += __shfl_xor(sq, 16); sq += __shfl_xor(sq, 32);
;                     if (fq == 0) { if (red) red[(ai * 128 + wr * 64 + m * 16 + fr) * 4 + wc] = sq; else atomicAdd(ssout + (size_t)(row0 + ai * 128 + m * 16) * 8 + u.pn, sq); } } }
	s_waitcnt lgkmcnt(0)
	s_setprio 1
	v_mfma_f32_16x16x32_bf16 v[60:63], v[128:131], v[154:157], v[60:63]
	v_mfma_f32_16x16x32_bf16 v[56:59], v[136:139], v[154:157], v[56:59]
	v_mfma_f32_16x16x32_bf16 v[44:47], v[128:131], v[182:185], v[44:47]
	v_mfma_f32_16x16x32_bf16 v[40:43], v[136:139], v[182:185], v[40:43]
	v_mfma_f32_16x16x32_bf16 v[28:31], v[128:131], v[190:193], v[28:31]
	v_mfma_f32_16x16x32_bf16 v[24:27], v[136:139], v[190:193], v[24:27]
	v_mfma_f32_16x16x32_bf16 v[12:15], v[128:131], v[214:217], v[12:15]
	v_mfma_f32_16x16x32_bf16 v[8:11], v[136:139], v[214:217], v[8:11]
	v_mfma_f32_16x16x32_bf16 v[60:63], v[132:135], v[174:177], v[60:63]
	v_mfma_f32_16x16x32_bf16 v[56:59], v[140:143], v[174:177], v[56:59]
	v_mfma_f32_16x16x32_bf16 v[44:47], v[132:135], v[186:189], v[44:47]
	v_mfma_f32_16x16x32_bf16 v[40:43], v[140:143], v[186:189], v[40:43]
	v_mfma_f32_16x16x32_bf16 v[28:31], v[132:135], v[194:197], v[28:31]
	v_mfma_f32_16x16x32_bf16 v[24:27], v[140:143], v[194:197], v[24:27]
	v_mfma_f32_16x16x32_bf16 v[12:15], v[132:135], v[218:221], v[12:15]
	v_mfma_f32_16x16x32_bf16 v[8:11], v[140:143], v[218:221], v[8:11]
	s_setprio 0
	s_barrier
	s_add_u32 s34, s34, 0x20080
	s_addc_u32 s35, s35, 0
	s_add_i32 s36, s36, s42
	v_lshl_add_u64 v[128:129], s[34:35], 0, v[160:161]
	s_mov_b32 m0, s36
	s_nop 0
	global_load_lds_dwordx4 v[128:129], off
	v_lshl_add_u64 v[128:129], s[34:35], 0, v[148:149]
	s_add_i32 m0, s36, 0x2000
	s_nop 0
	global_load_lds_dwordx4 v[128:129], off
	s_waitcnt vmcnt(6)
	s_barrier
	s_setprio 1
	v_mfma_f32_16x16x32_bf16 v[52:55], v[222:225], v[154:157], v[52:55]
	v_mfma_f32_16x16x32_bf16 v[48:51], v[230:233], v[154:157], v[48:51]
	v_mfma_f32_16x16x32_bf16 v[36:39], v[222:225], v[182:185], v[36:39]
	v_mfma_f32_16x16x32_bf16 v[32:35], v[230:233], v[182:185], v[32:35]
	v_mfma_f32_16x16x32_bf16 v[20:23], v[222:225], v[190:193], v[20:23]
	v_mfma_f32_16x16x32_bf16 v[16:19], v[230:233], v[190:193], v[16:19]
	v_mfma_f32_16x16x32_bf16 v[4:7], v[222:225], v[214:217], v[4:7]
	v_mfma_f32_16x16x32_bf16 v[0:3], v[230:233], v[214:217], v[0:3]
	v_mfma_f32_16x16x32_bf16 v[52:55], v[226:229], v[174:177], v[52:55]
	v_mfma_f32_16x16x32_bf16 v[48:51], v[234:237], v[174:177], v[48:51]
	v_mfma_f32_16x16x32_bf16 v[36:39], v[226:229], v[186:189], v[36:39]
	v_mfma_f32_16x16x32_bf16 v[32:35], v[234:237], v[186:189], v[32:35]
	v_mfma_f32_16x16x32_bf16 v[20:23], v[226:229], v[194:197], v[20:23]
	v_mfma_f32_16x16x32_bf16 v[16:19], v[234:237], v[194:197], v[16:19]
	v_mfma_f32_16x16x32_bf16 v[4:7], v[226:229], v[218:221], v[4:7]
	v_mfma_f32_16x16x32_bf16 v[0:3], v[234:237], v[218:221], v[0:3]
	s_setprio 0
	s_add_i32 s54, s54, 2
	s_add_u32 s30, s30, 0x100
	s_addc_u32 s31, s31, 0
	s_add_u32 s52, s52, 0x100
	s_addc_u32 s53, s53, 0
	s_cmp_gt_u32 s54, 5
	s_barrier
	s_cbranch_scc0 .LBB0_260
	v_lshl_add_u32 v156, s28, 8, v167
	v_lshl_or_b32 v154, s18, 8, v179
	v_readlane_b32 s28, v254, 16
	v_ashrrev_i32_e32 v155, 31, v154
	v_readlane_b32 s29, v254, 17
	v_ashrrev_i32_e32 v157, 31, v156
	v_lshlrev_b64 v[128:129], 13, v[156:157]
	v_lshl_add_u64 v[158:159], v[154:155], 2, s[28:29]
	v_lshl_add_u64 v[214:215], v[158:159], 0, v[128:129]
	global_load_dwordx4 v[182:185], v[214:215], off offset:16
	global_load_dwordx4 v[186:189], v[214:215], off
	global_load_dwordx4 v[190:193], v[214:215], off offset:528
	global_load_dwordx4 v[194:197], v[214:215], off offset:512
	v_or_b32_e32 v174, 16, v156
	v_ashrrev_i32_e32 v175, 31, v174
	v_lshlrev_b64 v[128:129], 13, v[174:175]
	v_lshl_add_u64 v[176:177], v[158:159], 0, v[128:129]
	global_load_dwordx4 v[136:139], v[176:177], off offset:16
	global_load_dwordx4 v[140:143], v[176:177], off
	global_load_dwordx4 v[128:131], v[176:177], off offset:528
	global_load_dwordx4 v[132:135], v[176:177], off offset:512
	v_lshlrev_b64 v[216:217], 11, v[156:157]
	v_readlane_b32 s28, v250, 9
	v_lshl_add_u64 v[216:217], v[216:217], 0, v[154:155]
	v_readlane_b32 s29, v250, 10
	v_cmp_lt_i32_e32 vcc, v208, v206
	s_ashr_i32 s19, s18, 31
	s_waitcnt vmcnt(0)
	v_pk_add_f32 v[120:121], v[120:121], v[182:183]
	v_pk_add_f32 v[126:127], v[126:127], v[188:189]
	v_pk_add_f32 v[124:125], v[124:125], v[186:187]
	v_pk_add_f32 v[122:123], v[122:123], v[184:185]
	global_store_dwordx4 v[214:215], v[124:127], off
	global_store_dwordx4 v[214:215], v[120:123], off offset:16
	v_cvt_pk_bf16_f32 v184, v120, v121
	v_cvt_pk_bf16_f32 v182, v124, v125
	v_mul_f32_e32 v121, v121, v121
	v_cvt_pk_bf16_f32 v183, v126, v127
	v_cvt_pk_bf16_f32 v185, v122, v123
	v_lshl_add_u64 v[186:187], v[216:217], 1, s[28:29]
	v_fmac_f32_e32 v121, v120, v120
	v_pk_add_f32 v[118:119], v[118:119], v[196:197]
	v_pk_add_f32 v[116:117], v[116:117], v[194:195]
	v_pk_add_f32 v[112:113], v[112:113], v[190:191]
	global_store_dwordx4 v[186:187], v[182:185], off
	v_mul_f32_e32 v125, v125, v125
	v_fmac_f32_e32 v121, v122, v122
	v_pk_add_f32 v[114:115], v[114:115], v[192:193]
	global_store_dwordx4 v[214:215], v[116:119], off offset:512
	global_store_dwordx4 v[214:215], v[112:115], off offset:528
	v_cvt_pk_bf16_f32 v120, v116, v117
	v_cvt_pk_bf16_f32 v122, v112, v113
	v_mul_f32_e32 v117, v117, v117
	v_mul_f32_e32 v113, v113, v113
	v_fmac_f32_e32 v125, v124, v124
	v_fmac_f32_e32 v117, v116, v116
	v_fmac_f32_e32 v113, v112, v112
	v_fmac_f32_e32 v125, v126, v126
	v_fmac_f32_e32 v117, v118, v118
	v_fmac_f32_e32 v113, v114, v114
	v_fmac_f32_e32 v125, v127, v127
	v_fmac_f32_e32 v121, v123, v123
	v_fmac_f32_e32 v117, v119, v119
	v_fmac_f32_e32 v113, v115, v115
	v_add_f32_e32 v124, v125, v121
	v_add_f32_e32 v112, v117, v113
	v_cndmask_b32_e32 v113, v204, v208, vcc
	v_cvt_pk_bf16_f32 v121, v118, v119
	v_add_f32_e32 v112, v124, v112
	v_lshlrev_b32_e32 v118, 2, v113
	ds_bpermute_b32 v113, v118, v112
	v_cmp_lt_i32_e32 vcc, v207, v206
	v_cvt_pk_bf16_f32 v123, v114, v115
	global_store_dwordx4 v[186:187], v[120:123], off offset:256
	s_waitcnt lgkmcnt(0)
	v_add_f32_e32 v112, v112, v113
	v_cndmask_b32_e32 v113, v204, v207, vcc
	v_lshlrev_b32_e32 v119, 2, v113
	ds_bpermute_b32 v113, v119, v112
	s_and_saveexec_b64 s[28:29], s[6:7]
	s_cbranch_execz .LBB0_266
	s_waitcnt lgkmcnt(0)
	v_add_f32_e32 v112, v112, v113
	s_mov_b64 s[30:31], -1
	s_and_b64 vcc, exec, s[16:17]
	s_cbranch_vccz .LBB0_264
	v_lshlrev_b64 v[114:115], 5, v[156:157]
	v_lshl_add_u64 v[114:115], s[12:13], 0, v[114:115]
	v_lshl_add_u64 v[114:115], s[18:19], 2, v[114:115]
	global_atomic_add_f32 v[114:115], v112, off
	s_mov_b64 s[30:31], 0

; #define PG8_STAGE(bufoff, gbase, voff) do { _Pragma("unroll") for (int _i = 0; _i < 2; ++_i) \
;         __builtin_amdgcn_global_load_lds((const unsigned*)((const char*)(gbase) + (voff)[_i]), (LAS unsigned*)(lds + (bufoff) + ldsw + _i * 8192), 16, 0, 0); } while (0)
; #define PG8_LDA(dst, b, h) do { _Pragma("unroll") for (int m = 0; m < 4; ++m) _Pragma("unroll") for (int k = 0; k < 2; ++k) dst[m][k] = *(const LAS bf16x8*)(lds + PG8_SA(b, h) + aoff + m * 2048 + k * 1024); } while (0)
; #define PG8_LDB(dst, b, h) do { _Pragma("unroll") for (int n = 0; n < 2; ++n) _Pragma("unroll") for (int k = 0; k < 2; ++k) dst[n][k] = *(const LAS bf16x8*)(lds + PG8_SB(b, h) + boff + n * 2048 + k * 1024); } while (0)
; #define PG8_MMA(ai, bj, At, Bt) do { __builtin_amdgcn_s_setprio(1); _Pragma("unroll") for (int m = 0; m < 4; ++m) _Pragma("unroll") for (int n = 0; n < 2; ++n) _Pragma("unroll") for (int k = 0; k < 2; ++k) \
;         acc[ai][bj][m][n] = __builtin_amdgcn_mfma_f32_16x16x32_bf16(Bt[n][k], At[m][k], acc[ai][bj][m][n], 0, 0, 0); __builtin_amdgcn_s_setprio(0); } while (0)
; #define PG8_WAIT_L(n) asm volatile("s_waitcnt lgkmcnt(" #n ")" ::: "memory")
; #define PG8_BAR __builtin_amdgcn_s_barrier()
; #define PG8_SCHED __builtin_amdgcn_sched_barrier(0)
; template <class Epi>
; DEV void gemm_phase(LAS unsigned char* lds, const Gemm g, const StaticOrder& S, const Epi& E) {
;     ...
;             PG8_LDB(B0, 0, 0); PG8_SCHED; PG8_LDA(At, 0, 0); PG8_STAGE(PG8_SA(1, 1), a1 + hstep, voffA);
;             PG8_WAIT_L(8); PG8_BAR; PG8_WAIT_L(0); PG8_MMA(0, 0, At, B0); PG8_BAR; PG8_SCHED;
;             PG8_LDB(B1, 0, 1); PG8_STAGE(PG8_SB(0, 0), b2, voffB);
;             PG8_BAR; PG8_WAIT_L(0); PG8_MMA(0, 1, At, B1); PG8_BAR;
;             PG8_LDA(At, 0, 1); PG8_STAGE(PG8_SA(0, 0), a2, voffA);
;             PG8_BAR; PG8_WAIT_L(0); PG8_MMA(1, 0, At, B0); PG8_BAR; PG8_SCHED;
.LBB0_344:
	s_add_u32 s20, s18, 0xfff80080
	s_addc_u32 s21, s19, -1
	s_add_i32 s45, 0, 0x10000
	v_add_u32_e32 v146, s45, v149
	ds_read_b128 v[128:131], v146
	ds_read_b128 v[132:135], v146 offset:1024
	ds_read_b128 v[142:145], v146 offset:2048
	ds_read_b128 v[150:153], v146 offset:3072
	s_cmp_eq_u32 s44, 28
	s_cselect_b32 s23, s1, s21
	s_cselect_b32 s22, s13, s20
	s_cselect_b32 s21, s11, s43
	s_cselect_b32 s20, s41, s42
	v_lshl_add_u64 v[154:155], s[18:19], 0, v[138:139]
	s_add_i32 m0, s30, 0xc000
	ds_read_b128 v[174:177], v159
	ds_read_b128 v[178:181], v159 offset:1024
	ds_read_b128 v[182:185], v159 offset:2048
	ds_read_b128 v[186:189], v159 offset:3072
	ds_read_b128 v[190:193], v159 offset:4096
	ds_read_b128 v[194:197], v159 offset:5120
	ds_read_b128 v[214:217], v159 offset:6144
	ds_read_b128 v[218:221], v159 offset:7168
	global_load_lds_dwordx4 v[154:155], off
	v_lshl_add_u64 v[154:155], s[18:19], 0, v[140:141]
	s_add_i32 m0, s30, 0xe000
	s_nop 0
	global_load_lds_dwordx4 v[154:155], off
	s_waitcnt lgkmcnt(8)
	s_barrier
	s_waitcnt lgkmcnt(0)
	s_setprio 1
	v_mfma_f32_16x16x32_bf16 v[124:127], v[128:131], v[174:177], v[124:127]
	v_mfma_f32_16x16x32_bf16 v[120:123], v[142:145], v[174:177], v[120:123]
	v_mfma_f32_16x16x32_bf16 v[116:119], v[128:131], v[182:185], v[116:119]
	v_mfma_f32_16x16x32_bf16 v[108:111], v[142:145], v[182:185], v[108:111]
	v_mfma_f32_16x16x32_bf16 v[100:103], v[128:131], v[190:193], v[100:103]
	v_mfma_f32_16x16x32_bf16 v[92:95], v[142:145], v[190:193], v[92:95]
	v_mfma_f32_16x16x32_bf16 v[84:87], v[128:131], v[214:217], v[84:87]
	v_mfma_f32_16x16x32_bf16 v[76:79], v[142:145], v[214:217], v[76:79]
	v_mfma_f32_16x16x32_bf16 v[124:127], v[132:135], v[178:181], v[124:127]
	v_mfma_f32_16x16x32_bf16 v[120:123], v[150:153], v[178:181], v[120:123]
	v_mfma_f32_16x16x32_bf16 v[116:119], v[132:135], v[186:189], v[116:119]
	v_mfma_f32_16x16x32_bf16 v[108:111], v[150:153], v[186:189], v[108:111]
	v_mfma_f32_16x16x32_bf16 v[100:103], v[132:135], v[194:197], v[100:103]
	v_mfma_f32_16x16x32_bf16 v[92:95], v[150:153], v[194:197], v[92:95]
	v_mfma_f32_16x16x32_bf16 v[84:87], v[132:135], v[218:221], v[84:87]
	v_mfma_f32_16x16x32_bf16 v[76:79], v[150:153], v[218:221], v[76:79]
	s_setprio 0
	s_barrier
	s_add_i32 s48, 0, 0x14000
	s_add_i32 s45, s45, s29
	v_add_u32_e32 v146, s48, v149
	v_lshl_add_u64 v[154:155], s[20:21], 0, v[160:161]
	s_mov_b32 m0, s45
	ds_read_b128 v[222:225], v146
	ds_read_b128 v[226:229], v146 offset:1024
	ds_read_b128 v[230:233], v146 offset:2048
	ds_read_b128 v[234:237], v146 offset:3072
	global_load_lds_dwordx4 v[154:155], off
	v_lshl_add_u64 v[238:239], s[20:21], 0, v[136:137]
	s_add_i32 m0, s45, 0x2000
	s_nop 0
	global_load_lds_dwordx4 v[238:239], off
	s_barrier
	s_waitcnt lgkmcnt(0)
	s_setprio 1
	v_mfma_f32_16x16x32_bf16 v[112:115], v[222:225], v[174:177], v[112:115]
	v_mfma_f32_16x16x32_bf16 v[104:107], v[230:233], v[174:177], v[104:107]
	v_mfma_f32_16x16x32_bf16 v[96:99], v[222:225], v[182:185], v[96:99]
	v_mfma_f32_16x16x32_bf16 v[88:91], v[230:233], v[182:185], v[88:91]
	v_mfma_f32_16x16x32_bf16 v[80:83], v[222:225], v[190:193], v[80:83]
	v_mfma_f32_16x16x32_bf16 v[72:75], v[230:233], v[190:193], v[72:75]
	v_mfma_f32_16x16x32_bf16 v[68:71], v[222:225], v[214:217], v[68:71]
	v_mfma_f32_16x16x32_bf16 v[64:67], v[230:233], v[214:217], v[64:67]
	v_mfma_f32_16x16x32_bf16 v[112:115], v[226:229], v[178:181], v[112:115]
	v_mfma_f32_16x16x32_bf16 v[104:107], v[234:237], v[178:181], v[104:107]
	v_mfma_f32_16x16x32_bf16 v[96:99], v[226:229], v[186:189], v[96:99]
	v_mfma_f32_16x16x32_bf16 v[88:91], v[234:237], v[186:189], v[88:91]
	v_mfma_f32_16x16x32_bf16 v[80:83], v[226:229], v[194:197], v[80:83]
	v_mfma_f32_16x16x32_bf16 v[72:75], v[234:237], v[194:197], v[72:75]
	v_mfma_f32_16x16x32_bf16 v[68:71], v[226:229], v[218:221], v[68:71]
	v_mfma_f32_16x16x32_bf16 v[64:67], v[234:237], v[218:221], v[64:67]
	s_setprio 0
	s_mov_b32 m0, s30
	v_lshl_add_u64 v[240:241], s[22:23], 0, v[160:161]
	s_barrier
	ds_read_b128 v[174:177], v159 offset:16384
	ds_read_b128 v[178:181], v159 offset:17408
	ds_read_b128 v[182:185], v159 offset:18432
	ds_read_b128 v[186:189], v159 offset:19456
	ds_read_b128 v[190:193], v159 offset:20480
	ds_read_b128 v[194:197], v159 offset:21504
	ds_read_b128 v[214:217], v159 offset:22528
	ds_read_b128 v[218:221], v159 offset:23552
	global_load_lds_dwordx4 v[240:241], off
	v_lshl_add_u64 v[242:243], s[22:23], 0, v[136:137]
	s_mov_b32 m0, s31
	s_nop 0
	global_load_lds_dwordx4 v[242:243], off
	s_barrier
	s_waitcnt lgkmcnt(0)
	s_setprio 1
	v_mfma_f32_16x16x32_bf16 v[60:63], v[128:131], v[174:177], v[60:63]
	v_mfma_f32_16x16x32_bf16 v[56:59], v[142:145], v[174:177], v[56:59]
	v_mfma_f32_16x16x32_bf16 v[52:55], v[128:131], v[182:185], v[52:55]
	v_mfma_f32_16x16x32_bf16 v[44:47], v[142:145], v[182:185], v[44:47]
	v_mfma_f32_16x16x32_bf16 v[36:39], v[128:131], v[190:193], v[36:39]
	v_mfma_f32_16x16x32_bf16 v[28:31], v[142:145], v[190:193], v[28:31]
	v_mfma_f32_16x16x32_bf16 v[20:23], v[128:131], v[214:217], v[20:23]
	v_mfma_f32_16x16x32_bf16 v[12:15], v[142:145], v[214:217], v[12:15]
	v_mfma_f32_16x16x32_bf16 v[60:63], v[132:135], v[178:181], v[60:63]
	v_mfma_f32_16x16x32_bf16 v[56:59], v[150:153], v[178:181], v[56:59]
	v_mfma_f32_16x16x32_bf16 v[52:55], v[132:135], v[186:189], v[52:55]
	v_mfma_f32_16x16x32_bf16 v[44:47], v[150:153], v[186:189], v[44:47]
	v_mfma_f32_16x16x32_bf16 v[36:39], v[132:135], v[194:197], v[36:39]
	v_mfma_f32_16x16x32_bf16 v[28:31], v[150:153], v[194:197], v[28:31]
	v_mfma_f32_16x16x32_bf16 v[20:23], v[132:135], v[218:221], v[20:23]
	v_mfma_f32_16x16x32_bf16 v[12:15], v[150:153], v[218:221], v[12:15]
	s_setprio 0
	s_barrier
; #define PG8_STAGE(bufoff, gbase, voff) do { _Pragma("unroll") for (int _i = 0; _i < 2; ++_i) \
;         __builtin_amdgcn_global_load_lds((const unsigned*)((const char*)(gbase) + (voff)[_i]), (LAS unsigned*)(lds + (bufoff) + ldsw + _i * 8192), 16, 0, 0); } while (0)
; #define PG8_LDA(dst, b, h) do { _Pragma("unroll") for (int m = 0; m < 4; ++m) _Pragma("unroll") for (int k = 0; k < 2; ++k) dst[m][k] = *(const LAS bf16x8*)(lds + PG8_SA(b, h) + aoff + m * 2048 + k * 1024); } while (0)
; #define PG8_LDB(dst, b, h) do { _Pragma("unroll") for (int n = 0; n < 2; ++n) _Pragma("unroll") for (int k = 0; k < 2; ++k) dst[n][k] = *(const LAS bf16x8*)(lds + PG8_SB(b, h) + boff + n * 2048 + k * 1024); } while (0)
; #define PG8_MMA(ai, bj, At, Bt) do { __builtin_amdgcn_s_setprio(1); _Pragma("unroll") for (int m = 0; m < 4; ++m) _Pragma("unroll") for (int n = 0; n < 2; ++n) _Pragma("unroll") for (int k = 0; k < 2; ++k) \
;         acc[ai][bj][m][n] = __builtin_amdgcn_mfma_f32_16x16x32_bf16(Bt[n][k], At[m][k], acc[ai][bj][m][n], 0, 0, 0); __builtin_amdgcn_s_setprio(0); } while (0)
; #define PG8_WAIT_V(n) asm volatile("s_waitcnt vmcnt(" #n ")" ::: "memory")
; #define PG8_WAIT_L(n) asm volatile("s_waitcnt lgkmcnt(" #n ")" ::: "memory")
; #define PG8_BAR __builtin_amdgcn_s_barrier()
; #define PG8_SCHED __builtin_amdgcn_sched_barrier(0)
; template <class Epi>
; DEV void gemm_phase(LAS unsigned char* lds, const Gemm g, const StaticOrder& S, const Epi& E) {
;     ...
;             PG8_STAGE(PG8_SB(0, 1), b2 + hstep, voffB);
;             PG8_WAIT_V(6); PG8_BAR; PG8_MMA(1, 1, At, B1); PG8_BAR;
;             PG8_LDB(B0, 1, 0); PG8_SCHED; PG8_LDA(At, 1, 0); PG8_STAGE(PG8_SA(0, 1), a2 + hstep, voffA);
;             PG8_WAIT_L(8); PG8_BAR; PG8_WAIT_L(0); PG8_MMA(0, 0, At, B0); PG8_BAR; PG8_SCHED;
;             PG8_LDB(B1, 1, 1); PG8_STAGE(PG8_SB(1, 0), b3, voffB);
;             PG8_BAR; PG8_WAIT_L(0); PG8_MMA(0, 1, At, B1); PG8_BAR;
;             PG8_LDA(At, 1, 1); PG8_STAGE(PG8_SA(1, 0), a3, voffA);
	s_add_u32 s46, s20, 0x80000
	s_addc_u32 s47, s21, 0
	s_add_i32 s45, s48, s29
	v_lshl_add_u64 v[128:129], s[46:47], 0, v[160:161]
	s_mov_b32 m0, s45
	s_nop 0
	global_load_lds_dwordx4 v[128:129], off
	v_lshl_add_u64 v[128:129], s[46:47], 0, v[136:137]
	s_add_i32 m0, s45, 0x2000
	s_nop 0
	global_load_lds_dwordx4 v[128:129], off
	s_waitcnt vmcnt(6)
	s_barrier
	s_setprio 1
	v_mfma_f32_16x16x32_bf16 v[48:51], v[222:225], v[174:177], v[48:51]
	v_mfma_f32_16x16x32_bf16 v[40:43], v[230:233], v[174:177], v[40:43]
	v_mfma_f32_16x16x32_bf16 v[32:35], v[222:225], v[182:185], v[32:35]
	v_mfma_f32_16x16x32_bf16 v[24:27], v[230:233], v[182:185], v[24:27]
	v_mfma_f32_16x16x32_bf16 v[16:19], v[222:225], v[190:193], v[16:19]
	v_mfma_f32_16x16x32_bf16 v[8:11], v[230:233], v[190:193], v[8:11]
	v_mfma_f32_16x16x32_bf16 v[4:7], v[222:225], v[214:217], v[4:7]
	v_mfma_f32_16x16x32_bf16 v[0:3], v[230:233], v[214:217], v[0:3]
	v_mfma_f32_16x16x32_bf16 v[48:51], v[226:229], v[178:181], v[48:51]
	v_mfma_f32_16x16x32_bf16 v[40:43], v[234:237], v[178:181], v[40:43]
	v_mfma_f32_16x16x32_bf16 v[32:35], v[226:229], v[186:189], v[32:35]
	v_mfma_f32_16x16x32_bf16 v[24:27], v[234:237], v[186:189], v[24:27]
	v_mfma_f32_16x16x32_bf16 v[16:19], v[226:229], v[194:197], v[16:19]
	v_mfma_f32_16x16x32_bf16 v[8:11], v[234:237], v[194:197], v[8:11]
	v_mfma_f32_16x16x32_bf16 v[4:7], v[226:229], v[218:221], v[4:7]
	v_mfma_f32_16x16x32_bf16 v[0:3], v[234:237], v[218:221], v[0:3]
	s_setprio 0
	s_add_i32 s45, 0, 0x18000
	v_add_u32_e32 v146, s45, v149
	s_barrier
	ds_read_b128 v[128:131], v146
	ds_read_b128 v[132:135], v146 offset:1024
	ds_read_b128 v[142:145], v146 offset:2048
	ds_read_b128 v[150:153], v146 offset:3072
	s_add_u32 s22, s22, 0x80000
	s_addc_u32 s23, s23, 0
	s_mov_b32 m0, s34
	v_lshl_add_u64 v[222:223], s[22:23], 0, v[160:161]
	ds_read_b128 v[174:177], v159 offset:32768
	ds_read_b128 v[178:181], v159 offset:33792
	ds_read_b128 v[182:185], v159 offset:34816
	ds_read_b128 v[186:189], v159 offset:35840
	ds_read_b128 v[190:193], v159 offset:36864
	ds_read_b128 v[194:197], v159 offset:37888
	ds_read_b128 v[214:217], v159 offset:38912
	ds_read_b128 v[218:221], v159 offset:39936
	global_load_lds_dwordx4 v[222:223], off
	v_lshl_add_u64 v[222:223], s[22:23], 0, v[136:137]
	s_mov_b32 m0, s35
	s_nop 0
	global_load_lds_dwordx4 v[222:223], off
	s_waitcnt lgkmcnt(8)
	s_barrier
	s_waitcnt lgkmcnt(0)
	s_setprio 1
	v_mfma_f32_16x16x32_bf16 v[124:127], v[128:131], v[174:177], v[124:127]
	v_mfma_f32_16x16x32_bf16 v[120:123], v[142:145], v[174:177], v[120:123]
	v_mfma_f32_16x16x32_bf16 v[116:119], v[128:131], v[182:185], v[116:119]
	v_mfma_f32_16x16x32_bf16 v[108:111], v[142:145], v[182:185], v[108:111]
	v_mfma_f32_16x16x32_bf16 v[100:103], v[128:131], v[190:193], v[100:103]
	v_mfma_f32_16x16x32_bf16 v[92:95], v[142:145], v[190:193], v[92:95]
	v_mfma_f32_16x16x32_bf16 v[84:87], v[128:131], v[214:217], v[84:87]
	v_mfma_f32_16x16x32_bf16 v[76:79], v[142:145], v[214:217], v[76:79]
	v_mfma_f32_16x16x32_bf16 v[124:127], v[132:135], v[178:181], v[124:127]
	v_mfma_f32_16x16x32_bf16 v[120:123], v[150:153], v[178:181], v[120:123]
	v_mfma_f32_16x16x32_bf16 v[116:119], v[132:135], v[186:189], v[116:119]
	v_mfma_f32_16x16x32_bf16 v[108:111], v[150:153], v[186:189], v[108:111]
	v_mfma_f32_16x16x32_bf16 v[100:103], v[132:135], v[194:197], v[100:103]
	v_mfma_f32_16x16x32_bf16 v[92:95], v[150:153], v[194:197], v[92:95]
	v_mfma_f32_16x16x32_bf16 v[84:87], v[132:135], v[218:221], v[84:87]
	v_mfma_f32_16x16x32_bf16 v[76:79], v[150:153], v[218:221], v[76:79]
	s_setprio 0
	s_barrier
	s_add_i32 s22, 0, 0x1c000
	s_add_i32 s23, s45, s29
	v_add_u32_e32 v146, s22, v149
	v_lshl_add_u64 v[154:155], v[154:155], 0, s[2:3]
	s_mov_b32 m0, s23
	ds_read_b128 v[222:225], v146
	ds_read_b128 v[226:229], v146 offset:1024
	ds_read_b128 v[230:233], v146 offset:2048
	ds_read_b128 v[234:237], v146 offset:3072
	global_load_lds_dwordx4 v[154:155], off
	v_lshl_add_u64 v[154:155], v[238:239], 0, s[2:3]
	s_add_i32 m0, s23, 0x2000
	s_nop 0
	global_load_lds_dwordx4 v[154:155], off
	s_barrier
	s_waitcnt lgkmcnt(0)
	s_setprio 1
	v_mfma_f32_16x16x32_bf16 v[112:115], v[222:225], v[174:177], v[112:115]
	v_mfma_f32_16x16x32_bf16 v[104:107], v[230:233], v[174:177], v[104:107]
	v_mfma_f32_16x16x32_bf16 v[96:99], v[222:225], v[182:185], v[96:99]
	v_mfma_f32_16x16x32_bf16 v[88:91], v[230:233], v[182:185], v[88:91]
	v_mfma_f32_16x16x32_bf16 v[80:83], v[222:225], v[190:193], v[80:83]
	v_mfma_f32_16x16x32_bf16 v[72:75], v[230:233], v[190:193], v[72:75]
	v_mfma_f32_16x16x32_bf16 v[68:71], v[222:225], v[214:217], v[68:71]
	v_mfma_f32_16x16x32_bf16 v[64:67], v[230:233], v[214:217], v[64:67]
	v_mfma_f32_16x16x32_bf16 v[112:115], v[226:229], v[178:181], v[112:115]
	v_mfma_f32_16x16x32_bf16 v[104:107], v[234:237], v[178:181], v[104:107]
	v_mfma_f32_16x16x32_bf16 v[96:99], v[226:229], v[186:189], v[96:99]
	v_mfma_f32_16x16x32_bf16 v[88:91], v[234:237], v[186:189], v[88:91]
	v_mfma_f32_16x16x32_bf16 v[80:83], v[226:229], v[194:197], v[80:83]
	v_mfma_f32_16x16x32_bf16 v[72:75], v[234:237], v[194:197], v[72:75]
	v_mfma_f32_16x16x32_bf16 v[68:71], v[226:229], v[218:221], v[68:71]
	v_mfma_f32_16x16x32_bf16 v[64:67], v[234:237], v[218:221], v[64:67]
	s_setprio 0
	s_mov_b32 m0, s37
	v_lshl_add_u64 v[154:155], v[240:241], 0, s[2:3]
	s_barrier
	ds_read_b128 v[174:177], v159 offset:49152
	ds_read_b128 v[178:181], v159 offset:50176
	ds_read_b128 v[182:185], v159 offset:51200
	ds_read_b128 v[186:189], v159 offset:52224
	ds_read_b128 v[190:193], v159 offset:53248
	ds_read_b128 v[194:197], v159 offset:54272
	ds_read_b128 v[214:217], v159 offset:55296
	ds_read_b128 v[218:221], v159 offset:56320
	global_load_lds_dwordx4 v[154:155], off
	v_lshl_add_u64 v[154:155], v[242:243], 0, s[2:3]
	s_mov_b32 m0, s38
	s_nop 0
	global_load_lds_dwordx4 v[154:155], off
	s_barrier
; #define PG8_STAGE(bufoff, gbase, voff) do { _Pragma("unroll") for (int _i = 0; _i < 2; ++_i) \
;         __builtin_amdgcn_global_load_lds((const unsigned*)((const char*)(gbase) + (voff)[_i]), (LAS unsigned*)(lds + (bufoff) + ldsw + _i * 8192), 16, 0, 0); } while (0)
; #define PG8_MMA(ai, bj, At, Bt) do { __builtin_amdgcn_s_setprio(1); _Pragma("unroll") for (int m = 0; m < 4; ++m) _Pragma("unroll") for (int n = 0; n < 2; ++n) _Pragma("unroll") for (int k = 0; k < 2; ++k) \
;         acc[ai][bj][m][n] = __builtin_amdgcn_mfma_f32_16x16x32_bf16(Bt[n][k], At[m][k], acc[ai][bj][m][n], 0, 0, 0); __builtin_amdgcn_s_setprio(0); } while (0)
; #define PG8_WAIT_V(n) asm volatile("s_waitcnt vmcnt(" #n ")" ::: "memory")
; #define PG8_WAIT_L(n) asm volatile("s_waitcnt lgkmcnt(" #n ")" ::: "memory")
; #define PG8_BAR __builtin_amdgcn_s_barrier()
; #define PG8_SCHED __builtin_amdgcn_sched_barrier(0)
; template <class Epi>
; DEV void gemm_phase(LAS unsigned char* lds, const Gemm g, const StaticOrder& S, const Epi& E) {
;     ...
;             PG8_BAR; PG8_WAIT_L(0); PG8_MMA(1, 0, At, B0); PG8_BAR; PG8_SCHED;
;             PG8_STAGE(PG8_SB(1, 1), b3 + hstep, voffB);
;             PG8_WAIT_V(6); PG8_BAR; PG8_MMA(1, 1, At, B1); PG8_BAR;
;         }
; DEV float rowscale(const float* ss, int row) { const f32x4 a = *(const f32x4*)(ss + (size_t)row * 8), b = *(const f32x4*)(ss + (size_t)row * 8 + 4);
;     return rsqrtf(((a[0] + a[1]) + (a[2] + a[3]) + (b[0] + b[1]) + (b[2] + b[3])) * (1.0f / 2048.0f) + EPS); }
	s_waitcnt lgkmcnt(0)
	s_setprio 1
	v_mfma_f32_16x16x32_bf16 v[60:63], v[128:131], v[174:177], v[60:63]
	v_mfma_f32_16x16x32_bf16 v[56:59], v[142:145], v[174:177], v[56:59]
	v_mfma_f32_16x16x32_bf16 v[52:55], v[128:131], v[182:185], v[52:55]
	v_mfma_f32_16x16x32_bf16 v[44:47], v[142:145], v[182:185], v[44:47]
	v_mfma_f32_16x16x32_bf16 v[36:39], v[128:131], v[190:193], v[36:39]
	v_mfma_f32_16x16x32_bf16 v[28:31], v[142:145], v[190:193], v[28:31]
	v_mfma_f32_16x16x32_bf16 v[20:23], v[128:131], v[214:217], v[20:23]
	v_mfma_f32_16x16x32_bf16 v[12:15], v[142:145], v[214:217], v[12:15]
	v_mfma_f32_16x16x32_bf16 v[60:63], v[132:135], v[178:181], v[60:63]
	v_mfma_f32_16x16x32_bf16 v[56:59], v[150:153], v[178:181], v[56:59]
	v_mfma_f32_16x16x32_bf16 v[52:55], v[132:135], v[186:189], v[52:55]
	v_mfma_f32_16x16x32_bf16 v[44:47], v[150:153], v[186:189], v[44:47]
	v_mfma_f32_16x16x32_bf16 v[36:39], v[132:135], v[194:197], v[36:39]
	v_mfma_f32_16x16x32_bf16 v[28:31], v[150:153], v[194:197], v[28:31]
	v_mfma_f32_16x16x32_bf16 v[20:23], v[132:135], v[218:221], v[20:23]
	v_mfma_f32_16x16x32_bf16 v[12:15], v[150:153], v[218:221], v[12:15]
	s_setprio 0
	s_barrier
	s_add_u32 s20, s20, 0x80080
	s_addc_u32 s21, s21, 0
	s_add_i32 s22, s22, s29
	v_lshl_add_u64 v[128:129], s[20:21], 0, v[160:161]
	s_mov_b32 m0, s22
	s_nop 0
	global_load_lds_dwordx4 v[128:129], off
	v_lshl_add_u64 v[128:129], s[20:21], 0, v[136:137]
	s_add_i32 m0, s22, 0x2000
	s_nop 0
	global_load_lds_dwordx4 v[128:129], off
	s_waitcnt vmcnt(6)
	s_barrier
	s_setprio 1
	v_mfma_f32_16x16x32_bf16 v[48:51], v[222:225], v[174:177], v[48:51]
	v_mfma_f32_16x16x32_bf16 v[40:43], v[230:233], v[174:177], v[40:43]
	v_mfma_f32_16x16x32_bf16 v[32:35], v[222:225], v[182:185], v[32:35]
	v_mfma_f32_16x16x32_bf16 v[24:27], v[230:233], v[182:185], v[24:27]
	v_mfma_f32_16x16x32_bf16 v[16:19], v[222:225], v[190:193], v[16:19]
	v_mfma_f32_16x16x32_bf16 v[8:11], v[230:233], v[190:193], v[8:11]
	v_mfma_f32_16x16x32_bf16 v[4:7], v[222:225], v[214:217], v[4:7]
	v_mfma_f32_16x16x32_bf16 v[0:3], v[230:233], v[214:217], v[0:3]
	v_mfma_f32_16x16x32_bf16 v[48:51], v[226:229], v[178:181], v[48:51]
	v_mfma_f32_16x16x32_bf16 v[40:43], v[234:237], v[178:181], v[40:43]
	v_mfma_f32_16x16x32_bf16 v[32:35], v[226:229], v[186:189], v[32:35]
	v_mfma_f32_16x16x32_bf16 v[24:27], v[234:237], v[186:189], v[24:27]
	v_mfma_f32_16x16x32_bf16 v[16:19], v[226:229], v[194:197], v[16:19]
	v_mfma_f32_16x16x32_bf16 v[8:11], v[234:237], v[194:197], v[8:11]
	v_mfma_f32_16x16x32_bf16 v[4:7], v[226:229], v[218:221], v[4:7]
	v_mfma_f32_16x16x32_bf16 v[0:3], v[234:237], v[218:221], v[0:3]
	s_setprio 0
	s_add_i32 s44, s44, 2
	s_add_u32 s18, s18, 0x100
	s_addc_u32 s19, s19, 0
	s_add_u32 s42, s42, 0x100
	s_addc_u32 s43, s43, 0
	s_cmp_gt_u32 s44, 29
	s_barrier
	s_cbranch_scc0 .LBB0_344
	v_lshl_add_u32 v142, s0, 8, v147
	v_ashrrev_i32_e32 v143, 31, v142
	v_lshlrev_b64 v[128:129], 5, v[142:143]
	v_lshl_add_u64 v[132:133], s[4:5], 0, v[128:129]
	global_load_dwordx4 v[128:131], v[132:133], off offset:16
	s_nop 0
	global_load_dwordx4 v[132:135], v[132:133], off
	s_mov_b32 s0, 0x3727c5ac
	s_mov_b32 s18, 0x3a000000
	s_mov_b32 s11, 0x800000
	s_mov_b64 s[20:21], s[16:17]
	s_waitcnt vmcnt(0)
	v_mov_b32_e32 v144, v133
	v_mov_b32_e32 v145, v134
	v_mov_b32_e32 v133, v135
	v_pk_add_f32 v[150:151], v[144:145], v[132:133]
	v_or_b32_e32 v144, 16, v142
	v_mov_b32_e32 v132, v130
	v_mov_b32_e32 v133, v128
	v_mov_b32_e32 v128, v131
	v_ashrrev_i32_e32 v145, 31, v144
	v_pk_add_f32 v[152:153], v[132:133], v[128:129]
	v_lshlrev_b64 v[128:129], 5, v[144:145]
	v_lshl_add_u64 v[132:133], s[4:5], 0, v[128:129]
	global_load_dwordx4 v[128:131], v[132:133], off offset:16
	s_nop 0
	global_load_dwordx4 v[132:135], v[132:133], off
	s_waitcnt vmcnt(0)
	v_mov_b32_e32 v154, v133
	v_mov_b32_e32 v155, v134
	v_mov_b32_e32 v133, v135
	v_pk_add_f32 v[132:133], v[154:155], v[132:133]
	v_mov_b32_e32 v134, v130
	v_mov_b32_e32 v135, v128
	v_mov_b32_e32 v128, v131
	v_pk_add_f32 v[128:129], v[134:135], v[128:129]
	v_mov_b32_e32 v130, v132
	v_mov_b32_e32 v131, v150
	v_mov_b32_e32 v150, v133
	v_pk_add_f32 v[130:131], v[130:131], v[150:151]
	v_mov_b32_e32 v132, v129
	v_mov_b32_e32 v133, v153
	v_pk_add_f32 v[130:131], v[130:131], v[132:133]
	v_mov_b32_e32 v129, v152
	v_pk_add_f32 v[128:129], v[128:129], v[130:131]
	v_mov_b64_e32 v[150:151], s[0:1]
	v_pk_fma_f32 v[128:129], v[128:129], s[18:19], v[150:151] op_sel_hi:[1,0,0]
	v_or_b32_e32 v152, 32, v142
	v_mul_f32_e32 v130, 0x4b800000, v129
	v_cmp_gt_f32_e64 s[0:1], s11, v129
	v_cmp_gt_f32_e32 vcc, s11, v128
	v_ashrrev_i32_e32 v153, 31, v152
	v_cndmask_b32_e64 v129, v129, v130, s[0:1]
	v_rsq_f32_e32 v129, v129
	s_nop 0
	v_mul_f32_e32 v130, 0x45800000, v129
	v_cndmask_b32_e64 v148, v129, v130, s[0:1]
	v_mul_f32_e32 v129, 0x4b800000, v128
	v_cndmask_b32_e32 v128, v128, v129, vcc
	v_rsq_f32_e32 v128, v128
	v_pk_mul_f32 v[106:107], v[106:107], v[148:149] op_sel_hi:[1,0]
	v_pk_mul_f32 v[104:105], v[104:105], v[148:149] op_sel_hi:[1,0]
	v_pk_mul_f32 v[114:115], v[114:115], v[148:149] op_sel_hi:[1,0]
	v_mul_f32_e32 v129, 0x45800000, v128
	v_cndmask_b32_e32 v146, v128, v129, vcc
	v_lshlrev_b64 v[128:129], 5, v[152:153]
	v_lshl_add_u64 v[132:133], s[4:5], 0, v[128:129]
	global_load_dwordx4 v[128:131], v[132:133], off offset:16
	s_nop 0
	global_load_dwordx4 v[132:135], v[132:133], off
	v_cvt_pk_bf16_f32 v104, v104, v105
	v_cvt_pk_bf16_f32 v105, v106, v107
	v_pk_mul_f32 v[90:91], v[90:91], v[146:147] op_sel_hi:[1,0]
	v_pk_mul_f32 v[88:89], v[88:89], v[146:147] op_sel_hi:[1,0]
	v_pk_mul_f32 v[112:113], v[112:113], v[148:149] op_sel_hi:[1,0]
	v_cvt_pk_bf16_f32 v88, v88, v89
	v_cvt_pk_bf16_f32 v89, v90, v91
	v_pk_mul_f32 v[98:99], v[98:99], v[146:147] op_sel_hi:[1,0]
	v_pk_mul_f32 v[96:97], v[96:97], v[146:147] op_sel_hi:[1,0]
	v_cvt_pk_bf16_f32 v112, v112, v113
	v_cvt_pk_bf16_f32 v113, v114, v115
	v_cvt_pk_bf16_f32 v96, v96, v97
	v_cvt_pk_bf16_f32 v97, v98, v99
	v_pk_mul_f32 v[126:127], v[126:127], v[148:149] op_sel_hi:[1,0]
	v_pk_mul_f32 v[124:125], v[124:125], v[148:149] op_sel_hi:[1,0]
	v_pk_mul_f32 v[122:123], v[122:123], v[148:149] op_sel_hi:[1,0]
	v_pk_mul_f32 v[120:121], v[120:121], v[148:149] op_sel_hi:[1,0]
	v_pk_mul_f32 v[106:107], v[118:119], v[146:147] op_sel_hi:[1,0]
	v_pk_mul_f32 v[110:111], v[110:111], v[146:147] op_sel_hi:[1,0]
	v_pk_mul_f32 v[108:109], v[108:109], v[146:147] op_sel_hi:[1,0]
	v_cvt_pk_bf16_f32 v124, v124, v125
	v_cvt_pk_bf16_f32 v125, v126, v127
	v_cvt_pk_bf16_f32 v120, v120, v121
	v_cvt_pk_bf16_f32 v121, v122, v123
	s_waitcnt vmcnt(0)
; DEV bf16x8 pack8(f32x4 a, f32x4 b) { u32x4 w; w.x = cvt_pk_bf16(a[0], a[1]); w.y = cvt_pk_bf16(a[2], a[3]); w.z = cvt_pk_bf16(b[0], b[1]); w.w = cvt_pk_bf16(b[2], b[3]); return __builtin_bit_cast(bf16x8, w); }
; DEV u32x2 pack4(f32x4 a) { u32x2 w; w.x = cvt_pk_bf16(a[0], a[1]); w.y = cvt_pk_bf16(a[2], a[3]); return w; }
; DEV f32x4 gelu4(f32x4 v) { f32x2 a = gelu_pk((f32x2){v[0], v[1]}), b = gelu_pk((f32x2){v[2], v[3]}); return (f32x4){a.x, a.y, b.x, b.y}; }
; DEV float rowscale(const float* ss, int row) { const f32x4 a = *(const f32x4*)(ss + (size_t)row * 8), b = *(const f32x4*)(ss + (size_t)row * 8 + 4);
;     return rsqrtf(((a[0] + a[1]) + (a[2] + a[3]) + (b[0] + b[1]) + (b[2] + b[3])) * (1.0f / 2048.0f) + EPS); }
; template <int ACT, bool PERM>
; DEV void store_bf16_tile(AccRef acc, u16* O, int ld, int row0, int col0, const float* ss) {
;     float rsv[2][4];
; #pragma unroll
;     for (int ai = 0; ai < 2; ++ai)
; #pragma unroll
;         for (int m = 0; m < 4; ++m) rsv[ai][m] = ss ? rowscale(ss, row0 + ai * 128 + m * 16) : 1.0f;
; #pragma unroll
;     for (int ai = 0; ai < 2; ++ai)
; #pragma unroll
;         for (int m = 0; m < 4; ++m) { u16* rowp = O + (size_t)(row0 + ai * 128 + m * 16) * ld + col0; const float rs = rsv[ai][m];
; #pragma unroll
;             for (int bj = 0; bj < 2; ++bj) { f32x4 v0 = acc[ai][bj][m][0] * rs, v1 = acc[ai][bj][m][1] * rs; if (ACT == 1) { v0 = gelu4(v0); v1 = gelu4(v1); }
;                 if (PERM) *(u32x4*)(rowp + bj * 128) = __builtin_bit_cast(u32x4, pack8(v0, v1));
;                 else { *(u32x2*)(rowp + bj * 128) = pack4(v0); *(u32x2*)(rowp + bj * 128 + 16) = pack4(v1); } } }
	v_mov_b32_e32 v154, v133
	v_mov_b32_e32 v155, v134
	v_mov_b32_e32 v133, v135
	v_pk_add_f32 v[174:175], v[154:155], v[132:133]
	v_or_b32_e32 v154, 48, v142
	v_mov_b32_e32 v132, v130
	v_mov_b32_e32 v133, v128
	v_mov_b32_e32 v128, v131
	v_ashrrev_i32_e32 v155, 31, v154
	v_pk_add_f32 v[176:177], v[132:133], v[128:129]
	v_lshlrev_b64 v[128:129], 5, v[154:155]
	v_lshl_add_u64 v[132:133], s[4:5], 0, v[128:129]
	global_load_dwordx4 v[128:131], v[132:133], off offset:16
	s_nop 0
	global_load_dwordx4 v[132:135], v[132:133], off
	s_waitcnt vmcnt(0)
	v_mov_b32_e32 v178, v133
	v_mov_b32_e32 v179, v134
	v_mov_b32_e32 v133, v135
	v_pk_add_f32 v[132:133], v[178:179], v[132:133]
	v_mov_b32_e32 v134, v130
	v_mov_b32_e32 v135, v128
	v_mov_b32_e32 v128, v131
	v_pk_add_f32 v[128:129], v[134:135], v[128:129]
	v_mov_b32_e32 v130, v132
	v_mov_b32_e32 v131, v174
	v_mov_b32_e32 v174, v133
	v_pk_add_f32 v[130:131], v[130:131], v[174:175]
	v_mov_b32_e32 v132, v129
	v_mov_b32_e32 v133, v177
	v_pk_add_f32 v[130:131], v[130:131], v[132:133]
	v_mov_b32_e32 v129, v176
	v_pk_add_f32 v[128:129], v[128:129], v[130:131]
	v_add_u32_e32 v174, 0x80, v142
	v_pk_fma_f32 v[128:129], v[128:129], s[18:19], v[150:151] op_sel_hi:[1,0,0]
	v_ashrrev_i32_e32 v175, 31, v174
	v_mul_f32_e32 v130, 0x4b800000, v129
	v_cmp_gt_f32_e64 s[0:1], s11, v129
	v_cmp_gt_f32_e32 vcc, s11, v128
	s_nop 0
	v_cndmask_b32_e64 v129, v129, v130, s[0:1]
	v_rsq_f32_e32 v129, v129
	s_nop 0
	v_mul_f32_e32 v130, 0x45800000, v129
	v_cndmask_b32_e64 v158, v129, v130, s[0:1]
	v_mul_f32_e32 v129, 0x4b800000, v128
	v_cndmask_b32_e32 v128, v128, v129, vcc
	v_rsq_f32_e32 v128, v128
	v_pk_mul_f32 v[74:75], v[74:75], v[158:159] op_sel_hi:[1,0]
	v_pk_mul_f32 v[72:73], v[72:73], v[158:159] op_sel_hi:[1,0]
	v_pk_mul_f32 v[82:83], v[82:83], v[158:159] op_sel_hi:[1,0]
	v_mul_f32_e32 v129, 0x45800000, v128
	v_cndmask_b32_e32 v156, v128, v129, vcc
	v_lshlrev_b64 v[128:129], 5, v[174:175]
	v_lshl_add_u64 v[132:133], s[4:5], 0, v[128:129]
	global_load_dwordx4 v[128:131], v[132:133], off offset:16
	s_nop 0
	global_load_dwordx4 v[132:135], v[132:133], off
	v_cvt_pk_bf16_f32 v72, v72, v73
	v_cvt_pk_bf16_f32 v73, v74, v75
	v_pk_mul_f32 v[66:67], v[66:67], v[156:157] op_sel_hi:[1,0]
	v_pk_mul_f32 v[64:65], v[64:65], v[156:157] op_sel_hi:[1,0]
	v_pk_mul_f32 v[80:81], v[80:81], v[158:159] op_sel_hi:[1,0]
	v_cvt_pk_bf16_f32 v64, v64, v65
	v_cvt_pk_bf16_f32 v65, v66, v67
	v_cvt_pk_bf16_f32 v80, v80, v81
	v_cvt_pk_bf16_f32 v81, v82, v83
	v_pk_mul_f32 v[90:91], v[102:103], v[158:159] op_sel_hi:[1,0]
	v_pk_mul_f32 v[94:95], v[94:95], v[158:159] op_sel_hi:[1,0]
	v_pk_mul_f32 v[92:93], v[92:93], v[158:159] op_sel_hi:[1,0]
	v_pk_mul_f32 v[74:75], v[86:87], v[156:157] op_sel_hi:[1,0]
	v_pk_mul_f32 v[78:79], v[78:79], v[156:157] op_sel_hi:[1,0]
	v_pk_mul_f32 v[76:77], v[76:77], v[156:157] op_sel_hi:[1,0]
	v_pk_mul_f32 v[70:71], v[70:71], v[156:157] op_sel_hi:[1,0]
	v_pk_mul_f32 v[68:69], v[68:69], v[156:157] op_sel_hi:[1,0]
	s_waitcnt vmcnt(0)
	v_mov_b32_e32 v176, v133
	v_mov_b32_e32 v177, v134
	v_mov_b32_e32 v133, v135
	v_pk_add_f32 v[178:179], v[176:177], v[132:133]
	v_add_u32_e32 v176, 0x90, v142
	v_mov_b32_e32 v132, v130
	v_mov_b32_e32 v133, v128
	v_mov_b32_e32 v128, v131
	v_ashrrev_i32_e32 v177, 31, v176
	v_pk_add_f32 v[180:181], v[132:133], v[128:129]
	v_lshlrev_b64 v[128:129], 5, v[176:177]
	v_lshl_add_u64 v[132:133], s[4:5], 0, v[128:129]
	global_load_dwordx4 v[128:131], v[132:133], off offset:16
	s_nop 0
	global_load_dwordx4 v[132:135], v[132:133], off
	v_cvt_pk_bf16_f32 v68, v68, v69
	v_cvt_pk_bf16_f32 v69, v70, v71
	s_waitcnt vmcnt(0)
	v_mov_b32_e32 v182, v133
	v_mov_b32_e32 v183, v134
	v_mov_b32_e32 v133, v135
	v_pk_add_f32 v[132:133], v[182:183], v[132:133]
	v_mov_b32_e32 v134, v130
	v_mov_b32_e32 v135, v128
	v_mov_b32_e32 v128, v131
	v_pk_add_f32 v[128:129], v[134:135], v[128:129]
	v_mov_b32_e32 v130, v132
	v_mov_b32_e32 v131, v178
	v_mov_b32_e32 v178, v133
	v_pk_add_f32 v[130:131], v[130:131], v[178:179]
	v_mov_b32_e32 v132, v129
	v_mov_b32_e32 v133, v181
	v_pk_add_f32 v[130:131], v[130:131], v[132:133]
	v_mov_b32_e32 v129, v180
	v_pk_add_f32 v[128:129], v[128:129], v[130:131]
	v_add_u32_e32 v182, 0xa0, v142
	v_pk_fma_f32 v[128:129], v[128:129], s[18:19], v[150:151] op_sel_hi:[1,0,0]
	v_ashrrev_i32_e32 v183, 31, v182
	v_mul_f32_e32 v130, 0x4b800000, v129
	v_cmp_gt_f32_e64 s[0:1], s11, v129
	v_cmp_gt_f32_e32 vcc, s11, v128
	s_nop 0
	v_cndmask_b32_e64 v129, v129, v130, s[0:1]
	v_rsq_f32_e32 v129, v129
	s_nop 0
	v_mul_f32_e32 v130, 0x45800000, v129
	v_cndmask_b32_e64 v180, v129, v130, s[0:1]
	v_mul_f32_e32 v129, 0x4b800000, v128
	v_cndmask_b32_e32 v128, v128, v129, vcc
	v_rsq_f32_e32 v128, v128
	v_pk_mul_f32 v[42:43], v[42:43], v[180:181] op_sel_hi:[1,0]
	v_pk_mul_f32 v[40:41], v[40:41], v[180:181] op_sel_hi:[1,0]
	v_pk_mul_f32 v[50:51], v[50:51], v[180:181] op_sel_hi:[1,0]
	v_mul_f32_e32 v129, 0x45800000, v128
	v_cndmask_b32_e32 v178, v128, v129, vcc
	v_lshlrev_b64 v[128:129], 5, v[182:183]
	v_lshl_add_u64 v[132:133], s[4:5], 0, v[128:129]
	global_load_dwordx4 v[128:131], v[132:133], off offset:16
	s_nop 0
	global_load_dwordx4 v[132:135], v[132:133], off
	v_cvt_pk_bf16_f32 v40, v40, v41
	v_cvt_pk_bf16_f32 v41, v42, v43
	v_pk_mul_f32 v[26:27], v[26:27], v[178:179] op_sel_hi:[1,0]
	v_pk_mul_f32 v[24:25], v[24:25], v[178:179] op_sel_hi:[1,0]
	v_pk_mul_f32 v[48:49], v[48:49], v[180:181] op_sel_hi:[1,0]
	v_cvt_pk_bf16_f32 v24, v24, v25
	v_cvt_pk_bf16_f32 v25, v26, v27
	v_pk_mul_f32 v[34:35], v[34:35], v[178:179] op_sel_hi:[1,0]
	v_pk_mul_f32 v[32:33], v[32:33], v[178:179] op_sel_hi:[1,0]
	v_cvt_pk_bf16_f32 v48, v48, v49
	v_cvt_pk_bf16_f32 v49, v50, v51
	v_cvt_pk_bf16_f32 v32, v32, v33
	v_cvt_pk_bf16_f32 v33, v34, v35
	v_pk_mul_f32 v[62:63], v[62:63], v[180:181] op_sel_hi:[1,0]
	v_pk_mul_f32 v[60:61], v[60:61], v[180:181] op_sel_hi:[1,0]
	v_pk_mul_f32 v[58:59], v[58:59], v[180:181] op_sel_hi:[1,0]
	v_pk_mul_f32 v[56:57], v[56:57], v[180:181] op_sel_hi:[1,0]
	v_pk_mul_f32 v[42:43], v[54:55], v[178:179] op_sel_hi:[1,0]
	v_pk_mul_f32 v[46:47], v[46:47], v[178:179] op_sel_hi:[1,0]
	v_pk_mul_f32 v[44:45], v[44:45], v[178:179] op_sel_hi:[1,0]
	v_cvt_pk_bf16_f32 v60, v60, v61
	v_cvt_pk_bf16_f32 v61, v62, v63
	v_cvt_pk_bf16_f32 v56, v56, v57
	v_cvt_pk_bf16_f32 v57, v58, v59
	s_waitcnt vmcnt(0)
; DEV bf16x8 pack8(f32x4 a, f32x4 b) { u32x4 w; w.x = cvt_pk_bf16(a[0], a[1]); w.y = cvt_pk_bf16(a[2], a[3]); w.z = cvt_pk_bf16(b[0], b[1]); w.w = cvt_pk_bf16(b[2], b[3]); return __builtin_bit_cast(bf16x8, w); }
; DEV u32x2 pack4(f32x4 a) { u32x2 w; w.x = cvt_pk_bf16(a[0], a[1]); w.y = cvt_pk_bf16(a[2], a[3]); return w; }
; DEV f32x4 gelu4(f32x4 v) { f32x2 a = gelu_pk((f32x2){v[0], v[1]}), b = gelu_pk((f32x2){v[2], v[3]}); return (f32x4){a.x, a.y, b.x, b.y}; }
; DEV float rowscale(const float* ss, int row) { const f32x4 a = *(const f32x4*)(ss + (size_t)row * 8), b = *(const f32x4*)(ss + (size_t)row * 8 + 4);
;     return rsqrtf(((a[0] + a[1]) + (a[2] + a[3]) + (b[0] + b[1]) + (b[2] + b[3])) * (1.0f / 2048.0f) + EPS); }
; template <int ACT, bool PERM>
; DEV void store_bf16_tile(AccRef acc, u16* O, int ld, int row0, int col0, const float* ss) {
;     float rsv[2][4];
; #pragma unroll
;     for (int ai = 0; ai < 2; ++ai)
; #pragma unroll
;         for (int m = 0; m < 4; ++m) rsv[ai][m] = ss ? rowscale(ss, row0 + ai * 128 + m * 16) : 1.0f;
; #pragma unroll
;     for (int ai = 0; ai < 2; ++ai)
; #pragma unroll
;         for (int m = 0; m < 4; ++m) { u16* rowp = O + (size_t)(row0 + ai * 128 + m * 16) * ld + col0; const float rs = rsv[ai][m];
; #pragma unroll
;             for (int bj = 0; bj < 2; ++bj) { f32x4 v0 = acc[ai][bj][m][0] * rs, v1 = acc[ai][bj][m][1] * rs; if (ACT == 1) { v0 = gelu4(v0); v1 = gelu4(v1); }
;                 if (PERM) *(u32x4*)(rowp + bj * 128) = __builtin_bit_cast(u32x4, pack8(v0, v1));
;                 else { *(u32x2*)(rowp + bj * 128) = pack4(v0); *(u32x2*)(rowp + bj * 128 + 16) = pack4(v1); } } }
	v_mov_b32_e32 v184, v133
	v_mov_b32_e32 v185, v134
	v_mov_b32_e32 v133, v135
	v_pk_add_f32 v[188:189], v[184:185], v[132:133]
	v_add_u32_e32 v184, 0xb0, v142
	v_mov_b32_e32 v132, v130
	v_mov_b32_e32 v133, v128
	v_mov_b32_e32 v128, v131
	v_ashrrev_i32_e32 v185, 31, v184
	v_pk_add_f32 v[186:187], v[132:133], v[128:129]
	v_lshlrev_b64 v[128:129], 5, v[184:185]
	v_lshl_add_u64 v[132:133], s[4:5], 0, v[128:129]
	global_load_dwordx4 v[128:131], v[132:133], off offset:16
	s_nop 0
	global_load_dwordx4 v[132:135], v[132:133], off
	s_waitcnt vmcnt(0)
	v_mov_b32_e32 v190, v133
	v_mov_b32_e32 v191, v134
	v_mov_b32_e32 v133, v135
	v_pk_add_f32 v[132:133], v[190:191], v[132:133]
	v_mov_b32_e32 v134, v130
	v_mov_b32_e32 v135, v128
	v_mov_b32_e32 v128, v131
	v_pk_add_f32 v[128:129], v[134:135], v[128:129]
	v_mov_b32_e32 v130, v132
	v_mov_b32_e32 v131, v188
	v_mov_b32_e32 v188, v133
	v_pk_add_f32 v[130:131], v[130:131], v[188:189]
	v_mov_b32_e32 v132, v129
	v_mov_b32_e32 v133, v187
	v_pk_add_f32 v[130:131], v[130:131], v[132:133]
	v_mov_b32_e32 v129, v186
	v_pk_add_f32 v[128:129], v[128:129], v[130:131]
	v_lshl_or_b32 v132, s40, 8, v157
	v_pk_fma_f32 v[128:129], v[128:129], s[18:19], v[150:151] op_sel_hi:[1,0,0]
	v_ashrrev_i32_e32 v133, 31, v132
	v_mul_f32_e32 v130, 0x4b800000, v129
	v_cmp_gt_f32_e64 s[0:1], s11, v129
	v_lshlrev_b64 v[134:135], 10, v[142:143]
	v_cmp_gt_f32_e32 vcc, s11, v128
	v_cndmask_b32_e64 v129, v129, v130, s[0:1]
	v_rsq_f32_e32 v129, v129
	s_mov_b32 s40, s10
	s_mov_b64 s[18:19], s[14:15]
	v_mul_f32_e32 v130, 0x45800000, v129
	v_cndmask_b32_e64 v130, v129, v130, s[0:1]
	v_readlane_b32 s0, v250, 11
	v_readlane_b32 s1, v250, 12
	v_mul_f32_e32 v129, 0x4b800000, v128
	v_cndmask_b32_e32 v128, v128, v129, vcc
	v_lshl_add_u64 v[132:133], v[132:133], 1, s[0:1]
	v_lshl_add_u64 v[134:135], v[132:133], 0, v[134:135]
	global_store_dwordx2 v[134:135], v[104:105], off offset:288
	v_lshlrev_b64 v[104:105], 10, v[144:145]
	v_lshl_add_u64 v[104:105], v[132:133], 0, v[104:105]
	global_store_dwordx2 v[104:105], v[88:89], off offset:288
	v_lshlrev_b64 v[88:89], 10, v[152:153]
	v_lshl_add_u64 v[88:89], v[132:133], 0, v[88:89]
	global_store_dwordx2 v[88:89], v[72:73], off offset:288
	v_lshlrev_b64 v[72:73], 10, v[154:155]
	v_lshl_add_u64 v[72:73], v[132:133], 0, v[72:73]
	v_rsq_f32_e32 v128, v128
	global_store_dwordx2 v[72:73], v[64:65], off offset:288
	v_lshlrev_b64 v[64:65], 10, v[174:175]
	v_lshl_add_u64 v[64:65], v[132:133], 0, v[64:65]
	global_store_dwordx2 v[64:65], v[40:41], off offset:288
	v_lshlrev_b64 v[40:41], 10, v[176:177]
	v_lshl_add_u64 v[40:41], v[132:133], 0, v[40:41]
	v_mul_f32_e32 v129, 0x45800000, v128
	global_store_dwordx2 v[40:41], v[24:25], off offset:288
	v_lshlrev_b64 v[24:25], 10, v[182:183]
	v_pk_mul_f32 v[18:19], v[18:19], v[130:131] op_sel_hi:[1,0]
	v_pk_mul_f32 v[16:17], v[16:17], v[130:131] op_sel_hi:[1,0]
	v_pk_mul_f32 v[10:11], v[10:11], v[130:131] op_sel_hi:[1,0]
	v_pk_mul_f32 v[8:9], v[8:9], v[130:131] op_sel_hi:[1,0]
	v_cndmask_b32_e32 v128, v128, v129, vcc
	v_lshl_add_u64 v[24:25], v[132:133], 0, v[24:25]
	v_cvt_pk_bf16_f32 v16, v16, v17
	v_cvt_pk_bf16_f32 v17, v18, v19
	v_cvt_pk_bf16_f32 v8, v8, v9
	v_cvt_pk_bf16_f32 v9, v10, v11
	global_store_dwordx2 v[134:135], v[112:113], off offset:256
	v_pk_mul_f32 v[112:113], v[116:117], v[146:147] op_sel_hi:[1,0]
	global_store_dwordx2 v[104:105], v[96:97], off offset:256
	v_pk_mul_f32 v[96:97], v[100:101], v[158:159] op_sel_hi:[1,0]
	global_store_dwordx2 v[88:89], v[80:81], off offset:256
	v_pk_mul_f32 v[80:81], v[84:85], v[156:157] op_sel_hi:[1,0]
	global_store_dwordx2 v[64:65], v[48:49], off offset:256
	v_pk_mul_f32 v[48:49], v[52:53], v[178:179] op_sel_hi:[1,0]
	global_store_dwordx2 v[40:41], v[32:33], off offset:256
	v_pk_mul_f32 v[26:27], v[38:39], v[130:131] op_sel_hi:[1,0]
	v_pk_mul_f32 v[32:33], v[36:37], v[130:131] op_sel_hi:[1,0]
	v_pk_mul_f32 v[30:31], v[30:31], v[130:131] op_sel_hi:[1,0]
	v_pk_mul_f32 v[28:29], v[28:29], v[130:131] op_sel_hi:[1,0]
	global_store_dwordx2 v[24:25], v[16:17], off offset:256
	global_store_dwordx2 v[24:25], v[8:9], off offset:288
	v_lshlrev_b64 v[8:9], 10, v[184:185]
	v_pk_mul_f32 v[10:11], v[22:23], v[128:129] op_sel_hi:[1,0]
	v_pk_mul_f32 v[16:17], v[20:21], v[128:129] op_sel_hi:[1,0]
	v_pk_mul_f32 v[14:15], v[14:15], v[128:129] op_sel_hi:[1,0]
	v_pk_mul_f32 v[12:13], v[12:13], v[128:129] op_sel_hi:[1,0]
	v_pk_mul_f32 v[6:7], v[6:7], v[128:129] op_sel_hi:[1,0]
	v_pk_mul_f32 v[4:5], v[4:5], v[128:129] op_sel_hi:[1,0]
	v_pk_mul_f32 v[2:3], v[2:3], v[128:129] op_sel_hi:[1,0]
	v_pk_mul_f32 v[0:1], v[0:1], v[128:129] op_sel_hi:[1,0]
	v_cvt_pk_bf16_f32 v112, v112, v113
	v_cvt_pk_bf16_f32 v113, v106, v107
	v_cvt_pk_bf16_f32 v106, v108, v109
	v_cvt_pk_bf16_f32 v107, v110, v111
	v_cvt_pk_bf16_f32 v96, v96, v97
	v_cvt_pk_bf16_f32 v97, v90, v91
	v_cvt_pk_bf16_f32 v90, v92, v93
	v_cvt_pk_bf16_f32 v91, v94, v95
	v_cvt_pk_bf16_f32 v80, v80, v81
	v_cvt_pk_bf16_f32 v81, v74, v75
	v_cvt_pk_bf16_f32 v74, v76, v77
	v_cvt_pk_bf16_f32 v75, v78, v79
	v_cvt_pk_bf16_f32 v48, v48, v49
	v_cvt_pk_bf16_f32 v49, v42, v43
	v_cvt_pk_bf16_f32 v42, v44, v45
	v_cvt_pk_bf16_f32 v43, v46, v47
	v_cvt_pk_bf16_f32 v32, v32, v33
	v_cvt_pk_bf16_f32 v33, v26, v27
	v_cvt_pk_bf16_f32 v26, v28, v29
	v_cvt_pk_bf16_f32 v27, v30, v31
	v_lshl_add_u64 v[8:9], v[132:133], 0, v[8:9]
	v_cvt_pk_bf16_f32 v16, v16, v17
	v_cvt_pk_bf16_f32 v17, v10, v11
	v_cvt_pk_bf16_f32 v10, v12, v13
	v_cvt_pk_bf16_f32 v11, v14, v15
	v_cvt_pk_bf16_f32 v4, v4, v5
	v_cvt_pk_bf16_f32 v5, v6, v7
	v_cvt_pk_bf16_f32 v0, v0, v1
	v_cvt_pk_bf16_f32 v1, v2, v3
	s_and_b64 vcc, exec, s[6:7]
	s_mov_b32 s0, s12
	global_store_dwordx2 v[134:135], v[124:125], off
	global_store_dwordx2 v[134:135], v[120:121], off offset:32
	global_store_dwordx2 v[104:105], v[112:113], off
	global_store_dwordx2 v[104:105], v[106:107], off offset:32
	global_store_dwordx2 v[88:89], v[96:97], off
	global_store_dwordx2 v[88:89], v[90:91], off offset:32
	global_store_dwordx2 v[72:73], v[80:81], off
	global_store_dwordx2 v[72:73], v[74:75], off offset:32
	global_store_dwordx2 v[72:73], v[68:69], off offset:256
	global_store_dwordx2 v[64:65], v[60:61], off
	global_store_dwordx2 v[64:65], v[56:57], off offset:32
	global_store_dwordx2 v[40:41], v[48:49], off
	global_store_dwordx2 v[40:41], v[42:43], off offset:32
	global_store_dwordx2 v[24:25], v[32:33], off
	global_store_dwordx2 v[24:25], v[26:27], off offset:32
	global_store_dwordx2 v[8:9], v[16:17], off
	global_store_dwordx2 v[8:9], v[10:11], off offset:32
	global_store_dwordx2 v[8:9], v[4:5], off offset:256
	global_store_dwordx2 v[8:9], v[0:1], off offset:288
	s_cbranch_vccz .LBB0_337
	s_waitcnt vmcnt(0)
	s_cmpk_gt_u32 s25, 0xff
	s_cbranch_scc1 .LBB0_348
	s_barrier

; #define PG8_STAGE(bufoff, gbase, voff) do { _Pragma("unroll") for (int _i = 0; _i < 2; ++_i) \
;         __builtin_amdgcn_global_load_lds((const unsigned*)((const char*)(gbase) + (voff)[_i]), (LAS unsigned*)(lds + (bufoff) + ldsw + _i * 8192), 16, 0, 0); } while (0)
; #define PG8_LDA(dst, b, h) do { _Pragma("unroll") for (int m = 0; m < 4; ++m) _Pragma("unroll") for (int k = 0; k < 2; ++k) dst[m][k] = *(const LAS bf16x8*)(lds + PG8_SA(b, h) + aoff + m * 2048 + k * 1024); } while (0)
; #define PG8_LDB(dst, b, h) do { _Pragma("unroll") for (int n = 0; n < 2; ++n) _Pragma("unroll") for (int k = 0; k < 2; ++k) dst[n][k] = *(const LAS bf16x8*)(lds + PG8_SB(b, h) + boff + n * 2048 + k * 1024); } while (0)
; #define PG8_MMA(ai, bj, At, Bt) do { __builtin_amdgcn_s_setprio(1); _Pragma("unroll") for (int m = 0; m < 4; ++m) _Pragma("unroll") for (int n = 0; n < 2; ++n) _Pragma("unroll") for (int k = 0; k < 2; ++k) \
;         acc[ai][bj][m][n] = __builtin_amdgcn_mfma_f32_16x16x32_bf16(Bt[n][k], At[m][k], acc[ai][bj][m][n], 0, 0, 0); __builtin_amdgcn_s_setprio(0); } while (0)
; #define PG8_WAIT_L(n) asm volatile("s_waitcnt lgkmcnt(" #n ")" ::: "memory")
; #define PG8_BAR __builtin_amdgcn_s_barrier()
; #define PG8_SCHED __builtin_amdgcn_sched_barrier(0)
; template <class Epi>
; DEV void gemm_phase(LAS unsigned char* lds, const Gemm g, const StaticOrder& S, const Epi& E) {
;     ...
;             PG8_LDB(B0, 0, 0); PG8_SCHED; PG8_LDA(At, 0, 0); PG8_STAGE(PG8_SA(1, 1), a1 + hstep, voffA);
;             PG8_WAIT_L(8); PG8_BAR; PG8_WAIT_L(0); PG8_MMA(0, 0, At, B0); PG8_BAR; PG8_SCHED;
;             PG8_LDB(B1, 0, 1); PG8_STAGE(PG8_SB(0, 0), b2, voffB);
;             PG8_BAR; PG8_WAIT_L(0); PG8_MMA(0, 1, At, B1); PG8_BAR;
;             PG8_LDA(At, 0, 1); PG8_STAGE(PG8_SA(0, 0), a2, voffA);
;             PG8_BAR; PG8_WAIT_L(0); PG8_MMA(1, 0, At, B0); PG8_BAR; PG8_SCHED;
.LBB0_362:
	s_add_u32 s26, s24, 0xfff80080
	s_addc_u32 s27, s25, -1
	s_add_i32 s56, 0, 0x10000
	v_add_u32_e32 v150, s56, v135
	ds_read_b128 v[138:141], v150
	ds_read_b128 v[142:145], v150 offset:1024
	ds_read_b128 v[146:149], v150 offset:2048
	ds_read_b128 v[150:153], v150 offset:3072
	s_cmp_eq_u32 s55, 28
	s_cselect_b32 s29, s19, s27
	s_cselect_b32 s28, s51, s26
	s_cselect_b32 s27, s17, s54
	s_cselect_b32 s26, s52, s53
	v_lshl_add_u64 v[158:159], s[24:25], 0, v[130:131]
	s_add_i32 m0, s13, 0xc000
	ds_read_b128 v[154:157], v137
	ds_read_b128 v[174:177], v137 offset:1024
	ds_read_b128 v[178:181], v137 offset:2048
	ds_read_b128 v[182:185], v137 offset:3072
	ds_read_b128 v[186:189], v137 offset:4096
	ds_read_b128 v[190:193], v137 offset:5120
	ds_read_b128 v[194:197], v137 offset:6144
	ds_read_b128 v[214:217], v137 offset:7168
	global_load_lds_dwordx4 v[158:159], off
	v_lshl_add_u64 v[158:159], s[24:25], 0, v[132:133]
	s_add_i32 m0, s13, 0xe000
	s_nop 0
	global_load_lds_dwordx4 v[158:159], off
	s_waitcnt lgkmcnt(8)
	s_barrier
	s_waitcnt lgkmcnt(0)
	s_setprio 1
	v_mfma_f32_16x16x32_bf16 v[124:127], v[138:141], v[154:157], v[124:127]
	v_mfma_f32_16x16x32_bf16 v[120:123], v[146:149], v[154:157], v[120:123]
	v_mfma_f32_16x16x32_bf16 v[116:119], v[138:141], v[178:181], v[116:119]
	v_mfma_f32_16x16x32_bf16 v[108:111], v[146:149], v[178:181], v[108:111]
	v_mfma_f32_16x16x32_bf16 v[100:103], v[138:141], v[186:189], v[100:103]
	v_mfma_f32_16x16x32_bf16 v[92:95], v[146:149], v[186:189], v[92:95]
	v_mfma_f32_16x16x32_bf16 v[84:87], v[138:141], v[194:197], v[84:87]
	v_mfma_f32_16x16x32_bf16 v[76:79], v[146:149], v[194:197], v[76:79]
	v_mfma_f32_16x16x32_bf16 v[124:127], v[142:145], v[174:177], v[124:127]
	v_mfma_f32_16x16x32_bf16 v[120:123], v[150:153], v[174:177], v[120:123]
	v_mfma_f32_16x16x32_bf16 v[116:119], v[142:145], v[182:185], v[116:119]
	v_mfma_f32_16x16x32_bf16 v[108:111], v[150:153], v[182:185], v[108:111]
	v_mfma_f32_16x16x32_bf16 v[100:103], v[142:145], v[190:193], v[100:103]
	v_mfma_f32_16x16x32_bf16 v[92:95], v[150:153], v[190:193], v[92:95]
	v_mfma_f32_16x16x32_bf16 v[84:87], v[142:145], v[214:217], v[84:87]
	v_mfma_f32_16x16x32_bf16 v[76:79], v[150:153], v[214:217], v[76:79]
	s_setprio 0
	s_barrier
	s_add_i32 s58, 0, 0x14000
	v_add_u32_e32 v158, s58, v135
	s_add_i32 s56, s56, s41
	ds_read_b128 v[218:221], v158
	ds_read_b128 v[222:225], v158 offset:1024
	ds_read_b128 v[226:229], v158 offset:2048
	ds_read_b128 v[230:233], v158 offset:3072
	v_lshl_add_u64 v[158:159], s[26:27], 0, v[160:161]
	s_mov_b32 m0, s56
	v_lshl_add_u64 v[234:235], s[26:27], 0, v[128:129]
	global_load_lds_dwordx4 v[158:159], off
	s_add_i32 m0, s56, 0x2000
	s_nop 0
	global_load_lds_dwordx4 v[234:235], off
	s_barrier
	s_waitcnt lgkmcnt(0)
	s_setprio 1
	v_mfma_f32_16x16x32_bf16 v[112:115], v[218:221], v[154:157], v[112:115]
	v_mfma_f32_16x16x32_bf16 v[104:107], v[226:229], v[154:157], v[104:107]
	v_mfma_f32_16x16x32_bf16 v[96:99], v[218:221], v[178:181], v[96:99]
	v_mfma_f32_16x16x32_bf16 v[88:91], v[226:229], v[178:181], v[88:91]
	v_mfma_f32_16x16x32_bf16 v[80:83], v[218:221], v[186:189], v[80:83]
	v_mfma_f32_16x16x32_bf16 v[72:75], v[226:229], v[186:189], v[72:75]
	v_mfma_f32_16x16x32_bf16 v[68:71], v[218:221], v[194:197], v[68:71]
	v_mfma_f32_16x16x32_bf16 v[64:67], v[226:229], v[194:197], v[64:67]
	v_mfma_f32_16x16x32_bf16 v[112:115], v[222:225], v[174:177], v[112:115]
	v_mfma_f32_16x16x32_bf16 v[104:107], v[230:233], v[174:177], v[104:107]
	v_mfma_f32_16x16x32_bf16 v[96:99], v[222:225], v[182:185], v[96:99]
	v_mfma_f32_16x16x32_bf16 v[88:91], v[230:233], v[182:185], v[88:91]
	v_mfma_f32_16x16x32_bf16 v[80:83], v[222:225], v[190:193], v[80:83]
	v_mfma_f32_16x16x32_bf16 v[72:75], v[230:233], v[190:193], v[72:75]
	v_mfma_f32_16x16x32_bf16 v[68:71], v[222:225], v[214:217], v[68:71]
	v_mfma_f32_16x16x32_bf16 v[64:67], v[230:233], v[214:217], v[64:67]
	s_setprio 0
	s_mov_b32 m0, s13
	v_lshl_add_u64 v[236:237], s[28:29], 0, v[160:161]
	s_barrier
	ds_read_b128 v[154:157], v137 offset:16384
	ds_read_b128 v[174:177], v137 offset:17408
	ds_read_b128 v[178:181], v137 offset:18432
	ds_read_b128 v[182:185], v137 offset:19456
	ds_read_b128 v[186:189], v137 offset:20480
	ds_read_b128 v[190:193], v137 offset:21504
	ds_read_b128 v[194:197], v137 offset:22528
	ds_read_b128 v[214:217], v137 offset:23552
	global_load_lds_dwordx4 v[236:237], off
	v_lshl_add_u64 v[238:239], s[28:29], 0, v[128:129]
	s_mov_b32 m0, s43
	s_nop 0
	global_load_lds_dwordx4 v[238:239], off
	s_barrier
	s_waitcnt lgkmcnt(0)
	s_setprio 1
	v_mfma_f32_16x16x32_bf16 v[60:63], v[138:141], v[154:157], v[60:63]
	v_mfma_f32_16x16x32_bf16 v[56:59], v[146:149], v[154:157], v[56:59]
	v_mfma_f32_16x16x32_bf16 v[52:55], v[138:141], v[178:181], v[52:55]
	v_mfma_f32_16x16x32_bf16 v[44:47], v[146:149], v[178:181], v[44:47]
	v_mfma_f32_16x16x32_bf16 v[36:39], v[138:141], v[186:189], v[36:39]
	v_mfma_f32_16x16x32_bf16 v[28:31], v[146:149], v[186:189], v[28:31]
	v_mfma_f32_16x16x32_bf16 v[20:23], v[138:141], v[194:197], v[20:23]
	v_mfma_f32_16x16x32_bf16 v[12:15], v[146:149], v[194:197], v[12:15]
	v_mfma_f32_16x16x32_bf16 v[60:63], v[142:145], v[174:177], v[60:63]
	v_mfma_f32_16x16x32_bf16 v[56:59], v[150:153], v[174:177], v[56:59]
	v_mfma_f32_16x16x32_bf16 v[52:55], v[142:145], v[182:185], v[52:55]
	v_mfma_f32_16x16x32_bf16 v[44:47], v[150:153], v[182:185], v[44:47]
	v_mfma_f32_16x16x32_bf16 v[36:39], v[142:145], v[190:193], v[36:39]
	v_mfma_f32_16x16x32_bf16 v[28:31], v[150:153], v[190:193], v[28:31]
	v_mfma_f32_16x16x32_bf16 v[20:23], v[142:145], v[214:217], v[20:23]
	v_mfma_f32_16x16x32_bf16 v[12:15], v[150:153], v[214:217], v[12:15]
	s_setprio 0
	s_barrier
; #define PG8_STAGE(bufoff, gbase, voff) do { _Pragma("unroll") for (int _i = 0; _i < 2; ++_i) \
;         __builtin_amdgcn_global_load_lds((const unsigned*)((const char*)(gbase) + (voff)[_i]), (LAS unsigned*)(lds + (bufoff) + ldsw + _i * 8192), 16, 0, 0); } while (0)
; #define PG8_LDA(dst, b, h) do { _Pragma("unroll") for (int m = 0; m < 4; ++m) _Pragma("unroll") for (int k = 0; k < 2; ++k) dst[m][k] = *(const LAS bf16x8*)(lds + PG8_SA(b, h) + aoff + m * 2048 + k * 1024); } while (0)
; #define PG8_LDB(dst, b, h) do { _Pragma("unroll") for (int n = 0; n < 2; ++n) _Pragma("unroll") for (int k = 0; k < 2; ++k) dst[n][k] = *(const LAS bf16x8*)(lds + PG8_SB(b, h) + boff + n * 2048 + k * 1024); } while (0)
; #define PG8_MMA(ai, bj, At, Bt) do { __builtin_amdgcn_s_setprio(1); _Pragma("unroll") for (int m = 0; m < 4; ++m) _Pragma("unroll") for (int n = 0; n < 2; ++n) _Pragma("unroll") for (int k = 0; k < 2; ++k) \
;         acc[ai][bj][m][n] = __builtin_amdgcn_mfma_f32_16x16x32_bf16(Bt[n][k], At[m][k], acc[ai][bj][m][n], 0, 0, 0); __builtin_amdgcn_s_setprio(0); } while (0)
; #define PG8_WAIT_V(n) asm volatile("s_waitcnt vmcnt(" #n ")" ::: "memory")
; #define PG8_WAIT_L(n) asm volatile("s_waitcnt lgkmcnt(" #n ")" ::: "memory")
; #define PG8_BAR __builtin_amdgcn_s_barrier()
; #define PG8_SCHED __builtin_amdgcn_sched_barrier(0)
; template <class Epi>
; DEV void gemm_phase(LAS unsigned char* lds, const Gemm g, const StaticOrder& S, const Epi& E) {
;     ...
;             PG8_STAGE(PG8_SB(0, 1), b2 + hstep, voffB);
;             PG8_WAIT_V(6); PG8_BAR; PG8_MMA(1, 1, At, B1); PG8_BAR;
;             PG8_LDB(B0, 1, 0); PG8_SCHED; PG8_LDA(At, 1, 0); PG8_STAGE(PG8_SA(0, 1), a2 + hstep, voffA);
;             PG8_WAIT_L(8); PG8_BAR; PG8_WAIT_L(0); PG8_MMA(0, 0, At, B0); PG8_BAR; PG8_SCHED;
;             PG8_LDB(B1, 1, 1); PG8_STAGE(PG8_SB(1, 0), b3, voffB);
;             PG8_BAR; PG8_WAIT_L(0); PG8_MMA(0, 1, At, B1); PG8_BAR;
;             PG8_LDA(At, 1, 1); PG8_STAGE(PG8_SA(1, 0), a3, voffA);
	s_add_u32 s56, s26, 0x80000
	s_addc_u32 s57, s27, 0
	s_add_i32 s58, s58, s41
	v_lshl_add_u64 v[138:139], s[56:57], 0, v[160:161]
	s_mov_b32 m0, s58
	s_nop 0
	global_load_lds_dwordx4 v[138:139], off
	v_lshl_add_u64 v[138:139], s[56:57], 0, v[128:129]
	s_add_i32 m0, s58, 0x2000
	s_nop 0
	global_load_lds_dwordx4 v[138:139], off
	s_waitcnt vmcnt(6)
	s_barrier
	s_setprio 1
	v_mfma_f32_16x16x32_bf16 v[48:51], v[218:221], v[154:157], v[48:51]
	v_mfma_f32_16x16x32_bf16 v[40:43], v[226:229], v[154:157], v[40:43]
	v_mfma_f32_16x16x32_bf16 v[32:35], v[218:221], v[178:181], v[32:35]
	v_mfma_f32_16x16x32_bf16 v[24:27], v[226:229], v[178:181], v[24:27]
	v_mfma_f32_16x16x32_bf16 v[16:19], v[218:221], v[186:189], v[16:19]
	v_mfma_f32_16x16x32_bf16 v[8:11], v[226:229], v[186:189], v[8:11]
	v_mfma_f32_16x16x32_bf16 v[4:7], v[218:221], v[194:197], v[4:7]
	v_mfma_f32_16x16x32_bf16 v[0:3], v[226:229], v[194:197], v[0:3]
	v_mfma_f32_16x16x32_bf16 v[48:51], v[222:225], v[174:177], v[48:51]
	v_mfma_f32_16x16x32_bf16 v[40:43], v[230:233], v[174:177], v[40:43]
	v_mfma_f32_16x16x32_bf16 v[32:35], v[222:225], v[182:185], v[32:35]
	v_mfma_f32_16x16x32_bf16 v[24:27], v[230:233], v[182:185], v[24:27]
	v_mfma_f32_16x16x32_bf16 v[16:19], v[222:225], v[190:193], v[16:19]
	v_mfma_f32_16x16x32_bf16 v[8:11], v[230:233], v[190:193], v[8:11]
	v_mfma_f32_16x16x32_bf16 v[4:7], v[222:225], v[214:217], v[4:7]
	v_mfma_f32_16x16x32_bf16 v[0:3], v[230:233], v[214:217], v[0:3]
	s_setprio 0
	s_add_i32 s56, 0, 0x18000
	v_add_u32_e32 v150, s56, v135
	s_barrier
	ds_read_b128 v[138:141], v150
	ds_read_b128 v[142:145], v150 offset:1024
	ds_read_b128 v[146:149], v150 offset:2048
	ds_read_b128 v[150:153], v150 offset:3072
	s_add_u32 s28, s28, 0x80000
	s_addc_u32 s29, s29, 0
	s_mov_b32 m0, s44
	v_lshl_add_u64 v[218:219], s[28:29], 0, v[160:161]
	ds_read_b128 v[154:157], v137 offset:32768
	ds_read_b128 v[174:177], v137 offset:33792
	ds_read_b128 v[178:181], v137 offset:34816
	ds_read_b128 v[182:185], v137 offset:35840
	ds_read_b128 v[186:189], v137 offset:36864
	ds_read_b128 v[190:193], v137 offset:37888
	ds_read_b128 v[194:197], v137 offset:38912
	ds_read_b128 v[214:217], v137 offset:39936
	global_load_lds_dwordx4 v[218:219], off
	v_lshl_add_u64 v[218:219], s[28:29], 0, v[128:129]
	s_mov_b32 m0, s45
	s_nop 0
	global_load_lds_dwordx4 v[218:219], off
	s_waitcnt lgkmcnt(8)
	s_barrier
	s_waitcnt lgkmcnt(0)
	s_setprio 1
	v_mfma_f32_16x16x32_bf16 v[124:127], v[138:141], v[154:157], v[124:127]
	v_mfma_f32_16x16x32_bf16 v[120:123], v[146:149], v[154:157], v[120:123]
	v_mfma_f32_16x16x32_bf16 v[116:119], v[138:141], v[178:181], v[116:119]
	v_mfma_f32_16x16x32_bf16 v[108:111], v[146:149], v[178:181], v[108:111]
	v_mfma_f32_16x16x32_bf16 v[100:103], v[138:141], v[186:189], v[100:103]
	v_mfma_f32_16x16x32_bf16 v[92:95], v[146:149], v[186:189], v[92:95]
	v_mfma_f32_16x16x32_bf16 v[84:87], v[138:141], v[194:197], v[84:87]
	v_mfma_f32_16x16x32_bf16 v[76:79], v[146:149], v[194:197], v[76:79]
	v_mfma_f32_16x16x32_bf16 v[124:127], v[142:145], v[174:177], v[124:127]
	v_mfma_f32_16x16x32_bf16 v[120:123], v[150:153], v[174:177], v[120:123]
	v_mfma_f32_16x16x32_bf16 v[116:119], v[142:145], v[182:185], v[116:119]
	v_mfma_f32_16x16x32_bf16 v[108:111], v[150:153], v[182:185], v[108:111]
	v_mfma_f32_16x16x32_bf16 v[100:103], v[142:145], v[190:193], v[100:103]
	v_mfma_f32_16x16x32_bf16 v[92:95], v[150:153], v[190:193], v[92:95]
	v_mfma_f32_16x16x32_bf16 v[84:87], v[142:145], v[214:217], v[84:87]
	v_mfma_f32_16x16x32_bf16 v[76:79], v[150:153], v[214:217], v[76:79]
	s_setprio 0
	s_barrier
	s_add_i32 s28, 0, 0x1c000
	s_add_i32 s29, s56, s41
	v_add_u32_e32 v167, s28, v135
	v_lshl_add_u64 v[158:159], v[158:159], 0, s[2:3]
	s_mov_b32 m0, s29
	ds_read_b128 v[218:221], v167
	ds_read_b128 v[222:225], v167 offset:1024
	ds_read_b128 v[226:229], v167 offset:2048
	ds_read_b128 v[230:233], v167 offset:3072
	global_load_lds_dwordx4 v[158:159], off
	v_lshl_add_u64 v[158:159], v[234:235], 0, s[2:3]
	s_add_i32 m0, s29, 0x2000
	s_nop 0
	global_load_lds_dwordx4 v[158:159], off
	s_barrier
	s_waitcnt lgkmcnt(0)
	s_setprio 1
	v_mfma_f32_16x16x32_bf16 v[112:115], v[218:221], v[154:157], v[112:115]
	v_mfma_f32_16x16x32_bf16 v[104:107], v[226:229], v[154:157], v[104:107]
	v_mfma_f32_16x16x32_bf16 v[96:99], v[218:221], v[178:181], v[96:99]
	v_mfma_f32_16x16x32_bf16 v[88:91], v[226:229], v[178:181], v[88:91]
	v_mfma_f32_16x16x32_bf16 v[80:83], v[218:221], v[186:189], v[80:83]
	v_mfma_f32_16x16x32_bf16 v[72:75], v[226:229], v[186:189], v[72:75]
	v_mfma_f32_16x16x32_bf16 v[68:71], v[218:221], v[194:197], v[68:71]
	v_mfma_f32_16x16x32_bf16 v[64:67], v[226:229], v[194:197], v[64:67]
	v_mfma_f32_16x16x32_bf16 v[112:115], v[222:225], v[174:177], v[112:115]
	v_mfma_f32_16x16x32_bf16 v[104:107], v[230:233], v[174:177], v[104:107]
	v_mfma_f32_16x16x32_bf16 v[96:99], v[222:225], v[182:185], v[96:99]
	v_mfma_f32_16x16x32_bf16 v[88:91], v[230:233], v[182:185], v[88:91]
	v_mfma_f32_16x16x32_bf16 v[80:83], v[222:225], v[190:193], v[80:83]
	v_mfma_f32_16x16x32_bf16 v[72:75], v[230:233], v[190:193], v[72:75]
	v_mfma_f32_16x16x32_bf16 v[68:71], v[222:225], v[214:217], v[68:71]
	v_mfma_f32_16x16x32_bf16 v[64:67], v[230:233], v[214:217], v[64:67]
	s_setprio 0
	s_mov_b32 m0, s46
	v_lshl_add_u64 v[158:159], v[236:237], 0, s[2:3]
	s_barrier
	ds_read_b128 v[154:157], v137 offset:49152
	ds_read_b128 v[174:177], v137 offset:50176
	ds_read_b128 v[178:181], v137 offset:51200
	ds_read_b128 v[182:185], v137 offset:52224
	ds_read_b128 v[186:189], v137 offset:53248
	ds_read_b128 v[190:193], v137 offset:54272
	ds_read_b128 v[194:197], v137 offset:55296
	ds_read_b128 v[214:217], v137 offset:56320
	global_load_lds_dwordx4 v[158:159], off
	v_lshl_add_u64 v[158:159], v[238:239], 0, s[2:3]
	s_mov_b32 m0, s47
	s_nop 0
	global_load_lds_dwordx4 v[158:159], off
	s_barrier
; #define PG8_STAGE(bufoff, gbase, voff) do { _Pragma("unroll") for (int _i = 0; _i < 2; ++_i) \
;         __builtin_amdgcn_global_load_lds((const unsigned*)((const char*)(gbase) + (voff)[_i]), (LAS unsigned*)(lds + (bufoff) + ldsw + _i * 8192), 16, 0, 0); } while (0)
; #define PG8_MMA(ai, bj, At, Bt) do { __builtin_amdgcn_s_setprio(1); _Pragma("unroll") for (int m = 0; m < 4; ++m) _Pragma("unroll") for (int n = 0; n < 2; ++n) _Pragma("unroll") for (int k = 0; k < 2; ++k) \
;         acc[ai][bj][m][n] = __builtin_amdgcn_mfma_f32_16x16x32_bf16(Bt[n][k], At[m][k], acc[ai][bj][m][n], 0, 0, 0); __builtin_amdgcn_s_setprio(0); } while (0)
; #define PG8_WAIT_V(n) asm volatile("s_waitcnt vmcnt(" #n ")" ::: "memory")
; #define PG8_WAIT_L(n) asm volatile("s_waitcnt lgkmcnt(" #n ")" ::: "memory")
; #define PG8_BAR __builtin_amdgcn_s_barrier()
; #define PG8_SCHED __builtin_amdgcn_sched_barrier(0)
; template <class Epi>
; DEV void gemm_phase(LAS unsigned char* lds, const Gemm g, const StaticOrder& S, const Epi& E) {
;     ...
;             PG8_BAR; PG8_WAIT_L(0); PG8_MMA(1, 0, At, B0); PG8_BAR; PG8_SCHED;
;             PG8_STAGE(PG8_SB(1, 1), b3 + hstep, voffB);
;             PG8_WAIT_V(6); PG8_BAR; PG8_MMA(1, 1, At, B1); PG8_BAR;
;         }
	s_waitcnt lgkmcnt(0)
	s_setprio 1
	v_mfma_f32_16x16x32_bf16 v[60:63], v[138:141], v[154:157], v[60:63]
	v_mfma_f32_16x16x32_bf16 v[56:59], v[146:149], v[154:157], v[56:59]
	v_mfma_f32_16x16x32_bf16 v[52:55], v[138:141], v[178:181], v[52:55]
	v_mfma_f32_16x16x32_bf16 v[44:47], v[146:149], v[178:181], v[44:47]
	v_mfma_f32_16x16x32_bf16 v[36:39], v[138:141], v[186:189], v[36:39]
	v_mfma_f32_16x16x32_bf16 v[28:31], v[146:149], v[186:189], v[28:31]
	v_mfma_f32_16x16x32_bf16 v[20:23], v[138:141], v[194:197], v[20:23]
	v_mfma_f32_16x16x32_bf16 v[12:15], v[146:149], v[194:197], v[12:15]
	v_mfma_f32_16x16x32_bf16 v[60:63], v[142:145], v[174:177], v[60:63]
	v_mfma_f32_16x16x32_bf16 v[56:59], v[150:153], v[174:177], v[56:59]
	v_mfma_f32_16x16x32_bf16 v[52:55], v[142:145], v[182:185], v[52:55]
	v_mfma_f32_16x16x32_bf16 v[44:47], v[150:153], v[182:185], v[44:47]
	v_mfma_f32_16x16x32_bf16 v[36:39], v[142:145], v[190:193], v[36:39]
	v_mfma_f32_16x16x32_bf16 v[28:31], v[150:153], v[190:193], v[28:31]
	v_mfma_f32_16x16x32_bf16 v[20:23], v[142:145], v[214:217], v[20:23]
	v_mfma_f32_16x16x32_bf16 v[12:15], v[150:153], v[214:217], v[12:15]
	s_setprio 0
	s_barrier
	s_add_u32 s26, s26, 0x80080
	s_addc_u32 s27, s27, 0
	s_add_i32 s28, s28, s41
	v_lshl_add_u64 v[138:139], s[26:27], 0, v[160:161]
	s_mov_b32 m0, s28
	s_nop 0
	global_load_lds_dwordx4 v[138:139], off
	v_lshl_add_u64 v[138:139], s[26:27], 0, v[128:129]
	s_add_i32 m0, s28, 0x2000
	s_nop 0
	global_load_lds_dwordx4 v[138:139], off
	s_waitcnt vmcnt(6)
	s_barrier
	s_setprio 1
	v_mfma_f32_16x16x32_bf16 v[48:51], v[218:221], v[154:157], v[48:51]
	v_mfma_f32_16x16x32_bf16 v[40:43], v[226:229], v[154:157], v[40:43]
	v_mfma_f32_16x16x32_bf16 v[32:35], v[218:221], v[178:181], v[32:35]
	v_mfma_f32_16x16x32_bf16 v[24:27], v[226:229], v[178:181], v[24:27]
	v_mfma_f32_16x16x32_bf16 v[16:19], v[218:221], v[186:189], v[16:19]
	v_mfma_f32_16x16x32_bf16 v[8:11], v[226:229], v[186:189], v[8:11]
	v_mfma_f32_16x16x32_bf16 v[4:7], v[218:221], v[194:197], v[4:7]
	v_mfma_f32_16x16x32_bf16 v[0:3], v[226:229], v[194:197], v[0:3]
	v_mfma_f32_16x16x32_bf16 v[48:51], v[222:225], v[174:177], v[48:51]
	v_mfma_f32_16x16x32_bf16 v[40:43], v[230:233], v[174:177], v[40:43]
	v_mfma_f32_16x16x32_bf16 v[32:35], v[222:225], v[182:185], v[32:35]
	v_mfma_f32_16x16x32_bf16 v[24:27], v[230:233], v[182:185], v[24:27]
	v_mfma_f32_16x16x32_bf16 v[16:19], v[222:225], v[190:193], v[16:19]
	v_mfma_f32_16x16x32_bf16 v[8:11], v[230:233], v[190:193], v[8:11]
	v_mfma_f32_16x16x32_bf16 v[4:7], v[222:225], v[214:217], v[4:7]
	v_mfma_f32_16x16x32_bf16 v[0:3], v[230:233], v[214:217], v[0:3]
	s_setprio 0
	s_add_i32 s55, s55, 2
	s_add_u32 s24, s24, 0x100
	s_addc_u32 s25, s25, 0
	s_add_u32 s53, s53, 0x100
	s_addc_u32 s54, s54, 0
	s_cmp_gt_u32 s55, 29
	s_barrier
	s_cbranch_scc0 .LBB0_362
; DEV bf16x8 pack8(f32x4 a, f32x4 b) { u32x4 w; w.x = cvt_pk_bf16(a[0], a[1]); w.y = cvt_pk_bf16(a[2], a[3]); w.z = cvt_pk_bf16(b[0], b[1]); w.w = cvt_pk_bf16(b[2], b[3]); return __builtin_bit_cast(bf16x8, w); }
; DEV u32x2 pack4(f32x4 a) { u32x2 w; w.x = cvt_pk_bf16(a[0], a[1]); w.y = cvt_pk_bf16(a[2], a[3]); return w; }
; DEV f32x4 gelu4(f32x4 v) { f32x2 a = gelu_pk((f32x2){v[0], v[1]}), b = gelu_pk((f32x2){v[2], v[3]}); return (f32x4){a.x, a.y, b.x, b.y}; }
; template <int ACT, bool PERM>
; DEV void store_bf16_tile(AccRef acc, u16* O, int ld, int row0, int col0, const float* ss) {
;     ...
; #pragma unroll
;     for (int ai = 0; ai < 2; ++ai)
; #pragma unroll
;         for (int m = 0; m < 4; ++m) { u16* rowp = O + (size_t)(row0 + ai * 128 + m * 16) * ld + col0; const float rs = rsv[ai][m];
; #pragma unroll
;             for (int bj = 0; bj < 2; ++bj) { f32x4 v0 = acc[ai][bj][m][0] * rs, v1 = acc[ai][bj][m][1] * rs; if (ACT == 1) { v0 = gelu4(v0); v1 = gelu4(v1); }
;                 if (PERM) *(u32x4*)(rowp + bj * 128) = __builtin_bit_cast(u32x4, pack8(v0, v1));
;                 else { *(u32x2*)(rowp + bj * 128) = pack4(v0); *(u32x2*)(rowp + bj * 128 + 16) = pack4(v1); } } }
; }
;     DEV void operator()(AccRef acc, const pg8::Unit& u, int wr, int wc, int fr, int fq) const { store_bf16_tile<0, false>(acc, O, ld, u.pm * 256 + wr * 64 + fr, u.pn * 256 + wc * 32 + 4 * fq, ss); }
	v_lshl_add_u32 v138, s12, 8, v134
	v_lshl_or_b32 v140, s50, 8, v136
	v_ashrrev_i32_e32 v141, 31, v140
	v_ashrrev_i32_e32 v139, 31, v138
	v_lshl_add_u64 v[140:141], v[140:141], 1, s[10:11]
	v_lshlrev_b64 v[142:143], 11, v[138:139]
	v_lshl_add_u64 v[142:143], v[140:141], 0, v[142:143]
	v_cvt_pk_bf16_f32 v104, v104, v105
	v_cvt_pk_bf16_f32 v105, v106, v107
	global_store_dwordx2 v[142:143], v[104:105], off offset:288
	v_or_b32_e32 v104, 16, v138
	v_ashrrev_i32_e32 v105, 31, v104
	v_lshlrev_b64 v[104:105], 11, v[104:105]
	v_lshl_add_u64 v[104:105], v[140:141], 0, v[104:105]
	v_cvt_pk_bf16_f32 v88, v88, v89
	v_cvt_pk_bf16_f32 v89, v90, v91
	global_store_dwordx2 v[104:105], v[88:89], off offset:288
	v_or_b32_e32 v88, 32, v138
	v_ashrrev_i32_e32 v89, 31, v88
	v_lshlrev_b64 v[88:89], 11, v[88:89]
	v_lshl_add_u64 v[88:89], v[140:141], 0, v[88:89]
	v_cvt_pk_bf16_f32 v72, v72, v73
	v_cvt_pk_bf16_f32 v73, v74, v75
	global_store_dwordx2 v[88:89], v[72:73], off offset:288
	v_or_b32_e32 v72, 48, v138
	v_ashrrev_i32_e32 v73, 31, v72
	v_lshlrev_b64 v[72:73], 11, v[72:73]
	s_mov_b32 s12, 0x40000
	v_lshl_add_u64 v[72:73], v[140:141], 0, v[72:73]
	v_cvt_pk_bf16_f32 v64, v64, v65
	v_cvt_pk_bf16_f32 v65, v66, v67
	s_mov_b64 s[24:25], 0x40000
	v_cvt_pk_bf16_f32 v60, v60, v61
	v_cvt_pk_bf16_f32 v61, v62, v63
	v_add_co_u32_e32 v62, vcc, s12, v142
	global_store_dwordx2 v[72:73], v[64:65], off offset:288
	v_lshl_add_u64 v[64:65], v[142:143], 0, s[24:25]
	v_addc_co_u32_e32 v63, vcc, 0, v143, vcc
	v_cvt_pk_bf16_f32 v48, v48, v49
	v_cvt_pk_bf16_f32 v49, v50, v51
	s_mov_b32 s12, 0x48000
	global_store_dwordx2 v[64:65], v[48:49], off offset:256
	v_cvt_pk_bf16_f32 v40, v40, v41
	v_cvt_pk_bf16_f32 v41, v42, v43
	s_mov_b64 s[24:25], 0x48000
	v_add_co_u32_e32 v48, vcc, s12, v142
	global_store_dwordx2 v[64:65], v[40:41], off offset:288
	v_lshl_add_u64 v[40:41], v[142:143], 0, s[24:25]
	v_addc_co_u32_e32 v49, vcc, 0, v143, vcc
	v_cvt_pk_bf16_f32 v32, v32, v33
	v_cvt_pk_bf16_f32 v33, v34, v35
	s_mov_b32 s12, 0x50000
	global_store_dwordx2 v[40:41], v[32:33], off offset:256
	v_cvt_pk_bf16_f32 v24, v24, v25
	v_cvt_pk_bf16_f32 v25, v26, v27
	s_mov_b64 s[24:25], 0x50000
	v_add_co_u32_e32 v32, vcc, s12, v142
	global_store_dwordx2 v[40:41], v[24:25], off offset:288
	v_lshl_add_u64 v[24:25], v[142:143], 0, s[24:25]
	v_addc_co_u32_e32 v33, vcc, 0, v143, vcc
	v_cvt_pk_bf16_f32 v16, v16, v17
	v_cvt_pk_bf16_f32 v17, v18, v19
	global_store_dwordx2 v[24:25], v[16:17], off offset:256
	v_add_co_u32_e32 v16, vcc, s59, v142
	v_cvt_pk_bf16_f32 v106, v116, v117
	v_cvt_pk_bf16_f32 v107, v118, v119
	v_cvt_pk_bf16_f32 v90, v100, v101
	v_cvt_pk_bf16_f32 v91, v102, v103
	v_cvt_pk_bf16_f32 v74, v84, v85
	v_cvt_pk_bf16_f32 v75, v86, v87
	v_cvt_pk_bf16_f32 v42, v52, v53
	v_cvt_pk_bf16_f32 v43, v54, v55
	v_cvt_pk_bf16_f32 v26, v36, v37
	v_cvt_pk_bf16_f32 v27, v38, v39
	v_cvt_pk_bf16_f32 v8, v8, v9
	v_cvt_pk_bf16_f32 v9, v10, v11
	s_mov_b64 s[24:25], 0x58000
	v_cvt_pk_bf16_f32 v10, v20, v21
	v_cvt_pk_bf16_f32 v11, v22, v23
	v_addc_co_u32_e32 v17, vcc, 0, v143, vcc
	v_cvt_pk_bf16_f32 v124, v124, v125
	v_cvt_pk_bf16_f32 v125, v126, v127
	v_cvt_pk_bf16_f32 v120, v120, v121
	v_cvt_pk_bf16_f32 v121, v122, v123
	v_cvt_pk_bf16_f32 v112, v112, v113
	v_cvt_pk_bf16_f32 v113, v114, v115
	global_store_dwordx2 v[104:105], v[106:107], off
	v_cvt_pk_bf16_f32 v106, v108, v109
	v_cvt_pk_bf16_f32 v107, v110, v111
	v_cvt_pk_bf16_f32 v96, v96, v97
	v_cvt_pk_bf16_f32 v97, v98, v99
	global_store_dwordx2 v[88:89], v[90:91], off
	v_cvt_pk_bf16_f32 v90, v92, v93
	v_cvt_pk_bf16_f32 v91, v94, v95
	v_cvt_pk_bf16_f32 v80, v80, v81
	v_cvt_pk_bf16_f32 v81, v82, v83
	global_store_dwordx2 v[72:73], v[74:75], off
	v_cvt_pk_bf16_f32 v74, v76, v77
	v_cvt_pk_bf16_f32 v75, v78, v79
	v_cvt_pk_bf16_f32 v68, v68, v69
	v_cvt_pk_bf16_f32 v69, v70, v71
	v_cvt_pk_bf16_f32 v56, v56, v57
	v_cvt_pk_bf16_f32 v57, v58, v59
	global_store_dwordx2 v[48:49], v[42:43], off
	v_cvt_pk_bf16_f32 v42, v44, v45
	v_cvt_pk_bf16_f32 v43, v46, v47
	global_store_dwordx2 v[32:33], v[26:27], off
	v_cvt_pk_bf16_f32 v26, v28, v29
	v_cvt_pk_bf16_f32 v27, v30, v31
	global_store_dwordx2 v[24:25], v[8:9], off offset:288
	v_lshl_add_u64 v[8:9], v[142:143], 0, s[24:25]
	global_store_dwordx2 v[16:17], v[10:11], off
	v_cvt_pk_bf16_f32 v10, v12, v13
	v_cvt_pk_bf16_f32 v11, v14, v15
	v_cvt_pk_bf16_f32 v4, v4, v5
	v_cvt_pk_bf16_f32 v5, v6, v7
	v_cvt_pk_bf16_f32 v0, v0, v1
	v_cvt_pk_bf16_f32 v1, v2, v3
	s_and_b64 vcc, exec, s[14:15]
	s_mov_b32 s50, s16
	s_mov_b32 s12, s18
	s_mov_b64 s[26:27], s[22:23]
	s_mov_b64 s[24:25], s[20:21]
	global_store_dwordx2 v[142:143], v[124:125], off
	global_store_dwordx2 v[142:143], v[120:121], off offset:32
	global_store_dwordx2 v[142:143], v[112:113], off offset:256
	global_store_dwordx2 v[104:105], v[106:107], off offset:32
	global_store_dwordx2 v[104:105], v[96:97], off offset:256
	global_store_dwordx2 v[88:89], v[90:91], off offset:32
	global_store_dwordx2 v[88:89], v[80:81], off offset:256
	global_store_dwordx2 v[72:73], v[74:75], off offset:32
	global_store_dwordx2 v[72:73], v[68:69], off offset:256
	global_store_dwordx2 v[62:63], v[60:61], off
	global_store_dwordx2 v[64:65], v[56:57], off offset:32
	global_store_dwordx2 v[40:41], v[42:43], off offset:32
	global_store_dwordx2 v[24:25], v[26:27], off offset:32
	global_store_dwordx2 v[8:9], v[10:11], off offset:32
	global_store_dwordx2 v[8:9], v[4:5], off offset:256
	global_store_dwordx2 v[8:9], v[0:1], off offset:288
	s_cbranch_vccz .LBB0_359
	s_waitcnt vmcnt(0)
	s_cmpk_gt_u32 s36, 0xff
	s_cbranch_scc1 .LBB0_353
	s_barrier
	s_branch .LBB0_353

; #define PG8_STAGE(bufoff, gbase, voff) do { _Pragma("unroll") for (int _i = 0; _i < 2; ++_i) \
;         __builtin_amdgcn_global_load_lds((const unsigned*)((const char*)(gbase) + (voff)[_i]), (LAS unsigned*)(lds + (bufoff) + ldsw + _i * 8192), 16, 0, 0); } while (0)
; #define PG8_LDA(dst, b, h) do { _Pragma("unroll") for (int m = 0; m < 4; ++m) _Pragma("unroll") for (int k = 0; k < 2; ++k) dst[m][k] = *(const LAS bf16x8*)(lds + PG8_SA(b, h) + aoff + m * 2048 + k * 1024); } while (0)
; #define PG8_LDB(dst, b, h) do { _Pragma("unroll") for (int n = 0; n < 2; ++n) _Pragma("unroll") for (int k = 0; k < 2; ++k) dst[n][k] = *(const LAS bf16x8*)(lds + PG8_SB(b, h) + boff + n * 2048 + k * 1024); } while (0)
; #define PG8_MMA(ai, bj, At, Bt) do { __builtin_amdgcn_s_setprio(1); _Pragma("unroll") for (int m = 0; m < 4; ++m) _Pragma("unroll") for (int n = 0; n < 2; ++n) _Pragma("unroll") for (int k = 0; k < 2; ++k) \
;         acc[ai][bj][m][n] = __builtin_amdgcn_mfma_f32_16x16x32_bf16(Bt[n][k], At[m][k], acc[ai][bj][m][n], 0, 0, 0); __builtin_amdgcn_s_setprio(0); } while (0)
; #define PG8_WAIT_L(n) asm volatile("s_waitcnt lgkmcnt(" #n ")" ::: "memory")
; #define PG8_BAR __builtin_amdgcn_s_barrier()
; #define PG8_SCHED __builtin_amdgcn_sched_barrier(0)
; template <class Epi>
; DEV void gemm_phase(LAS unsigned char* lds, const Gemm g, const StaticOrder& S, const Epi& E) {
;     ...
;             PG8_LDB(B0, 0, 0); PG8_SCHED; PG8_LDA(At, 0, 0); PG8_STAGE(PG8_SA(1, 1), a1 + hstep, voffA);
;             PG8_WAIT_L(8); PG8_BAR; PG8_WAIT_L(0); PG8_MMA(0, 0, At, B0); PG8_BAR; PG8_SCHED;
;             PG8_LDB(B1, 0, 1); PG8_STAGE(PG8_SB(0, 0), b2, voffB);
;             PG8_BAR; PG8_WAIT_L(0); PG8_MMA(0, 1, At, B1); PG8_BAR;
;             PG8_LDA(At, 0, 1); PG8_STAGE(PG8_SA(0, 0), a2, voffA);
;             PG8_BAR; PG8_WAIT_L(0); PG8_MMA(1, 0, At, B0); PG8_BAR; PG8_SCHED;
.LBB0_404:
	s_add_u32 s28, s26, 0xfff00080
	s_addc_u32 s29, s27, -1
	s_add_i32 s49, 0, 0x10000
	v_add_u32_e32 v140, s49, v178
	ds_read_b128 v[128:131], v140
	ds_read_b128 v[132:135], v140 offset:1024
	ds_read_b128 v[136:139], v140 offset:2048
	ds_read_b128 v[140:143], v140 offset:3072
	s_cmp_eq_u32 s48, 60
	s_cselect_b32 s31, s15, s29
	s_cselect_b32 s30, s19, s28
	s_cselect_b32 s29, s17, s47
	s_cselect_b32 s28, s25, s46
	v_lshl_add_u64 v[158:159], s[26:27], 0, v[150:151]
	s_add_i32 m0, s37, 0xc000
	ds_read_b128 v[154:157], v181
	ds_read_b128 v[174:177], v181 offset:1024
	ds_read_b128 v[182:185], v181 offset:2048
	ds_read_b128 v[186:189], v181 offset:3072
	ds_read_b128 v[190:193], v181 offset:4096
	ds_read_b128 v[194:197], v181 offset:5120
	ds_read_b128 v[214:217], v181 offset:6144
	ds_read_b128 v[218:221], v181 offset:7168
	global_load_lds_dwordx4 v[158:159], off
	v_lshl_add_u64 v[158:159], s[26:27], 0, v[152:153]
	s_add_i32 m0, s37, 0xe000
	s_nop 0
	global_load_lds_dwordx4 v[158:159], off
	s_waitcnt lgkmcnt(8)
	s_barrier
	s_waitcnt lgkmcnt(0)
	s_setprio 1
	v_mfma_f32_16x16x32_bf16 v[124:127], v[128:131], v[154:157], v[124:127]
	v_mfma_f32_16x16x32_bf16 v[120:123], v[136:139], v[154:157], v[120:123]
	v_mfma_f32_16x16x32_bf16 v[108:111], v[128:131], v[182:185], v[108:111]
	v_mfma_f32_16x16x32_bf16 v[104:107], v[136:139], v[182:185], v[104:107]
	v_mfma_f32_16x16x32_bf16 v[92:95], v[128:131], v[190:193], v[92:95]
	v_mfma_f32_16x16x32_bf16 v[88:91], v[136:139], v[190:193], v[88:91]
	v_mfma_f32_16x16x32_bf16 v[76:79], v[128:131], v[214:217], v[76:79]
	v_mfma_f32_16x16x32_bf16 v[72:75], v[136:139], v[214:217], v[72:75]
	v_mfma_f32_16x16x32_bf16 v[124:127], v[132:135], v[174:177], v[124:127]
	v_mfma_f32_16x16x32_bf16 v[120:123], v[140:143], v[174:177], v[120:123]
	v_mfma_f32_16x16x32_bf16 v[108:111], v[132:135], v[186:189], v[108:111]
	v_mfma_f32_16x16x32_bf16 v[104:107], v[140:143], v[186:189], v[104:107]
	v_mfma_f32_16x16x32_bf16 v[92:95], v[132:135], v[194:197], v[92:95]
	v_mfma_f32_16x16x32_bf16 v[88:91], v[140:143], v[194:197], v[88:91]
	v_mfma_f32_16x16x32_bf16 v[76:79], v[132:135], v[218:221], v[76:79]
	v_mfma_f32_16x16x32_bf16 v[72:75], v[140:143], v[218:221], v[72:75]
	s_setprio 0
	s_barrier
	s_add_i32 s52, 0, 0x14000
	v_add_u32_e32 v158, s52, v178
	s_add_i32 s49, s49, s36
	ds_read_b128 v[222:225], v158
	ds_read_b128 v[226:229], v158 offset:1024
	ds_read_b128 v[230:233], v158 offset:2048
	ds_read_b128 v[234:237], v158 offset:3072
	v_lshl_add_u64 v[158:159], s[28:29], 0, v[160:161]
	s_mov_b32 m0, s49
	v_lshl_add_u64 v[238:239], s[28:29], 0, v[148:149]
	global_load_lds_dwordx4 v[158:159], off
	s_add_i32 m0, s49, 0x2000
	s_nop 0
	global_load_lds_dwordx4 v[238:239], off
	s_barrier
	s_waitcnt lgkmcnt(0)
	s_setprio 1
	v_mfma_f32_16x16x32_bf16 v[116:119], v[222:225], v[154:157], v[116:119]
	v_mfma_f32_16x16x32_bf16 v[112:115], v[230:233], v[154:157], v[112:115]
	v_mfma_f32_16x16x32_bf16 v[100:103], v[222:225], v[182:185], v[100:103]
	v_mfma_f32_16x16x32_bf16 v[96:99], v[230:233], v[182:185], v[96:99]
	v_mfma_f32_16x16x32_bf16 v[84:87], v[222:225], v[190:193], v[84:87]
	v_mfma_f32_16x16x32_bf16 v[80:83], v[230:233], v[190:193], v[80:83]
	v_mfma_f32_16x16x32_bf16 v[68:71], v[222:225], v[214:217], v[68:71]
	v_mfma_f32_16x16x32_bf16 v[64:67], v[230:233], v[214:217], v[64:67]
	v_mfma_f32_16x16x32_bf16 v[116:119], v[226:229], v[174:177], v[116:119]
	v_mfma_f32_16x16x32_bf16 v[112:115], v[234:237], v[174:177], v[112:115]
	v_mfma_f32_16x16x32_bf16 v[100:103], v[226:229], v[186:189], v[100:103]
	v_mfma_f32_16x16x32_bf16 v[96:99], v[234:237], v[186:189], v[96:99]
	v_mfma_f32_16x16x32_bf16 v[84:87], v[226:229], v[194:197], v[84:87]
	v_mfma_f32_16x16x32_bf16 v[80:83], v[234:237], v[194:197], v[80:83]
	v_mfma_f32_16x16x32_bf16 v[68:71], v[226:229], v[218:221], v[68:71]
	v_mfma_f32_16x16x32_bf16 v[64:67], v[234:237], v[218:221], v[64:67]
	s_setprio 0
	s_mov_b32 m0, s37
	v_lshl_add_u64 v[240:241], s[30:31], 0, v[144:145]
	s_barrier
	ds_read_b128 v[154:157], v181 offset:16384
	ds_read_b128 v[174:177], v181 offset:17408
	ds_read_b128 v[182:185], v181 offset:18432
	ds_read_b128 v[186:189], v181 offset:19456
	ds_read_b128 v[190:193], v181 offset:20480
	ds_read_b128 v[194:197], v181 offset:21504
	ds_read_b128 v[214:217], v181 offset:22528
	ds_read_b128 v[218:221], v181 offset:23552
	global_load_lds_dwordx4 v[240:241], off
	v_lshl_add_u64 v[242:243], s[30:31], 0, v[146:147]
	s_mov_b32 m0, s38
	s_nop 0
	global_load_lds_dwordx4 v[242:243], off
	s_barrier
	s_waitcnt lgkmcnt(0)
	s_setprio 1
	v_mfma_f32_16x16x32_bf16 v[60:63], v[128:131], v[154:157], v[60:63]
	v_mfma_f32_16x16x32_bf16 v[56:59], v[136:139], v[154:157], v[56:59]
	v_mfma_f32_16x16x32_bf16 v[44:47], v[128:131], v[182:185], v[44:47]
	v_mfma_f32_16x16x32_bf16 v[40:43], v[136:139], v[182:185], v[40:43]
	v_mfma_f32_16x16x32_bf16 v[28:31], v[128:131], v[190:193], v[28:31]
	v_mfma_f32_16x16x32_bf16 v[24:27], v[136:139], v[190:193], v[24:27]
	v_mfma_f32_16x16x32_bf16 v[12:15], v[128:131], v[214:217], v[12:15]
	v_mfma_f32_16x16x32_bf16 v[8:11], v[136:139], v[214:217], v[8:11]
	v_mfma_f32_16x16x32_bf16 v[60:63], v[132:135], v[174:177], v[60:63]
	v_mfma_f32_16x16x32_bf16 v[56:59], v[140:143], v[174:177], v[56:59]
	v_mfma_f32_16x16x32_bf16 v[44:47], v[132:135], v[186:189], v[44:47]
	v_mfma_f32_16x16x32_bf16 v[40:43], v[140:143], v[186:189], v[40:43]
	v_mfma_f32_16x16x32_bf16 v[28:31], v[132:135], v[194:197], v[28:31]
	v_mfma_f32_16x16x32_bf16 v[24:27], v[140:143], v[194:197], v[24:27]
	v_mfma_f32_16x16x32_bf16 v[12:15], v[132:135], v[218:221], v[12:15]
	v_mfma_f32_16x16x32_bf16 v[8:11], v[140:143], v[218:221], v[8:11]
	s_setprio 0
	s_barrier
; #define PG8_STAGE(bufoff, gbase, voff) do { _Pragma("unroll") for (int _i = 0; _i < 2; ++_i) \
;         __builtin_amdgcn_global_load_lds((const unsigned*)((const char*)(gbase) + (voff)[_i]), (LAS unsigned*)(lds + (bufoff) + ldsw + _i * 8192), 16, 0, 0); } while (0)
; #define PG8_LDA(dst, b, h) do { _Pragma("unroll") for (int m = 0; m < 4; ++m) _Pragma("unroll") for (int k = 0; k < 2; ++k) dst[m][k] = *(const LAS bf16x8*)(lds + PG8_SA(b, h) + aoff + m * 2048 + k * 1024); } while (0)
; #define PG8_LDB(dst, b, h) do { _Pragma("unroll") for (int n = 0; n < 2; ++n) _Pragma("unroll") for (int k = 0; k < 2; ++k) dst[n][k] = *(const LAS bf16x8*)(lds + PG8_SB(b, h) + boff + n * 2048 + k * 1024); } while (0)
; #define PG8_MMA(ai, bj, At, Bt) do { __builtin_amdgcn_s_setprio(1); _Pragma("unroll") for (int m = 0; m < 4; ++m) _Pragma("unroll") for (int n = 0; n < 2; ++n) _Pragma("unroll") for (int k = 0; k < 2; ++k) \
;         acc[ai][bj][m][n] = __builtin_amdgcn_mfma_f32_16x16x32_bf16(Bt[n][k], At[m][k], acc[ai][bj][m][n], 0, 0, 0); __builtin_amdgcn_s_setprio(0); } while (0)
; #define PG8_WAIT_V(n) asm volatile("s_waitcnt vmcnt(" #n ")" ::: "memory")
; #define PG8_WAIT_L(n) asm volatile("s_waitcnt lgkmcnt(" #n ")" ::: "memory")
; #define PG8_BAR __builtin_amdgcn_s_barrier()
; #define PG8_SCHED __builtin_amdgcn_sched_barrier(0)
; template <class Epi>
; DEV void gemm_phase(LAS unsigned char* lds, const Gemm g, const StaticOrder& S, const Epi& E) {
;     ...
;             PG8_STAGE(PG8_SB(0, 1), b2 + hstep, voffB);
;             PG8_WAIT_V(6); PG8_BAR; PG8_MMA(1, 1, At, B1); PG8_BAR;
;             PG8_LDB(B0, 1, 0); PG8_SCHED; PG8_LDA(At, 1, 0); PG8_STAGE(PG8_SA(0, 1), a2 + hstep, voffA);
;             PG8_WAIT_L(8); PG8_BAR; PG8_WAIT_L(0); PG8_MMA(0, 0, At, B0); PG8_BAR; PG8_SCHED;
;             PG8_LDB(B1, 1, 1); PG8_STAGE(PG8_SB(1, 0), b3, voffB);
;             PG8_BAR; PG8_WAIT_L(0); PG8_MMA(0, 1, At, B1); PG8_BAR;
;             PG8_LDA(At, 1, 1); PG8_STAGE(PG8_SA(1, 0), a3, voffA);
	s_add_u32 s50, s28, 0x100000
	s_addc_u32 s51, s29, 0
	s_add_i32 s49, s52, s36
	v_lshl_add_u64 v[128:129], s[50:51], 0, v[160:161]
	s_mov_b32 m0, s49
	s_nop 0
	global_load_lds_dwordx4 v[128:129], off
	v_lshl_add_u64 v[128:129], s[50:51], 0, v[148:149]
	s_add_i32 m0, s49, 0x2000
	s_nop 0
	global_load_lds_dwordx4 v[128:129], off
	s_waitcnt vmcnt(6)
	s_barrier
	s_setprio 1
	v_mfma_f32_16x16x32_bf16 v[52:55], v[222:225], v[154:157], v[52:55]
	v_mfma_f32_16x16x32_bf16 v[48:51], v[230:233], v[154:157], v[48:51]
	v_mfma_f32_16x16x32_bf16 v[36:39], v[222:225], v[182:185], v[36:39]
	v_mfma_f32_16x16x32_bf16 v[32:35], v[230:233], v[182:185], v[32:35]
	v_mfma_f32_16x16x32_bf16 v[20:23], v[222:225], v[190:193], v[20:23]
	v_mfma_f32_16x16x32_bf16 v[16:19], v[230:233], v[190:193], v[16:19]
	v_mfma_f32_16x16x32_bf16 v[4:7], v[222:225], v[214:217], v[4:7]
	v_mfma_f32_16x16x32_bf16 v[0:3], v[230:233], v[214:217], v[0:3]
	v_mfma_f32_16x16x32_bf16 v[52:55], v[226:229], v[174:177], v[52:55]
	v_mfma_f32_16x16x32_bf16 v[48:51], v[234:237], v[174:177], v[48:51]
	v_mfma_f32_16x16x32_bf16 v[36:39], v[226:229], v[186:189], v[36:39]
	v_mfma_f32_16x16x32_bf16 v[32:35], v[234:237], v[186:189], v[32:35]
	v_mfma_f32_16x16x32_bf16 v[20:23], v[226:229], v[194:197], v[20:23]
	v_mfma_f32_16x16x32_bf16 v[16:19], v[234:237], v[194:197], v[16:19]
	v_mfma_f32_16x16x32_bf16 v[4:7], v[226:229], v[218:221], v[4:7]
	v_mfma_f32_16x16x32_bf16 v[0:3], v[234:237], v[218:221], v[0:3]
	s_setprio 0
	s_add_i32 s49, 0, 0x18000
	v_add_u32_e32 v140, s49, v178
	s_barrier
	ds_read_b128 v[128:131], v140
	ds_read_b128 v[132:135], v140 offset:1024
	ds_read_b128 v[136:139], v140 offset:2048
	ds_read_b128 v[140:143], v140 offset:3072
	s_add_u32 s30, s30, 0x100000
	s_addc_u32 s31, s31, 0
	s_mov_b32 m0, s39
	v_lshl_add_u64 v[222:223], s[30:31], 0, v[144:145]
	ds_read_b128 v[154:157], v181 offset:32768
	ds_read_b128 v[174:177], v181 offset:33792
	ds_read_b128 v[182:185], v181 offset:34816
	ds_read_b128 v[186:189], v181 offset:35840
	ds_read_b128 v[190:193], v181 offset:36864
	ds_read_b128 v[194:197], v181 offset:37888
	ds_read_b128 v[214:217], v181 offset:38912
	ds_read_b128 v[218:221], v181 offset:39936
	global_load_lds_dwordx4 v[222:223], off
	v_lshl_add_u64 v[222:223], s[30:31], 0, v[146:147]
	s_mov_b32 m0, s40
	s_nop 0
	global_load_lds_dwordx4 v[222:223], off
	s_waitcnt lgkmcnt(8)
	s_barrier
	s_waitcnt lgkmcnt(0)
	s_setprio 1
	v_mfma_f32_16x16x32_bf16 v[124:127], v[128:131], v[154:157], v[124:127]
	v_mfma_f32_16x16x32_bf16 v[120:123], v[136:139], v[154:157], v[120:123]
	v_mfma_f32_16x16x32_bf16 v[108:111], v[128:131], v[182:185], v[108:111]
	v_mfma_f32_16x16x32_bf16 v[104:107], v[136:139], v[182:185], v[104:107]
	v_mfma_f32_16x16x32_bf16 v[92:95], v[128:131], v[190:193], v[92:95]
	v_mfma_f32_16x16x32_bf16 v[88:91], v[136:139], v[190:193], v[88:91]
	v_mfma_f32_16x16x32_bf16 v[76:79], v[128:131], v[214:217], v[76:79]
	v_mfma_f32_16x16x32_bf16 v[72:75], v[136:139], v[214:217], v[72:75]
	v_mfma_f32_16x16x32_bf16 v[124:127], v[132:135], v[174:177], v[124:127]
	v_mfma_f32_16x16x32_bf16 v[120:123], v[140:143], v[174:177], v[120:123]
	v_mfma_f32_16x16x32_bf16 v[108:111], v[132:135], v[186:189], v[108:111]
	v_mfma_f32_16x16x32_bf16 v[104:107], v[140:143], v[186:189], v[104:107]
	v_mfma_f32_16x16x32_bf16 v[92:95], v[132:135], v[194:197], v[92:95]
	v_mfma_f32_16x16x32_bf16 v[88:91], v[140:143], v[194:197], v[88:91]
	v_mfma_f32_16x16x32_bf16 v[76:79], v[132:135], v[218:221], v[76:79]
	v_mfma_f32_16x16x32_bf16 v[72:75], v[140:143], v[218:221], v[72:75]
	s_setprio 0
	s_barrier
	s_add_i32 s30, 0, 0x1c000
	s_add_i32 s31, s49, s36
	v_add_u32_e32 v234, s30, v178
	v_lshl_add_u64 v[158:159], v[158:159], 0, s[2:3]
	s_mov_b32 m0, s31
	ds_read_b128 v[222:225], v234
	ds_read_b128 v[226:229], v234 offset:1024
	ds_read_b128 v[230:233], v234 offset:2048
	ds_read_b128 v[234:237], v234 offset:3072
	global_load_lds_dwordx4 v[158:159], off
	v_lshl_add_u64 v[158:159], v[238:239], 0, s[2:3]
	s_add_i32 m0, s31, 0x2000
	s_nop 0
	global_load_lds_dwordx4 v[158:159], off
	s_barrier
	s_waitcnt lgkmcnt(0)
	s_setprio 1
	v_mfma_f32_16x16x32_bf16 v[116:119], v[222:225], v[154:157], v[116:119]
	v_mfma_f32_16x16x32_bf16 v[112:115], v[230:233], v[154:157], v[112:115]
	v_mfma_f32_16x16x32_bf16 v[100:103], v[222:225], v[182:185], v[100:103]
	v_mfma_f32_16x16x32_bf16 v[96:99], v[230:233], v[182:185], v[96:99]
	v_mfma_f32_16x16x32_bf16 v[84:87], v[222:225], v[190:193], v[84:87]
	v_mfma_f32_16x16x32_bf16 v[80:83], v[230:233], v[190:193], v[80:83]
	v_mfma_f32_16x16x32_bf16 v[68:71], v[222:225], v[214:217], v[68:71]
	v_mfma_f32_16x16x32_bf16 v[64:67], v[230:233], v[214:217], v[64:67]
	v_mfma_f32_16x16x32_bf16 v[116:119], v[226:229], v[174:177], v[116:119]
	v_mfma_f32_16x16x32_bf16 v[112:115], v[234:237], v[174:177], v[112:115]
	v_mfma_f32_16x16x32_bf16 v[100:103], v[226:229], v[186:189], v[100:103]
	v_mfma_f32_16x16x32_bf16 v[96:99], v[234:237], v[186:189], v[96:99]
	v_mfma_f32_16x16x32_bf16 v[84:87], v[226:229], v[194:197], v[84:87]
	v_mfma_f32_16x16x32_bf16 v[80:83], v[234:237], v[194:197], v[80:83]
	v_mfma_f32_16x16x32_bf16 v[68:71], v[226:229], v[218:221], v[68:71]
	v_mfma_f32_16x16x32_bf16 v[64:67], v[234:237], v[218:221], v[64:67]
	s_setprio 0
	s_mov_b32 m0, s41
	v_lshl_add_u64 v[158:159], v[240:241], 0, s[2:3]
	s_barrier
	ds_read_b128 v[154:157], v181 offset:49152
	ds_read_b128 v[174:177], v181 offset:50176
	ds_read_b128 v[182:185], v181 offset:51200
	ds_read_b128 v[186:189], v181 offset:52224
	ds_read_b128 v[190:193], v181 offset:53248
	ds_read_b128 v[194:197], v181 offset:54272
	ds_read_b128 v[214:217], v181 offset:55296
	ds_read_b128 v[218:221], v181 offset:56320
	global_load_lds_dwordx4 v[158:159], off
	v_lshl_add_u64 v[158:159], v[242:243], 0, s[2:3]
	s_mov_b32 m0, s42
	s_nop 0
	global_load_lds_dwordx4 v[158:159], off
	s_barrier
; DEV bf16x8 pack8(f32x4 a, f32x4 b) { u32x4 w; w.x = cvt_pk_bf16(a[0], a[1]); w.y = cvt_pk_bf16(a[2], a[3]); w.z = cvt_pk_bf16(b[0], b[1]); w.w = cvt_pk_bf16(b[2], b[3]); return __builtin_bit_cast(bf16x8, w); }
; #define PG8_WAIT_V(n) asm volatile("s_waitcnt vmcnt(" #n ")" ::: "memory")
; template <class Epi>
; DEV void gemm_phase(LAS unsigned char* lds, const Gemm g, const StaticOrder& S, const Epi& E) {
;     ...
;             PG8_BAR; PG8_WAIT_L(0); PG8_MMA(0, 1, At, B1); PG8_BAR;
;             PG8_LDA(At, 1, 1); PG8_STAGE(PG8_SA(1, 0), a3, voffA);
;             PG8_BAR; PG8_WAIT_L(0); PG8_MMA(1, 0, At, B0); PG8_BAR; PG8_SCHED;
;             PG8_STAGE(PG8_SB(1, 1), b3 + hstep, voffB);
;             PG8_WAIT_V(6); PG8_BAR; PG8_MMA(1, 1, At, B1); PG8_BAR;
;     DEV void operator()(AccRef acc, const pg8::Unit& u, int wr, int wc, int fr, int fq) const {
;         const int row0 = u.pm * 256 + wr * 64 + fr, col0 = u.pn * 256 + wc * 32 + 8 * fq;
; #pragma unroll
;         for (int am = 0; am < 4; ++am) { const int ai = am >> 1, m0 = (am & 1) * 2;
;             f32x4 bv[4][2][2];
; #pragma unroll
;             for (int m = m0; m < m0 + 2; ++m)
; #pragma unroll
;                 for (int bj = 0; bj < 2; ++bj)
; #pragma unroll
;                     for (int n = 0; n < 2; ++n) bv[m][bj][n] = *(const f32x4*)(base + (size_t)(row0 + ai * 128 + m * 16) * 2048 + col0 + bj * 128 + n * 4);
; #pragma unroll
;             for (int m = m0; m < m0 + 2; ++m) { const size_t off = (size_t)(row0 + ai * 128 + m * 16) * 2048 + col0; float sq = 0.f;
; #pragma unroll
;                 for (int bj = 0; bj < 2; ++bj) { const f32x4 o0 = bv[m][bj][0] + scale * acc[ai][bj][m][0], o1 = bv[m][bj][1] + scale * acc[ai][bj][m][1];
;                     *(f32x4*)(out + off + bj * 128) = o0; *(f32x4*)(out + off + bj * 128 + 4) = o1;
;                     if (xb) { *(u32x4*)(xb + off + bj * 128) = __builtin_bit_cast(u32x4, pack8(o0, o1));
;                         sq += (o0[0] * o0[0] + o0[1] * o0[1] + o0[2] * o0[2] + o0[3] * o0[3]) + (o1[0] * o1[0] + o1[1] * o1[1] + o1[2] * o1[2] + o1[3] * o1[3]); } }
;                 if (ssout) { sq += __shfl_xor(sq, 16); sq += __shfl_xor(sq, 32);
;                     if (fq == 0) { if (red) red[(ai * 128 + wr * 64 + m * 16 + fr) * 4 + wc] = sq; else atomicAdd(ssout + (size_t)(row0 + ai * 128 + m * 16) * 8 + u.pn, sq); } } }
	s_waitcnt lgkmcnt(0)
	s_setprio 1
	v_mfma_f32_16x16x32_bf16 v[60:63], v[128:131], v[154:157], v[60:63]
	v_mfma_f32_16x16x32_bf16 v[56:59], v[136:139], v[154:157], v[56:59]
	v_mfma_f32_16x16x32_bf16 v[44:47], v[128:131], v[182:185], v[44:47]
	v_mfma_f32_16x16x32_bf16 v[40:43], v[136:139], v[182:185], v[40:43]
	v_mfma_f32_16x16x32_bf16 v[28:31], v[128:131], v[190:193], v[28:31]
	v_mfma_f32_16x16x32_bf16 v[24:27], v[136:139], v[190:193], v[24:27]
	v_mfma_f32_16x16x32_bf16 v[12:15], v[128:131], v[214:217], v[12:15]
	v_mfma_f32_16x16x32_bf16 v[8:11], v[136:139], v[214:217], v[8:11]
	v_mfma_f32_16x16x32_bf16 v[60:63], v[132:135], v[174:177], v[60:63]
	v_mfma_f32_16x16x32_bf16 v[56:59], v[140:143], v[174:177], v[56:59]
	v_mfma_f32_16x16x32_bf16 v[44:47], v[132:135], v[186:189], v[44:47]
	v_mfma_f32_16x16x32_bf16 v[40:43], v[140:143], v[186:189], v[40:43]
	v_mfma_f32_16x16x32_bf16 v[28:31], v[132:135], v[194:197], v[28:31]
	v_mfma_f32_16x16x32_bf16 v[24:27], v[140:143], v[194:197], v[24:27]
	v_mfma_f32_16x16x32_bf16 v[12:15], v[132:135], v[218:221], v[12:15]
	v_mfma_f32_16x16x32_bf16 v[8:11], v[140:143], v[218:221], v[8:11]
	s_setprio 0
	s_barrier
	s_add_u32 s28, s28, 0x100080
	s_addc_u32 s29, s29, 0
	s_add_i32 s30, s30, s36
	v_lshl_add_u64 v[128:129], s[28:29], 0, v[160:161]
	s_mov_b32 m0, s30
	s_nop 0
	global_load_lds_dwordx4 v[128:129], off
	v_lshl_add_u64 v[128:129], s[28:29], 0, v[148:149]
	s_add_i32 m0, s30, 0x2000
	s_nop 0
	global_load_lds_dwordx4 v[128:129], off
	s_waitcnt vmcnt(6)
	s_barrier
	s_setprio 1
	v_mfma_f32_16x16x32_bf16 v[52:55], v[222:225], v[154:157], v[52:55]
	v_mfma_f32_16x16x32_bf16 v[48:51], v[230:233], v[154:157], v[48:51]
	v_mfma_f32_16x16x32_bf16 v[36:39], v[222:225], v[182:185], v[36:39]
	v_mfma_f32_16x16x32_bf16 v[32:35], v[230:233], v[182:185], v[32:35]
	v_mfma_f32_16x16x32_bf16 v[20:23], v[222:225], v[190:193], v[20:23]
	v_mfma_f32_16x16x32_bf16 v[16:19], v[230:233], v[190:193], v[16:19]
	v_mfma_f32_16x16x32_bf16 v[4:7], v[222:225], v[214:217], v[4:7]
	v_mfma_f32_16x16x32_bf16 v[0:3], v[230:233], v[214:217], v[0:3]
	v_mfma_f32_16x16x32_bf16 v[52:55], v[226:229], v[174:177], v[52:55]
	v_mfma_f32_16x16x32_bf16 v[48:51], v[234:237], v[174:177], v[48:51]
	v_mfma_f32_16x16x32_bf16 v[36:39], v[226:229], v[186:189], v[36:39]
	v_mfma_f32_16x16x32_bf16 v[32:35], v[234:237], v[186:189], v[32:35]
	v_mfma_f32_16x16x32_bf16 v[20:23], v[226:229], v[194:197], v[20:23]
	v_mfma_f32_16x16x32_bf16 v[16:19], v[234:237], v[194:197], v[16:19]
	v_mfma_f32_16x16x32_bf16 v[4:7], v[226:229], v[218:221], v[4:7]
	v_mfma_f32_16x16x32_bf16 v[0:3], v[234:237], v[218:221], v[0:3]
	s_setprio 0
	s_add_i32 s48, s48, 2
	s_add_u32 s26, s26, 0x100
	s_addc_u32 s27, s27, 0
	s_add_u32 s46, s46, 0x100
	s_addc_u32 s47, s47, 0
	s_cmp_gt_u32 s48, 61
	s_barrier
	s_cbranch_scc0 .LBB0_404
	v_lshl_add_u32 v156, s24, 8, v167
	v_lshl_or_b32 v154, s14, 8, v179
	v_readlane_b32 s24, v254, 16
	v_ashrrev_i32_e32 v155, 31, v154
	v_readlane_b32 s25, v254, 17
	v_ashrrev_i32_e32 v157, 31, v156
	v_lshlrev_b64 v[128:129], 13, v[156:157]
	v_lshl_add_u64 v[158:159], v[154:155], 2, s[24:25]
	v_lshl_add_u64 v[214:215], v[158:159], 0, v[128:129]
	global_load_dwordx4 v[182:185], v[214:215], off offset:16
	global_load_dwordx4 v[186:189], v[214:215], off
	global_load_dwordx4 v[190:193], v[214:215], off offset:528
	global_load_dwordx4 v[194:197], v[214:215], off offset:512
	v_or_b32_e32 v174, 16, v156
	v_ashrrev_i32_e32 v175, 31, v174
	v_lshlrev_b64 v[128:129], 13, v[174:175]
	v_lshl_add_u64 v[176:177], v[158:159], 0, v[128:129]
	global_load_dwordx4 v[136:139], v[176:177], off offset:16
	global_load_dwordx4 v[140:143], v[176:177], off
	global_load_dwordx4 v[128:131], v[176:177], off offset:528
	global_load_dwordx4 v[132:135], v[176:177], off offset:512
	v_lshlrev_b64 v[216:217], 11, v[156:157]
	v_readlane_b32 s24, v250, 9
	v_lshl_add_u64 v[216:217], v[216:217], 0, v[154:155]
	v_readlane_b32 s25, v250, 10
	v_cmp_lt_i32_e32 vcc, v208, v206
	s_ashr_i32 s15, s14, 31
	s_waitcnt vmcnt(0)
	v_pk_add_f32 v[120:121], v[120:121], v[182:183]
	v_pk_add_f32 v[126:127], v[126:127], v[188:189]
	v_pk_add_f32 v[124:125], v[124:125], v[186:187]
	v_pk_add_f32 v[122:123], v[122:123], v[184:185]
	global_store_dwordx4 v[214:215], v[124:127], off
	global_store_dwordx4 v[214:215], v[120:123], off offset:16
	v_cvt_pk_bf16_f32 v184, v120, v121
	v_cvt_pk_bf16_f32 v182, v124, v125
	v_mul_f32_e32 v121, v121, v121
	v_cvt_pk_bf16_f32 v183, v126, v127
	v_cvt_pk_bf16_f32 v185, v122, v123
	v_lshl_add_u64 v[186:187], v[216:217], 1, s[24:25]
	v_fmac_f32_e32 v121, v120, v120
	v_pk_add_f32 v[118:119], v[118:119], v[196:197]
	v_pk_add_f32 v[116:117], v[116:117], v[194:195]
	v_pk_add_f32 v[112:113], v[112:113], v[190:191]
	global_store_dwordx4 v[186:187], v[182:185], off
	v_mul_f32_e32 v125, v125, v125
	v_fmac_f32_e32 v121, v122, v122
	v_pk_add_f32 v[114:115], v[114:115], v[192:193]
	global_store_dwordx4 v[214:215], v[116:119], off offset:512
	global_store_dwordx4 v[214:215], v[112:115], off offset:528
	v_cvt_pk_bf16_f32 v120, v116, v117
	v_cvt_pk_bf16_f32 v122, v112, v113
	v_mul_f32_e32 v117, v117, v117
	v_mul_f32_e32 v113, v113, v113
	v_fmac_f32_e32 v125, v124, v124
	v_fmac_f32_e32 v117, v116, v116
	v_fmac_f32_e32 v113, v112, v112
	v_fmac_f32_e32 v125, v126, v126
	v_fmac_f32_e32 v117, v118, v118
	v_fmac_f32_e32 v113, v114, v114
	v_fmac_f32_e32 v125, v127, v127
	v_fmac_f32_e32 v121, v123, v123
	v_fmac_f32_e32 v117, v119, v119
	v_fmac_f32_e32 v113, v115, v115
	v_add_f32_e32 v124, v125, v121
	v_add_f32_e32 v112, v117, v113
	v_cndmask_b32_e32 v113, v204, v208, vcc
	v_cvt_pk_bf16_f32 v121, v118, v119
	v_add_f32_e32 v112, v124, v112
	v_lshlrev_b32_e32 v118, 2, v113
	ds_bpermute_b32 v113, v118, v112
	v_cmp_lt_i32_e32 vcc, v207, v206
	v_cvt_pk_bf16_f32 v123, v114, v115
	global_store_dwordx4 v[186:187], v[120:123], off offset:256
	s_waitcnt lgkmcnt(0)
	v_add_f32_e32 v112, v112, v113
	v_cndmask_b32_e32 v113, v204, v207, vcc
	v_lshlrev_b32_e32 v119, 2, v113
	ds_bpermute_b32 v113, v119, v112
	s_and_saveexec_b64 s[24:25], s[6:7]
	s_cbranch_execz .LBB0_410
	s_waitcnt lgkmcnt(0)
	v_add_f32_e32 v112, v112, v113
	s_mov_b64 s[26:27], -1
	s_and_b64 vcc, exec, s[12:13]
	s_cbranch_vccz .LBB0_408
	v_readlane_b32 s26, v250, 59
	v_lshlrev_b64 v[114:115], 5, v[156:157]
	v_readlane_b32 s27, v250, 60
	s_nop 1
	v_lshl_add_u64 v[114:115], s[26:27], 0, v[114:115]
	v_lshl_add_u64 v[114:115], s[14:15], 2, v[114:115]
	global_atomic_add_f32 v[114:115], v112, off
	s_mov_b64 s[26:27], 0

; #define PG8_STAGE(bufoff, gbase, voff) do { _Pragma("unroll") for (int _i = 0; _i < 2; ++_i) \
;         __builtin_amdgcn_global_load_lds((const unsigned*)((const char*)(gbase) + (voff)[_i]), (LAS unsigned*)(lds + (bufoff) + ldsw + _i * 8192), 16, 0, 0); } while (0)
; #define PG8_LDA(dst, b, h) do { _Pragma("unroll") for (int m = 0; m < 4; ++m) _Pragma("unroll") for (int k = 0; k < 2; ++k) dst[m][k] = *(const LAS bf16x8*)(lds + PG8_SA(b, h) + aoff + m * 2048 + k * 1024); } while (0)
; #define PG8_LDB(dst, b, h) do { _Pragma("unroll") for (int n = 0; n < 2; ++n) _Pragma("unroll") for (int k = 0; k < 2; ++k) dst[n][k] = *(const LAS bf16x8*)(lds + PG8_SB(b, h) + boff + n * 2048 + k * 1024); } while (0)
; #define PG8_MMA(ai, bj, At, Bt) do { __builtin_amdgcn_s_setprio(1); _Pragma("unroll") for (int m = 0; m < 4; ++m) _Pragma("unroll") for (int n = 0; n < 2; ++n) _Pragma("unroll") for (int k = 0; k < 2; ++k) \
;         acc[ai][bj][m][n] = __builtin_amdgcn_mfma_f32_16x16x32_bf16(Bt[n][k], At[m][k], acc[ai][bj][m][n], 0, 0, 0); __builtin_amdgcn_s_setprio(0); } while (0)
; #define PG8_WAIT_L(n) asm volatile("s_waitcnt lgkmcnt(" #n ")" ::: "memory")
; #define PG8_BAR __builtin_amdgcn_s_barrier()
; #define PG8_SCHED __builtin_amdgcn_sched_barrier(0)
; template <class Epi>
; DEV void gemm_phase(LAS unsigned char* lds, const Gemm g, const StaticOrder& S, const Epi& E) {
;     ...
;             PG8_LDB(B0, 0, 0); PG8_SCHED; PG8_LDA(At, 0, 0); PG8_STAGE(PG8_SA(1, 1), a1 + hstep, voffA);
;             PG8_WAIT_L(8); PG8_BAR; PG8_WAIT_L(0); PG8_MMA(0, 0, At, B0); PG8_BAR; PG8_SCHED;
;             PG8_LDB(B1, 0, 1); PG8_STAGE(PG8_SB(0, 0), b2, voffB);
;             PG8_BAR; PG8_WAIT_L(0); PG8_MMA(0, 1, At, B1); PG8_BAR;
;             PG8_LDA(At, 0, 1); PG8_STAGE(PG8_SA(0, 0), a2, voffA);
;             PG8_BAR; PG8_WAIT_L(0); PG8_MMA(1, 0, At, B0); PG8_BAR; PG8_SCHED;
.LBB0_588:
	s_add_u32 s16, s14, 0xfff80080
	s_addc_u32 s17, s15, -1
	s_add_i32 s41, 0, 0x10000
	v_add_u32_e32 v154, s41, v167
	ds_read_b128 v[128:131], v154
	ds_read_b128 v[132:135], v154 offset:1024
	ds_read_b128 v[150:153], v154 offset:2048
	ds_read_b128 v[174:177], v154 offset:3072
	s_cmp_eq_u32 s40, 28
	s_cselect_b32 s19, s1, s17
	s_cselect_b32 s18, s9, s16
	s_cselect_b32 s17, s7, s37
	s_cselect_b32 s16, s35, s36
	v_lshl_add_u64 v[154:155], s[14:15], 0, v[146:147]
	s_add_i32 m0, s24, 0xc000
	ds_read_b128 v[182:185], v219
	ds_read_b128 v[190:193], v219 offset:1024
	ds_read_b128 v[194:197], v219 offset:2048
	ds_read_b128 v[220:223], v219 offset:3072
	ds_read_b128 v[224:227], v219 offset:4096
	ds_read_b128 v[228:231], v219 offset:5120
	ds_read_b128 v[232:235], v219 offset:6144
	ds_read_b128 v[236:239], v219 offset:7168
	global_load_lds_dwordx4 v[154:155], off
	v_lshl_add_u64 v[154:155], s[14:15], 0, v[148:149]
	s_add_i32 m0, s24, 0xe000
	s_nop 0
	global_load_lds_dwordx4 v[154:155], off
	s_waitcnt lgkmcnt(8)
	s_barrier
	s_waitcnt lgkmcnt(0)
	s_setprio 1
	v_mfma_f32_16x16x32_bf16 v[124:127], v[128:131], v[182:185], v[124:127]
	v_mfma_f32_16x16x32_bf16 v[120:123], v[150:153], v[182:185], v[120:123]
	v_mfma_f32_16x16x32_bf16 v[108:111], v[128:131], v[194:197], v[108:111]
	v_mfma_f32_16x16x32_bf16 v[104:107], v[150:153], v[194:197], v[104:107]
	v_mfma_f32_16x16x32_bf16 v[92:95], v[128:131], v[224:227], v[92:95]
	v_mfma_f32_16x16x32_bf16 v[88:91], v[150:153], v[224:227], v[88:91]
	v_mfma_f32_16x16x32_bf16 v[76:79], v[128:131], v[232:235], v[76:79]
	v_mfma_f32_16x16x32_bf16 v[72:75], v[150:153], v[232:235], v[72:75]
	v_mfma_f32_16x16x32_bf16 v[124:127], v[132:135], v[190:193], v[124:127]
	v_mfma_f32_16x16x32_bf16 v[120:123], v[174:177], v[190:193], v[120:123]
	v_mfma_f32_16x16x32_bf16 v[108:111], v[132:135], v[220:223], v[108:111]
	v_mfma_f32_16x16x32_bf16 v[104:107], v[174:177], v[220:223], v[104:107]
	v_mfma_f32_16x16x32_bf16 v[92:95], v[132:135], v[228:231], v[92:95]
	v_mfma_f32_16x16x32_bf16 v[88:91], v[174:177], v[228:231], v[88:91]
	v_mfma_f32_16x16x32_bf16 v[76:79], v[132:135], v[236:239], v[76:79]
	v_mfma_f32_16x16x32_bf16 v[72:75], v[174:177], v[236:239], v[72:75]
	s_setprio 0
	s_barrier
	s_add_i32 s44, 0, 0x14000
	v_add_u32_e32 v154, s44, v167
	s_add_i32 s41, s41, s22
	ds_read_b128 v[240:243], v154
	ds_read_b128 v[244:247], v154 offset:1024
	ds_read_b128 v[186:189], v154 offset:2048
	ds_read_b128 v[214:217], v154 offset:3072
	v_lshl_add_u64 v[154:155], s[16:17], 0, v[140:141]
	s_mov_b32 m0, s41
	v_lshl_add_u64 v[158:159], s[16:17], 0, v[136:137]
	global_load_lds_dwordx4 v[154:155], off
	s_add_i32 m0, s41, 0x2000
	s_nop 0
	global_load_lds_dwordx4 v[158:159], off
	s_barrier
	s_waitcnt lgkmcnt(0)
	s_setprio 1
	v_mfma_f32_16x16x32_bf16 v[116:119], v[240:243], v[182:185], v[116:119]
	v_mfma_f32_16x16x32_bf16 v[112:115], v[186:189], v[182:185], v[112:115]
	v_mfma_f32_16x16x32_bf16 v[100:103], v[240:243], v[194:197], v[100:103]
	v_mfma_f32_16x16x32_bf16 v[96:99], v[186:189], v[194:197], v[96:99]
	v_mfma_f32_16x16x32_bf16 v[84:87], v[240:243], v[224:227], v[84:87]
	v_mfma_f32_16x16x32_bf16 v[80:83], v[186:189], v[224:227], v[80:83]
	v_mfma_f32_16x16x32_bf16 v[68:71], v[240:243], v[232:235], v[68:71]
	v_mfma_f32_16x16x32_bf16 v[64:67], v[186:189], v[232:235], v[64:67]
	v_mfma_f32_16x16x32_bf16 v[116:119], v[244:247], v[190:193], v[116:119]
	v_mfma_f32_16x16x32_bf16 v[112:115], v[214:217], v[190:193], v[112:115]
	v_mfma_f32_16x16x32_bf16 v[100:103], v[244:247], v[220:223], v[100:103]
	v_mfma_f32_16x16x32_bf16 v[96:99], v[214:217], v[220:223], v[96:99]
	v_mfma_f32_16x16x32_bf16 v[84:87], v[244:247], v[228:231], v[84:87]
	v_mfma_f32_16x16x32_bf16 v[80:83], v[214:217], v[228:231], v[80:83]
	v_mfma_f32_16x16x32_bf16 v[68:71], v[244:247], v[236:239], v[68:71]
	v_mfma_f32_16x16x32_bf16 v[64:67], v[214:217], v[236:239], v[64:67]
	s_setprio 0
	s_mov_b32 m0, s24
	v_lshl_add_u64 v[178:179], s[18:19], 0, v[142:143]
	s_barrier
	ds_read_b128 v[182:185], v219 offset:16384
	ds_read_b128 v[190:193], v219 offset:17408
	ds_read_b128 v[194:197], v219 offset:18432
	ds_read_b128 v[220:223], v219 offset:19456
	ds_read_b128 v[224:227], v219 offset:20480
	ds_read_b128 v[228:231], v219 offset:21504
	ds_read_b128 v[232:235], v219 offset:22528
	ds_read_b128 v[236:239], v219 offset:23552
	global_load_lds_dwordx4 v[178:179], off
	v_lshl_add_u64 v[248:249], s[18:19], 0, v[138:139]
	s_mov_b32 m0, s25
	s_nop 0
	global_load_lds_dwordx4 v[248:249], off
	s_barrier
	s_waitcnt lgkmcnt(0)
	s_setprio 1
	v_mfma_f32_16x16x32_bf16 v[60:63], v[128:131], v[182:185], v[60:63]
	v_mfma_f32_16x16x32_bf16 v[56:59], v[150:153], v[182:185], v[56:59]
	v_mfma_f32_16x16x32_bf16 v[44:47], v[128:131], v[194:197], v[44:47]
	v_mfma_f32_16x16x32_bf16 v[40:43], v[150:153], v[194:197], v[40:43]
	v_mfma_f32_16x16x32_bf16 v[28:31], v[128:131], v[224:227], v[28:31]
	v_mfma_f32_16x16x32_bf16 v[24:27], v[150:153], v[224:227], v[24:27]
	v_mfma_f32_16x16x32_bf16 v[12:15], v[128:131], v[232:235], v[12:15]
	v_mfma_f32_16x16x32_bf16 v[8:11], v[150:153], v[232:235], v[8:11]
	v_mfma_f32_16x16x32_bf16 v[60:63], v[132:135], v[190:193], v[60:63]
	v_mfma_f32_16x16x32_bf16 v[56:59], v[174:177], v[190:193], v[56:59]
	v_mfma_f32_16x16x32_bf16 v[44:47], v[132:135], v[220:223], v[44:47]
	v_mfma_f32_16x16x32_bf16 v[40:43], v[174:177], v[220:223], v[40:43]
	v_mfma_f32_16x16x32_bf16 v[28:31], v[132:135], v[228:231], v[28:31]
	v_mfma_f32_16x16x32_bf16 v[24:27], v[174:177], v[228:231], v[24:27]
	v_mfma_f32_16x16x32_bf16 v[12:15], v[132:135], v[236:239], v[12:15]
	v_mfma_f32_16x16x32_bf16 v[8:11], v[174:177], v[236:239], v[8:11]
	s_setprio 0
	s_barrier
; #define PG8_STAGE(bufoff, gbase, voff) do { _Pragma("unroll") for (int _i = 0; _i < 2; ++_i) \
;         __builtin_amdgcn_global_load_lds((const unsigned*)((const char*)(gbase) + (voff)[_i]), (LAS unsigned*)(lds + (bufoff) + ldsw + _i * 8192), 16, 0, 0); } while (0)
; #define PG8_LDA(dst, b, h) do { _Pragma("unroll") for (int m = 0; m < 4; ++m) _Pragma("unroll") for (int k = 0; k < 2; ++k) dst[m][k] = *(const LAS bf16x8*)(lds + PG8_SA(b, h) + aoff + m * 2048 + k * 1024); } while (0)
; #define PG8_LDB(dst, b, h) do { _Pragma("unroll") for (int n = 0; n < 2; ++n) _Pragma("unroll") for (int k = 0; k < 2; ++k) dst[n][k] = *(const LAS bf16x8*)(lds + PG8_SB(b, h) + boff + n * 2048 + k * 1024); } while (0)
; #define PG8_MMA(ai, bj, At, Bt) do { __builtin_amdgcn_s_setprio(1); _Pragma("unroll") for (int m = 0; m < 4; ++m) _Pragma("unroll") for (int n = 0; n < 2; ++n) _Pragma("unroll") for (int k = 0; k < 2; ++k) \
;         acc[ai][bj][m][n] = __builtin_amdgcn_mfma_f32_16x16x32_bf16(Bt[n][k], At[m][k], acc[ai][bj][m][n], 0, 0, 0); __builtin_amdgcn_s_setprio(0); } while (0)
; #define PG8_WAIT_V(n) asm volatile("s_waitcnt vmcnt(" #n ")" ::: "memory")
; #define PG8_WAIT_L(n) asm volatile("s_waitcnt lgkmcnt(" #n ")" ::: "memory")
; #define PG8_BAR __builtin_amdgcn_s_barrier()
; #define PG8_SCHED __builtin_amdgcn_sched_barrier(0)
; template <class Epi>
; DEV void gemm_phase(LAS unsigned char* lds, const Gemm g, const StaticOrder& S, const Epi& E) {
;     ...
;             PG8_STAGE(PG8_SB(0, 1), b2 + hstep, voffB);
;             PG8_WAIT_V(6); PG8_BAR; PG8_MMA(1, 1, At, B1); PG8_BAR;
;             PG8_LDB(B0, 1, 0); PG8_SCHED; PG8_LDA(At, 1, 0); PG8_STAGE(PG8_SA(0, 1), a2 + hstep, voffA);
;             PG8_WAIT_L(8); PG8_BAR; PG8_WAIT_L(0); PG8_MMA(0, 0, At, B0); PG8_BAR; PG8_SCHED;
;             PG8_LDB(B1, 1, 1); PG8_STAGE(PG8_SB(1, 0), b3, voffB);
;             PG8_BAR; PG8_WAIT_L(0); PG8_MMA(0, 1, At, B1); PG8_BAR;
;             PG8_LDA(At, 1, 1); PG8_STAGE(PG8_SA(1, 0), a3, voffA);
	s_add_u32 s42, s16, 0x80000
	s_addc_u32 s43, s17, 0
	s_add_i32 s41, s44, s22
	v_lshl_add_u64 v[128:129], s[42:43], 0, v[140:141]
	s_mov_b32 m0, s41
	s_nop 0
	global_load_lds_dwordx4 v[128:129], off
	v_lshl_add_u64 v[128:129], s[42:43], 0, v[136:137]
	s_add_i32 m0, s41, 0x2000
	s_nop 0
	global_load_lds_dwordx4 v[128:129], off
	s_waitcnt vmcnt(6)
	s_barrier
	s_setprio 1
	v_mfma_f32_16x16x32_bf16 v[52:55], v[240:243], v[182:185], v[52:55]
	v_mfma_f32_16x16x32_bf16 v[48:51], v[186:189], v[182:185], v[48:51]
	v_mfma_f32_16x16x32_bf16 v[36:39], v[240:243], v[194:197], v[36:39]
	v_mfma_f32_16x16x32_bf16 v[32:35], v[186:189], v[194:197], v[32:35]
	v_mfma_f32_16x16x32_bf16 v[20:23], v[240:243], v[224:227], v[20:23]
	v_mfma_f32_16x16x32_bf16 v[16:19], v[186:189], v[224:227], v[16:19]
	v_mfma_f32_16x16x32_bf16 v[4:7], v[240:243], v[232:235], v[4:7]
	v_mfma_f32_16x16x32_bf16 v[0:3], v[186:189], v[232:235], v[0:3]
	v_mfma_f32_16x16x32_bf16 v[52:55], v[244:247], v[190:193], v[52:55]
	v_mfma_f32_16x16x32_bf16 v[48:51], v[214:217], v[190:193], v[48:51]
	v_mfma_f32_16x16x32_bf16 v[36:39], v[244:247], v[220:223], v[36:39]
	v_mfma_f32_16x16x32_bf16 v[32:35], v[214:217], v[220:223], v[32:35]
	v_mfma_f32_16x16x32_bf16 v[20:23], v[244:247], v[228:231], v[20:23]
	v_mfma_f32_16x16x32_bf16 v[16:19], v[214:217], v[228:231], v[16:19]
	v_mfma_f32_16x16x32_bf16 v[4:7], v[244:247], v[236:239], v[4:7]
	v_mfma_f32_16x16x32_bf16 v[0:3], v[214:217], v[236:239], v[0:3]
	s_setprio 0
	s_add_i32 s41, 0, 0x18000
	v_add_u32_e32 v156, s41, v167
	s_barrier
	ds_read_b128 v[128:131], v156
	ds_read_b128 v[132:135], v156 offset:1024
	ds_read_b128 v[150:153], v156 offset:2048
	ds_read_b128 v[174:177], v156 offset:3072
	s_add_u32 s18, s18, 0x80000
	s_addc_u32 s19, s19, 0
	s_mov_b32 m0, s26
	v_lshl_add_u64 v[232:233], s[18:19], 0, v[142:143]
	ds_read_b128 v[182:185], v219 offset:32768
	ds_read_b128 v[186:189], v219 offset:33792
	ds_read_b128 v[190:193], v219 offset:34816
	ds_read_b128 v[194:197], v219 offset:35840
	ds_read_b128 v[214:217], v219 offset:36864
	ds_read_b128 v[220:223], v219 offset:37888
	ds_read_b128 v[224:227], v219 offset:38912
	ds_read_b128 v[228:231], v219 offset:39936
	global_load_lds_dwordx4 v[232:233], off
	v_lshl_add_u64 v[232:233], s[18:19], 0, v[138:139]
	s_mov_b32 m0, s27
	s_nop 0
	global_load_lds_dwordx4 v[232:233], off
	s_waitcnt lgkmcnt(8)
	s_barrier
	s_waitcnt lgkmcnt(0)
	s_setprio 1
	v_mfma_f32_16x16x32_bf16 v[124:127], v[128:131], v[182:185], v[124:127]
	v_mfma_f32_16x16x32_bf16 v[120:123], v[150:153], v[182:185], v[120:123]
	v_mfma_f32_16x16x32_bf16 v[108:111], v[128:131], v[190:193], v[108:111]
	v_mfma_f32_16x16x32_bf16 v[104:107], v[150:153], v[190:193], v[104:107]
	v_mfma_f32_16x16x32_bf16 v[92:95], v[128:131], v[214:217], v[92:95]
	v_mfma_f32_16x16x32_bf16 v[88:91], v[150:153], v[214:217], v[88:91]
	v_mfma_f32_16x16x32_bf16 v[76:79], v[128:131], v[224:227], v[76:79]
	v_mfma_f32_16x16x32_bf16 v[72:75], v[150:153], v[224:227], v[72:75]
	v_mfma_f32_16x16x32_bf16 v[124:127], v[132:135], v[186:189], v[124:127]
	v_mfma_f32_16x16x32_bf16 v[120:123], v[174:177], v[186:189], v[120:123]
	v_mfma_f32_16x16x32_bf16 v[108:111], v[132:135], v[194:197], v[108:111]
	v_mfma_f32_16x16x32_bf16 v[104:107], v[174:177], v[194:197], v[104:107]
	v_mfma_f32_16x16x32_bf16 v[92:95], v[132:135], v[220:223], v[92:95]
	v_mfma_f32_16x16x32_bf16 v[88:91], v[174:177], v[220:223], v[88:91]
	v_mfma_f32_16x16x32_bf16 v[76:79], v[132:135], v[228:231], v[76:79]
	v_mfma_f32_16x16x32_bf16 v[72:75], v[174:177], v[228:231], v[72:75]
	s_setprio 0
	s_barrier
	s_add_i32 s18, 0, 0x1c000
	s_add_i32 s19, s41, s22
	v_add_u32_e32 v156, s18, v167
	v_lshl_add_u64 v[154:155], v[154:155], 0, s[2:3]
	s_mov_b32 m0, s19
	ds_read_b128 v[232:235], v156
	ds_read_b128 v[236:239], v156 offset:1024
	ds_read_b128 v[240:243], v156 offset:2048
	ds_read_b128 v[244:247], v156 offset:3072
	global_load_lds_dwordx4 v[154:155], off
	v_lshl_add_u64 v[154:155], v[158:159], 0, s[2:3]
	s_add_i32 m0, s19, 0x2000
	s_nop 0
	global_load_lds_dwordx4 v[154:155], off
	s_barrier
	s_waitcnt lgkmcnt(0)
	s_setprio 1
	v_mfma_f32_16x16x32_bf16 v[116:119], v[232:235], v[182:185], v[116:119]
	v_mfma_f32_16x16x32_bf16 v[112:115], v[240:243], v[182:185], v[112:115]
	v_mfma_f32_16x16x32_bf16 v[100:103], v[232:235], v[190:193], v[100:103]
	v_mfma_f32_16x16x32_bf16 v[96:99], v[240:243], v[190:193], v[96:99]
	v_mfma_f32_16x16x32_bf16 v[84:87], v[232:235], v[214:217], v[84:87]
	v_mfma_f32_16x16x32_bf16 v[80:83], v[240:243], v[214:217], v[80:83]
	v_mfma_f32_16x16x32_bf16 v[68:71], v[232:235], v[224:227], v[68:71]
	v_mfma_f32_16x16x32_bf16 v[64:67], v[240:243], v[224:227], v[64:67]
	v_mfma_f32_16x16x32_bf16 v[116:119], v[236:239], v[186:189], v[116:119]
	v_mfma_f32_16x16x32_bf16 v[112:115], v[244:247], v[186:189], v[112:115]
	v_mfma_f32_16x16x32_bf16 v[100:103], v[236:239], v[194:197], v[100:103]
	v_mfma_f32_16x16x32_bf16 v[96:99], v[244:247], v[194:197], v[96:99]
	v_mfma_f32_16x16x32_bf16 v[84:87], v[236:239], v[220:223], v[84:87]
	v_mfma_f32_16x16x32_bf16 v[80:83], v[244:247], v[220:223], v[80:83]
	v_mfma_f32_16x16x32_bf16 v[68:71], v[236:239], v[228:231], v[68:71]
	v_mfma_f32_16x16x32_bf16 v[64:67], v[244:247], v[228:231], v[64:67]
	s_setprio 0
	s_mov_b32 m0, s28
	v_lshl_add_u64 v[154:155], v[178:179], 0, s[2:3]
	s_barrier
	ds_read_b128 v[182:185], v219 offset:49152
	ds_read_b128 v[186:189], v219 offset:50176
	ds_read_b128 v[190:193], v219 offset:51200
	ds_read_b128 v[194:197], v219 offset:52224
	ds_read_b128 v[214:217], v219 offset:53248
	ds_read_b128 v[220:223], v219 offset:54272
	ds_read_b128 v[224:227], v219 offset:55296
	ds_read_b128 v[228:231], v219 offset:56320
	global_load_lds_dwordx4 v[154:155], off
	v_lshl_add_u64 v[154:155], v[248:249], 0, s[2:3]
	s_mov_b32 m0, s29
	s_nop 0
	global_load_lds_dwordx4 v[154:155], off
	s_barrier
; #define PG8_STAGE(bufoff, gbase, voff) do { _Pragma("unroll") for (int _i = 0; _i < 2; ++_i) \
;         __builtin_amdgcn_global_load_lds((const unsigned*)((const char*)(gbase) + (voff)[_i]), (LAS unsigned*)(lds + (bufoff) + ldsw + _i * 8192), 16, 0, 0); } while (0)
; #define PG8_MMA(ai, bj, At, Bt) do { __builtin_amdgcn_s_setprio(1); _Pragma("unroll") for (int m = 0; m < 4; ++m) _Pragma("unroll") for (int n = 0; n < 2; ++n) _Pragma("unroll") for (int k = 0; k < 2; ++k) \
;         acc[ai][bj][m][n] = __builtin_amdgcn_mfma_f32_16x16x32_bf16(Bt[n][k], At[m][k], acc[ai][bj][m][n], 0, 0, 0); __builtin_amdgcn_s_setprio(0); } while (0)
; #define PG8_WAIT_V(n) asm volatile("s_waitcnt vmcnt(" #n ")" ::: "memory")
; #define PG8_WAIT_L(n) asm volatile("s_waitcnt lgkmcnt(" #n ")" ::: "memory")
; #define PG8_BAR __builtin_amdgcn_s_barrier()
; #define PG8_SCHED __builtin_amdgcn_sched_barrier(0)
; template <class Epi>
; DEV void gemm_phase(LAS unsigned char* lds, const Gemm g, const StaticOrder& S, const Epi& E) {
;     ...
;             PG8_BAR; PG8_WAIT_L(0); PG8_MMA(1, 0, At, B0); PG8_BAR; PG8_SCHED;
;             PG8_STAGE(PG8_SB(1, 1), b3 + hstep, voffB);
;             PG8_WAIT_V(6); PG8_BAR; PG8_MMA(1, 1, At, B1); PG8_BAR;
;     DEV void operator()(AccRef acc, const pg8::Unit& u, int wr, int wc, int fr, int fq) const {
;     ...
;         else if (wc == 0) {
; #pragma unroll
;             for (int ai = 0; ai < 2; ++ai)
; #pragma unroll
;                 for (int m = 0; m < 4; ++m) { const float rs = rowscale(ss, row0 + ai * 128 + m * 16);
; #pragma unroll
;                     for (int n = 0; n < 2; ++n) *(f32x4*)(DTR + (size_t)(row0 + ai * 128 + m * 16) * 32 + 8 * fq + 4 * n) = acc[ai][0][m][n] * rs; }
	s_waitcnt lgkmcnt(0)
	s_setprio 1
	v_mfma_f32_16x16x32_bf16 v[60:63], v[128:131], v[182:185], v[60:63]
	v_mfma_f32_16x16x32_bf16 v[56:59], v[150:153], v[182:185], v[56:59]
	v_mfma_f32_16x16x32_bf16 v[44:47], v[128:131], v[190:193], v[44:47]
	v_mfma_f32_16x16x32_bf16 v[40:43], v[150:153], v[190:193], v[40:43]
	v_mfma_f32_16x16x32_bf16 v[28:31], v[128:131], v[214:217], v[28:31]
	v_mfma_f32_16x16x32_bf16 v[24:27], v[150:153], v[214:217], v[24:27]
	v_mfma_f32_16x16x32_bf16 v[12:15], v[128:131], v[224:227], v[12:15]
	v_mfma_f32_16x16x32_bf16 v[8:11], v[150:153], v[224:227], v[8:11]
	v_mfma_f32_16x16x32_bf16 v[60:63], v[132:135], v[186:189], v[60:63]
	v_mfma_f32_16x16x32_bf16 v[56:59], v[174:177], v[186:189], v[56:59]
	v_mfma_f32_16x16x32_bf16 v[44:47], v[132:135], v[194:197], v[44:47]
	v_mfma_f32_16x16x32_bf16 v[40:43], v[174:177], v[194:197], v[40:43]
	v_mfma_f32_16x16x32_bf16 v[28:31], v[132:135], v[220:223], v[28:31]
	v_mfma_f32_16x16x32_bf16 v[24:27], v[174:177], v[220:223], v[24:27]
	v_mfma_f32_16x16x32_bf16 v[12:15], v[132:135], v[228:231], v[12:15]
	v_mfma_f32_16x16x32_bf16 v[8:11], v[174:177], v[228:231], v[8:11]
	s_setprio 0
	s_barrier
	s_add_u32 s16, s16, 0x80080
	s_addc_u32 s17, s17, 0
	s_add_i32 s18, s18, s22
	v_lshl_add_u64 v[128:129], s[16:17], 0, v[140:141]
	s_mov_b32 m0, s18
	s_nop 0
	global_load_lds_dwordx4 v[128:129], off
	v_lshl_add_u64 v[128:129], s[16:17], 0, v[136:137]
	s_add_i32 m0, s18, 0x2000
	s_nop 0
	global_load_lds_dwordx4 v[128:129], off
	s_waitcnt vmcnt(6)
	s_barrier
	s_setprio 1
	v_mfma_f32_16x16x32_bf16 v[52:55], v[232:235], v[182:185], v[52:55]
	v_mfma_f32_16x16x32_bf16 v[48:51], v[240:243], v[182:185], v[48:51]
	v_mfma_f32_16x16x32_bf16 v[36:39], v[232:235], v[190:193], v[36:39]
	v_mfma_f32_16x16x32_bf16 v[32:35], v[240:243], v[190:193], v[32:35]
	v_mfma_f32_16x16x32_bf16 v[20:23], v[232:235], v[214:217], v[20:23]
	v_mfma_f32_16x16x32_bf16 v[16:19], v[240:243], v[214:217], v[16:19]
	v_mfma_f32_16x16x32_bf16 v[4:7], v[232:235], v[224:227], v[4:7]
	v_mfma_f32_16x16x32_bf16 v[0:3], v[240:243], v[224:227], v[0:3]
	v_mfma_f32_16x16x32_bf16 v[52:55], v[236:239], v[186:189], v[52:55]
	v_mfma_f32_16x16x32_bf16 v[48:51], v[244:247], v[186:189], v[48:51]
	v_mfma_f32_16x16x32_bf16 v[36:39], v[236:239], v[194:197], v[36:39]
	v_mfma_f32_16x16x32_bf16 v[32:35], v[244:247], v[194:197], v[32:35]
	v_mfma_f32_16x16x32_bf16 v[20:23], v[236:239], v[220:223], v[20:23]
	v_mfma_f32_16x16x32_bf16 v[16:19], v[244:247], v[220:223], v[16:19]
	v_mfma_f32_16x16x32_bf16 v[4:7], v[236:239], v[228:231], v[4:7]
	v_mfma_f32_16x16x32_bf16 v[0:3], v[244:247], v[228:231], v[0:3]
	s_setprio 0
	s_add_i32 s40, s40, 2
	s_add_u32 s14, s14, 0x100
	s_addc_u32 s15, s15, 0
	s_add_u32 s36, s36, 0x100
	s_addc_u32 s37, s37, 0
	s_cmp_gt_u32 s40, 29
	s_barrier
	s_cbranch_scc0 .LBB0_588
	s_lshl_b32 s7, s34, 8
	v_lshl_add_u32 v150, s0, 8, v157
	s_cmp_gt_i32 s34, 15
	s_mov_b64 s[0:1], -1
	s_cbranch_scc0 .LBB0_601
	s_cmp_gt_u32 s34, 23
	s_cbranch_scc0 .LBB0_598
	s_cmp_gt_u32 s34, 35
	s_cbranch_scc0 .LBB0_595
	s_andn2_b64 vcc, exec, s[4:5]
	s_cbranch_vccnz .LBB0_594
	v_ashrrev_i32_e32 v151, 31, v150
	v_readlane_b32 s0, v251, 39
	v_lshlrev_b64 v[128:129], 5, v[150:151]
	v_readlane_b32 s1, v251, 40
	s_mov_b32 s9, 0x800000
	s_nop 0
	v_lshl_add_u64 v[132:133], s[0:1], 0, v[128:129]
	global_load_dwordx4 v[128:131], v[132:133], off offset:16
	s_nop 0
	global_load_dwordx4 v[132:135], v[132:133], off
	s_waitcnt vmcnt(0)
	v_mov_b32_e32 v152, v133
	v_mov_b32_e32 v153, v134
	v_mov_b32_e32 v133, v135
	v_pk_add_f32 v[132:133], v[152:153], v[132:133]
	v_mov_b32_e32 v134, v130
	v_mov_b32_e32 v135, v128
	v_mov_b32_e32 v128, v131
	v_pk_add_f32 v[128:129], v[134:135], v[128:129]
	v_add_f32_e32 v130, v132, v133
	v_add_f32_e32 v129, v130, v129
	v_add_f32_e32 v128, v128, v129
	v_fmamk_f32 v128, v128, 0x3a000000, v199
	v_cmp_gt_f32_e32 vcc, s9, v128
	v_mul_f32_e32 v129, 0x4b800000, v128
	v_lshlrev_b64 v[134:135], 7, v[150:151]
	v_cndmask_b32_e32 v128, v128, v129, vcc
	v_rsq_f32_e32 v128, v128
	v_lshl_add_u64 v[134:135], v[144:145], 0, v[134:135]
	v_or_b32_e32 v152, 16, v150
	v_ashrrev_i32_e32 v153, 31, v152
	v_mul_f32_e32 v129, 0x45800000, v128
	v_cndmask_b32_e32 v132, v128, v129, vcc
	v_pk_mul_f32 v[130:131], v[126:127], v[132:133] op_sel_hi:[1,0]
	v_pk_mul_f32 v[128:129], v[124:125], v[132:133] op_sel_hi:[1,0]
	global_store_dwordx4 v[134:135], v[128:131], off
	s_nop 1
	v_pk_mul_f32 v[130:131], v[122:123], v[132:133] op_sel_hi:[1,0]
	v_pk_mul_f32 v[128:129], v[120:121], v[132:133] op_sel_hi:[1,0]
	global_store_dwordx4 v[134:135], v[128:131], off offset:16
	s_nop 1
	v_lshlrev_b64 v[128:129], 5, v[152:153]
	v_lshl_add_u64 v[132:133], s[0:1], 0, v[128:129]
	global_load_dwordx4 v[128:131], v[132:133], off offset:16
	s_nop 0
	global_load_dwordx4 v[132:135], v[132:133], off
	s_waitcnt vmcnt(0)
	v_mov_b32_e32 v154, v133
	v_mov_b32_e32 v155, v134
	v_mov_b32_e32 v133, v135
	v_pk_add_f32 v[132:133], v[154:155], v[132:133]
	v_mov_b32_e32 v134, v130
	v_mov_b32_e32 v135, v128
	v_mov_b32_e32 v128, v131
	v_pk_add_f32 v[128:129], v[134:135], v[128:129]
	v_add_f32_e32 v130, v132, v133
	v_add_f32_e32 v129, v130, v129
	v_add_f32_e32 v128, v128, v129
	v_fmamk_f32 v128, v128, 0x3a000000, v199
	v_cmp_gt_f32_e32 vcc, s9, v128
	v_mul_f32_e32 v129, 0x4b800000, v128
	v_lshlrev_b64 v[134:135], 7, v[152:153]
	v_cndmask_b32_e32 v128, v128, v129, vcc
	v_rsq_f32_e32 v128, v128
	v_lshl_add_u64 v[134:135], v[144:145], 0, v[134:135]
	v_or_b32_e32 v152, 32, v150
	v_ashrrev_i32_e32 v153, 31, v152
	v_mul_f32_e32 v129, 0x45800000, v128
	v_cndmask_b32_e32 v132, v128, v129, vcc
	v_pk_mul_f32 v[130:131], v[110:111], v[132:133] op_sel_hi:[1,0]
	v_pk_mul_f32 v[128:129], v[108:109], v[132:133] op_sel_hi:[1,0]
	global_store_dwordx4 v[134:135], v[128:131], off
	s_nop 1
	v_pk_mul_f32 v[130:131], v[106:107], v[132:133] op_sel_hi:[1,0]
	v_pk_mul_f32 v[128:129], v[104:105], v[132:133] op_sel_hi:[1,0]
	global_store_dwordx4 v[134:135], v[128:131], off offset:16
	s_nop 1
	v_lshlrev_b64 v[128:129], 5, v[152:153]
	v_lshl_add_u64 v[132:133], s[0:1], 0, v[128:129]
	global_load_dwordx4 v[128:131], v[132:133], off offset:16
	s_nop 0
	global_load_dwordx4 v[132:135], v[132:133], off
	s_waitcnt vmcnt(0)
; DEV float rowscale(const float* ss, int row) { const f32x4 a = *(const f32x4*)(ss + (size_t)row * 8), b = *(const f32x4*)(ss + (size_t)row * 8 + 4);
;     return rsqrtf(((a[0] + a[1]) + (a[2] + a[3]) + (b[0] + b[1]) + (b[2] + b[3])) * (1.0f / 2048.0f) + EPS); }
;     DEV void operator()(AccRef acc, const pg8::Unit& u, int wr, int wc, int fr, int fq) const {
;     ...
;             for (int ai = 0; ai < 2; ++ai)
; #pragma unroll
;                 for (int m = 0; m < 4; ++m) { const float rs = rowscale(ss, row0 + ai * 128 + m * 16);
; #pragma unroll
;                     for (int n = 0; n < 2; ++n) *(f32x4*)(DTR + (size_t)(row0 + ai * 128 + m * 16) * 32 + 8 * fq + 4 * n) = acc[ai][0][m][n] * rs; }
	v_mov_b32_e32 v154, v133
	v_mov_b32_e32 v155, v134
	v_mov_b32_e32 v133, v135
	v_pk_add_f32 v[132:133], v[154:155], v[132:133]
	v_mov_b32_e32 v134, v130
	v_mov_b32_e32 v135, v128
	v_mov_b32_e32 v128, v131
	v_pk_add_f32 v[128:129], v[134:135], v[128:129]
	v_add_f32_e32 v130, v132, v133
	v_add_f32_e32 v129, v130, v129
	v_add_f32_e32 v128, v128, v129
	v_fmamk_f32 v128, v128, 0x3a000000, v199
	v_cmp_gt_f32_e32 vcc, s9, v128
	v_mul_f32_e32 v129, 0x4b800000, v128
	v_lshlrev_b64 v[134:135], 7, v[152:153]
	v_cndmask_b32_e32 v128, v128, v129, vcc
	v_rsq_f32_e32 v128, v128
	v_lshl_add_u64 v[134:135], v[144:145], 0, v[134:135]
	v_or_b32_e32 v152, 48, v150
	v_ashrrev_i32_e32 v153, 31, v152
	v_mul_f32_e32 v129, 0x45800000, v128
	v_cndmask_b32_e32 v132, v128, v129, vcc
	v_pk_mul_f32 v[130:131], v[94:95], v[132:133] op_sel_hi:[1,0]
	v_pk_mul_f32 v[128:129], v[92:93], v[132:133] op_sel_hi:[1,0]
	global_store_dwordx4 v[134:135], v[128:131], off
	s_nop 1
	v_pk_mul_f32 v[130:131], v[90:91], v[132:133] op_sel_hi:[1,0]
	v_pk_mul_f32 v[128:129], v[88:89], v[132:133] op_sel_hi:[1,0]
	global_store_dwordx4 v[134:135], v[128:131], off offset:16
	s_nop 1
	v_lshlrev_b64 v[128:129], 5, v[152:153]
	v_lshl_add_u64 v[132:133], s[0:1], 0, v[128:129]
	global_load_dwordx4 v[128:131], v[132:133], off offset:16
	s_nop 0
	global_load_dwordx4 v[132:135], v[132:133], off
	s_waitcnt vmcnt(0)
	v_mov_b32_e32 v154, v133
	v_mov_b32_e32 v155, v134
	v_mov_b32_e32 v133, v135
	v_pk_add_f32 v[132:133], v[154:155], v[132:133]
	v_mov_b32_e32 v134, v130
	v_mov_b32_e32 v135, v128
	v_mov_b32_e32 v128, v131
	v_pk_add_f32 v[128:129], v[134:135], v[128:129]
	v_add_f32_e32 v130, v132, v133
	v_add_f32_e32 v129, v130, v129
	v_add_f32_e32 v128, v128, v129
	v_fmamk_f32 v128, v128, 0x3a000000, v199
	v_cmp_gt_f32_e32 vcc, s9, v128
	v_mul_f32_e32 v129, 0x4b800000, v128
	v_lshlrev_b64 v[134:135], 7, v[152:153]
	v_cndmask_b32_e32 v128, v128, v129, vcc
	v_rsq_f32_e32 v128, v128
	v_lshl_add_u64 v[134:135], v[144:145], 0, v[134:135]
	v_add_u32_e32 v152, 0x80, v150
	v_ashrrev_i32_e32 v153, 31, v152
	v_mul_f32_e32 v129, 0x45800000, v128
	v_cndmask_b32_e32 v132, v128, v129, vcc
	v_pk_mul_f32 v[130:131], v[78:79], v[132:133] op_sel_hi:[1,0]
	v_pk_mul_f32 v[128:129], v[76:77], v[132:133] op_sel_hi:[1,0]
	global_store_dwordx4 v[134:135], v[128:131], off
	s_nop 1
	v_pk_mul_f32 v[130:131], v[74:75], v[132:133] op_sel_hi:[1,0]
	v_pk_mul_f32 v[128:129], v[72:73], v[132:133] op_sel_hi:[1,0]
	global_store_dwordx4 v[134:135], v[128:131], off offset:16
	s_nop 1
	v_lshlrev_b64 v[128:129], 5, v[152:153]
	v_lshl_add_u64 v[132:133], s[0:1], 0, v[128:129]
	global_load_dwordx4 v[128:131], v[132:133], off offset:16
	s_nop 0
	global_load_dwordx4 v[132:135], v[132:133], off
	s_waitcnt vmcnt(0)
	v_mov_b32_e32 v154, v133
	v_mov_b32_e32 v155, v134
	v_mov_b32_e32 v133, v135
	v_pk_add_f32 v[132:133], v[154:155], v[132:133]
	v_mov_b32_e32 v134, v130
	v_mov_b32_e32 v135, v128
	v_mov_b32_e32 v128, v131
	v_pk_add_f32 v[128:129], v[134:135], v[128:129]
	v_add_f32_e32 v130, v132, v133
	v_add_f32_e32 v129, v130, v129
	v_add_f32_e32 v128, v128, v129
	v_fmamk_f32 v128, v128, 0x3a000000, v199
	v_cmp_gt_f32_e32 vcc, s9, v128
	v_mul_f32_e32 v129, 0x4b800000, v128
	v_lshlrev_b64 v[134:135], 7, v[152:153]
	v_cndmask_b32_e32 v128, v128, v129, vcc
	v_rsq_f32_e32 v128, v128
	v_lshl_add_u64 v[134:135], v[144:145], 0, v[134:135]
	v_add_u32_e32 v152, 0x90, v150
	v_ashrrev_i32_e32 v153, 31, v152
	v_mul_f32_e32 v129, 0x45800000, v128
	v_cndmask_b32_e32 v132, v128, v129, vcc
	v_pk_mul_f32 v[130:131], v[62:63], v[132:133] op_sel_hi:[1,0]
	v_pk_mul_f32 v[128:129], v[60:61], v[132:133] op_sel_hi:[1,0]
	global_store_dwordx4 v[134:135], v[128:131], off
	s_nop 1
	v_pk_mul_f32 v[130:131], v[58:59], v[132:133] op_sel_hi:[1,0]
	v_pk_mul_f32 v[128:129], v[56:57], v[132:133] op_sel_hi:[1,0]
	global_store_dwordx4 v[134:135], v[128:131], off offset:16
	s_nop 1
	v_lshlrev_b64 v[128:129], 5, v[152:153]
	v_lshl_add_u64 v[132:133], s[0:1], 0, v[128:129]
	global_load_dwordx4 v[128:131], v[132:133], off offset:16
	s_nop 0
	global_load_dwordx4 v[132:135], v[132:133], off
	s_waitcnt vmcnt(0)
; DEV float rowscale(const float* ss, int row) { const f32x4 a = *(const f32x4*)(ss + (size_t)row * 8), b = *(const f32x4*)(ss + (size_t)row * 8 + 4);
;     return rsqrtf(((a[0] + a[1]) + (a[2] + a[3]) + (b[0] + b[1]) + (b[2] + b[3])) * (1.0f / 2048.0f) + EPS); }
;     DEV void operator()(AccRef acc, const pg8::Unit& u, int wr, int wc, int fr, int fq) const {
;     ...
;             for (int ai = 0; ai < 2; ++ai)
; #pragma unroll
;                 for (int m = 0; m < 4; ++m) { const float rs = rowscale(ss, row0 + ai * 128 + m * 16);
; #pragma unroll
;                     for (int n = 0; n < 2; ++n) *(f32x4*)(DTR + (size_t)(row0 + ai * 128 + m * 16) * 32 + 8 * fq + 4 * n) = acc[ai][0][m][n] * rs; }
	v_mov_b32_e32 v154, v133
	v_mov_b32_e32 v155, v134
	v_mov_b32_e32 v133, v135
	v_pk_add_f32 v[132:133], v[154:155], v[132:133]
	v_mov_b32_e32 v134, v130
	v_mov_b32_e32 v135, v128
	v_mov_b32_e32 v128, v131
	v_pk_add_f32 v[128:129], v[134:135], v[128:129]
	v_add_f32_e32 v130, v132, v133
	v_add_f32_e32 v129, v130, v129
	v_add_f32_e32 v128, v128, v129
	v_fmamk_f32 v128, v128, 0x3a000000, v199
	v_cmp_gt_f32_e32 vcc, s9, v128
	v_mul_f32_e32 v129, 0x4b800000, v128
	v_lshlrev_b64 v[134:135], 7, v[152:153]
	v_cndmask_b32_e32 v128, v128, v129, vcc
	v_rsq_f32_e32 v128, v128
	v_lshl_add_u64 v[134:135], v[144:145], 0, v[134:135]
	v_add_u32_e32 v152, 0xa0, v150
	v_ashrrev_i32_e32 v153, 31, v152
	v_mul_f32_e32 v129, 0x45800000, v128
	v_cndmask_b32_e32 v132, v128, v129, vcc
	v_pk_mul_f32 v[130:131], v[46:47], v[132:133] op_sel_hi:[1,0]
	v_pk_mul_f32 v[128:129], v[44:45], v[132:133] op_sel_hi:[1,0]
	global_store_dwordx4 v[134:135], v[128:131], off
	s_nop 1
	v_pk_mul_f32 v[130:131], v[42:43], v[132:133] op_sel_hi:[1,0]
	v_pk_mul_f32 v[128:129], v[40:41], v[132:133] op_sel_hi:[1,0]
	global_store_dwordx4 v[134:135], v[128:131], off offset:16
	s_nop 1
	v_lshlrev_b64 v[128:129], 5, v[152:153]
	v_lshl_add_u64 v[132:133], s[0:1], 0, v[128:129]
	global_load_dwordx4 v[128:131], v[132:133], off offset:16
	s_nop 0
	global_load_dwordx4 v[132:135], v[132:133], off
	s_waitcnt vmcnt(0)
	v_mov_b32_e32 v154, v133
	v_mov_b32_e32 v155, v134
	v_mov_b32_e32 v133, v135
	v_pk_add_f32 v[132:133], v[154:155], v[132:133]
	v_mov_b32_e32 v134, v130
	v_mov_b32_e32 v135, v128
	v_mov_b32_e32 v128, v131
	v_pk_add_f32 v[128:129], v[134:135], v[128:129]
	v_add_f32_e32 v130, v132, v133
	v_add_f32_e32 v129, v130, v129
	v_add_f32_e32 v128, v128, v129
	v_fmamk_f32 v128, v128, 0x3a000000, v199
	v_cmp_gt_f32_e32 vcc, s9, v128
	v_mul_f32_e32 v129, 0x4b800000, v128
	v_lshlrev_b64 v[134:135], 7, v[152:153]
	v_cndmask_b32_e32 v128, v128, v129, vcc
	v_rsq_f32_e32 v128, v128
	v_lshl_add_u64 v[134:135], v[144:145], 0, v[134:135]
	v_add_u32_e32 v152, 0xb0, v150
	v_ashrrev_i32_e32 v153, 31, v152
	v_mul_f32_e32 v129, 0x45800000, v128
	v_cndmask_b32_e32 v132, v128, v129, vcc
	v_pk_mul_f32 v[130:131], v[30:31], v[132:133] op_sel_hi:[1,0]
	v_pk_mul_f32 v[128:129], v[28:29], v[132:133] op_sel_hi:[1,0]
	global_store_dwordx4 v[134:135], v[128:131], off
	s_nop 1
	v_pk_mul_f32 v[130:131], v[26:27], v[132:133] op_sel_hi:[1,0]
	v_pk_mul_f32 v[128:129], v[24:25], v[132:133] op_sel_hi:[1,0]
	global_store_dwordx4 v[134:135], v[128:131], off offset:16
	s_nop 1
	v_lshlrev_b64 v[128:129], 5, v[152:153]
	v_lshl_add_u64 v[132:133], s[0:1], 0, v[128:129]
	global_load_dwordx4 v[128:131], v[132:133], off offset:16
	s_nop 0
	global_load_dwordx4 v[132:135], v[132:133], off
	s_waitcnt vmcnt(0)
	v_mov_b32_e32 v154, v133
	v_mov_b32_e32 v155, v134
	v_mov_b32_e32 v133, v135
	v_pk_add_f32 v[132:133], v[154:155], v[132:133]
	v_mov_b32_e32 v134, v130
	v_mov_b32_e32 v135, v128
	v_mov_b32_e32 v128, v131
	v_pk_add_f32 v[128:129], v[134:135], v[128:129]
	v_add_f32_e32 v130, v132, v133
	v_add_f32_e32 v129, v130, v129
	v_add_f32_e32 v128, v128, v129
	v_fmamk_f32 v128, v128, 0x3a000000, v199
	v_cmp_gt_f32_e32 vcc, s9, v128
	v_mul_f32_e32 v129, 0x4b800000, v128
	v_lshlrev_b64 v[134:135], 7, v[152:153]
	v_cndmask_b32_e32 v128, v128, v129, vcc
	v_rsq_f32_e32 v128, v128
	v_lshl_add_u64 v[134:135], v[144:145], 0, v[134:135]
	v_mul_f32_e32 v129, 0x45800000, v128
	v_cndmask_b32_e32 v132, v128, v129, vcc
	v_pk_mul_f32 v[130:131], v[14:15], v[132:133] op_sel_hi:[1,0]
	v_pk_mul_f32 v[128:129], v[12:13], v[132:133] op_sel_hi:[1,0]
	global_store_dwordx4 v[134:135], v[128:131], off
	s_nop 1
	v_pk_mul_f32 v[130:131], v[10:11], v[132:133] op_sel_hi:[1,0]
	v_pk_mul_f32 v[128:129], v[8:9], v[132:133] op_sel_hi:[1,0]
	global_store_dwordx4 v[134:135], v[128:131], off offset:16

; #define PG8_STAGE(bufoff, gbase, voff) do { _Pragma("unroll") for (int _i = 0; _i < 2; ++_i) \
;         __builtin_amdgcn_global_load_lds((const unsigned*)((const char*)(gbase) + (voff)[_i]), (LAS unsigned*)(lds + (bufoff) + ldsw + _i * 8192), 16, 0, 0); } while (0)
; #define PG8_LDA(dst, b, h) do { _Pragma("unroll") for (int m = 0; m < 4; ++m) _Pragma("unroll") for (int k = 0; k < 2; ++k) dst[m][k] = *(const LAS bf16x8*)(lds + PG8_SA(b, h) + aoff + m * 2048 + k * 1024); } while (0)
; #define PG8_LDB(dst, b, h) do { _Pragma("unroll") for (int n = 0; n < 2; ++n) _Pragma("unroll") for (int k = 0; k < 2; ++k) dst[n][k] = *(const LAS bf16x8*)(lds + PG8_SB(b, h) + boff + n * 2048 + k * 1024); } while (0)
; #define PG8_MMA(ai, bj, At, Bt) do { __builtin_amdgcn_s_setprio(1); _Pragma("unroll") for (int m = 0; m < 4; ++m) _Pragma("unroll") for (int n = 0; n < 2; ++n) _Pragma("unroll") for (int k = 0; k < 2; ++k) \
;         acc[ai][bj][m][n] = __builtin_amdgcn_mfma_f32_16x16x32_bf16(Bt[n][k], At[m][k], acc[ai][bj][m][n], 0, 0, 0); __builtin_amdgcn_s_setprio(0); } while (0)
; #define PG8_WAIT_L(n) asm volatile("s_waitcnt lgkmcnt(" #n ")" ::: "memory")
; #define PG8_BAR __builtin_amdgcn_s_barrier()
; #define PG8_SCHED __builtin_amdgcn_sched_barrier(0)
; template <class Epi>
; DEV void gemm_phase(LAS unsigned char* lds, const Gemm g, const StaticOrder& S, const Epi& E) {
;     ...
;             PG8_LDB(B0, 0, 0); PG8_SCHED; PG8_LDA(At, 0, 0); PG8_STAGE(PG8_SA(1, 1), a1 + hstep, voffA);
;             PG8_WAIT_L(8); PG8_BAR; PG8_WAIT_L(0); PG8_MMA(0, 0, At, B0); PG8_BAR; PG8_SCHED;
;             PG8_LDB(B1, 0, 1); PG8_STAGE(PG8_SB(0, 0), b2, voffB);
;             PG8_BAR; PG8_WAIT_L(0); PG8_MMA(0, 1, At, B1); PG8_BAR;
;             PG8_LDA(At, 0, 1); PG8_STAGE(PG8_SA(0, 0), a2, voffA);
;             PG8_BAR; PG8_WAIT_L(0); PG8_MMA(1, 0, At, B0); PG8_BAR; PG8_SCHED;
.LBB0_657:
	s_add_u32 s6, s28, 0x100
	s_addc_u32 s7, s29, 0
	s_add_i32 s55, 0, 0x10000
	v_add_u32_e32 v140, s55, v196
	ds_read_b128 v[128:131], v140
	ds_read_b128 v[132:135], v140 offset:1024
	ds_read_b128 v[136:139], v140 offset:2048
	ds_read_b128 v[140:143], v140 offset:3072
	s_cmpk_eq_i32 s54, 0x54
	s_cselect_b32 s35, s27, s7
	s_cselect_b32 s34, s26, s6
	s_cselect_b32 s31, s9, s53
	s_cselect_b32 s30, s8, s52
	v_lshl_add_u64 v[214:215], s[28:29], 0, v[180:181]
	s_add_i32 m0, s41, 0xc000
	ds_read_b128 v[144:147], v219
	ds_read_b128 v[148:151], v219 offset:1024
	ds_read_b128 v[152:155], v219 offset:2048
	ds_read_b128 v[156:159], v219 offset:3072
	ds_read_b128 v[184:187], v219 offset:4096
	ds_read_b128 v[188:191], v219 offset:5120
	ds_read_b128 v[192:195], v219 offset:6144
	ds_read_b128 v[220:223], v219 offset:7168
	global_load_lds_dwordx4 v[214:215], off
	v_lshl_add_u64 v[214:215], s[28:29], 0, v[182:183]
	s_add_i32 m0, s41, 0xe000
	s_nop 0
	global_load_lds_dwordx4 v[214:215], off
	s_waitcnt lgkmcnt(8)
	s_barrier
	s_waitcnt lgkmcnt(0)
	s_setprio 1
	v_mfma_f32_16x16x32_bf16 v[124:127], v[128:131], v[144:147], v[124:127]
	v_mfma_f32_16x16x32_bf16 v[120:123], v[136:139], v[144:147], v[120:123]
	v_mfma_f32_16x16x32_bf16 v[112:115], v[128:131], v[152:155], v[112:115]
	v_mfma_f32_16x16x32_bf16 v[104:107], v[136:139], v[152:155], v[104:107]
	v_mfma_f32_16x16x32_bf16 v[92:95], v[128:131], v[184:187], v[92:95]
	v_mfma_f32_16x16x32_bf16 v[88:91], v[136:139], v[184:187], v[88:91]
	v_mfma_f32_16x16x32_bf16 v[80:83], v[128:131], v[192:195], v[80:83]
	v_mfma_f32_16x16x32_bf16 v[72:75], v[136:139], v[192:195], v[72:75]
	v_mfma_f32_16x16x32_bf16 v[124:127], v[132:135], v[148:151], v[124:127]
	v_mfma_f32_16x16x32_bf16 v[120:123], v[140:143], v[148:151], v[120:123]
	v_mfma_f32_16x16x32_bf16 v[112:115], v[132:135], v[156:159], v[112:115]
	v_mfma_f32_16x16x32_bf16 v[104:107], v[140:143], v[156:159], v[104:107]
	v_mfma_f32_16x16x32_bf16 v[92:95], v[132:135], v[188:191], v[92:95]
	v_mfma_f32_16x16x32_bf16 v[88:91], v[140:143], v[188:191], v[88:91]
	v_mfma_f32_16x16x32_bf16 v[80:83], v[132:135], v[220:223], v[80:83]
	v_mfma_f32_16x16x32_bf16 v[72:75], v[140:143], v[220:223], v[72:75]
	s_setprio 0
	s_barrier
	s_add_i32 s56, 0, 0x14000
	v_add_u32_e32 v214, s56, v196
	s_add_i32 s28, s55, s40
	ds_read_b128 v[224:227], v214
	ds_read_b128 v[228:231], v214 offset:1024
	ds_read_b128 v[232:235], v214 offset:2048
	ds_read_b128 v[236:239], v214 offset:3072
	v_lshl_add_u64 v[214:215], s[30:31], 0, v[160:161]
	s_mov_b32 m0, s28
	v_lshl_add_u64 v[216:217], s[30:31], 0, v[178:179]
	global_load_lds_dwordx4 v[214:215], off
	s_add_i32 m0, s28, 0x2000
	s_nop 0
	global_load_lds_dwordx4 v[216:217], off
	s_barrier
	s_waitcnt lgkmcnt(0)
	s_setprio 1
	v_mfma_f32_16x16x32_bf16 v[116:119], v[224:227], v[144:147], v[116:119]
	v_mfma_f32_16x16x32_bf16 v[108:111], v[232:235], v[144:147], v[108:111]
	v_mfma_f32_16x16x32_bf16 v[100:103], v[224:227], v[152:155], v[100:103]
	v_mfma_f32_16x16x32_bf16 v[96:99], v[232:235], v[152:155], v[96:99]
	v_mfma_f32_16x16x32_bf16 v[84:87], v[224:227], v[184:187], v[84:87]
	v_mfma_f32_16x16x32_bf16 v[76:79], v[232:235], v[184:187], v[76:79]
	v_mfma_f32_16x16x32_bf16 v[68:71], v[224:227], v[192:195], v[68:71]
	v_mfma_f32_16x16x32_bf16 v[64:67], v[232:235], v[192:195], v[64:67]
	v_mfma_f32_16x16x32_bf16 v[116:119], v[228:231], v[148:151], v[116:119]
	v_mfma_f32_16x16x32_bf16 v[108:111], v[236:239], v[148:151], v[108:111]
	v_mfma_f32_16x16x32_bf16 v[100:103], v[228:231], v[156:159], v[100:103]
	v_mfma_f32_16x16x32_bf16 v[96:99], v[236:239], v[156:159], v[96:99]
	v_mfma_f32_16x16x32_bf16 v[84:87], v[228:231], v[188:191], v[84:87]
	v_mfma_f32_16x16x32_bf16 v[76:79], v[236:239], v[188:191], v[76:79]
	v_mfma_f32_16x16x32_bf16 v[68:71], v[228:231], v[220:223], v[68:71]
	v_mfma_f32_16x16x32_bf16 v[64:67], v[236:239], v[220:223], v[64:67]
	s_setprio 0
	s_mov_b32 m0, s41
	v_lshl_add_u64 v[240:241], s[34:35], 0, v[174:175]
	s_barrier
	ds_read_b128 v[144:147], v219 offset:16384
	ds_read_b128 v[148:151], v219 offset:17408
	ds_read_b128 v[152:155], v219 offset:18432
	ds_read_b128 v[156:159], v219 offset:19456
	ds_read_b128 v[184:187], v219 offset:20480
	ds_read_b128 v[188:191], v219 offset:21504
	ds_read_b128 v[192:195], v219 offset:22528
	ds_read_b128 v[220:223], v219 offset:23552
	global_load_lds_dwordx4 v[240:241], off
	v_lshl_add_u64 v[242:243], s[34:35], 0, v[176:177]
	s_mov_b32 m0, s42
	s_nop 0
	global_load_lds_dwordx4 v[242:243], off
	s_barrier
	s_waitcnt lgkmcnt(0)
	s_setprio 1
	v_mfma_f32_16x16x32_bf16 v[60:63], v[128:131], v[144:147], v[60:63]
	v_mfma_f32_16x16x32_bf16 v[56:59], v[136:139], v[144:147], v[56:59]
	v_mfma_f32_16x16x32_bf16 v[48:51], v[128:131], v[152:155], v[48:51]
	v_mfma_f32_16x16x32_bf16 v[40:43], v[136:139], v[152:155], v[40:43]
	v_mfma_f32_16x16x32_bf16 v[28:31], v[128:131], v[184:187], v[28:31]
	v_mfma_f32_16x16x32_bf16 v[24:27], v[136:139], v[184:187], v[24:27]
	v_mfma_f32_16x16x32_bf16 v[16:19], v[128:131], v[192:195], v[16:19]
	v_mfma_f32_16x16x32_bf16 v[8:11], v[136:139], v[192:195], v[8:11]
	v_mfma_f32_16x16x32_bf16 v[60:63], v[132:135], v[148:151], v[60:63]
	v_mfma_f32_16x16x32_bf16 v[56:59], v[140:143], v[148:151], v[56:59]
	v_mfma_f32_16x16x32_bf16 v[48:51], v[132:135], v[156:159], v[48:51]
	v_mfma_f32_16x16x32_bf16 v[40:43], v[140:143], v[156:159], v[40:43]
	v_mfma_f32_16x16x32_bf16 v[28:31], v[132:135], v[188:191], v[28:31]
	v_mfma_f32_16x16x32_bf16 v[24:27], v[140:143], v[188:191], v[24:27]
	v_mfma_f32_16x16x32_bf16 v[16:19], v[132:135], v[220:223], v[16:19]
	v_mfma_f32_16x16x32_bf16 v[8:11], v[140:143], v[220:223], v[8:11]
	s_setprio 0
	s_barrier
; #define PG8_STAGE(bufoff, gbase, voff) do { _Pragma("unroll") for (int _i = 0; _i < 2; ++_i) \
;         __builtin_amdgcn_global_load_lds((const unsigned*)((const char*)(gbase) + (voff)[_i]), (LAS unsigned*)(lds + (bufoff) + ldsw + _i * 8192), 16, 0, 0); } while (0)
; #define PG8_LDA(dst, b, h) do { _Pragma("unroll") for (int m = 0; m < 4; ++m) _Pragma("unroll") for (int k = 0; k < 2; ++k) dst[m][k] = *(const LAS bf16x8*)(lds + PG8_SA(b, h) + aoff + m * 2048 + k * 1024); } while (0)
; #define PG8_LDB(dst, b, h) do { _Pragma("unroll") for (int n = 0; n < 2; ++n) _Pragma("unroll") for (int k = 0; k < 2; ++k) dst[n][k] = *(const LAS bf16x8*)(lds + PG8_SB(b, h) + boff + n * 2048 + k * 1024); } while (0)
; #define PG8_MMA(ai, bj, At, Bt) do { __builtin_amdgcn_s_setprio(1); _Pragma("unroll") for (int m = 0; m < 4; ++m) _Pragma("unroll") for (int n = 0; n < 2; ++n) _Pragma("unroll") for (int k = 0; k < 2; ++k) \
;         acc[ai][bj][m][n] = __builtin_amdgcn_mfma_f32_16x16x32_bf16(Bt[n][k], At[m][k], acc[ai][bj][m][n], 0, 0, 0); __builtin_amdgcn_s_setprio(0); } while (0)
; #define PG8_WAIT_V(n) asm volatile("s_waitcnt vmcnt(" #n ")" ::: "memory")
; #define PG8_WAIT_L(n) asm volatile("s_waitcnt lgkmcnt(" #n ")" ::: "memory")
; #define PG8_BAR __builtin_amdgcn_s_barrier()
; #define PG8_SCHED __builtin_amdgcn_sched_barrier(0)
; template <class Epi>
; DEV void gemm_phase(LAS unsigned char* lds, const Gemm g, const StaticOrder& S, const Epi& E) {
;     ...
;             PG8_STAGE(PG8_SB(0, 1), b2 + hstep, voffB);
;             PG8_WAIT_V(6); PG8_BAR; PG8_MMA(1, 1, At, B1); PG8_BAR;
;             PG8_LDB(B0, 1, 0); PG8_SCHED; PG8_LDA(At, 1, 0); PG8_STAGE(PG8_SA(0, 1), a2 + hstep, voffA);
;             PG8_WAIT_L(8); PG8_BAR; PG8_WAIT_L(0); PG8_MMA(0, 0, At, B0); PG8_BAR; PG8_SCHED;
;             PG8_LDB(B1, 1, 1); PG8_STAGE(PG8_SB(1, 0), b3, voffB);
;             PG8_BAR; PG8_WAIT_L(0); PG8_MMA(0, 1, At, B1); PG8_BAR;
;             PG8_LDA(At, 1, 1); PG8_STAGE(PG8_SA(1, 0), a3, voffA);
	s_add_u32 s28, s30, 0x160000
	s_addc_u32 s29, s31, 0
	s_add_i32 s55, s56, s40
	v_lshl_add_u64 v[128:129], s[28:29], 0, v[160:161]
	s_mov_b32 m0, s55
	s_nop 0
	global_load_lds_dwordx4 v[128:129], off
	v_lshl_add_u64 v[128:129], s[28:29], 0, v[178:179]
	s_add_i32 m0, s55, 0x2000
	s_nop 0
	global_load_lds_dwordx4 v[128:129], off
	s_waitcnt vmcnt(6)
	s_barrier
	s_setprio 1
	v_mfma_f32_16x16x32_bf16 v[52:55], v[224:227], v[144:147], v[52:55]
	v_mfma_f32_16x16x32_bf16 v[44:47], v[232:235], v[144:147], v[44:47]
	v_mfma_f32_16x16x32_bf16 v[36:39], v[224:227], v[152:155], v[36:39]
	v_mfma_f32_16x16x32_bf16 v[32:35], v[232:235], v[152:155], v[32:35]
	v_mfma_f32_16x16x32_bf16 v[20:23], v[224:227], v[184:187], v[20:23]
	v_mfma_f32_16x16x32_bf16 v[12:15], v[232:235], v[184:187], v[12:15]
	v_mfma_f32_16x16x32_bf16 v[4:7], v[224:227], v[192:195], v[4:7]
	v_mfma_f32_16x16x32_bf16 v[0:3], v[232:235], v[192:195], v[0:3]
	v_mfma_f32_16x16x32_bf16 v[52:55], v[228:231], v[148:151], v[52:55]
	v_mfma_f32_16x16x32_bf16 v[44:47], v[236:239], v[148:151], v[44:47]
	v_mfma_f32_16x16x32_bf16 v[36:39], v[228:231], v[156:159], v[36:39]
	v_mfma_f32_16x16x32_bf16 v[32:35], v[236:239], v[156:159], v[32:35]
	v_mfma_f32_16x16x32_bf16 v[20:23], v[228:231], v[188:191], v[20:23]
	v_mfma_f32_16x16x32_bf16 v[12:15], v[236:239], v[188:191], v[12:15]
	v_mfma_f32_16x16x32_bf16 v[4:7], v[228:231], v[220:223], v[4:7]
	v_mfma_f32_16x16x32_bf16 v[0:3], v[236:239], v[220:223], v[0:3]
	s_setprio 0
	s_add_i32 s55, 0, 0x18000
	v_add_u32_e32 v140, s55, v196
	s_barrier
	ds_read_b128 v[128:131], v140
	ds_read_b128 v[132:135], v140 offset:1024
	ds_read_b128 v[136:139], v140 offset:2048
	ds_read_b128 v[140:143], v140 offset:3072
	s_add_u32 s28, s34, 0x160000
	s_addc_u32 s29, s35, 0
	s_mov_b32 m0, s43
	v_lshl_add_u64 v[224:225], s[28:29], 0, v[174:175]
	ds_read_b128 v[144:147], v219 offset:32768
	ds_read_b128 v[148:151], v219 offset:33792
	ds_read_b128 v[152:155], v219 offset:34816
	ds_read_b128 v[156:159], v219 offset:35840
	ds_read_b128 v[184:187], v219 offset:36864
	ds_read_b128 v[188:191], v219 offset:37888
	ds_read_b128 v[192:195], v219 offset:38912
	ds_read_b128 v[220:223], v219 offset:39936
	global_load_lds_dwordx4 v[224:225], off
	v_lshl_add_u64 v[224:225], s[28:29], 0, v[176:177]
	s_mov_b32 m0, s44
	s_nop 0
	global_load_lds_dwordx4 v[224:225], off
	s_waitcnt lgkmcnt(8)
	s_barrier
	s_waitcnt lgkmcnt(0)
	s_setprio 1
	v_mfma_f32_16x16x32_bf16 v[124:127], v[128:131], v[144:147], v[124:127]
	v_mfma_f32_16x16x32_bf16 v[120:123], v[136:139], v[144:147], v[120:123]
	v_mfma_f32_16x16x32_bf16 v[112:115], v[128:131], v[152:155], v[112:115]
	v_mfma_f32_16x16x32_bf16 v[104:107], v[136:139], v[152:155], v[104:107]
	v_mfma_f32_16x16x32_bf16 v[92:95], v[128:131], v[184:187], v[92:95]
	v_mfma_f32_16x16x32_bf16 v[88:91], v[136:139], v[184:187], v[88:91]
	v_mfma_f32_16x16x32_bf16 v[80:83], v[128:131], v[192:195], v[80:83]
	v_mfma_f32_16x16x32_bf16 v[72:75], v[136:139], v[192:195], v[72:75]
	v_mfma_f32_16x16x32_bf16 v[124:127], v[132:135], v[148:151], v[124:127]
	v_mfma_f32_16x16x32_bf16 v[120:123], v[140:143], v[148:151], v[120:123]
	v_mfma_f32_16x16x32_bf16 v[112:115], v[132:135], v[156:159], v[112:115]
	v_mfma_f32_16x16x32_bf16 v[104:107], v[140:143], v[156:159], v[104:107]
	v_mfma_f32_16x16x32_bf16 v[92:95], v[132:135], v[188:191], v[92:95]
	v_mfma_f32_16x16x32_bf16 v[88:91], v[140:143], v[188:191], v[88:91]
	v_mfma_f32_16x16x32_bf16 v[80:83], v[132:135], v[220:223], v[80:83]
	v_mfma_f32_16x16x32_bf16 v[72:75], v[140:143], v[220:223], v[72:75]
	s_setprio 0
	s_barrier
	s_add_i32 s34, 0, 0x1c000
	s_add_i32 s28, s55, s40
	v_add_u32_e32 v236, s34, v196
	v_lshl_add_u64 v[214:215], v[214:215], 0, s[2:3]
	s_mov_b32 m0, s28
	ds_read_b128 v[224:227], v236
	ds_read_b128 v[228:231], v236 offset:1024
	ds_read_b128 v[232:235], v236 offset:2048
	ds_read_b128 v[236:239], v236 offset:3072
	global_load_lds_dwordx4 v[214:215], off
	v_lshl_add_u64 v[214:215], v[216:217], 0, s[2:3]
	s_add_i32 m0, s28, 0x2000
	s_nop 0
	global_load_lds_dwordx4 v[214:215], off
	s_barrier
	s_waitcnt lgkmcnt(0)
	s_setprio 1
	v_mfma_f32_16x16x32_bf16 v[116:119], v[224:227], v[144:147], v[116:119]
	v_mfma_f32_16x16x32_bf16 v[108:111], v[232:235], v[144:147], v[108:111]
	v_mfma_f32_16x16x32_bf16 v[100:103], v[224:227], v[152:155], v[100:103]
	v_mfma_f32_16x16x32_bf16 v[96:99], v[232:235], v[152:155], v[96:99]
	v_mfma_f32_16x16x32_bf16 v[84:87], v[224:227], v[184:187], v[84:87]
	v_mfma_f32_16x16x32_bf16 v[76:79], v[232:235], v[184:187], v[76:79]
	v_mfma_f32_16x16x32_bf16 v[68:71], v[224:227], v[192:195], v[68:71]
	v_mfma_f32_16x16x32_bf16 v[64:67], v[232:235], v[192:195], v[64:67]
	v_mfma_f32_16x16x32_bf16 v[116:119], v[228:231], v[148:151], v[116:119]
	v_mfma_f32_16x16x32_bf16 v[108:111], v[236:239], v[148:151], v[108:111]
	v_mfma_f32_16x16x32_bf16 v[100:103], v[228:231], v[156:159], v[100:103]
	v_mfma_f32_16x16x32_bf16 v[96:99], v[236:239], v[156:159], v[96:99]
	v_mfma_f32_16x16x32_bf16 v[84:87], v[228:231], v[188:191], v[84:87]
	v_mfma_f32_16x16x32_bf16 v[76:79], v[236:239], v[188:191], v[76:79]
	v_mfma_f32_16x16x32_bf16 v[68:71], v[228:231], v[220:223], v[68:71]
	v_mfma_f32_16x16x32_bf16 v[64:67], v[236:239], v[220:223], v[64:67]
	s_setprio 0
	s_mov_b32 m0, s45
	v_lshl_add_u64 v[214:215], v[240:241], 0, s[2:3]
	s_barrier
	ds_read_b128 v[144:147], v219 offset:49152
	ds_read_b128 v[148:151], v219 offset:50176
	ds_read_b128 v[152:155], v219 offset:51200
	ds_read_b128 v[156:159], v219 offset:52224
	ds_read_b128 v[184:187], v219 offset:53248
	ds_read_b128 v[188:191], v219 offset:54272
	ds_read_b128 v[192:195], v219 offset:55296
	ds_read_b128 v[220:223], v219 offset:56320
	global_load_lds_dwordx4 v[214:215], off
	v_lshl_add_u64 v[214:215], v[242:243], 0, s[2:3]
	s_mov_b32 m0, s46
	s_nop 0
	global_load_lds_dwordx4 v[214:215], off
	s_barrier
; DEV bf16x8 pack8(f32x4 a, f32x4 b) { u32x4 w; w.x = cvt_pk_bf16(a[0], a[1]); w.y = cvt_pk_bf16(a[2], a[3]); w.z = cvt_pk_bf16(b[0], b[1]); w.w = cvt_pk_bf16(b[2], b[3]); return __builtin_bit_cast(bf16x8, w); }
; #define PG8_WAIT_V(n) asm volatile("s_waitcnt vmcnt(" #n ")" ::: "memory")
; #define PG8_WAIT_L(n) asm volatile("s_waitcnt lgkmcnt(" #n ")" ::: "memory")
; #define PG8_BAR __builtin_amdgcn_s_barrier()
; #define PG8_SCHED __builtin_amdgcn_sched_barrier(0)
; template <class Epi>
; DEV void gemm_phase(LAS unsigned char* lds, const Gemm g, const StaticOrder& S, const Epi& E) {
;     ...
;             PG8_BAR; PG8_WAIT_L(0); PG8_MMA(1, 0, At, B0); PG8_BAR; PG8_SCHED;
;             PG8_STAGE(PG8_SB(1, 1), b3 + hstep, voffB);
;             PG8_WAIT_V(6); PG8_BAR; PG8_MMA(1, 1, At, B1); PG8_BAR;
;     DEV void operator()(AccRef acc, const pg8::Unit& u, int wr, int wc, int fr, int fq) const {
;         const int row0 = u.pm * 256 + wr * 64 + fr, col0 = u.pn * 256 + wc * 32 + 8 * fq;
; #pragma unroll
;         for (int am = 0; am < 4; ++am) { const int ai = am >> 1, m0 = (am & 1) * 2;
;             f32x4 bv[4][2][2];
; #pragma unroll
;             for (int m = m0; m < m0 + 2; ++m)
; #pragma unroll
;                 for (int bj = 0; bj < 2; ++bj)
; #pragma unroll
;                     for (int n = 0; n < 2; ++n) bv[m][bj][n] = *(const f32x4*)(base + (size_t)(row0 + ai * 128 + m * 16) * 2048 + col0 + bj * 128 + n * 4);
; #pragma unroll
;             for (int m = m0; m < m0 + 2; ++m) { const size_t off = (size_t)(row0 + ai * 128 + m * 16) * 2048 + col0; float sq = 0.f;
; #pragma unroll
;                 for (int bj = 0; bj < 2; ++bj) { const f32x4 o0 = bv[m][bj][0] + scale * acc[ai][bj][m][0], o1 = bv[m][bj][1] + scale * acc[ai][bj][m][1];
;                     *(f32x4*)(out + off + bj * 128) = o0; *(f32x4*)(out + off + bj * 128 + 4) = o1;
;                     if (xb) { *(u32x4*)(xb + off + bj * 128) = __builtin_bit_cast(u32x4, pack8(o0, o1));
;                         sq += (o0[0] * o0[0] + o0[1] * o0[1] + o0[2] * o0[2] + o0[3] * o0[3]) + (o1[0] * o1[0] + o1[1] * o1[1] + o1[2] * o1[2] + o1[3] * o1[3]); } }
;                 if (ssout) { sq += __shfl_xor(sq, 16); sq += __shfl_xor(sq, 32);
;                     if (fq == 0) { if (red) red[(ai * 128 + wr * 64 + m * 16 + fr) * 4 + wc] = sq; else atomicAdd(ssout + (size_t)(row0 + ai * 128 + m * 16) * 8 + u.pn, sq); } } }
	s_waitcnt lgkmcnt(0)
	s_setprio 1
	v_mfma_f32_16x16x32_bf16 v[60:63], v[128:131], v[144:147], v[60:63]
	v_mfma_f32_16x16x32_bf16 v[56:59], v[136:139], v[144:147], v[56:59]
	v_mfma_f32_16x16x32_bf16 v[48:51], v[128:131], v[152:155], v[48:51]
	v_mfma_f32_16x16x32_bf16 v[40:43], v[136:139], v[152:155], v[40:43]
	v_mfma_f32_16x16x32_bf16 v[28:31], v[128:131], v[184:187], v[28:31]
	v_mfma_f32_16x16x32_bf16 v[24:27], v[136:139], v[184:187], v[24:27]
	v_mfma_f32_16x16x32_bf16 v[16:19], v[128:131], v[192:195], v[16:19]
	v_mfma_f32_16x16x32_bf16 v[8:11], v[136:139], v[192:195], v[8:11]
	v_mfma_f32_16x16x32_bf16 v[60:63], v[132:135], v[148:151], v[60:63]
	v_mfma_f32_16x16x32_bf16 v[56:59], v[140:143], v[148:151], v[56:59]
	v_mfma_f32_16x16x32_bf16 v[48:51], v[132:135], v[156:159], v[48:51]
	v_mfma_f32_16x16x32_bf16 v[40:43], v[140:143], v[156:159], v[40:43]
	v_mfma_f32_16x16x32_bf16 v[28:31], v[132:135], v[188:191], v[28:31]
	v_mfma_f32_16x16x32_bf16 v[24:27], v[140:143], v[188:191], v[24:27]
	v_mfma_f32_16x16x32_bf16 v[16:19], v[132:135], v[220:223], v[16:19]
	v_mfma_f32_16x16x32_bf16 v[8:11], v[140:143], v[220:223], v[8:11]
	s_setprio 0
	s_barrier
	s_add_u32 s28, s30, 0x160080
	s_addc_u32 s29, s31, 0
	s_add_i32 s30, s34, s40
	v_lshl_add_u64 v[128:129], s[28:29], 0, v[160:161]
	s_mov_b32 m0, s30
	s_nop 0
	global_load_lds_dwordx4 v[128:129], off
	v_lshl_add_u64 v[128:129], s[28:29], 0, v[178:179]
	s_add_i32 m0, s30, 0x2000
	s_nop 0
	global_load_lds_dwordx4 v[128:129], off
	s_waitcnt vmcnt(6)
	s_barrier
	s_setprio 1
	v_mfma_f32_16x16x32_bf16 v[52:55], v[224:227], v[144:147], v[52:55]
	v_mfma_f32_16x16x32_bf16 v[44:47], v[232:235], v[144:147], v[44:47]
	v_mfma_f32_16x16x32_bf16 v[36:39], v[224:227], v[152:155], v[36:39]
	v_mfma_f32_16x16x32_bf16 v[32:35], v[232:235], v[152:155], v[32:35]
	v_mfma_f32_16x16x32_bf16 v[20:23], v[224:227], v[184:187], v[20:23]
	v_mfma_f32_16x16x32_bf16 v[12:15], v[232:235], v[184:187], v[12:15]
	v_mfma_f32_16x16x32_bf16 v[4:7], v[224:227], v[192:195], v[4:7]
	v_mfma_f32_16x16x32_bf16 v[0:3], v[232:235], v[192:195], v[0:3]
	v_mfma_f32_16x16x32_bf16 v[52:55], v[228:231], v[148:151], v[52:55]
	v_mfma_f32_16x16x32_bf16 v[44:47], v[236:239], v[148:151], v[44:47]
	v_mfma_f32_16x16x32_bf16 v[36:39], v[228:231], v[156:159], v[36:39]
	v_mfma_f32_16x16x32_bf16 v[32:35], v[236:239], v[156:159], v[32:35]
	v_mfma_f32_16x16x32_bf16 v[20:23], v[228:231], v[188:191], v[20:23]
	v_mfma_f32_16x16x32_bf16 v[12:15], v[236:239], v[188:191], v[12:15]
	v_mfma_f32_16x16x32_bf16 v[4:7], v[228:231], v[220:223], v[4:7]
	v_mfma_f32_16x16x32_bf16 v[0:3], v[236:239], v[220:223], v[0:3]
	s_setprio 0
	s_add_i32 s54, s54, 2
	s_add_u32 s52, s52, 0x100
	s_addc_u32 s53, s53, 0
	s_cmpk_gt_u32 s54, 0x55
	s_mov_b64 s[28:29], s[6:7]
	s_barrier
	s_cbranch_scc0 .LBB0_657
	v_lshl_add_u32 v186, s23, 8, v167
	v_lshl_or_b32 v184, s22, 8, v197
	v_ashrrev_i32_e32 v185, 31, v184
	v_ashrrev_i32_e32 v187, 31, v186
	v_lshl_add_u64 v[188:189], v[184:185], 2, s[24:25]
	v_lshlrev_b64 v[128:129], 13, v[186:187]
	v_or_b32_e32 v190, 16, v186
	v_lshl_add_u64 v[128:129], v[188:189], 0, v[128:129]
	v_ashrrev_i32_e32 v191, 31, v190
	global_load_dwordx4 v[152:155], v[128:129], off offset:16
	global_load_dwordx4 v[156:159], v[128:129], off
	global_load_dwordx4 v[144:147], v[128:129], off offset:528
	global_load_dwordx4 v[148:151], v[128:129], off offset:512
	v_lshlrev_b64 v[128:129], 13, v[190:191]
	v_lshl_add_u64 v[132:133], v[188:189], 0, v[128:129]
	global_load_dwordx4 v[136:139], v[132:133], off offset:16
	global_load_dwordx4 v[140:143], v[132:133], off
	global_load_dwordx4 v[128:131], v[132:133], off offset:528
	s_nop 0
	global_load_dwordx4 v[132:135], v[132:133], off offset:512
	v_lshlrev_b64 v[192:193], 11, v[186:187]
	v_lshl_add_u64 v[194:195], v[192:193], 0, v[184:185]
	s_ashr_i32 s23, s22, 31
	v_lshl_add_u64 v[192:193], v[194:195], 2, s[68:69]
	s_mov_b64 s[28:29], -1
	s_andn2_b64 vcc, exec, s[18:19]
	s_waitcnt vmcnt(0)
	v_pk_fma_f32 v[152:153], v[120:121], 0.5, v[152:153] op_sel_hi:[1,0,1]
	v_cndmask_b32_e64 v120, 0, 1, s[18:19]
	v_pk_fma_f32 v[158:159], v[126:127], 0.5, v[158:159] op_sel_hi:[1,0,1]
	v_pk_fma_f32 v[156:157], v[124:125], 0.5, v[156:157] op_sel_hi:[1,0,1]
	v_pk_fma_f32 v[154:155], v[122:123], 0.5, v[154:155] op_sel_hi:[1,0,1]
	v_cmp_ne_u32_e64 s[6:7], 1, v120
	v_pk_fma_f32 v[120:121], v[116:117], 0.5, v[148:149] op_sel_hi:[1,0,1]
	v_pk_fma_f32 v[124:125], v[108:109], 0.5, v[144:145] op_sel_hi:[1,0,1]
	global_store_dwordx4 v[192:193], v[156:159], off
	global_store_dwordx4 v[192:193], v[152:155], off offset:16
	s_cbranch_vccnz .LBB0_665
	v_mul_f32_e32 v108, v157, v157
	v_mul_f32_e32 v109, v153, v153
	v_fmac_f32_e32 v108, v156, v156
	v_fmac_f32_e32 v109, v152, v152
	v_fmac_f32_e32 v108, v158, v158
	v_fmac_f32_e32 v109, v154, v154
	v_fmac_f32_e32 v108, v159, v159
	v_fmac_f32_e32 v109, v155, v155
	v_add_f32_e32 v108, v108, v109
	v_mul_f32_e32 v109, v121, v121
	v_mul_f32_e32 v144, v125, v125
	v_pk_fma_f32 v[122:123], v[118:119], 0.5, v[150:151] op_sel_hi:[1,0,1]
	v_pk_fma_f32 v[126:127], v[110:111], 0.5, v[146:147] op_sel_hi:[1,0,1]
	v_fmac_f32_e32 v109, v120, v120
	v_fmac_f32_e32 v144, v124, v124
	v_fmac_f32_e32 v109, v122, v122
	v_fmac_f32_e32 v144, v126, v126
	v_fmac_f32_e32 v109, v123, v123
	v_fmac_f32_e32 v144, v127, v127
	v_add_f32_e32 v109, v109, v144
	v_cmp_lt_i32_e32 vcc, v208, v206
	v_add_f32_e32 v108, v108, v109
	v_readlane_b32 s28, v250, 9
	v_cndmask_b32_e32 v109, v204, v208, vcc
	v_lshlrev_b32_e32 v109, 2, v109
	ds_bpermute_b32 v109, v109, v108
	v_cmp_lt_i32_e32 vcc, v207, v206
	v_readlane_b32 s29, v250, 10
	v_cvt_pk_bf16_f32 v220, v156, v157
	v_cvt_pk_bf16_f32 v221, v158, v159
	s_waitcnt lgkmcnt(0)
	v_add_f32_e32 v108, v108, v109
	v_cndmask_b32_e32 v109, v204, v207, vcc
	v_lshlrev_b32_e32 v109, 2, v109
	ds_bpermute_b32 v109, v109, v108
	v_cvt_pk_bf16_f32 v222, v152, v153
	v_cvt_pk_bf16_f32 v223, v154, v155
	v_lshl_add_u64 v[116:117], v[194:195], 1, s[28:29]
	v_cvt_pk_bf16_f32 v152, v120, v121
	v_cvt_pk_bf16_f32 v153, v122, v123
	v_cvt_pk_bf16_f32 v154, v124, v125
	v_cvt_pk_bf16_f32 v155, v126, v127
	global_store_dwordx4 v[116:117], v[220:223], off
	global_store_dwordx4 v[192:193], v[120:123], off offset:512
	global_store_dwordx4 v[192:193], v[124:127], off offset:528
	global_store_dwordx4 v[116:117], v[152:155], off offset:256
	s_and_saveexec_b64 s[28:29], s[10:11]
	s_cbranch_execz .LBB0_664
	s_waitcnt lgkmcnt(0)
	v_add_f32_e32 v108, v108, v109
	s_andn2_b64 vcc, exec, s[20:21]
	s_mov_b64 s[30:31], -1
	s_cbranch_vccnz .LBB0_662
	s_mov_b64 s[30:31], 0
	ds_write_b32 v218, v108

; #define PG8_STAGE(bufoff, gbase, voff) do { _Pragma("unroll") for (int _i = 0; _i < 2; ++_i) \
;         __builtin_amdgcn_global_load_lds((const unsigned*)((const char*)(gbase) + (voff)[_i]), (LAS unsigned*)(lds + (bufoff) + ldsw + _i * 8192), 16, 0, 0); } while (0)
; #define PG8_LDA(dst, b, h) do { _Pragma("unroll") for (int m = 0; m < 4; ++m) _Pragma("unroll") for (int k = 0; k < 2; ++k) dst[m][k] = *(const LAS bf16x8*)(lds + PG8_SA(b, h) + aoff + m * 2048 + k * 1024); } while (0)
; #define PG8_LDB(dst, b, h) do { _Pragma("unroll") for (int n = 0; n < 2; ++n) _Pragma("unroll") for (int k = 0; k < 2; ++k) dst[n][k] = *(const LAS bf16x8*)(lds + PG8_SB(b, h) + boff + n * 2048 + k * 1024); } while (0)
; #define PG8_MMA(ai, bj, At, Bt) do { __builtin_amdgcn_s_setprio(1); _Pragma("unroll") for (int m = 0; m < 4; ++m) _Pragma("unroll") for (int n = 0; n < 2; ++n) _Pragma("unroll") for (int k = 0; k < 2; ++k) \
;         acc[ai][bj][m][n] = __builtin_amdgcn_mfma_f32_16x16x32_bf16(Bt[n][k], At[m][k], acc[ai][bj][m][n], 0, 0, 0); __builtin_amdgcn_s_setprio(0); } while (0)
; #define PG8_WAIT_L(n) asm volatile("s_waitcnt lgkmcnt(" #n ")" ::: "memory")
; #define PG8_BAR __builtin_amdgcn_s_barrier()
; #define PG8_SCHED __builtin_amdgcn_sched_barrier(0)
; template <class Epi>
; DEV void gemm_phase(LAS unsigned char* lds, const Gemm g, const StaticOrder& S, const Epi& E) {
;     ...
;             PG8_LDB(B0, 0, 0); PG8_SCHED; PG8_LDA(At, 0, 0); PG8_STAGE(PG8_SA(1, 1), a1 + hstep, voffA);
;             PG8_WAIT_L(8); PG8_BAR; PG8_WAIT_L(0); PG8_MMA(0, 0, At, B0); PG8_BAR; PG8_SCHED;
;             PG8_LDB(B1, 0, 1); PG8_STAGE(PG8_SB(0, 0), b2, voffB);
;             PG8_BAR; PG8_WAIT_L(0); PG8_MMA(0, 1, At, B1); PG8_BAR;
;             PG8_LDA(At, 0, 1); PG8_STAGE(PG8_SA(0, 0), a2, voffA);
;             PG8_BAR; PG8_WAIT_L(0); PG8_MMA(1, 0, At, B0); PG8_BAR; PG8_SCHED;
.LBB0_755:
	s_add_u32 s22, s20, 0xfff80080
	s_addc_u32 s23, s21, -1
	s_add_i32 s47, 0, 0x10000
	v_add_u32_e32 v146, s47, v155
	ds_read_b128 v[128:131], v146
	ds_read_b128 v[132:135], v146 offset:1024
	ds_read_b128 v[150:153], v146 offset:2048
	ds_read_b128 v[174:177], v146 offset:3072
	s_cmp_eq_u32 s46, 28
	s_cselect_b32 s25, s5, s23
	s_cselect_b32 s24, s15, s22
	s_cselect_b32 s23, s11, s45
	s_cselect_b32 s22, s43, s44
	v_lshl_add_u64 v[146:147], s[20:21], 0, v[142:143]
	s_add_i32 m0, s34, 0xc000
	ds_read_b128 v[178:181], v167
	ds_read_b128 v[182:185], v167 offset:1024
	ds_read_b128 v[186:189], v167 offset:2048
	ds_read_b128 v[190:193], v167 offset:3072
	ds_read_b128 v[194:197], v167 offset:4096
	ds_read_b128 v[218:221], v167 offset:5120
	ds_read_b128 v[222:225], v167 offset:6144
	ds_read_b128 v[226:229], v167 offset:7168
	global_load_lds_dwordx4 v[146:147], off
	v_lshl_add_u64 v[146:147], s[20:21], 0, v[144:145]
	s_add_i32 m0, s34, 0xe000
	s_nop 0
	global_load_lds_dwordx4 v[146:147], off
	s_waitcnt lgkmcnt(8)
	s_barrier
	s_waitcnt lgkmcnt(0)
	s_setprio 1
	v_mfma_f32_16x16x32_bf16 v[124:127], v[128:131], v[178:181], v[124:127]
	v_mfma_f32_16x16x32_bf16 v[116:119], v[150:153], v[178:181], v[116:119]
	v_mfma_f32_16x16x32_bf16 v[108:111], v[128:131], v[186:189], v[108:111]
	v_mfma_f32_16x16x32_bf16 v[100:103], v[150:153], v[186:189], v[100:103]
	v_mfma_f32_16x16x32_bf16 v[92:95], v[128:131], v[194:197], v[92:95]
	v_mfma_f32_16x16x32_bf16 v[84:87], v[150:153], v[194:197], v[84:87]
	v_mfma_f32_16x16x32_bf16 v[76:79], v[128:131], v[222:225], v[76:79]
	v_mfma_f32_16x16x32_bf16 v[68:71], v[150:153], v[222:225], v[68:71]
	v_mfma_f32_16x16x32_bf16 v[124:127], v[132:135], v[182:185], v[124:127]
	v_mfma_f32_16x16x32_bf16 v[116:119], v[174:177], v[182:185], v[116:119]
	v_mfma_f32_16x16x32_bf16 v[108:111], v[132:135], v[190:193], v[108:111]
	v_mfma_f32_16x16x32_bf16 v[100:103], v[174:177], v[190:193], v[100:103]
	v_mfma_f32_16x16x32_bf16 v[92:95], v[132:135], v[218:221], v[92:95]
	v_mfma_f32_16x16x32_bf16 v[84:87], v[174:177], v[218:221], v[84:87]
	v_mfma_f32_16x16x32_bf16 v[76:79], v[132:135], v[226:229], v[76:79]
	v_mfma_f32_16x16x32_bf16 v[68:71], v[174:177], v[226:229], v[68:71]
	s_setprio 0
	s_barrier
	s_add_i32 s50, 0, 0x14000
	v_add_u32_e32 v146, s50, v155
	s_add_i32 s47, s47, s30
	ds_read_b128 v[230:233], v146
	ds_read_b128 v[234:237], v146 offset:1024
	ds_read_b128 v[238:241], v146 offset:2048
	ds_read_b128 v[242:245], v146 offset:3072
	v_lshl_add_u64 v[146:147], s[22:23], 0, v[160:161]
	s_mov_b32 m0, s47
	v_lshl_add_u64 v[158:159], s[22:23], 0, v[136:137]
	global_load_lds_dwordx4 v[146:147], off
	s_add_i32 m0, s47, 0x2000
	s_nop 0
	global_load_lds_dwordx4 v[158:159], off
	s_barrier
	s_waitcnt lgkmcnt(0)
	s_setprio 1
	v_mfma_f32_16x16x32_bf16 v[120:123], v[230:233], v[178:181], v[120:123]
	v_mfma_f32_16x16x32_bf16 v[112:115], v[238:241], v[178:181], v[112:115]
	v_mfma_f32_16x16x32_bf16 v[104:107], v[230:233], v[186:189], v[104:107]
	v_mfma_f32_16x16x32_bf16 v[96:99], v[238:241], v[186:189], v[96:99]
	v_mfma_f32_16x16x32_bf16 v[88:91], v[230:233], v[194:197], v[88:91]
	v_mfma_f32_16x16x32_bf16 v[80:83], v[238:241], v[194:197], v[80:83]
	v_mfma_f32_16x16x32_bf16 v[72:75], v[230:233], v[222:225], v[72:75]
	v_mfma_f32_16x16x32_bf16 v[64:67], v[238:241], v[222:225], v[64:67]
	v_mfma_f32_16x16x32_bf16 v[120:123], v[234:237], v[182:185], v[120:123]
	v_mfma_f32_16x16x32_bf16 v[112:115], v[242:245], v[182:185], v[112:115]
	v_mfma_f32_16x16x32_bf16 v[104:107], v[234:237], v[190:193], v[104:107]
	v_mfma_f32_16x16x32_bf16 v[96:99], v[242:245], v[190:193], v[96:99]
	v_mfma_f32_16x16x32_bf16 v[88:91], v[234:237], v[218:221], v[88:91]
	v_mfma_f32_16x16x32_bf16 v[80:83], v[242:245], v[218:221], v[80:83]
	v_mfma_f32_16x16x32_bf16 v[72:75], v[234:237], v[226:229], v[72:75]
	v_mfma_f32_16x16x32_bf16 v[64:67], v[242:245], v[226:229], v[64:67]
	s_setprio 0
	s_mov_b32 m0, s34
	v_lshl_add_u64 v[214:215], s[24:25], 0, v[140:141]
	s_barrier
	ds_read_b128 v[178:181], v167 offset:16384
	ds_read_b128 v[182:185], v167 offset:17408
	ds_read_b128 v[186:189], v167 offset:18432
	ds_read_b128 v[190:193], v167 offset:19456
	ds_read_b128 v[194:197], v167 offset:20480
	ds_read_b128 v[218:221], v167 offset:21504
	ds_read_b128 v[222:225], v167 offset:22528
	ds_read_b128 v[226:229], v167 offset:23552
	global_load_lds_dwordx4 v[214:215], off
	v_lshl_add_u64 v[216:217], s[24:25], 0, v[138:139]
	s_mov_b32 m0, s35
	s_nop 0
	global_load_lds_dwordx4 v[216:217], off
	s_barrier
	s_waitcnt lgkmcnt(0)
	s_setprio 1
	v_mfma_f32_16x16x32_bf16 v[60:63], v[128:131], v[178:181], v[60:63]
	v_mfma_f32_16x16x32_bf16 v[52:55], v[150:153], v[178:181], v[52:55]
	v_mfma_f32_16x16x32_bf16 v[44:47], v[128:131], v[186:189], v[44:47]
	v_mfma_f32_16x16x32_bf16 v[36:39], v[150:153], v[186:189], v[36:39]
	v_mfma_f32_16x16x32_bf16 v[28:31], v[128:131], v[194:197], v[28:31]
	v_mfma_f32_16x16x32_bf16 v[20:23], v[150:153], v[194:197], v[20:23]
	v_mfma_f32_16x16x32_bf16 v[12:15], v[128:131], v[222:225], v[12:15]
	v_mfma_f32_16x16x32_bf16 v[4:7], v[150:153], v[222:225], v[4:7]
	v_mfma_f32_16x16x32_bf16 v[60:63], v[132:135], v[182:185], v[60:63]
	v_mfma_f32_16x16x32_bf16 v[52:55], v[174:177], v[182:185], v[52:55]
	v_mfma_f32_16x16x32_bf16 v[44:47], v[132:135], v[190:193], v[44:47]
	v_mfma_f32_16x16x32_bf16 v[36:39], v[174:177], v[190:193], v[36:39]
	v_mfma_f32_16x16x32_bf16 v[28:31], v[132:135], v[218:221], v[28:31]
	v_mfma_f32_16x16x32_bf16 v[20:23], v[174:177], v[218:221], v[20:23]
	v_mfma_f32_16x16x32_bf16 v[12:15], v[132:135], v[226:229], v[12:15]
	v_mfma_f32_16x16x32_bf16 v[4:7], v[174:177], v[226:229], v[4:7]
	s_setprio 0
	s_barrier
; #define PG8_STAGE(bufoff, gbase, voff) do { _Pragma("unroll") for (int _i = 0; _i < 2; ++_i) \
;         __builtin_amdgcn_global_load_lds((const unsigned*)((const char*)(gbase) + (voff)[_i]), (LAS unsigned*)(lds + (bufoff) + ldsw + _i * 8192), 16, 0, 0); } while (0)
; #define PG8_LDA(dst, b, h) do { _Pragma("unroll") for (int m = 0; m < 4; ++m) _Pragma("unroll") for (int k = 0; k < 2; ++k) dst[m][k] = *(const LAS bf16x8*)(lds + PG8_SA(b, h) + aoff + m * 2048 + k * 1024); } while (0)
; #define PG8_LDB(dst, b, h) do { _Pragma("unroll") for (int n = 0; n < 2; ++n) _Pragma("unroll") for (int k = 0; k < 2; ++k) dst[n][k] = *(const LAS bf16x8*)(lds + PG8_SB(b, h) + boff + n * 2048 + k * 1024); } while (0)
; #define PG8_MMA(ai, bj, At, Bt) do { __builtin_amdgcn_s_setprio(1); _Pragma("unroll") for (int m = 0; m < 4; ++m) _Pragma("unroll") for (int n = 0; n < 2; ++n) _Pragma("unroll") for (int k = 0; k < 2; ++k) \
;         acc[ai][bj][m][n] = __builtin_amdgcn_mfma_f32_16x16x32_bf16(Bt[n][k], At[m][k], acc[ai][bj][m][n], 0, 0, 0); __builtin_amdgcn_s_setprio(0); } while (0)
; #define PG8_WAIT_V(n) asm volatile("s_waitcnt vmcnt(" #n ")" ::: "memory")
; #define PG8_WAIT_L(n) asm volatile("s_waitcnt lgkmcnt(" #n ")" ::: "memory")
; #define PG8_BAR __builtin_amdgcn_s_barrier()
; #define PG8_SCHED __builtin_amdgcn_sched_barrier(0)
; template <class Epi>
; DEV void gemm_phase(LAS unsigned char* lds, const Gemm g, const StaticOrder& S, const Epi& E) {
;     ...
;             PG8_STAGE(PG8_SB(0, 1), b2 + hstep, voffB);
;             PG8_WAIT_V(6); PG8_BAR; PG8_MMA(1, 1, At, B1); PG8_BAR;
;             PG8_LDB(B0, 1, 0); PG8_SCHED; PG8_LDA(At, 1, 0); PG8_STAGE(PG8_SA(0, 1), a2 + hstep, voffA);
;             PG8_WAIT_L(8); PG8_BAR; PG8_WAIT_L(0); PG8_MMA(0, 0, At, B0); PG8_BAR; PG8_SCHED;
;             PG8_LDB(B1, 1, 1); PG8_STAGE(PG8_SB(1, 0), b3, voffB);
;             PG8_BAR; PG8_WAIT_L(0); PG8_MMA(0, 1, At, B1); PG8_BAR;
;             PG8_LDA(At, 1, 1); PG8_STAGE(PG8_SA(1, 0), a3, voffA);
	s_add_u32 s48, s22, 0x80000
	s_addc_u32 s49, s23, 0
	s_add_i32 s47, s50, s30
	v_lshl_add_u64 v[128:129], s[48:49], 0, v[160:161]
	s_mov_b32 m0, s47
	s_nop 0
	global_load_lds_dwordx4 v[128:129], off
	v_lshl_add_u64 v[128:129], s[48:49], 0, v[136:137]
	s_add_i32 m0, s47, 0x2000
	s_nop 0
	global_load_lds_dwordx4 v[128:129], off
	s_waitcnt vmcnt(6)
	s_barrier
	s_setprio 1
	v_mfma_f32_16x16x32_bf16 v[56:59], v[230:233], v[178:181], v[56:59]
	v_mfma_f32_16x16x32_bf16 v[48:51], v[238:241], v[178:181], v[48:51]
	v_mfma_f32_16x16x32_bf16 v[40:43], v[230:233], v[186:189], v[40:43]
	v_mfma_f32_16x16x32_bf16 v[32:35], v[238:241], v[186:189], v[32:35]
	v_mfma_f32_16x16x32_bf16 v[24:27], v[230:233], v[194:197], v[24:27]
	v_mfma_f32_16x16x32_bf16 v[16:19], v[238:241], v[194:197], v[16:19]
	v_mfma_f32_16x16x32_bf16 v[8:11], v[230:233], v[222:225], v[8:11]
	v_mfma_f32_16x16x32_bf16 v[0:3], v[238:241], v[222:225], v[0:3]
	v_mfma_f32_16x16x32_bf16 v[56:59], v[234:237], v[182:185], v[56:59]
	v_mfma_f32_16x16x32_bf16 v[48:51], v[242:245], v[182:185], v[48:51]
	v_mfma_f32_16x16x32_bf16 v[40:43], v[234:237], v[190:193], v[40:43]
	v_mfma_f32_16x16x32_bf16 v[32:35], v[242:245], v[190:193], v[32:35]
	v_mfma_f32_16x16x32_bf16 v[24:27], v[234:237], v[218:221], v[24:27]
	v_mfma_f32_16x16x32_bf16 v[16:19], v[242:245], v[218:221], v[16:19]
	v_mfma_f32_16x16x32_bf16 v[8:11], v[234:237], v[226:229], v[8:11]
	v_mfma_f32_16x16x32_bf16 v[0:3], v[242:245], v[226:229], v[0:3]
	s_setprio 0
	s_add_i32 s47, 0, 0x18000
	v_add_u32_e32 v148, s47, v155
	s_barrier
	ds_read_b128 v[128:131], v148
	ds_read_b128 v[132:135], v148 offset:1024
	ds_read_b128 v[150:153], v148 offset:2048
	ds_read_b128 v[174:177], v148 offset:3072
	s_add_u32 s24, s24, 0x80000
	s_addc_u32 s25, s25, 0
	s_mov_b32 m0, s36
	v_lshl_add_u64 v[230:231], s[24:25], 0, v[140:141]
	ds_read_b128 v[178:181], v167 offset:32768
	ds_read_b128 v[182:185], v167 offset:33792
	ds_read_b128 v[186:189], v167 offset:34816
	ds_read_b128 v[190:193], v167 offset:35840
	ds_read_b128 v[194:197], v167 offset:36864
	ds_read_b128 v[218:221], v167 offset:37888
	ds_read_b128 v[222:225], v167 offset:38912
	ds_read_b128 v[226:229], v167 offset:39936
	global_load_lds_dwordx4 v[230:231], off
	v_lshl_add_u64 v[230:231], s[24:25], 0, v[138:139]
	s_mov_b32 m0, s37
	s_nop 0
	global_load_lds_dwordx4 v[230:231], off
	s_waitcnt lgkmcnt(8)
	s_barrier
	s_waitcnt lgkmcnt(0)
	s_setprio 1
	v_mfma_f32_16x16x32_bf16 v[124:127], v[128:131], v[178:181], v[124:127]
	v_mfma_f32_16x16x32_bf16 v[116:119], v[150:153], v[178:181], v[116:119]
	v_mfma_f32_16x16x32_bf16 v[108:111], v[128:131], v[186:189], v[108:111]
	v_mfma_f32_16x16x32_bf16 v[100:103], v[150:153], v[186:189], v[100:103]
	v_mfma_f32_16x16x32_bf16 v[92:95], v[128:131], v[194:197], v[92:95]
	v_mfma_f32_16x16x32_bf16 v[84:87], v[150:153], v[194:197], v[84:87]
	v_mfma_f32_16x16x32_bf16 v[76:79], v[128:131], v[222:225], v[76:79]
	v_mfma_f32_16x16x32_bf16 v[68:71], v[150:153], v[222:225], v[68:71]
	v_mfma_f32_16x16x32_bf16 v[124:127], v[132:135], v[182:185], v[124:127]
	v_mfma_f32_16x16x32_bf16 v[116:119], v[174:177], v[182:185], v[116:119]
	v_mfma_f32_16x16x32_bf16 v[108:111], v[132:135], v[190:193], v[108:111]
	v_mfma_f32_16x16x32_bf16 v[100:103], v[174:177], v[190:193], v[100:103]
	v_mfma_f32_16x16x32_bf16 v[92:95], v[132:135], v[218:221], v[92:95]
	v_mfma_f32_16x16x32_bf16 v[84:87], v[174:177], v[218:221], v[84:87]
	v_mfma_f32_16x16x32_bf16 v[76:79], v[132:135], v[226:229], v[76:79]
	v_mfma_f32_16x16x32_bf16 v[68:71], v[174:177], v[226:229], v[68:71]
	s_setprio 0
	s_barrier
	s_add_i32 s24, 0, 0x1c000
	s_add_i32 s25, s47, s30
	v_add_u32_e32 v148, s24, v155
	v_lshl_add_u64 v[146:147], v[146:147], 0, s[2:3]
	s_mov_b32 m0, s25
	ds_read_b128 v[230:233], v148
	ds_read_b128 v[234:237], v148 offset:1024
	ds_read_b128 v[238:241], v148 offset:2048
	ds_read_b128 v[242:245], v148 offset:3072
	global_load_lds_dwordx4 v[146:147], off
	v_lshl_add_u64 v[146:147], v[158:159], 0, s[2:3]
	s_add_i32 m0, s25, 0x2000
	s_nop 0
	global_load_lds_dwordx4 v[146:147], off
	s_barrier
	s_waitcnt lgkmcnt(0)
	s_setprio 1
	v_mfma_f32_16x16x32_bf16 v[120:123], v[230:233], v[178:181], v[120:123]
	v_mfma_f32_16x16x32_bf16 v[112:115], v[238:241], v[178:181], v[112:115]
	v_mfma_f32_16x16x32_bf16 v[104:107], v[230:233], v[186:189], v[104:107]
	v_mfma_f32_16x16x32_bf16 v[96:99], v[238:241], v[186:189], v[96:99]
	v_mfma_f32_16x16x32_bf16 v[88:91], v[230:233], v[194:197], v[88:91]
	v_mfma_f32_16x16x32_bf16 v[80:83], v[238:241], v[194:197], v[80:83]
	v_mfma_f32_16x16x32_bf16 v[72:75], v[230:233], v[222:225], v[72:75]
	v_mfma_f32_16x16x32_bf16 v[64:67], v[238:241], v[222:225], v[64:67]
	v_mfma_f32_16x16x32_bf16 v[120:123], v[234:237], v[182:185], v[120:123]
	v_mfma_f32_16x16x32_bf16 v[112:115], v[242:245], v[182:185], v[112:115]
	v_mfma_f32_16x16x32_bf16 v[104:107], v[234:237], v[190:193], v[104:107]
	v_mfma_f32_16x16x32_bf16 v[96:99], v[242:245], v[190:193], v[96:99]
	v_mfma_f32_16x16x32_bf16 v[88:91], v[234:237], v[218:221], v[88:91]
	v_mfma_f32_16x16x32_bf16 v[80:83], v[242:245], v[218:221], v[80:83]
	v_mfma_f32_16x16x32_bf16 v[72:75], v[234:237], v[226:229], v[72:75]
	v_mfma_f32_16x16x32_bf16 v[64:67], v[242:245], v[226:229], v[64:67]
	s_setprio 0
	s_mov_b32 m0, s38
	v_lshl_add_u64 v[146:147], v[214:215], 0, s[2:3]
	s_barrier
	ds_read_b128 v[178:181], v167 offset:49152
	ds_read_b128 v[182:185], v167 offset:50176
	ds_read_b128 v[186:189], v167 offset:51200
	ds_read_b128 v[190:193], v167 offset:52224
	ds_read_b128 v[194:197], v167 offset:53248
	ds_read_b128 v[218:221], v167 offset:54272
	ds_read_b128 v[222:225], v167 offset:55296
	ds_read_b128 v[226:229], v167 offset:56320
	global_load_lds_dwordx4 v[146:147], off
	v_lshl_add_u64 v[146:147], v[216:217], 0, s[2:3]
	s_mov_b32 m0, s39
	s_nop 0
	global_load_lds_dwordx4 v[146:147], off
	s_barrier
; #define PG8_STAGE(bufoff, gbase, voff) do { _Pragma("unroll") for (int _i = 0; _i < 2; ++_i) \
;         __builtin_amdgcn_global_load_lds((const unsigned*)((const char*)(gbase) + (voff)[_i]), (LAS unsigned*)(lds + (bufoff) + ldsw + _i * 8192), 16, 0, 0); } while (0)
; #define PG8_MMA(ai, bj, At, Bt) do { __builtin_amdgcn_s_setprio(1); _Pragma("unroll") for (int m = 0; m < 4; ++m) _Pragma("unroll") for (int n = 0; n < 2; ++n) _Pragma("unroll") for (int k = 0; k < 2; ++k) \
;         acc[ai][bj][m][n] = __builtin_amdgcn_mfma_f32_16x16x32_bf16(Bt[n][k], At[m][k], acc[ai][bj][m][n], 0, 0, 0); __builtin_amdgcn_s_setprio(0); } while (0)
; #define PG8_WAIT_V(n) asm volatile("s_waitcnt vmcnt(" #n ")" ::: "memory")
; #define PG8_WAIT_L(n) asm volatile("s_waitcnt lgkmcnt(" #n ")" ::: "memory")
; #define PG8_BAR __builtin_amdgcn_s_barrier()
; #define PG8_SCHED __builtin_amdgcn_sched_barrier(0)
;     DEV void operator()(AccRef acc, const pg8::Unit& u, int wr, int wc, int fr, int fq) const { store_bf16_tile<0, false>(acc, O, ld, u.pm * 256 + wr * 64 + fr, u.pn * 256 + wc * 32 + 4 * fq, ss); }
; template <class Epi>
; DEV void gemm_phase(LAS unsigned char* lds, const Gemm g, const StaticOrder& S, const Epi& E) {
;     ...
;             PG8_BAR; PG8_WAIT_L(0); PG8_MMA(1, 0, At, B0); PG8_BAR; PG8_SCHED;
;             PG8_STAGE(PG8_SB(1, 1), b3 + hstep, voffB);
;             PG8_WAIT_V(6); PG8_BAR; PG8_MMA(1, 1, At, B1); PG8_BAR;
; DEV float rowscale(const float* ss, int row) { const f32x4 a = *(const f32x4*)(ss + (size_t)row * 8), b = *(const f32x4*)(ss + (size_t)row * 8 + 4);
;     return rsqrtf(((a[0] + a[1]) + (a[2] + a[3]) + (b[0] + b[1]) + (b[2] + b[3])) * (1.0f / 2048.0f) + EPS); }
;     DEV void operator()(AccRef acc, const pg8::Unit& u, int wr, int wc, int fr, int fq) const {
;         const int row0 = u.pm * 256 + wr * 64 + fr, col0 = u.pn * 128 + wc * 32 + 8 * fq;
;         float rsv[2][4];
; #pragma unroll
;         for (int ai = 0; ai < 2; ++ai)
; #pragma unroll
;             for (int m = 0; m < 4; ++m) rsv[ai][m] = rowscale(ss, row0 + ai * 128 + m * 16);
	s_waitcnt lgkmcnt(0)
	s_setprio 1
	v_mfma_f32_16x16x32_bf16 v[60:63], v[128:131], v[178:181], v[60:63]
	v_mfma_f32_16x16x32_bf16 v[52:55], v[150:153], v[178:181], v[52:55]
	v_mfma_f32_16x16x32_bf16 v[44:47], v[128:131], v[186:189], v[44:47]
	v_mfma_f32_16x16x32_bf16 v[36:39], v[150:153], v[186:189], v[36:39]
	v_mfma_f32_16x16x32_bf16 v[28:31], v[128:131], v[194:197], v[28:31]
	v_mfma_f32_16x16x32_bf16 v[20:23], v[150:153], v[194:197], v[20:23]
	v_mfma_f32_16x16x32_bf16 v[12:15], v[128:131], v[222:225], v[12:15]
	v_mfma_f32_16x16x32_bf16 v[4:7], v[150:153], v[222:225], v[4:7]
	v_mfma_f32_16x16x32_bf16 v[60:63], v[132:135], v[182:185], v[60:63]
	v_mfma_f32_16x16x32_bf16 v[52:55], v[174:177], v[182:185], v[52:55]
	v_mfma_f32_16x16x32_bf16 v[44:47], v[132:135], v[190:193], v[44:47]
	v_mfma_f32_16x16x32_bf16 v[36:39], v[174:177], v[190:193], v[36:39]
	v_mfma_f32_16x16x32_bf16 v[28:31], v[132:135], v[218:221], v[28:31]
	v_mfma_f32_16x16x32_bf16 v[20:23], v[174:177], v[218:221], v[20:23]
	v_mfma_f32_16x16x32_bf16 v[12:15], v[132:135], v[226:229], v[12:15]
	v_mfma_f32_16x16x32_bf16 v[4:7], v[174:177], v[226:229], v[4:7]
	s_setprio 0
	s_barrier
	s_add_u32 s22, s22, 0x80080
	s_addc_u32 s23, s23, 0
	s_add_i32 s24, s24, s30
	v_lshl_add_u64 v[128:129], s[22:23], 0, v[160:161]
	s_mov_b32 m0, s24
	s_nop 0
	global_load_lds_dwordx4 v[128:129], off
	v_lshl_add_u64 v[128:129], s[22:23], 0, v[136:137]
	s_add_i32 m0, s24, 0x2000
	s_nop 0
	global_load_lds_dwordx4 v[128:129], off
	s_waitcnt vmcnt(6)
	s_barrier
	s_setprio 1
	v_mfma_f32_16x16x32_bf16 v[56:59], v[230:233], v[178:181], v[56:59]
	v_mfma_f32_16x16x32_bf16 v[48:51], v[238:241], v[178:181], v[48:51]
	v_mfma_f32_16x16x32_bf16 v[40:43], v[230:233], v[186:189], v[40:43]
	v_mfma_f32_16x16x32_bf16 v[32:35], v[238:241], v[186:189], v[32:35]
	v_mfma_f32_16x16x32_bf16 v[24:27], v[230:233], v[194:197], v[24:27]
	v_mfma_f32_16x16x32_bf16 v[16:19], v[238:241], v[194:197], v[16:19]
	v_mfma_f32_16x16x32_bf16 v[8:11], v[230:233], v[222:225], v[8:11]
	v_mfma_f32_16x16x32_bf16 v[0:3], v[238:241], v[222:225], v[0:3]
	v_mfma_f32_16x16x32_bf16 v[56:59], v[234:237], v[182:185], v[56:59]
	v_mfma_f32_16x16x32_bf16 v[48:51], v[242:245], v[182:185], v[48:51]
	v_mfma_f32_16x16x32_bf16 v[40:43], v[234:237], v[190:193], v[40:43]
	v_mfma_f32_16x16x32_bf16 v[32:35], v[242:245], v[190:193], v[32:35]
	v_mfma_f32_16x16x32_bf16 v[24:27], v[234:237], v[218:221], v[24:27]
	v_mfma_f32_16x16x32_bf16 v[16:19], v[242:245], v[218:221], v[16:19]
	v_mfma_f32_16x16x32_bf16 v[8:11], v[234:237], v[226:229], v[8:11]
	v_mfma_f32_16x16x32_bf16 v[0:3], v[242:245], v[226:229], v[0:3]
	s_setprio 0
	s_add_i32 s46, s46, 2
	s_add_u32 s20, s20, 0x100
	s_addc_u32 s21, s21, 0
	s_add_u32 s44, s44, 0x100
	s_addc_u32 s45, s45, 0
	s_cmp_gt_u32 s46, 29
	s_barrier
	s_cbranch_scc0 .LBB0_755
	v_lshl_add_u32 v186, s4, 8, v149
	v_ashrrev_i32_e32 v187, 31, v186
	v_lshlrev_b64 v[146:147], 5, v[186:187]
	v_lshl_add_u64 v[146:147], s[8:9], 0, v[146:147]
	v_add_co_u32_e32 v158, vcc, 0x1000, v146
	global_load_dwordx4 v[218:221], v[146:147], off
	global_load_dwordx4 v[222:225], v[146:147], off offset:16
	v_addc_co_u32_e32 v159, vcc, 0, v147, vcc
	global_load_dwordx4 v[174:177], v[146:147], off offset:512
	global_load_dwordx4 v[230:233], v[146:147], off offset:528
	global_load_dwordx4 v[234:237], v[146:147], off offset:1024
	global_load_dwordx4 v[238:241], v[146:147], off offset:1040
	global_load_dwordx4 v[242:245], v[146:147], off offset:1536
	global_load_dwordx4 v[246:249], v[146:147], off offset:1552
	global_load_dwordx4 v[190:193], v[158:159], off
	global_load_dwordx4 v[194:197], v[158:159], off offset:16
	global_load_dwordx4 v[214:217], v[158:159], off offset:512
	global_load_dwordx4 v[132:135], v[158:159], off offset:528
	global_load_dwordx4 v[150:153], v[158:159], off offset:1024
	global_load_dwordx4 v[128:131], v[158:159], off offset:1040
	global_load_dwordx4 v[226:229], v[158:159], off offset:1536
	global_load_dwordx4 v[180:183], v[158:159], off offset:1552
	s_mov_b32 s12, 0x3a000000
	s_mov_b64 s[22:23], s[18:19]
	s_mov_b64 s[20:21], s[16:17]
	s_movk_i32 s11, 0x2c00
	v_readlane_b32 s4, v250, 11
	v_readlane_b32 s5, v250, 12
	s_waitcnt vmcnt(14)
	v_add_f32_e32 v218, v218, v219
	v_add_f32_e32 v220, v220, v221
	v_add_f32_e32 v222, v222, v223
	v_add_f32_e32 v224, v224, v225
	v_add_f32_e32 v218, v218, v220
	v_add_f32_e32 v218, v218, v222
	v_add_f32_e32 v218, v218, v224
	v_fmamk_f32 v218, v218, 0x3a000000, v199
	v_rsq_f32_e32 v184, v218
	s_waitcnt vmcnt(12)
	v_add_f32_e32 v174, v174, v175
	v_add_f32_e32 v176, v176, v177
	v_add_f32_e32 v230, v230, v231
	v_add_f32_e32 v232, v232, v233
	v_add_f32_e32 v174, v174, v176
	v_add_f32_e32 v174, v174, v230
	v_add_f32_e32 v174, v174, v232
	v_fmamk_f32 v174, v174, 0x3a000000, v199
	v_rsq_f32_e32 v176, v174
	v_pk_mul_f32 v[124:125], v[124:125], v[184:185] op_sel_hi:[1,0]
	v_pk_mul_f32 v[120:121], v[120:121], v[184:185] op_sel_hi:[1,0]
	v_pk_mul_f32 v[122:123], v[122:123], v[184:185] op_sel_hi:[1,0]
	v_pk_mul_f32 v[116:117], v[116:117], v[184:185] op_sel_hi:[1,0]
	v_pk_mul_f32 v[112:113], v[112:113], v[184:185] op_sel_hi:[1,0]
	v_pk_mul_f32 v[114:115], v[114:115], v[184:185] op_sel_hi:[1,0]
	s_waitcnt vmcnt(10)
	v_add_f32_e32 v234, v234, v235
	v_add_f32_e32 v236, v236, v237
	v_add_f32_e32 v238, v238, v239
	v_add_f32_e32 v240, v240, v241
	v_add_f32_e32 v234, v234, v236
	v_add_f32_e32 v234, v234, v238
	v_add_f32_e32 v234, v234, v240
	v_fmamk_f32 v234, v234, 0x3a000000, v199
	v_rsq_f32_e32 v178, v234
	v_pk_mul_f32 v[108:109], v[108:109], v[176:177] op_sel_hi:[1,0]
	v_pk_mul_f32 v[104:105], v[104:105], v[176:177] op_sel_hi:[1,0]
	v_pk_mul_f32 v[106:107], v[106:107], v[176:177] op_sel_hi:[1,0]
	v_pk_mul_f32 v[100:101], v[100:101], v[176:177] op_sel_hi:[1,0]
	v_pk_mul_f32 v[96:97], v[96:97], v[176:177] op_sel_hi:[1,0]
	v_pk_mul_f32 v[98:99], v[98:99], v[176:177] op_sel_hi:[1,0]
	s_waitcnt vmcnt(8)
; DEV float siluf(float x) { return x * __builtin_amdgcn_rcpf(1.0f + __builtin_amdgcn_exp2f(x * -1.4426950408889634f)); }
; DEV bf16x8 pack8(f32x4 a, f32x4 b) { u32x4 w; w.x = cvt_pk_bf16(a[0], a[1]); w.y = cvt_pk_bf16(a[2], a[3]); w.z = cvt_pk_bf16(b[0], b[1]); w.w = cvt_pk_bf16(b[2], b[3]); return __builtin_bit_cast(bf16x8, w); }
;     DEV void operator()(AccRef acc, const pg8::Unit& u, int wr, int wc, int fr, int fq) const { store_bf16_tile<0, false>(acc, O, ld, u.pm * 256 + wr * 64 + fr, u.pn * 256 + wc * 32 + 4 * fq, ss); }
; DEV float rowscale(const float* ss, int row) { const f32x4 a = *(const f32x4*)(ss + (size_t)row * 8), b = *(const f32x4*)(ss + (size_t)row * 8 + 4);
;     return rsqrtf(((a[0] + a[1]) + (a[2] + a[3]) + (b[0] + b[1]) + (b[2] + b[3])) * (1.0f / 2048.0f) + EPS); }
;     DEV void operator()(AccRef acc, const pg8::Unit& u, int wr, int wc, int fr, int fq) const {
;         const int row0 = u.pm * 256 + wr * 64 + fr, col0 = u.pn * 128 + wc * 32 + 8 * fq;
;         float rsv[2][4];
; #pragma unroll
;         for (int ai = 0; ai < 2; ++ai)
; #pragma unroll
;             for (int m = 0; m < 4; ++m) rsv[ai][m] = rowscale(ss, row0 + ai * 128 + m * 16);
; #pragma unroll
;         for (int ai = 0; ai < 2; ++ai)
; #pragma unroll
;             for (int m = 0; m < 4; ++m) { u16* rowp = O + (size_t)(row0 + ai * 128 + m * 16) * 5632 + col0; const float rs = rsv[ai][m]; f32x4 r[2];
; #pragma unroll
;                 for (int n = 0; n < 2; ++n) { const f32x4 g = acc[ai][0][m][n] * rs, uu = acc[ai][1][m][n] * rs;
; #pragma unroll
;                     for (int e = 0; e < 4; ++e) r[n][e] = siluf(g[e]) * uu[e]; }
;                 *(u32x4*)rowp = __builtin_bit_cast(u32x4, pack8(r[0], r[1])); }
	v_add_f32_e32 v242, v242, v243
	v_add_f32_e32 v244, v244, v245
	v_add_f32_e32 v246, v246, v247
	v_add_f32_e32 v248, v248, v249
	v_add_f32_e32 v242, v242, v244
	v_add_f32_e32 v242, v242, v246
	v_add_f32_e32 v242, v242, v248
	v_fmamk_f32 v242, v242, 0x3a000000, v199
	v_rsq_f32_e32 v154, v242
	v_pk_mul_f32 v[92:93], v[92:93], v[178:179] op_sel_hi:[1,0]
	v_pk_mul_f32 v[88:89], v[88:89], v[178:179] op_sel_hi:[1,0]
	v_pk_mul_f32 v[90:91], v[90:91], v[178:179] op_sel_hi:[1,0]
	v_pk_mul_f32 v[84:85], v[84:85], v[178:179] op_sel_hi:[1,0]
	v_pk_mul_f32 v[80:81], v[80:81], v[178:179] op_sel_hi:[1,0]
	v_pk_mul_f32 v[82:83], v[82:83], v[178:179] op_sel_hi:[1,0]
	s_waitcnt vmcnt(6)
	v_add_f32_e32 v190, v190, v191
	v_add_f32_e32 v192, v192, v193
	v_add_f32_e32 v194, v194, v195
	v_add_f32_e32 v196, v196, v197
	v_add_f32_e32 v190, v190, v192
	v_add_f32_e32 v190, v190, v194
	v_add_f32_e32 v190, v190, v196
	v_fmamk_f32 v190, v190, 0x3a000000, v199
	v_rsq_f32_e32 v156, v190
	v_pk_mul_f32 v[76:77], v[76:77], v[154:155] op_sel_hi:[1,0]
	v_pk_mul_f32 v[72:73], v[72:73], v[154:155] op_sel_hi:[1,0]
	v_pk_mul_f32 v[74:75], v[74:75], v[154:155] op_sel_hi:[1,0]
	v_pk_mul_f32 v[68:69], v[68:69], v[154:155] op_sel_hi:[1,0]
	v_pk_mul_f32 v[64:65], v[64:65], v[154:155] op_sel_hi:[1,0]
	v_pk_mul_f32 v[66:67], v[66:67], v[154:155] op_sel_hi:[1,0]
	s_waitcnt vmcnt(4)
	v_add_f32_e32 v214, v214, v215
	v_add_f32_e32 v216, v216, v217
	v_add_f32_e32 v132, v132, v133
	v_add_f32_e32 v134, v134, v135
	v_add_f32_e32 v214, v214, v216
	v_add_f32_e32 v214, v214, v132
	v_add_f32_e32 v214, v214, v134
	v_fmamk_f32 v214, v214, 0x3a000000, v199
	v_rsq_f32_e32 v148, v214
	v_pk_mul_f32 v[60:61], v[60:61], v[156:157] op_sel_hi:[1,0]
	v_pk_mul_f32 v[56:57], v[56:57], v[156:157] op_sel_hi:[1,0]
	v_pk_mul_f32 v[58:59], v[58:59], v[156:157] op_sel_hi:[1,0]
	v_pk_mul_f32 v[52:53], v[52:53], v[156:157] op_sel_hi:[1,0]
	v_pk_mul_f32 v[48:49], v[48:49], v[156:157] op_sel_hi:[1,0]
	v_pk_mul_f32 v[50:51], v[50:51], v[156:157] op_sel_hi:[1,0]
	s_waitcnt vmcnt(2)
	v_add_f32_e32 v150, v150, v151
	v_add_f32_e32 v152, v152, v153
	v_add_f32_e32 v128, v128, v129
	v_add_f32_e32 v130, v130, v131
	v_add_f32_e32 v150, v150, v152
	v_add_f32_e32 v150, v150, v128
	v_add_f32_e32 v150, v150, v130
	v_fmamk_f32 v150, v150, 0x3a000000, v199
	v_rsq_f32_e32 v130, v150
	v_pk_mul_f32 v[44:45], v[44:45], v[148:149] op_sel_hi:[1,0]
	v_pk_mul_f32 v[40:41], v[40:41], v[148:149] op_sel_hi:[1,0]
	v_pk_mul_f32 v[42:43], v[42:43], v[148:149] op_sel_hi:[1,0]
	v_pk_mul_f32 v[36:37], v[36:37], v[148:149] op_sel_hi:[1,0]
	v_pk_mul_f32 v[32:33], v[32:33], v[148:149] op_sel_hi:[1,0]
	v_pk_mul_f32 v[34:35], v[34:35], v[148:149] op_sel_hi:[1,0]
	s_waitcnt vmcnt(0)
	v_add_f32_e32 v226, v226, v227
	v_add_f32_e32 v228, v228, v229
	v_add_f32_e32 v180, v180, v181
	v_add_f32_e32 v182, v182, v183
	v_add_f32_e32 v226, v226, v228
	v_add_f32_e32 v226, v226, v180
	v_add_f32_e32 v226, v226, v182
	v_fmamk_f32 v226, v226, 0x3a000000, v199
	v_rsq_f32_e32 v128, v226
	v_pk_mul_f32 v[28:29], v[28:29], v[130:131] op_sel_hi:[1,0]
	v_or_b32_e32 v182, 16, v186
	v_ashrrev_i32_e32 v183, 31, v182
	v_or_b32_e32 v180, 32, v186
	v_ashrrev_i32_e32 v181, 31, v180
	v_or_b32_e32 v174, 48, v186
	v_ashrrev_i32_e32 v175, 31, v174
	v_add_u32_e32 v158, 0x80, v186
	v_ashrrev_i32_e32 v159, 31, v158
	v_add_u32_e32 v152, 0x90, v186
	v_ashrrev_i32_e32 v153, 31, v152
	v_add_u32_e32 v150, 0xa0, v186
	v_ashrrev_i32_e32 v151, 31, v150
	v_add_u32_e32 v146, 0xb0, v186
	v_ashrrev_i32_e32 v147, 31, v146
	v_lshl_or_b32 v134, s42, 7, v157
	v_ashrrev_i32_e32 v135, 31, v134
	s_mov_b32 s42, s10
	v_mul_f32_e32 v129, 0xbfb8aa3b, v124
	v_exp_f32_e32 v129, v129
	v_mov_b64_e32 v[132:133], s[4:5]
	v_mad_i64_i32 v[186:187], s[4:5], v186, s11, v[132:133]
	v_add_f32_e32 v129, 1.0, v129
	v_rcp_f32_e32 v188, v129
	v_mul_f32_e32 v129, 0xbfb8aa3b, v125
	v_exp_f32_e32 v129, v129
	v_pk_mul_f32 v[24:25], v[24:25], v[130:131] op_sel_hi:[1,0]
	v_pk_mul_f32 v[26:27], v[26:27], v[130:131] op_sel_hi:[1,0]
	v_pk_mul_f32 v[20:21], v[20:21], v[130:131] op_sel_hi:[1,0]
	v_add_f32_e32 v129, 1.0, v129
	v_rcp_f32_e32 v189, v129
	v_pk_mul_f32 v[16:17], v[16:17], v[130:131] op_sel_hi:[1,0]
	v_pk_mul_f32 v[18:19], v[18:19], v[130:131] op_sel_hi:[1,0]
	v_pk_mul_f32 v[12:13], v[12:13], v[128:129] op_sel_hi:[1,0]
	v_pk_mul_f32 v[124:125], v[124:125], v[188:189]
	v_pk_mul_f32 v[8:9], v[8:9], v[128:129] op_sel_hi:[1,0]
	v_pk_mul_f32 v[120:121], v[120:121], v[124:125]
	v_pk_mul_f32 v[124:125], v[126:127], v[184:185] op_sel_hi:[1,0]
	v_pk_mul_f32 v[10:11], v[10:11], v[128:129] op_sel_hi:[1,0]
	v_mul_f32_e32 v126, 0xbfb8aa3b, v124
	v_mul_f32_e32 v127, 0xbfb8aa3b, v125
	v_exp_f32_e32 v126, v126
	v_exp_f32_e32 v127, v127
	v_pk_mul_f32 v[4:5], v[4:5], v[128:129] op_sel_hi:[1,0]
	v_pk_mul_f32 v[0:1], v[0:1], v[128:129] op_sel_hi:[1,0]
	v_add_f32_e32 v126, 1.0, v126
	v_add_f32_e32 v127, 1.0, v127
	v_rcp_f32_e32 v126, v126
	v_rcp_f32_e32 v127, v127
	v_pk_mul_f32 v[2:3], v[2:3], v[128:129] op_sel_hi:[1,0]
	s_and_b64 vcc, exec, s[0:1]
	v_pk_mul_f32 v[124:125], v[124:125], v[126:127]
	s_nop 0
	v_pk_mul_f32 v[122:123], v[122:123], v[124:125]
	v_mul_f32_e32 v124, 0xbfb8aa3b, v116
	v_mul_f32_e32 v125, 0xbfb8aa3b, v117
	v_exp_f32_e32 v124, v124
	v_exp_f32_e32 v125, v125
	v_add_f32_e32 v124, 1.0, v124
	v_add_f32_e32 v125, 1.0, v125
	v_rcp_f32_e32 v124, v124
	v_rcp_f32_e32 v125, v125
	s_nop 0
	v_pk_mul_f32 v[116:117], v[116:117], v[124:125]
	s_nop 0
	v_pk_mul_f32 v[116:117], v[112:113], v[116:117]
	v_pk_mul_f32 v[112:113], v[118:119], v[184:185] op_sel_hi:[1,0]
	v_cvt_pk_bf16_f32 v116, v116, v117
	v_mul_f32_e32 v118, 0xbfb8aa3b, v112
; DEV float siluf(float x) { return x * __builtin_amdgcn_rcpf(1.0f + __builtin_amdgcn_exp2f(x * -1.4426950408889634f)); }
; DEV bf16x8 pack8(f32x4 a, f32x4 b) { u32x4 w; w.x = cvt_pk_bf16(a[0], a[1]); w.y = cvt_pk_bf16(a[2], a[3]); w.z = cvt_pk_bf16(b[0], b[1]); w.w = cvt_pk_bf16(b[2], b[3]); return __builtin_bit_cast(bf16x8, w); }
;     DEV void operator()(AccRef acc, const pg8::Unit& u, int wr, int wc, int fr, int fq) const {
;     ...
;             for (int m = 0; m < 4; ++m) { u16* rowp = O + (size_t)(row0 + ai * 128 + m * 16) * 5632 + col0; const float rs = rsv[ai][m]; f32x4 r[2];
; #pragma unroll
;                 for (int n = 0; n < 2; ++n) { const f32x4 g = acc[ai][0][m][n] * rs, uu = acc[ai][1][m][n] * rs;
; #pragma unroll
;                     for (int e = 0; e < 4; ++e) r[n][e] = siluf(g[e]) * uu[e]; }
;                 *(u32x4*)rowp = __builtin_bit_cast(u32x4, pack8(r[0], r[1])); }
	v_mul_f32_e32 v119, 0xbfb8aa3b, v113
	v_exp_f32_e32 v118, v118
	v_exp_f32_e32 v119, v119
	v_add_f32_e32 v118, 1.0, v118
	v_add_f32_e32 v119, 1.0, v119
	v_rcp_f32_e32 v118, v118
	v_rcp_f32_e32 v119, v119
	s_nop 0
	v_pk_mul_f32 v[112:113], v[112:113], v[118:119]
	s_nop 0
	v_pk_mul_f32 v[118:119], v[114:115], v[112:113]
	v_lshlrev_b64 v[112:113], 1, v[134:135]
	v_lshl_add_u64 v[124:125], v[186:187], 0, v[112:113]
	v_cvt_pk_bf16_f32 v114, v120, v121
	v_cvt_pk_bf16_f32 v115, v122, v123
	v_cvt_pk_bf16_f32 v117, v118, v119
	global_store_dwordx4 v[124:125], v[114:117], off
	s_nop 1
	v_mul_f32_e32 v116, 0xbfb8aa3b, v108
	v_mul_f32_e32 v117, 0xbfb8aa3b, v109
	v_exp_f32_e32 v116, v116
	v_exp_f32_e32 v117, v117
	v_mad_i64_i32 v[114:115], s[4:5], v182, s11, v[132:133]
	v_add_f32_e32 v116, 1.0, v116
	v_add_f32_e32 v117, 1.0, v117
	v_rcp_f32_e32 v116, v116
	v_rcp_f32_e32 v117, v117
	s_nop 0
	v_pk_mul_f32 v[108:109], v[108:109], v[116:117]
	s_nop 0
	v_pk_mul_f32 v[104:105], v[104:105], v[108:109]
	v_pk_mul_f32 v[108:109], v[110:111], v[176:177] op_sel_hi:[1,0]
	s_nop 0
	v_mul_f32_e32 v110, 0xbfb8aa3b, v108
	v_mul_f32_e32 v111, 0xbfb8aa3b, v109
	v_exp_f32_e32 v110, v110
	v_exp_f32_e32 v111, v111
	v_add_f32_e32 v110, 1.0, v110
	v_add_f32_e32 v111, 1.0, v111
	v_rcp_f32_e32 v110, v110
	v_rcp_f32_e32 v111, v111
	s_nop 0
	v_pk_mul_f32 v[108:109], v[108:109], v[110:111]
	s_nop 0
	v_pk_mul_f32 v[106:107], v[106:107], v[108:109]
	v_mul_f32_e32 v108, 0xbfb8aa3b, v100
	v_mul_f32_e32 v109, 0xbfb8aa3b, v101
	v_exp_f32_e32 v108, v108
	v_exp_f32_e32 v109, v109
	v_add_f32_e32 v108, 1.0, v108
	v_add_f32_e32 v109, 1.0, v109
	v_rcp_f32_e32 v108, v108
	v_rcp_f32_e32 v109, v109
	s_nop 0
	v_pk_mul_f32 v[100:101], v[100:101], v[108:109]
	s_nop 0
	v_pk_mul_f32 v[100:101], v[96:97], v[100:101]
	v_pk_mul_f32 v[96:97], v[102:103], v[176:177] op_sel_hi:[1,0]
	v_lshl_add_u64 v[108:109], v[114:115], 0, v[112:113]
	v_mul_f32_e32 v102, 0xbfb8aa3b, v96
	v_mul_f32_e32 v103, 0xbfb8aa3b, v97
	v_exp_f32_e32 v102, v102
	v_exp_f32_e32 v103, v103
	v_add_f32_e32 v102, 1.0, v102
	v_add_f32_e32 v103, 1.0, v103
	v_rcp_f32_e32 v102, v102
	v_rcp_f32_e32 v103, v103
	s_nop 0
	v_pk_mul_f32 v[96:97], v[96:97], v[102:103]
	s_nop 0
	v_pk_mul_f32 v[102:103], v[98:99], v[96:97]
	v_cvt_pk_bf16_f32 v96, v104, v105
	v_cvt_pk_bf16_f32 v97, v106, v107
	v_cvt_pk_bf16_f32 v98, v100, v101
	v_cvt_pk_bf16_f32 v99, v102, v103
	global_store_dwordx4 v[108:109], v[96:99], off
	s_nop 1
	v_mul_f32_e32 v98, 0xbfb8aa3b, v92
	v_mul_f32_e32 v99, 0xbfb8aa3b, v93
	v_exp_f32_e32 v98, v98
	v_exp_f32_e32 v99, v99
	v_mad_i64_i32 v[96:97], s[4:5], v180, s11, v[132:133]
	v_add_f32_e32 v98, 1.0, v98
	v_add_f32_e32 v99, 1.0, v99
	v_rcp_f32_e32 v98, v98
	v_rcp_f32_e32 v99, v99
	s_nop 0
	v_pk_mul_f32 v[92:93], v[92:93], v[98:99]
	s_nop 0
	v_pk_mul_f32 v[88:89], v[88:89], v[92:93]
	v_pk_mul_f32 v[92:93], v[94:95], v[178:179] op_sel_hi:[1,0]
	s_nop 0
	v_mul_f32_e32 v94, 0xbfb8aa3b, v92
	v_mul_f32_e32 v95, 0xbfb8aa3b, v93
	v_exp_f32_e32 v94, v94
	v_exp_f32_e32 v95, v95
	v_add_f32_e32 v94, 1.0, v94
	v_add_f32_e32 v95, 1.0, v95
	v_rcp_f32_e32 v94, v94
	v_rcp_f32_e32 v95, v95
	s_nop 0
	v_pk_mul_f32 v[92:93], v[92:93], v[94:95]
	s_nop 0
	v_pk_mul_f32 v[90:91], v[90:91], v[92:93]
	v_mul_f32_e32 v92, 0xbfb8aa3b, v84
	v_mul_f32_e32 v93, 0xbfb8aa3b, v85
	v_exp_f32_e32 v92, v92
	v_exp_f32_e32 v93, v93
	v_add_f32_e32 v92, 1.0, v92
	v_add_f32_e32 v93, 1.0, v93
	v_rcp_f32_e32 v92, v92
	v_rcp_f32_e32 v93, v93
	s_nop 0
	v_pk_mul_f32 v[84:85], v[84:85], v[92:93]
	s_nop 0
	v_pk_mul_f32 v[84:85], v[80:81], v[84:85]
	v_pk_mul_f32 v[80:81], v[86:87], v[178:179] op_sel_hi:[1,0]
	v_lshl_add_u64 v[92:93], v[96:97], 0, v[112:113]
	v_mul_f32_e32 v86, 0xbfb8aa3b, v80
	v_mul_f32_e32 v87, 0xbfb8aa3b, v81
	v_exp_f32_e32 v86, v86
	v_exp_f32_e32 v87, v87
	v_add_f32_e32 v86, 1.0, v86
	v_add_f32_e32 v87, 1.0, v87
	v_rcp_f32_e32 v86, v86
	v_rcp_f32_e32 v87, v87
	s_nop 0
	v_pk_mul_f32 v[80:81], v[80:81], v[86:87]
	s_nop 0
	v_pk_mul_f32 v[86:87], v[82:83], v[80:81]
	v_cvt_pk_bf16_f32 v80, v88, v89
	v_cvt_pk_bf16_f32 v81, v90, v91
	v_cvt_pk_bf16_f32 v82, v84, v85
	v_cvt_pk_bf16_f32 v83, v86, v87
	global_store_dwordx4 v[92:93], v[80:83], off
	s_nop 1
	v_mul_f32_e32 v82, 0xbfb8aa3b, v76
	v_mul_f32_e32 v83, 0xbfb8aa3b, v77
	v_exp_f32_e32 v82, v82
	v_exp_f32_e32 v83, v83
	v_mad_i64_i32 v[80:81], s[4:5], v174, s11, v[132:133]
	v_add_f32_e32 v82, 1.0, v82
	v_add_f32_e32 v83, 1.0, v83
	v_rcp_f32_e32 v82, v82
	v_rcp_f32_e32 v83, v83
	s_nop 0
	v_pk_mul_f32 v[76:77], v[76:77], v[82:83]
	s_nop 0
	v_pk_mul_f32 v[72:73], v[72:73], v[76:77]
	v_pk_mul_f32 v[76:77], v[78:79], v[154:155] op_sel_hi:[1,0]
	s_nop 0
	v_mul_f32_e32 v78, 0xbfb8aa3b, v76
	v_mul_f32_e32 v79, 0xbfb8aa3b, v77
	v_exp_f32_e32 v78, v78
	v_exp_f32_e32 v79, v79
	v_add_f32_e32 v78, 1.0, v78
	v_add_f32_e32 v79, 1.0, v79
	v_rcp_f32_e32 v78, v78
	v_rcp_f32_e32 v79, v79
	s_nop 0
	v_pk_mul_f32 v[76:77], v[76:77], v[78:79]
	s_nop 0
	v_pk_mul_f32 v[74:75], v[74:75], v[76:77]
	v_mul_f32_e32 v76, 0xbfb8aa3b, v68
	v_mul_f32_e32 v77, 0xbfb8aa3b, v69
	v_exp_f32_e32 v76, v76
	v_exp_f32_e32 v77, v77
	v_add_f32_e32 v76, 1.0, v76
	v_add_f32_e32 v77, 1.0, v77
	v_rcp_f32_e32 v76, v76
	v_rcp_f32_e32 v77, v77
	s_nop 0
	v_pk_mul_f32 v[68:69], v[68:69], v[76:77]
	s_nop 0
	v_pk_mul_f32 v[68:69], v[64:65], v[68:69]
	v_pk_mul_f32 v[64:65], v[70:71], v[154:155] op_sel_hi:[1,0]
	v_lshl_add_u64 v[76:77], v[80:81], 0, v[112:113]
	v_mul_f32_e32 v70, 0xbfb8aa3b, v64
	v_mul_f32_e32 v71, 0xbfb8aa3b, v65
	v_exp_f32_e32 v70, v70
	v_exp_f32_e32 v71, v71
	v_add_f32_e32 v70, 1.0, v70
	v_add_f32_e32 v71, 1.0, v71
	v_rcp_f32_e32 v70, v70
	v_rcp_f32_e32 v71, v71
; DEV float siluf(float x) { return x * __builtin_amdgcn_rcpf(1.0f + __builtin_amdgcn_exp2f(x * -1.4426950408889634f)); }
; DEV bf16x8 pack8(f32x4 a, f32x4 b) { u32x4 w; w.x = cvt_pk_bf16(a[0], a[1]); w.y = cvt_pk_bf16(a[2], a[3]); w.z = cvt_pk_bf16(b[0], b[1]); w.w = cvt_pk_bf16(b[2], b[3]); return __builtin_bit_cast(bf16x8, w); }
;     DEV void operator()(AccRef acc, const pg8::Unit& u, int wr, int wc, int fr, int fq) const {
;     ...
;             for (int m = 0; m < 4; ++m) { u16* rowp = O + (size_t)(row0 + ai * 128 + m * 16) * 5632 + col0; const float rs = rsv[ai][m]; f32x4 r[2];
; #pragma unroll
;                 for (int n = 0; n < 2; ++n) { const f32x4 g = acc[ai][0][m][n] * rs, uu = acc[ai][1][m][n] * rs;
; #pragma unroll
;                     for (int e = 0; e < 4; ++e) r[n][e] = siluf(g[e]) * uu[e]; }
;                 *(u32x4*)rowp = __builtin_bit_cast(u32x4, pack8(r[0], r[1])); }
	s_nop 0
	v_pk_mul_f32 v[64:65], v[64:65], v[70:71]
	s_nop 0
	v_pk_mul_f32 v[70:71], v[66:67], v[64:65]
	v_cvt_pk_bf16_f32 v64, v72, v73
	v_cvt_pk_bf16_f32 v65, v74, v75
	v_cvt_pk_bf16_f32 v66, v68, v69
	v_cvt_pk_bf16_f32 v67, v70, v71
	global_store_dwordx4 v[76:77], v[64:67], off
	s_nop 1
	v_mul_f32_e32 v66, 0xbfb8aa3b, v60
	v_mul_f32_e32 v67, 0xbfb8aa3b, v61
	v_exp_f32_e32 v66, v66
	v_exp_f32_e32 v67, v67
	v_mad_i64_i32 v[64:65], s[4:5], v158, s11, v[132:133]
	v_add_f32_e32 v66, 1.0, v66
	v_add_f32_e32 v67, 1.0, v67
	v_rcp_f32_e32 v66, v66
	v_rcp_f32_e32 v67, v67
	s_nop 0
	v_pk_mul_f32 v[60:61], v[60:61], v[66:67]
	s_nop 0
	v_pk_mul_f32 v[56:57], v[56:57], v[60:61]
	v_pk_mul_f32 v[60:61], v[62:63], v[156:157] op_sel_hi:[1,0]
	s_nop 0
	v_mul_f32_e32 v62, 0xbfb8aa3b, v60
	v_mul_f32_e32 v63, 0xbfb8aa3b, v61
	v_exp_f32_e32 v62, v62
	v_exp_f32_e32 v63, v63
	v_add_f32_e32 v62, 1.0, v62
	v_add_f32_e32 v63, 1.0, v63
	v_rcp_f32_e32 v62, v62
	v_rcp_f32_e32 v63, v63
	s_nop 0
	v_pk_mul_f32 v[60:61], v[60:61], v[62:63]
	s_nop 0
	v_pk_mul_f32 v[58:59], v[58:59], v[60:61]
	v_mul_f32_e32 v60, 0xbfb8aa3b, v52
	v_mul_f32_e32 v61, 0xbfb8aa3b, v53
	v_exp_f32_e32 v60, v60
	v_exp_f32_e32 v61, v61
	v_add_f32_e32 v60, 1.0, v60
	v_add_f32_e32 v61, 1.0, v61
	v_rcp_f32_e32 v60, v60
	v_rcp_f32_e32 v61, v61
	s_nop 0
	v_pk_mul_f32 v[52:53], v[52:53], v[60:61]
	s_nop 0
	v_pk_mul_f32 v[52:53], v[48:49], v[52:53]
	v_pk_mul_f32 v[48:49], v[54:55], v[156:157] op_sel_hi:[1,0]
	v_lshl_add_u64 v[60:61], v[64:65], 0, v[112:113]
	v_mul_f32_e32 v54, 0xbfb8aa3b, v48
	v_mul_f32_e32 v55, 0xbfb8aa3b, v49
	v_exp_f32_e32 v54, v54
	v_exp_f32_e32 v55, v55
	v_add_f32_e32 v54, 1.0, v54
	v_add_f32_e32 v55, 1.0, v55
	v_rcp_f32_e32 v54, v54
	v_rcp_f32_e32 v55, v55
	s_nop 0
	v_pk_mul_f32 v[48:49], v[48:49], v[54:55]
	s_nop 0
	v_pk_mul_f32 v[54:55], v[50:51], v[48:49]
	v_cvt_pk_bf16_f32 v48, v56, v57
	v_cvt_pk_bf16_f32 v49, v58, v59
	v_cvt_pk_bf16_f32 v50, v52, v53
	v_cvt_pk_bf16_f32 v51, v54, v55
	global_store_dwordx4 v[60:61], v[48:51], off
	s_nop 1
	v_mul_f32_e32 v50, 0xbfb8aa3b, v44
	v_mul_f32_e32 v51, 0xbfb8aa3b, v45
	v_exp_f32_e32 v50, v50
	v_exp_f32_e32 v51, v51
	v_mad_i64_i32 v[48:49], s[4:5], v152, s11, v[132:133]
	v_add_f32_e32 v50, 1.0, v50
	v_add_f32_e32 v51, 1.0, v51
	v_rcp_f32_e32 v50, v50
	v_rcp_f32_e32 v51, v51
	s_nop 0
	v_pk_mul_f32 v[44:45], v[44:45], v[50:51]
	s_nop 0
	v_pk_mul_f32 v[40:41], v[40:41], v[44:45]
	v_pk_mul_f32 v[44:45], v[46:47], v[148:149] op_sel_hi:[1,0]
	s_nop 0
	v_mul_f32_e32 v46, 0xbfb8aa3b, v44
	v_mul_f32_e32 v47, 0xbfb8aa3b, v45
	v_exp_f32_e32 v46, v46
	v_exp_f32_e32 v47, v47
	v_add_f32_e32 v46, 1.0, v46
	v_add_f32_e32 v47, 1.0, v47
	v_rcp_f32_e32 v46, v46
	v_rcp_f32_e32 v47, v47
	s_nop 0
	v_pk_mul_f32 v[44:45], v[44:45], v[46:47]
	s_nop 0
	v_pk_mul_f32 v[42:43], v[42:43], v[44:45]
	v_mul_f32_e32 v44, 0xbfb8aa3b, v36
	v_mul_f32_e32 v45, 0xbfb8aa3b, v37
	v_exp_f32_e32 v44, v44
	v_exp_f32_e32 v45, v45
	v_add_f32_e32 v44, 1.0, v44
	v_add_f32_e32 v45, 1.0, v45
	v_rcp_f32_e32 v44, v44
	v_rcp_f32_e32 v45, v45
	s_nop 0
	v_pk_mul_f32 v[36:37], v[36:37], v[44:45]
	s_nop 0
	v_pk_mul_f32 v[36:37], v[32:33], v[36:37]
	v_pk_mul_f32 v[32:33], v[38:39], v[148:149] op_sel_hi:[1,0]
	v_lshl_add_u64 v[44:45], v[48:49], 0, v[112:113]
	v_mul_f32_e32 v38, 0xbfb8aa3b, v32
	v_mul_f32_e32 v39, 0xbfb8aa3b, v33
	v_exp_f32_e32 v38, v38
	v_exp_f32_e32 v39, v39
	v_add_f32_e32 v38, 1.0, v38
	v_add_f32_e32 v39, 1.0, v39
	v_rcp_f32_e32 v38, v38
	v_rcp_f32_e32 v39, v39
	s_nop 0
	v_pk_mul_f32 v[32:33], v[32:33], v[38:39]
	s_nop 0
	v_pk_mul_f32 v[38:39], v[34:35], v[32:33]
	v_cvt_pk_bf16_f32 v32, v40, v41
	v_cvt_pk_bf16_f32 v33, v42, v43
; DEV float siluf(float x) { return x * __builtin_amdgcn_rcpf(1.0f + __builtin_amdgcn_exp2f(x * -1.4426950408889634f)); }
; DEV bf16x8 pack8(f32x4 a, f32x4 b) { u32x4 w; w.x = cvt_pk_bf16(a[0], a[1]); w.y = cvt_pk_bf16(a[2], a[3]); w.z = cvt_pk_bf16(b[0], b[1]); w.w = cvt_pk_bf16(b[2], b[3]); return __builtin_bit_cast(bf16x8, w); }
; #define PG8_WAIT_V(n) asm volatile("s_waitcnt vmcnt(" #n ")" ::: "memory")
; #define PG8_BAR __builtin_amdgcn_s_barrier()
; template <class Epi>
; DEV void gemm_phase(LAS unsigned char* lds, const Gemm g, const StaticOrder& S, const Epi& E) {
;     ...
;     PG8_WAIT_V(0);
;     if (wr == 0) PG8_BAR;
;     PG8_BAR;
;     DEV void operator()(AccRef acc, const pg8::Unit& u, int wr, int wc, int fr, int fq) const {
;     ...
;             for (int m = 0; m < 4; ++m) { u16* rowp = O + (size_t)(row0 + ai * 128 + m * 16) * 5632 + col0; const float rs = rsv[ai][m]; f32x4 r[2];
; #pragma unroll
;                 for (int n = 0; n < 2; ++n) { const f32x4 g = acc[ai][0][m][n] * rs, uu = acc[ai][1][m][n] * rs;
; #pragma unroll
;                     for (int e = 0; e < 4; ++e) r[n][e] = siluf(g[e]) * uu[e]; }
;                 *(u32x4*)rowp = __builtin_bit_cast(u32x4, pack8(r[0], r[1])); }
	v_cvt_pk_bf16_f32 v34, v36, v37
	v_cvt_pk_bf16_f32 v35, v38, v39
	global_store_dwordx4 v[44:45], v[32:35], off
	s_nop 1
	v_mul_f32_e32 v34, 0xbfb8aa3b, v28
	v_mul_f32_e32 v35, 0xbfb8aa3b, v29
	v_exp_f32_e32 v34, v34
	v_exp_f32_e32 v35, v35
	v_mad_i64_i32 v[32:33], s[4:5], v150, s11, v[132:133]
	v_add_f32_e32 v34, 1.0, v34
	v_add_f32_e32 v35, 1.0, v35
	v_rcp_f32_e32 v34, v34
	v_rcp_f32_e32 v35, v35
	s_nop 0
	v_pk_mul_f32 v[28:29], v[28:29], v[34:35]
	s_nop 0
	v_pk_mul_f32 v[24:25], v[24:25], v[28:29]
	v_pk_mul_f32 v[28:29], v[30:31], v[130:131] op_sel_hi:[1,0]
	s_nop 0
	v_mul_f32_e32 v30, 0xbfb8aa3b, v28
	v_mul_f32_e32 v31, 0xbfb8aa3b, v29
	v_exp_f32_e32 v30, v30
	v_exp_f32_e32 v31, v31
	v_add_f32_e32 v30, 1.0, v30
	v_add_f32_e32 v31, 1.0, v31
	v_rcp_f32_e32 v30, v30
	v_rcp_f32_e32 v31, v31
	s_nop 0
	v_pk_mul_f32 v[28:29], v[28:29], v[30:31]
	s_nop 0
	v_pk_mul_f32 v[26:27], v[26:27], v[28:29]
	v_mul_f32_e32 v28, 0xbfb8aa3b, v20
	v_mul_f32_e32 v29, 0xbfb8aa3b, v21
	v_exp_f32_e32 v28, v28
	v_exp_f32_e32 v29, v29
	v_add_f32_e32 v28, 1.0, v28
	v_add_f32_e32 v29, 1.0, v29
	v_rcp_f32_e32 v28, v28
	v_rcp_f32_e32 v29, v29
	s_nop 0
	v_pk_mul_f32 v[20:21], v[20:21], v[28:29]
	s_nop 0
	v_pk_mul_f32 v[20:21], v[16:17], v[20:21]
	v_pk_mul_f32 v[16:17], v[22:23], v[130:131] op_sel_hi:[1,0]
	v_lshl_add_u64 v[28:29], v[32:33], 0, v[112:113]
	v_mul_f32_e32 v22, 0xbfb8aa3b, v16
	v_mul_f32_e32 v23, 0xbfb8aa3b, v17
	v_exp_f32_e32 v22, v22
	v_exp_f32_e32 v23, v23
	v_add_f32_e32 v22, 1.0, v22
	v_add_f32_e32 v23, 1.0, v23
	v_rcp_f32_e32 v22, v22
	v_rcp_f32_e32 v23, v23
	s_nop 0
	v_pk_mul_f32 v[16:17], v[16:17], v[22:23]
	s_nop 0
	v_pk_mul_f32 v[22:23], v[18:19], v[16:17]
	v_cvt_pk_bf16_f32 v16, v24, v25
	v_cvt_pk_bf16_f32 v17, v26, v27
	v_cvt_pk_bf16_f32 v18, v20, v21
	v_cvt_pk_bf16_f32 v19, v22, v23
	global_store_dwordx4 v[28:29], v[16:19], off
	s_nop 1
	v_mul_f32_e32 v18, 0xbfb8aa3b, v12
	v_mul_f32_e32 v19, 0xbfb8aa3b, v13
	v_exp_f32_e32 v18, v18
	v_exp_f32_e32 v19, v19
	v_mad_i64_i32 v[16:17], s[4:5], v146, s11, v[132:133]
	v_add_f32_e32 v18, 1.0, v18
	v_add_f32_e32 v19, 1.0, v19
	v_rcp_f32_e32 v18, v18
	v_rcp_f32_e32 v19, v19
	s_mov_b32 s4, s14
	v_pk_mul_f32 v[12:13], v[12:13], v[18:19]
	s_nop 0
	v_pk_mul_f32 v[8:9], v[8:9], v[12:13]
	v_pk_mul_f32 v[12:13], v[14:15], v[128:129] op_sel_hi:[1,0]
	s_nop 0
	v_mul_f32_e32 v14, 0xbfb8aa3b, v12
	v_mul_f32_e32 v15, 0xbfb8aa3b, v13
	v_exp_f32_e32 v14, v14
	v_exp_f32_e32 v15, v15
	v_add_f32_e32 v14, 1.0, v14
	v_add_f32_e32 v15, 1.0, v15
	v_rcp_f32_e32 v14, v14
	v_rcp_f32_e32 v15, v15
	s_nop 0
	v_pk_mul_f32 v[12:13], v[12:13], v[14:15]
	s_nop 0
	v_pk_mul_f32 v[10:11], v[10:11], v[12:13]
	v_mul_f32_e32 v12, 0xbfb8aa3b, v4
	v_mul_f32_e32 v13, 0xbfb8aa3b, v5
	v_exp_f32_e32 v12, v12
	v_exp_f32_e32 v13, v13
	v_add_f32_e32 v12, 1.0, v12
	v_add_f32_e32 v13, 1.0, v13
	v_rcp_f32_e32 v12, v12
	v_rcp_f32_e32 v13, v13
	s_nop 0
	v_pk_mul_f32 v[4:5], v[4:5], v[12:13]
	s_nop 0
	v_pk_mul_f32 v[4:5], v[0:1], v[4:5]
	v_pk_mul_f32 v[0:1], v[6:7], v[128:129] op_sel_hi:[1,0]
	v_lshl_add_u64 v[12:13], v[16:17], 0, v[112:113]
	v_mul_f32_e32 v6, 0xbfb8aa3b, v0
	v_mul_f32_e32 v7, 0xbfb8aa3b, v1
	v_exp_f32_e32 v6, v6
	v_exp_f32_e32 v7, v7
	v_add_f32_e32 v6, 1.0, v6
	v_add_f32_e32 v7, 1.0, v7
	v_rcp_f32_e32 v6, v6
	v_rcp_f32_e32 v7, v7
	s_nop 0
	v_pk_mul_f32 v[0:1], v[0:1], v[6:7]
	s_nop 0
	v_pk_mul_f32 v[6:7], v[2:3], v[0:1]
	v_cvt_pk_bf16_f32 v0, v8, v9
	v_cvt_pk_bf16_f32 v1, v10, v11
	v_cvt_pk_bf16_f32 v2, v4, v5
	v_cvt_pk_bf16_f32 v3, v6, v7
	global_store_dwordx4 v[12:13], v[0:3], off
	s_cbranch_vccz .LBB0_752
	s_waitcnt vmcnt(0)
	s_cmpk_gt_u32 s27, 0xff
	s_cbranch_scc1 .LBB0_759
	s_barrier
